# GEMM epilogues (conv+SiLU, HGRN gates, GLU): IEEE div sequences replaced by v_rcp_f32+v_mul_f32 (f32, ~1ulp)
# speedup vs baseline: 1.0162x; 1.0162x over previous
.LBB0_513:
	v_lshl_add_u64 v[10:11], v[6:7], 0, s[4:5]
	global_load_dwordx2 v[14:15], v[10:11], off
	s_waitcnt lgkmcnt(0)
	v_pk_mul_f32 v[12:13], v[4:5], v[8:9] op_sel:[0,1] op_sel_hi:[1,0]
	global_store_dwordx2 v[10:11], v[8:9], off
	v_pk_fma_f32 v[16:17], v[2:3], v[8:9], v[12:13] neg_lo:[0,0,1] neg_hi:[0,0,1]
	v_pk_fma_f32 v[8:9], v[2:3], v[8:9], v[12:13]
	s_add_u32 s4, s4, 0x800
	v_mov_b32_e32 v17, v9
	s_addc_u32 s5, s5, 0
	s_cmpk_lg_u32 s4, 0x8800
	s_waitcnt vmcnt(1)
	v_pk_add_f32 v[8:9], v[16:17], v[14:15]
	global_load_dwordx2 v[14:15], v[10:11], off offset:512
	v_pk_mul_f32 v[12:13], v[4:5], v[8:9] op_sel:[0,1] op_sel_hi:[1,0]
	global_store_dwordx2 v[10:11], v[8:9], off offset:512
	v_pk_fma_f32 v[16:17], v[2:3], v[8:9], v[12:13] neg_lo:[0,0,1] neg_hi:[0,0,1]
	v_pk_fma_f32 v[8:9], v[2:3], v[8:9], v[12:13]
	s_nop 0
	v_mov_b32_e32 v17, v9
	s_waitcnt vmcnt(1)
	v_pk_add_f32 v[8:9], v[16:17], v[14:15]
	global_load_dwordx2 v[14:15], v[10:11], off offset:1024
	v_pk_mul_f32 v[12:13], v[4:5], v[8:9] op_sel:[0,1] op_sel_hi:[1,0]
	global_store_dwordx2 v[10:11], v[8:9], off offset:1024
	v_pk_fma_f32 v[16:17], v[2:3], v[8:9], v[12:13] neg_lo:[0,0,1] neg_hi:[0,0,1]
	v_pk_fma_f32 v[8:9], v[2:3], v[8:9], v[12:13]
	s_nop 0
	v_mov_b32_e32 v17, v9
	s_waitcnt vmcnt(1)
	v_pk_add_f32 v[8:9], v[16:17], v[14:15]
	global_load_dwordx2 v[14:15], v[10:11], off offset:1536
	v_pk_mul_f32 v[12:13], v[4:5], v[8:9] op_sel:[0,1] op_sel_hi:[1,0]
	global_store_dwordx2 v[10:11], v[8:9], off offset:1536
	v_pk_fma_f32 v[10:11], v[2:3], v[8:9], v[12:13] neg_lo:[0,0,1] neg_hi:[0,0,1]
	v_pk_fma_f32 v[8:9], v[2:3], v[8:9], v[12:13]
	s_nop 0
	v_mov_b32_e32 v11, v9
	s_waitcnt vmcnt(1)
	v_pk_add_f32 v[8:9], v[10:11], v[14:15]
	s_cbranch_scc1 .LBB0_513
	v_readlane_b32 s4, v254, 48
	v_readlane_b32 s3, v252, 59
	s_add_i32 s6, s6, s4
	s_add_i32 s2, s2, s3
	s_cmp_gt_i32 s6, 63
	v_readlane_b32 s5, v254, 49
	s_cbranch_scc0 .LBB0_512

.LBB0_645:
	v_add_u32_e32 v168, s14, v0
	v_add_u32_e32 v169, s14, v167
	v_add_u32_e32 v171, 1, v168
	v_add_u32_e32 v170, 1, v169
	s_mov_b32 s2, 0x8800
	v_cmp_gt_i32_e32 vcc, s33, v171
	v_cmp_gt_i32_e64 s[4:5], s2, v170
	s_and_b64 s[4:5], vcc, s[4:5]
	s_and_saveexec_b64 s[2:3], s[4:5]
	s_cbranch_execz .LBB0_647
	s_mov_b32 s4, 0x78787879
	v_mul_hi_i32 v171, v170, s4
	v_lshrrev_b32_e32 v172, 31, v171
	v_ashrrev_i32_e32 v171, 11, v171
	v_add_u32_e32 v171, v171, v172
	ds_read2_b64 v[176:179], v166 offset0:66 offset1:98
	ds_read2_b64 v[180:183], v166 offset1:32
	v_mul_i32_i24_e32 v171, 0x1100, v171
	ds_read2_b64 v[184:187], v166 offset0:132 offset1:164
	v_sub_u32_e32 v171, v170, v171
	v_and_b32_e32 v172, 0xfffffeff, v171
	v_and_b32_e32 v171, 0xffffefff, v171
	v_cmp_eq_u32_e32 vcc, 0, v172
	s_waitcnt lgkmcnt(2)
	v_and_b32_e32 v229, 0xffff0000, v178
	v_lshlrev_b32_e32 v228, 16, v178
	v_cndmask_b32_e64 v172, 1.0, 0, vcc
	v_cmp_eq_u32_e32 vcc, s33, v171
	s_waitcnt lgkmcnt(1)
	v_and_b32_e32 v231, 0xffff0000, v182
	v_lshlrev_b32_e32 v230, 16, v182
	v_cndmask_b32_e64 v200, 1.0, 0, vcc
	s_waitcnt lgkmcnt(0)
	v_and_b32_e32 v233, 0xffff0000, v186
	v_lshlrev_b32_e32 v232, 16, v186
	v_pk_fma_f32 v[228:229], v[146:147], v[228:229], v[158:159]
	v_pk_mul_f32 v[230:231], v[172:173], v[230:231] op_sel_hi:[0,1]
	v_pk_fma_f32 v[228:229], v[142:143], v[230:231], v[228:229]
	v_pk_mul_f32 v[230:231], v[200:201], v[232:233] op_sel_hi:[0,1]
	v_pk_fma_f32 v[228:229], v[150:151], v[230:231], v[228:229]
	v_and_b32_e32 v227, 0xffff0000, v180
	v_mul_f32_e32 v171, 0xbfb8aa3b, v228
	v_exp_f32_e32 v230, v171
	v_mul_f32_e32 v171, 0xbfb8aa3b, v229
	v_exp_f32_e32 v231, v171
	v_lshlrev_b32_e32 v226, 16, v180
	v_pk_mul_f32 v[226:227], v[172:173], v[226:227] op_sel_hi:[0,1]
	v_and_b32_e32 v203, 0xffff0000, v176
	v_pk_add_f32 v[230:231], v[230:231], 1.0 op_sel_hi:[1,0]
	v_lshlrev_b32_e32 v202, 16, v176
	v_rcp_f32_e32 v173, v231
	v_pk_fma_f32 v[202:203], v[134:135], v[202:203], v[154:155]
	v_lshlrev_b32_e32 v180, 16, v179
	v_pk_fma_f32 v[202:203], v[130:131], v[226:227], v[202:203]
	v_rcp_f32_e32 v178, v230
	v_and_b32_e32 v227, 0xffff0000, v184
	v_lshlrev_b32_e32 v226, 16, v184
	v_pk_mul_f32 v[226:227], v[200:201], v[226:227] op_sel_hi:[0,1]
	v_mul_f32_e32 v171, v229, v173
	v_pk_fma_f32 v[202:203], v[138:139], v[226:227], v[202:203]
	v_mov_b32_e32 v227, v171
	v_mul_f32_e32 v171, v228, v178
	v_mov_b32_e32 v226, v171
	v_pk_mul_f32 v[202:203], v[202:203], v[226:227]
	v_and_b32_e32 v227, 0xffff0000, v177
	v_lshlrev_b32_e32 v226, 16, v177
	v_and_b32_e32 v177, 0xffff0000, v181
	v_lshlrev_b32_e32 v176, 16, v181
	v_and_b32_e32 v181, 0xffff0000, v179
	v_and_b32_e32 v179, 0xffff0000, v183
	v_lshlrev_b32_e32 v178, 16, v183
	v_and_b32_e32 v183, 0xffff0000, v187
	v_lshlrev_b32_e32 v182, 16, v187
	v_pk_fma_f32 v[180:181], v[148:149], v[180:181], v[160:161]
	v_pk_mul_f32 v[178:179], v[172:173], v[178:179] op_sel_hi:[0,1]
	v_pk_fma_f32 v[178:179], v[144:145], v[178:179], v[180:181]
	v_pk_mul_f32 v[180:181], v[200:201], v[182:183] op_sel_hi:[0,1]
	v_pk_fma_f32 v[178:179], v[152:153], v[180:181], v[178:179]
	v_pk_fma_f32 v[182:183], v[136:137], v[226:227], v[156:157]
	v_mul_f32_e32 v171, 0xbfb8aa3b, v178
	v_exp_f32_e32 v180, v171
	v_mul_f32_e32 v171, 0xbfb8aa3b, v179
	v_exp_f32_e32 v181, v171
	v_pk_mul_f32 v[172:173], v[172:173], v[176:177] op_sel_hi:[0,1]
	v_and_b32_e32 v177, 0xffff0000, v185
	v_lshlrev_b32_e32 v176, 16, v185
	v_pk_add_f32 v[180:181], v[180:181], 1.0 op_sel_hi:[1,0]
	v_pk_fma_f32 v[172:173], v[132:133], v[172:173], v[182:183]
	v_rcp_f32_e32 v175, v181
	v_pk_mul_f32 v[176:177], v[200:201], v[176:177] op_sel_hi:[0,1]
	v_pk_fma_f32 v[172:173], v[140:141], v[176:177], v[172:173]
	v_rcp_f32_e32 v182, v180
	v_mul_f32_e32 v171, v179, v175
	v_mov_b32_e32 v177, v171
	s_movk_i32 s4, 0x1600
	v_mul_f32_e32 v171, v178, v182
	v_mov_b32_e32 v176, v171
	v_pk_mul_f32 v[172:173], v[172:173], v[176:177]
	v_bfe_u32 v176, v203, 16, 1
	v_bfe_u32 v171, v173, 16, 1
	v_bfe_u32 v175, v172, 16, 1
	v_bfe_u32 v177, v202, 16, 1
	v_add3_u32 v177, v202, v177, s0
	v_add3_u32 v176, v203, v176, s0
	v_add3_u32 v172, v172, v175, s0
	v_add3_u32 v171, v173, v171, s0
	v_perm_b32 v173, v171, v172, s19
	v_perm_b32 v172, v176, v177, s19
	v_mad_i64_i32 v[170:171], s[4:5], v170, s4, v[164:165]
	global_store_dwordx2 v[170:171], v[172:173], off
.LBB0_647:
	s_or_b64 exec, exec, s[2:3]
	v_add_u32_e32 v171, 17, v168
	v_add_u32_e32 v170, 17, v169
	s_mov_b32 s2, 0x8800
	v_cmp_gt_i32_e32 vcc, s33, v171
	v_cmp_gt_i32_e64 s[4:5], s2, v170
	s_and_b64 s[4:5], vcc, s[4:5]
	s_and_saveexec_b64 s[2:3], s[4:5]
	s_cbranch_execz .LBB0_649
	s_mov_b32 s4, 0x78787879
	v_mul_hi_i32 v171, v170, s4
	v_lshrrev_b32_e32 v172, 31, v171
	v_ashrrev_i32_e32 v171, 11, v171
	v_add_u32_e32 v173, 0x2000, v166
	v_add_u32_e32 v171, v171, v172
	ds_read2_b64 v[176:179], v173 offset0:98 offset1:130
	ds_read2_b64 v[180:183], v173 offset0:32 offset1:64
	v_mul_i32_i24_e32 v171, 0x1100, v171
	ds_read2_b64 v[184:187], v173 offset0:164 offset1:196
	v_sub_u32_e32 v171, v170, v171
	v_and_b32_e32 v172, 0xfffffeff, v171
	v_and_b32_e32 v171, 0xffffefff, v171
	v_cmp_eq_u32_e32 vcc, 0, v172
	s_waitcnt lgkmcnt(2)
	v_and_b32_e32 v229, 0xffff0000, v178
	v_lshlrev_b32_e32 v228, 16, v178
	v_cndmask_b32_e64 v172, 1.0, 0, vcc
	v_cmp_eq_u32_e32 vcc, s33, v171
	s_waitcnt lgkmcnt(1)
	v_and_b32_e32 v231, 0xffff0000, v182
	v_lshlrev_b32_e32 v230, 16, v182
	v_cndmask_b32_e64 v200, 1.0, 0, vcc
	s_waitcnt lgkmcnt(0)
	v_and_b32_e32 v233, 0xffff0000, v186
	v_lshlrev_b32_e32 v232, 16, v186
	v_pk_fma_f32 v[228:229], v[146:147], v[228:229], v[158:159]
	v_pk_mul_f32 v[230:231], v[172:173], v[230:231] op_sel_hi:[0,1]
	v_pk_fma_f32 v[228:229], v[142:143], v[230:231], v[228:229]
	v_pk_mul_f32 v[230:231], v[200:201], v[232:233] op_sel_hi:[0,1]
	v_pk_fma_f32 v[228:229], v[150:151], v[230:231], v[228:229]
	v_and_b32_e32 v227, 0xffff0000, v180
	v_mul_f32_e32 v171, 0xbfb8aa3b, v228
	v_exp_f32_e32 v230, v171
	v_mul_f32_e32 v171, 0xbfb8aa3b, v229
	v_exp_f32_e32 v231, v171
	v_lshlrev_b32_e32 v226, 16, v180
	v_pk_mul_f32 v[226:227], v[172:173], v[226:227] op_sel_hi:[0,1]
	v_and_b32_e32 v203, 0xffff0000, v176
	v_pk_add_f32 v[230:231], v[230:231], 1.0 op_sel_hi:[1,0]
	v_lshlrev_b32_e32 v202, 16, v176
	v_rcp_f32_e32 v173, v231
	v_pk_fma_f32 v[202:203], v[134:135], v[202:203], v[154:155]
	v_lshlrev_b32_e32 v180, 16, v179
	v_pk_fma_f32 v[202:203], v[130:131], v[226:227], v[202:203]
	v_rcp_f32_e32 v178, v230
	v_and_b32_e32 v227, 0xffff0000, v184
	v_lshlrev_b32_e32 v226, 16, v184
	v_pk_mul_f32 v[226:227], v[200:201], v[226:227] op_sel_hi:[0,1]
	v_mul_f32_e32 v171, v229, v173
	v_pk_fma_f32 v[202:203], v[138:139], v[226:227], v[202:203]
	v_mov_b32_e32 v227, v171
	v_mul_f32_e32 v171, v228, v178
	v_mov_b32_e32 v226, v171
	v_pk_mul_f32 v[202:203], v[202:203], v[226:227]
	v_and_b32_e32 v227, 0xffff0000, v177
	v_lshlrev_b32_e32 v226, 16, v177
	v_and_b32_e32 v177, 0xffff0000, v181
	v_lshlrev_b32_e32 v176, 16, v181
	v_and_b32_e32 v181, 0xffff0000, v179
	v_and_b32_e32 v179, 0xffff0000, v183
	v_lshlrev_b32_e32 v178, 16, v183
	v_and_b32_e32 v183, 0xffff0000, v187
	v_lshlrev_b32_e32 v182, 16, v187
	v_pk_fma_f32 v[180:181], v[148:149], v[180:181], v[160:161]
	v_pk_mul_f32 v[178:179], v[172:173], v[178:179] op_sel_hi:[0,1]
	v_pk_fma_f32 v[178:179], v[144:145], v[178:179], v[180:181]
	v_pk_mul_f32 v[180:181], v[200:201], v[182:183] op_sel_hi:[0,1]
	v_pk_fma_f32 v[178:179], v[152:153], v[180:181], v[178:179]
	v_pk_fma_f32 v[182:183], v[136:137], v[226:227], v[156:157]
	v_mul_f32_e32 v171, 0xbfb8aa3b, v178
	v_exp_f32_e32 v180, v171
	v_mul_f32_e32 v171, 0xbfb8aa3b, v179
	v_exp_f32_e32 v181, v171
	v_pk_mul_f32 v[172:173], v[172:173], v[176:177] op_sel_hi:[0,1]
	v_and_b32_e32 v177, 0xffff0000, v185
	v_lshlrev_b32_e32 v176, 16, v185
	v_pk_add_f32 v[180:181], v[180:181], 1.0 op_sel_hi:[1,0]
	v_pk_fma_f32 v[172:173], v[132:133], v[172:173], v[182:183]
	v_rcp_f32_e32 v175, v181
	v_pk_mul_f32 v[176:177], v[200:201], v[176:177] op_sel_hi:[0,1]
	v_pk_fma_f32 v[172:173], v[140:141], v[176:177], v[172:173]
	v_rcp_f32_e32 v182, v180
	v_mul_f32_e32 v171, v179, v175
	v_mov_b32_e32 v177, v171
	s_movk_i32 s4, 0x1600
	v_mul_f32_e32 v171, v178, v182
	v_mov_b32_e32 v176, v171
	v_pk_mul_f32 v[172:173], v[172:173], v[176:177]
	v_bfe_u32 v176, v203, 16, 1
	v_bfe_u32 v171, v173, 16, 1
	v_bfe_u32 v175, v172, 16, 1
	v_bfe_u32 v177, v202, 16, 1
	v_add3_u32 v177, v202, v177, s0
	v_add3_u32 v176, v203, v176, s0
	v_add3_u32 v172, v172, v175, s0
	v_add3_u32 v171, v173, v171, s0
	v_perm_b32 v173, v171, v172, s19
	v_perm_b32 v172, v176, v177, s19
	v_mad_i64_i32 v[170:171], s[4:5], v170, s4, v[164:165]
	global_store_dwordx2 v[170:171], v[172:173], off
.LBB0_649:
	s_or_b64 exec, exec, s[2:3]
	v_add_u32_e32 v171, 33, v168
	v_add_u32_e32 v170, 33, v169
	s_mov_b32 s2, 0x8800
	v_cmp_gt_i32_e32 vcc, s33, v171
	v_cmp_gt_i32_e64 s[4:5], s2, v170
	s_and_b64 s[4:5], vcc, s[4:5]
	s_and_saveexec_b64 s[2:3], s[4:5]
	s_cbranch_execz .LBB0_651
	s_mov_b32 s4, 0x78787879
	v_mul_hi_i32 v171, v170, s4
	v_lshrrev_b32_e32 v172, 31, v171
	v_ashrrev_i32_e32 v171, 11, v171
	v_add_u32_e32 v173, 0x4000, v166
	v_add_u32_e32 v171, v171, v172
	ds_read2_b64 v[176:179], v173 offset0:130 offset1:162
	ds_read2_b64 v[180:183], v173 offset0:64 offset1:96
	v_mul_i32_i24_e32 v171, 0x1100, v171
	ds_read2_b64 v[184:187], v173 offset0:196 offset1:228
	v_sub_u32_e32 v171, v170, v171
	v_and_b32_e32 v172, 0xfffffeff, v171
	v_and_b32_e32 v171, 0xffffefff, v171
	v_cmp_eq_u32_e32 vcc, 0, v172
	s_waitcnt lgkmcnt(2)
	v_and_b32_e32 v229, 0xffff0000, v178
	v_lshlrev_b32_e32 v228, 16, v178
	v_cndmask_b32_e64 v172, 1.0, 0, vcc
	v_cmp_eq_u32_e32 vcc, s33, v171
	s_waitcnt lgkmcnt(1)
	v_and_b32_e32 v231, 0xffff0000, v182
	v_lshlrev_b32_e32 v230, 16, v182
	v_cndmask_b32_e64 v200, 1.0, 0, vcc
	s_waitcnt lgkmcnt(0)
	v_and_b32_e32 v233, 0xffff0000, v186
	v_lshlrev_b32_e32 v232, 16, v186
	v_pk_fma_f32 v[228:229], v[146:147], v[228:229], v[158:159]
	v_pk_mul_f32 v[230:231], v[172:173], v[230:231] op_sel_hi:[0,1]
	v_pk_fma_f32 v[228:229], v[142:143], v[230:231], v[228:229]
	v_pk_mul_f32 v[230:231], v[200:201], v[232:233] op_sel_hi:[0,1]
	v_pk_fma_f32 v[228:229], v[150:151], v[230:231], v[228:229]
	v_and_b32_e32 v227, 0xffff0000, v180
	v_mul_f32_e32 v171, 0xbfb8aa3b, v228
	v_exp_f32_e32 v230, v171
	v_mul_f32_e32 v171, 0xbfb8aa3b, v229
	v_exp_f32_e32 v231, v171
	v_lshlrev_b32_e32 v226, 16, v180
	v_pk_mul_f32 v[226:227], v[172:173], v[226:227] op_sel_hi:[0,1]
	v_and_b32_e32 v203, 0xffff0000, v176
	v_pk_add_f32 v[230:231], v[230:231], 1.0 op_sel_hi:[1,0]
	v_lshlrev_b32_e32 v202, 16, v176
	v_rcp_f32_e32 v173, v231
	v_pk_fma_f32 v[202:203], v[134:135], v[202:203], v[154:155]
	v_lshlrev_b32_e32 v180, 16, v179
	v_pk_fma_f32 v[202:203], v[130:131], v[226:227], v[202:203]
	v_rcp_f32_e32 v178, v230
	v_and_b32_e32 v227, 0xffff0000, v184
	v_lshlrev_b32_e32 v226, 16, v184
	v_pk_mul_f32 v[226:227], v[200:201], v[226:227] op_sel_hi:[0,1]
	v_mul_f32_e32 v171, v229, v173
	v_pk_fma_f32 v[202:203], v[138:139], v[226:227], v[202:203]
	v_mov_b32_e32 v227, v171
	v_mul_f32_e32 v171, v228, v178
	v_mov_b32_e32 v226, v171
	v_pk_mul_f32 v[202:203], v[202:203], v[226:227]
	v_and_b32_e32 v227, 0xffff0000, v177
	v_lshlrev_b32_e32 v226, 16, v177
	v_and_b32_e32 v177, 0xffff0000, v181
	v_lshlrev_b32_e32 v176, 16, v181
	v_and_b32_e32 v181, 0xffff0000, v179
	v_and_b32_e32 v179, 0xffff0000, v183
	v_lshlrev_b32_e32 v178, 16, v183
	v_and_b32_e32 v183, 0xffff0000, v187
	v_lshlrev_b32_e32 v182, 16, v187
	v_pk_fma_f32 v[180:181], v[148:149], v[180:181], v[160:161]
	v_pk_mul_f32 v[178:179], v[172:173], v[178:179] op_sel_hi:[0,1]
	v_pk_fma_f32 v[178:179], v[144:145], v[178:179], v[180:181]
	v_pk_mul_f32 v[180:181], v[200:201], v[182:183] op_sel_hi:[0,1]
	v_pk_fma_f32 v[178:179], v[152:153], v[180:181], v[178:179]
	v_pk_fma_f32 v[182:183], v[136:137], v[226:227], v[156:157]
	v_mul_f32_e32 v171, 0xbfb8aa3b, v178
	v_exp_f32_e32 v180, v171
	v_mul_f32_e32 v171, 0xbfb8aa3b, v179
	v_exp_f32_e32 v181, v171
	v_pk_mul_f32 v[172:173], v[172:173], v[176:177] op_sel_hi:[0,1]
	v_and_b32_e32 v177, 0xffff0000, v185
	v_lshlrev_b32_e32 v176, 16, v185
	v_pk_add_f32 v[180:181], v[180:181], 1.0 op_sel_hi:[1,0]
	v_pk_fma_f32 v[172:173], v[132:133], v[172:173], v[182:183]
	v_rcp_f32_e32 v175, v181
	v_pk_mul_f32 v[176:177], v[200:201], v[176:177] op_sel_hi:[0,1]
	v_pk_fma_f32 v[172:173], v[140:141], v[176:177], v[172:173]
	v_rcp_f32_e32 v182, v180
	v_mul_f32_e32 v171, v179, v175
	v_mov_b32_e32 v177, v171
	s_movk_i32 s4, 0x1600
	v_mul_f32_e32 v171, v178, v182
	v_mov_b32_e32 v176, v171
	v_pk_mul_f32 v[172:173], v[172:173], v[176:177]
	v_bfe_u32 v176, v203, 16, 1
	v_bfe_u32 v171, v173, 16, 1
	v_bfe_u32 v175, v172, 16, 1
	v_bfe_u32 v177, v202, 16, 1
	v_add3_u32 v177, v202, v177, s0
	v_add3_u32 v176, v203, v176, s0
	v_add3_u32 v172, v172, v175, s0
	v_add3_u32 v171, v173, v171, s0
	v_perm_b32 v173, v171, v172, s19
	v_perm_b32 v172, v176, v177, s19
	v_mad_i64_i32 v[170:171], s[4:5], v170, s4, v[164:165]
	global_store_dwordx2 v[170:171], v[172:173], off
.LBB0_651:
	s_or_b64 exec, exec, s[2:3]
	v_add_u32_e32 v170, 49, v168
	v_add_u32_e32 v168, 49, v169
	s_mov_b32 s2, 0x8800
	v_cmp_gt_i32_e32 vcc, s33, v170
	v_cmp_gt_i32_e64 s[4:5], s2, v168
	s_and_b64 s[4:5], vcc, s[4:5]
	s_and_saveexec_b64 s[2:3], s[4:5]
	s_cbranch_execz .LBB0_644
	s_mov_b32 s4, 0x78787879
	v_mul_hi_i32 v169, v168, s4
	v_lshrrev_b32_e32 v170, 31, v169
	v_ashrrev_i32_e32 v169, 11, v169
	v_add_u32_e32 v169, v169, v170
	v_mul_i32_i24_e32 v169, 0x1100, v169
	v_sub_u32_e32 v169, v168, v169
	v_and_b32_e32 v170, 0xfffffeff, v169
	v_and_b32_e32 v169, 0xffffefff, v169
	v_cmp_eq_u32_e32 vcc, 0, v170
	v_add_u32_e32 v175, 0x6000, v166
	ds_read2_b64 v[170:173], v175 offset0:162 offset1:194
	v_cndmask_b32_e64 v184, 1.0, 0, vcc
	v_cmp_eq_u32_e32 vcc, s33, v169
	ds_read2_b64 v[176:179], v175 offset0:96 offset1:128
	v_add_u32_e32 v169, 0x6400, v166
	ds_read2_b64 v[180:183], v169 offset0:100 offset1:132
	s_waitcnt lgkmcnt(2)
	v_and_b32_e32 v227, 0xffff0000, v172
	v_lshlrev_b32_e32 v226, 16, v172
	s_waitcnt lgkmcnt(1)
	v_and_b32_e32 v229, 0xffff0000, v178
	v_lshlrev_b32_e32 v228, 16, v178
	v_cndmask_b32_e64 v186, 1.0, 0, vcc
	s_waitcnt lgkmcnt(0)
	v_and_b32_e32 v231, 0xffff0000, v182
	v_lshlrev_b32_e32 v230, 16, v182
	v_pk_fma_f32 v[226:227], v[146:147], v[226:227], v[158:159]
	v_pk_mul_f32 v[228:229], v[184:185], v[228:229] op_sel_hi:[0,1]
	v_pk_fma_f32 v[226:227], v[142:143], v[228:229], v[226:227]
	v_pk_mul_f32 v[228:229], v[186:187], v[230:231] op_sel_hi:[0,1]
	v_pk_fma_f32 v[226:227], v[150:151], v[228:229], v[226:227]
	v_and_b32_e32 v201, 0xffff0000, v170
	v_mul_f32_e32 v169, 0xbfb8aa3b, v226
	v_exp_f32_e32 v228, v169
	v_mul_f32_e32 v169, 0xbfb8aa3b, v227
	v_exp_f32_e32 v229, v169
	v_lshlrev_b32_e32 v200, 16, v170
	v_and_b32_e32 v203, 0xffff0000, v176
	v_lshlrev_b32_e32 v202, 16, v176
	v_pk_add_f32 v[228:229], v[228:229], 1.0 op_sel_hi:[1,0]
	v_pk_fma_f32 v[200:201], v[134:135], v[200:201], v[154:155]
	v_rcp_f32_e32 v170, v229
	v_pk_mul_f32 v[202:203], v[184:185], v[202:203] op_sel_hi:[0,1]
	v_pk_fma_f32 v[200:201], v[130:131], v[202:203], v[200:201]
	v_and_b32_e32 v203, 0xffff0000, v180
	v_rcp_f32_e32 v176, v228
	v_lshlrev_b32_e32 v202, 16, v180
	v_pk_mul_f32 v[202:203], v[186:187], v[202:203] op_sel_hi:[0,1]
	v_mul_f32_e32 v169, v227, v170
	v_pk_fma_f32 v[200:201], v[138:139], v[202:203], v[200:201]
	v_mov_b32_e32 v203, v169
	v_mul_f32_e32 v169, v226, v176
	v_mov_b32_e32 v202, v169
	v_pk_mul_f32 v[200:201], v[200:201], v[202:203]
	v_and_b32_e32 v203, 0xffff0000, v171
	v_lshlrev_b32_e32 v202, 16, v171
	v_and_b32_e32 v171, 0xffff0000, v177
	v_lshlrev_b32_e32 v170, 16, v177
	v_and_b32_e32 v177, 0xffff0000, v173
	v_lshlrev_b32_e32 v176, 16, v173
	v_and_b32_e32 v173, 0xffff0000, v179
	v_lshlrev_b32_e32 v172, 16, v179
	v_and_b32_e32 v179, 0xffff0000, v183
	v_lshlrev_b32_e32 v178, 16, v183
	v_pk_fma_f32 v[176:177], v[148:149], v[176:177], v[160:161]
	v_pk_mul_f32 v[172:173], v[184:185], v[172:173] op_sel_hi:[0,1]
	v_pk_fma_f32 v[172:173], v[144:145], v[172:173], v[176:177]
	v_pk_mul_f32 v[176:177], v[186:187], v[178:179] op_sel_hi:[0,1]
	v_pk_fma_f32 v[172:173], v[152:153], v[176:177], v[172:173]
	v_pk_fma_f32 v[178:179], v[136:137], v[202:203], v[156:157]
	v_mul_f32_e32 v169, 0xbfb8aa3b, v172
	v_exp_f32_e32 v176, v169
	v_mul_f32_e32 v169, 0xbfb8aa3b, v173
	v_exp_f32_e32 v177, v169
	v_pk_mul_f32 v[170:171], v[184:185], v[170:171] op_sel_hi:[0,1]
	v_pk_fma_f32 v[170:171], v[132:133], v[170:171], v[178:179]
	v_and_b32_e32 v179, 0xffff0000, v181
	v_pk_add_f32 v[176:177], v[176:177], 1.0 op_sel_hi:[1,0]
	v_lshlrev_b32_e32 v178, 16, v181
	v_rcp_f32_e32 v175, v177
	v_pk_mul_f32 v[178:179], v[186:187], v[178:179] op_sel_hi:[0,1]
	v_pk_fma_f32 v[170:171], v[140:141], v[178:179], v[170:171]
	v_rcp_f32_e32 v180, v176
	v_mul_f32_e32 v169, v173, v175
	v_mov_b32_e32 v173, v169
	s_movk_i32 s4, 0x1600
	v_mul_f32_e32 v169, v172, v180
	v_mov_b32_e32 v172, v169
	v_pk_mul_f32 v[170:171], v[170:171], v[172:173]
	v_bfe_u32 v173, v201, 16, 1
	v_bfe_u32 v169, v171, 16, 1
	v_bfe_u32 v172, v170, 16, 1
	v_bfe_u32 v175, v200, 16, 1
	v_add3_u32 v175, v200, v175, s0
	v_add3_u32 v173, v201, v173, s0
	v_add3_u32 v170, v170, v172, s0
	v_add3_u32 v169, v171, v169, s0
	v_perm_b32 v171, v169, v170, s19
	v_perm_b32 v170, v173, v175, s19
	v_mad_i64_i32 v[168:169], s[4:5], v168, s4, v[164:165]
	global_store_dwordx2 v[168:169], v[170:171], off
	s_branch .LBB0_644

.LBB0_654:
	s_and_b64 vcc, exec, s[2:3]
	s_cbranch_vccz .LBB0_1040
	v_lshlrev_b32_e32 v0, 2, v223
	s_and_b32 s2, s6, 0x300
	v_or3_b32 v130, v0, s2, v224
	v_readlane_b32 s48, v254, 55
	v_lshlrev_b32_e32 v130, 2, v130
	v_readlane_b32 s60, v255, 3
	v_readlane_b32 s61, v255, 4
	s_nop 4
	global_load_dwordx4 v[142:145], v130, s[60:61]
	global_load_dwordx4 v[138:141], v130, s[60:61] offset:64
	global_load_dwordx4 v[134:137], v130, s[60:61] offset:128
	s_nop 0
	global_load_dwordx4 v[130:133], v130, s[60:61] offset:192
	s_ashr_i32 s34, s47, 2
	v_add_u32_e32 v146, s45, v225
	s_cmpk_gt_u32 s6, 0x3ff
	v_or3_b32 v148, v224, s2, v0
	v_subrev_u32_e32 v146, s39, v146
	s_cselect_b64 s[2:3], -1, 0
	v_ashrrev_i32_e32 v147, 31, v146
	s_mov_b64 s[4:5], -1
	s_and_b64 vcc, exec, s[2:3]
	v_readlane_b32 s49, v254, 56
	v_readlane_b32 s50, v254, 57
	v_readlane_b32 s51, v254, 58
	v_readlane_b32 s52, v254, 59
	v_readlane_b32 s53, v254, 60
	v_readlane_b32 s54, v254, 61
	v_readlane_b32 s55, v254, 62
	v_readlane_b32 s56, v254, 63
	v_readlane_b32 s57, v255, 0
	v_readlane_b32 s58, v255, 1
	v_readlane_b32 s59, v255, 2
	v_readlane_b32 s62, v255, 5
	v_readlane_b32 s63, v255, 6
	s_cbranch_vccz .LBB0_665
	s_cmp_gt_i32 s34, 2
	s_cbranch_scc0 .LBB0_662
	s_cmp_eq_u32 s34, 3
	s_cbranch_scc1 .LBB0_659
	v_mul_f32_e32 v0, 0xbfb8aa3b, v126
	v_exp_f32_e32 v150, v0
	v_mul_f32_e32 v0, 0xbfb8aa3b, v127
	v_exp_f32_e32 v151, v0
	v_readlane_b32 s48, v253, 4
	v_readlane_b32 s49, v253, 5
	v_readlane_b32 s50, v253, 6
	v_pk_add_f32 v[150:151], v[150:151], 1.0 op_sel_hi:[1,0]
	v_readlane_b32 s51, v253, 7
	v_rcp_f32_e32 v149, v150
	s_nop 0
	v_mul_f32_e32 v0, v126, v149
	v_rcp_f32_e32 v150, v151
	s_nop 0
	v_mul_f32_e32 v149, v127, v150
	v_mul_f32_e32 v150, 0xbfb8aa3b, v128
	v_mul_f32_e32 v151, 0xbfb8aa3b, v129
	v_exp_f32_e32 v150, v150
	v_exp_f32_e32 v151, v151
	s_nop 0
	v_pk_add_f32 v[150:151], v[150:151], 1.0 op_sel_hi:[1,0]
	s_nop 0
	v_rcp_f32_e32 v153, v150
	s_nop 0
	v_mul_f32_e32 v152, v128, v153
	v_mov_b32_e32 v150, v152
	v_rcp_f32_e32 v153, v151
	s_mov_b64 s[4:5], 0
	v_mul_f32_e32 v152, v129, v153
	v_mov_b32_e32 v151, v152
	v_bfe_u32 v152, v151, 16, 1
	v_bfe_u32 v153, v150, 16, 1
	v_bfe_u32 v154, v149, 16, 1
	v_bfe_u32 v155, v0, 16, 1
	v_add3_u32 v0, v0, v155, s0
	v_add3_u32 v149, v149, v154, s0
	v_add3_u32 v150, v150, v153, s0
	v_add3_u32 v151, v151, v152, s0
	v_lshlrev_b64 v[152:153], 11, v[146:147]
	v_perm_b32 v151, v151, v150, s19
	v_perm_b32 v150, v149, v0, s19
	v_lshl_add_u64 v[152:153], s[48:49], 0, v[152:153]
	v_lshlrev_b32_e32 v0, 1, v148
	v_lshl_add_u64 v[152:153], v[152:153], 0, v[0:1]
	global_store_dwordx2 v[152:153], v[150:151], off

.LBB0_662:
	s_andn2_b64 vcc, exec, s[4:5]
	s_cbranch_vccnz .LBB0_664
	v_mul_f32_e32 v149, 0xbfb8aa3b, v126
	v_exp_f32_e32 v149, v149
	s_waitcnt vmcnt(3)
	v_sub_f32_e32 v0, 1.0, v142
	s_mov_b32 s14, 0x800000
	s_mov_b32 s24, 0x3f317217
	v_add_f32_e32 v149, 1.0, v149
	v_rcp_f32_e32 v151, v149
	s_mov_b32 s15, 0x7f800000
	v_readlane_b32 s48, v252, 16
	v_readlane_b32 s60, v252, 28
	v_mov_b32_e32 v150, v151
	v_mov_b32_e32 v149, v150
	v_fma_f32 v0, v149, v0, v142
	v_cmp_gt_f32_e32 vcc, s14, v0
	v_mul_f32_e32 v150, 0xbfb8aa3b, v127
	v_exp_f32_e32 v150, v150
	v_cndmask_b32_e64 v149, 0, 32, vcc
	v_ldexp_f32 v0, v0, v149
	v_log_f32_e32 v0, v0
	v_add_f32_e32 v150, 1.0, v150
	v_readlane_b32 s61, v252, 29
	v_readlane_b32 s49, v252, 17
	v_mul_f32_e32 v149, 0x3f317217, v0
	v_fma_f32 v149, v0, s24, -v149
	v_fmac_f32_e32 v149, 0x3377d1cf, v0
	v_fmac_f32_e32 v149, 0x3f317217, v0
	v_cmp_lt_f32_e64 s[4:5], |v0|, s15
	v_readlane_b32 s50, v252, 18
	v_readlane_b32 s51, v252, 19
	v_cndmask_b32_e64 v0, v0, v149, s[4:5]
	v_rcp_f32_e32 v152, v150
	v_cndmask_b32_e32 v149, 0, v213, vcc
	v_sub_f32_e32 v0, v0, v149
	v_sub_f32_e32 v149, 1.0, v143
	v_mov_b32_e32 v151, v152
	v_mov_b32_e32 v150, v151
	v_fma_f32 v149, v150, v149, v143
	v_cmp_gt_f32_e32 vcc, s14, v149
	v_mul_f32_e32 v151, 0xbfb8aa3b, v128
	v_exp_f32_e32 v151, v151
	v_cndmask_b32_e64 v150, 0, 32, vcc
	v_ldexp_f32 v149, v149, v150
	v_log_f32_e32 v149, v149
	v_add_f32_e32 v151, 1.0, v151
	v_readlane_b32 s52, v252, 20
	v_readlane_b32 s53, v252, 21
	v_mul_f32_e32 v150, 0x3f317217, v149
	v_fma_f32 v150, v149, s24, -v150
	v_fmac_f32_e32 v150, 0x3377d1cf, v149
	v_fmac_f32_e32 v150, 0x3f317217, v149
	v_cmp_lt_f32_e64 s[4:5], |v149|, s15
	v_readlane_b32 s54, v252, 22
	v_readlane_b32 s55, v252, 23
	v_cndmask_b32_e64 v149, v149, v150, s[4:5]
	v_rcp_f32_e32 v153, v151
	v_cndmask_b32_e32 v150, 0, v213, vcc
	v_sub_f32_e32 v149, v149, v150
	v_sub_f32_e32 v150, 1.0, v144
	v_mov_b32_e32 v152, v153
	v_mov_b32_e32 v151, v152
	v_fma_f32 v150, v151, v150, v144
	v_cmp_gt_f32_e32 vcc, s14, v150
	v_mul_f32_e32 v152, 0xbfb8aa3b, v129
	v_exp_f32_e32 v152, v152
	v_cndmask_b32_e64 v151, 0, 32, vcc
	v_ldexp_f32 v150, v150, v151
	v_log_f32_e32 v150, v150
	v_add_f32_e32 v152, 1.0, v152
	v_readlane_b32 s56, v252, 24
	v_readlane_b32 s57, v252, 25
	v_mul_f32_e32 v151, 0x3f317217, v150
	v_fma_f32 v151, v150, s24, -v151
	v_fmac_f32_e32 v151, 0x3377d1cf, v150
	v_fmac_f32_e32 v151, 0x3f317217, v150
	v_cmp_lt_f32_e64 s[4:5], |v150|, s15
	v_readlane_b32 s58, v252, 26
	v_readlane_b32 s59, v252, 27
	v_cndmask_b32_e64 v150, v150, v151, s[4:5]
	v_rcp_f32_e32 v154, v152
	v_cndmask_b32_e32 v151, 0, v213, vcc
	v_sub_f32_e32 v150, v150, v151
	v_sub_f32_e32 v151, 1.0, v145
	v_mov_b32_e32 v153, v154
	v_mov_b32_e32 v152, v153
	v_fma_f32 v151, v152, v151, v145
	v_cmp_gt_f32_e32 vcc, s14, v151
	v_readlane_b32 s62, v252, 30
	v_readlane_b32 s63, v252, 31
	v_cndmask_b32_e64 v152, 0, 32, vcc
	v_ldexp_f32 v151, v151, v152
	v_log_f32_e32 v151, v151
	s_nop 0
	v_mul_f32_e32 v152, 0x3f317217, v151
	v_fma_f32 v152, v151, s24, -v152
	v_fmac_f32_e32 v152, 0x3377d1cf, v151
	v_fmac_f32_e32 v152, 0x3f317217, v151
	v_cmp_lt_f32_e64 s[4:5], |v151|, s15
	s_nop 1
	v_cndmask_b32_e64 v151, v151, v152, s[4:5]
	s_add_i32 s4, s34, -1
	s_mul_hi_i32 s5, s4, 0x2200000
	s_mul_i32 s4, s4, 0x2200000
	v_cndmask_b32_e32 v152, 0, v213, vcc
	s_add_u32 s4, s60, s4
	v_sub_f32_e32 v151, v151, v152
	s_addc_u32 s5, s61, s5
	v_lshlrev_b64 v[152:153], 11, v[146:147]
	v_cvt_pk_f16_f32 v151, v150, v151
	v_cvt_pk_f16_f32 v150, v0, v149
	v_lshl_add_u64 v[152:153], s[4:5], 0, v[152:153]
	v_lshlrev_b32_e32 v0, 1, v148
	v_lshl_add_u64 v[152:153], v[152:153], 0, v[0:1]
	global_store_dwordx2 v[152:153], v[150:151], off

.LBB0_665:
	v_readlane_b32 s48, v252, 16
	v_lshlrev_b64 v[150:151], 11, v[146:147]
	v_readlane_b32 s58, v252, 26
	v_readlane_b32 s59, v252, 27
	s_andn2_b64 vcc, exec, s[4:5]
	v_lshlrev_b32_e32 v0, 1, v148
	v_lshl_add_u64 v[148:149], s[58:59], 0, v[150:151]
	v_readlane_b32 s49, v252, 17
	v_readlane_b32 s50, v252, 18
	v_readlane_b32 s51, v252, 19
	v_readlane_b32 s52, v252, 20
	v_readlane_b32 s53, v252, 21
	v_readlane_b32 s54, v252, 22
	v_readlane_b32 s55, v252, 23
	v_readlane_b32 s56, v252, 24
	v_readlane_b32 s57, v252, 25
	v_readlane_b32 s60, v252, 28
	v_readlane_b32 s61, v252, 29
	v_readlane_b32 s62, v252, 30
	v_readlane_b32 s63, v252, 31
	s_cbranch_vccnz .LBB0_667
	v_mul_f32_e32 v147, 0xbfb8aa3b, v126
	v_exp_f32_e32 v152, v147
	v_mul_f32_e32 v147, 0xbfb8aa3b, v127
	v_exp_f32_e32 v153, v147
	s_mov_b32 s14, 0x3db504f3
	v_pk_add_f32 v[152:153], v[152:153], 1.0 op_sel_hi:[1,0]
	s_nop 0
	v_rcp_f32_e32 v154, v153
	s_nop 0
	v_mul_f32_e32 v147, v127, v154
	v_mov_b32_e32 v153, v147
	v_rcp_f32_e32 v154, v152
	s_nop 0
	v_mul_f32_e32 v147, v126, v154
	v_mov_b32_e32 v152, v147
	v_mul_f32_e32 v147, 0xbfb8aa3b, v128
	v_exp_f32_e32 v154, v147
	v_mul_f32_e32 v147, 0xbfb8aa3b, v129
	v_exp_f32_e32 v155, v147
	v_pk_mul_f32 v[152:153], v[152:153], s[14:15] op_sel_hi:[1,0]
	v_pk_add_f32 v[154:155], v[154:155], 1.0 op_sel_hi:[1,0]
	s_nop 0
	v_rcp_f32_e32 v156, v155
	s_nop 0
	v_mul_f32_e32 v147, v129, v156
	v_mov_b32_e32 v155, v147
	v_rcp_f32_e32 v156, v154
	s_nop 0
	v_mul_f32_e32 v147, v128, v156
	v_mov_b32_e32 v154, v147
	v_pk_mul_f32 v[154:155], v[154:155], s[14:15] op_sel_hi:[1,0]
	v_bfe_u32 v157, v153, 16, 1
	v_bfe_u32 v147, v155, 16, 1
	v_bfe_u32 v156, v154, 16, 1
	v_bfe_u32 v158, v152, 16, 1
	v_add3_u32 v152, v152, v158, s0
	v_add3_u32 v157, v153, v157, s0
	v_add3_u32 v153, v154, v156, s0
	v_add3_u32 v147, v155, v147, s0
	v_perm_b32 v153, v147, v153, s19
	v_perm_b32 v152, v157, v152, s19
	v_lshl_add_u64 v[154:155], v[148:149], 0, v[0:1]
	global_store_dwordx2 v[154:155], v[152:153], off
.LBB0_667:
	v_cndmask_b32_e64 v147, 0, 1, s[2:3]
	v_cmp_ne_u32_e64 s[40:41], 1, v147
	s_andn2_b64 vcc, exec, s[2:3]
	s_mov_b64 s[2:3], -1
	s_cbranch_vccnz .LBB0_677
	s_cmp_lt_i32 s34, 3
	s_cbranch_scc1 .LBB0_674
	s_cmp_eq_u32 s34, 3
	s_cbranch_scc1 .LBB0_671
	v_mul_f32_e32 v147, 0xbfb8aa3b, v122
	v_exp_f32_e32 v152, v147
	v_mul_f32_e32 v147, 0xbfb8aa3b, v123
	v_exp_f32_e32 v153, v147
	v_readlane_b32 s48, v253, 4
	v_readlane_b32 s49, v253, 5
	v_readlane_b32 s50, v253, 6
	v_pk_add_f32 v[152:153], v[152:153], 1.0 op_sel_hi:[1,0]
	v_readlane_b32 s51, v253, 7
	v_rcp_f32_e32 v154, v152
	s_nop 0
	v_mul_f32_e32 v147, v122, v154
	v_rcp_f32_e32 v154, v153
	s_nop 0
	v_mul_f32_e32 v152, v123, v154
	v_mov_b32_e32 v154, v152
	v_mul_f32_e32 v152, 0xbfb8aa3b, v124
	v_mul_f32_e32 v153, 0xbfb8aa3b, v125
	v_exp_f32_e32 v152, v152
	v_exp_f32_e32 v153, v153
	s_nop 0
	v_pk_add_f32 v[152:153], v[152:153], 1.0 op_sel_hi:[1,0]
	s_nop 0
	v_rcp_f32_e32 v156, v152
	s_nop 0
	v_mul_f32_e32 v155, v124, v156
	v_mov_b32_e32 v152, v155
	v_rcp_f32_e32 v156, v153
	s_mov_b64 s[2:3], 0
	v_mul_f32_e32 v155, v125, v156
	v_mov_b32_e32 v153, v155
	v_bfe_u32 v155, v153, 16, 1
	v_bfe_u32 v156, v152, 16, 1
	v_bfe_u32 v157, v154, 16, 1
	v_bfe_u32 v158, v147, 16, 1
	v_add3_u32 v147, v147, v158, s0
	v_add3_u32 v154, v154, v157, s0
	v_add3_u32 v152, v152, v156, s0
	v_add3_u32 v153, v153, v155, s0
	v_perm_b32 v153, v153, v152, s19
	v_perm_b32 v152, v154, v147, s19
	v_lshl_add_u64 v[154:155], s[48:49], 0, v[150:151]
	v_lshl_add_u64 v[154:155], v[154:155], 0, v[0:1]
	global_store_dwordx2 v[154:155], v[152:153], off offset:32

.LBB0_674:
	s_andn2_b64 vcc, exec, s[2:3]
	s_cbranch_vccnz .LBB0_676
	v_mul_f32_e32 v152, 0xbfb8aa3b, v122
	v_exp_f32_e32 v152, v152
	s_waitcnt vmcnt(2)
	v_sub_f32_e32 v147, 1.0, v138
	s_mov_b32 s14, 0x800000
	s_mov_b32 s24, 0x3f317217
	v_add_f32_e32 v152, 1.0, v152
	v_rcp_f32_e32 v154, v152
	s_mov_b32 s15, 0x7f800000
	v_readlane_b32 s48, v252, 16
	v_readlane_b32 s60, v252, 28
	v_mov_b32_e32 v153, v154
	v_mov_b32_e32 v152, v153
	v_fma_f32 v147, v152, v147, v138
	v_mul_f32_e32 v153, 0xbfb8aa3b, v123
	v_cmp_gt_f32_e32 vcc, s14, v147
	v_exp_f32_e32 v153, v153
	v_readlane_b32 s61, v252, 29
	v_cndmask_b32_e64 v152, 0, 32, vcc
	v_ldexp_f32 v147, v147, v152
	v_log_f32_e32 v147, v147
	v_add_f32_e32 v153, 1.0, v153
	v_rcp_f32_e32 v155, v153
	v_mul_f32_e32 v152, 0x3f317217, v147
	v_fma_f32 v152, v147, s24, -v152
	v_fmac_f32_e32 v152, 0x3377d1cf, v147
	v_fmac_f32_e32 v152, 0x3f317217, v147
	v_cmp_lt_f32_e64 s[4:5], |v147|, s15
	v_cndmask_b32_e64 v147, v147, v152, s[4:5]
	v_cndmask_b32_e32 v152, 0, v213, vcc
	v_mov_b32_e32 v154, v155
	v_sub_f32_e32 v147, v147, v152
	v_sub_f32_e32 v152, 1.0, v139
	v_mov_b32_e32 v153, v154
	v_fma_f32 v152, v153, v152, v139
	v_mul_f32_e32 v154, 0xbfb8aa3b, v124
	v_cmp_gt_f32_e32 vcc, s14, v152
	v_exp_f32_e32 v154, v154
	v_readlane_b32 s49, v252, 17
	v_cndmask_b32_e64 v153, 0, 32, vcc
	v_ldexp_f32 v152, v152, v153
	v_log_f32_e32 v152, v152
	v_add_f32_e32 v154, 1.0, v154
	v_rcp_f32_e32 v156, v154
	v_mul_f32_e32 v153, 0x3f317217, v152
	v_fma_f32 v153, v152, s24, -v153
	v_fmac_f32_e32 v153, 0x3377d1cf, v152
	v_fmac_f32_e32 v153, 0x3f317217, v152
	v_cmp_lt_f32_e64 s[4:5], |v152|, s15
	v_cndmask_b32_e64 v152, v152, v153, s[4:5]
	v_cndmask_b32_e32 v153, 0, v213, vcc
	v_mov_b32_e32 v155, v156
	v_sub_f32_e32 v152, v152, v153
	v_sub_f32_e32 v153, 1.0, v140
	v_mov_b32_e32 v154, v155
	v_fma_f32 v153, v154, v153, v140
	v_mul_f32_e32 v155, 0xbfb8aa3b, v125
	v_cmp_gt_f32_e32 vcc, s14, v153
	v_exp_f32_e32 v155, v155
	v_cvt_pk_f16_f32 v152, v147, v152
	v_cndmask_b32_e64 v154, 0, 32, vcc
	v_ldexp_f32 v153, v153, v154
	v_log_f32_e32 v153, v153
	v_add_f32_e32 v155, 1.0, v155
	v_rcp_f32_e32 v157, v155
	v_mul_f32_e32 v154, 0x3f317217, v153
	v_fma_f32 v154, v153, s24, -v154
	v_fmac_f32_e32 v154, 0x3377d1cf, v153
	v_fmac_f32_e32 v154, 0x3f317217, v153
	v_cmp_lt_f32_e64 s[4:5], |v153|, s15
	v_cndmask_b32_e64 v153, v153, v154, s[4:5]
	v_cndmask_b32_e32 v154, 0, v213, vcc
	v_mov_b32_e32 v156, v157
	v_sub_f32_e32 v153, v153, v154
	v_sub_f32_e32 v154, 1.0, v141
	v_mov_b32_e32 v155, v156
	v_fma_f32 v154, v155, v154, v141
	v_cmp_gt_f32_e32 vcc, s14, v154
	s_add_i32 s2, s34, -1
	s_mul_hi_i32 s3, s2, 0x2200000
	v_cndmask_b32_e64 v155, 0, 32, vcc
	v_ldexp_f32 v154, v154, v155
	v_log_f32_e32 v154, v154
	s_mul_i32 s2, s2, 0x2200000
	s_add_u32 s2, s60, s2
	s_addc_u32 s3, s61, s3
	v_mul_f32_e32 v155, 0x3f317217, v154
	v_fma_f32 v155, v154, s24, -v155
	v_fmac_f32_e32 v155, 0x3377d1cf, v154
	v_fmac_f32_e32 v155, 0x3f317217, v154
	v_cmp_lt_f32_e64 s[4:5], |v154|, s15
	v_readlane_b32 s50, v252, 18
	v_readlane_b32 s51, v252, 19
	v_cndmask_b32_e64 v154, v154, v155, s[4:5]
	v_cndmask_b32_e32 v155, 0, v213, vcc
	v_sub_f32_e32 v154, v154, v155
	v_cvt_pk_f16_f32 v153, v153, v154
	v_lshl_add_u64 v[154:155], s[2:3], 0, v[150:151]
	v_lshl_add_u64 v[154:155], v[154:155], 0, v[0:1]
	v_readlane_b32 s52, v252, 20
	v_readlane_b32 s53, v252, 21
	v_readlane_b32 s54, v252, 22
	v_readlane_b32 s55, v252, 23
	v_readlane_b32 s56, v252, 24
	v_readlane_b32 s57, v252, 25
	v_readlane_b32 s58, v252, 26
	v_readlane_b32 s59, v252, 27
	v_readlane_b32 s62, v252, 30
	v_readlane_b32 s63, v252, 31
	global_store_dwordx2 v[154:155], v[152:153], off offset:32

.LBB0_677:
	s_andn2_b64 vcc, exec, s[2:3]
	s_cbranch_vccnz .LBB0_679
	v_mul_f32_e32 v147, 0xbfb8aa3b, v122
	v_exp_f32_e32 v152, v147
	v_mul_f32_e32 v147, 0xbfb8aa3b, v123
	v_exp_f32_e32 v153, v147
	s_mov_b32 s4, 0x3db504f3
	v_pk_add_f32 v[152:153], v[152:153], 1.0 op_sel_hi:[1,0]
	s_nop 0
	v_rcp_f32_e32 v154, v153
	s_nop 0
	v_mul_f32_e32 v147, v123, v154
	v_mov_b32_e32 v153, v147
	v_rcp_f32_e32 v154, v152
	s_nop 0
	v_mul_f32_e32 v147, v122, v154
	v_mov_b32_e32 v152, v147
	v_mul_f32_e32 v147, 0xbfb8aa3b, v124
	v_exp_f32_e32 v154, v147
	v_mul_f32_e32 v147, 0xbfb8aa3b, v125
	v_exp_f32_e32 v155, v147
	v_pk_mul_f32 v[152:153], v[152:153], s[4:5] op_sel_hi:[1,0]
	v_pk_add_f32 v[154:155], v[154:155], 1.0 op_sel_hi:[1,0]
	s_nop 0
	v_rcp_f32_e32 v156, v155
	s_nop 0
	v_mul_f32_e32 v147, v125, v156
	v_mov_b32_e32 v155, v147
	v_rcp_f32_e32 v156, v154
	s_nop 0
	v_mul_f32_e32 v147, v124, v156
	v_mov_b32_e32 v154, v147
	v_pk_mul_f32 v[154:155], v[154:155], s[4:5] op_sel_hi:[1,0]
	v_bfe_u32 v157, v153, 16, 1
	v_bfe_u32 v147, v155, 16, 1
	v_bfe_u32 v156, v154, 16, 1
	v_bfe_u32 v158, v152, 16, 1
	v_add3_u32 v152, v152, v158, s0
	v_add3_u32 v157, v153, v157, s0
	v_add3_u32 v153, v154, v156, s0
	v_add3_u32 v147, v155, v147, s0
	v_perm_b32 v153, v147, v153, s19
	v_perm_b32 v152, v157, v152, s19
	v_lshl_add_u64 v[154:155], v[148:149], 0, v[0:1]
	global_store_dwordx2 v[154:155], v[152:153], off offset:32
.LBB0_679:
	s_and_b64 vcc, exec, s[40:41]
	s_mov_b64 s[2:3], -1
	s_cbranch_vccnz .LBB0_689
	s_cmp_lt_i32 s34, 3
	s_cbranch_scc1 .LBB0_686
	s_cmp_eq_u32 s34, 3
	s_cbranch_scc1 .LBB0_683
	v_mul_f32_e32 v147, 0xbfb8aa3b, v118
	v_exp_f32_e32 v152, v147
	v_mul_f32_e32 v147, 0xbfb8aa3b, v119
	v_exp_f32_e32 v153, v147
	v_readlane_b32 s48, v253, 4
	v_readlane_b32 s49, v253, 5
	v_readlane_b32 s50, v253, 6
	v_pk_add_f32 v[152:153], v[152:153], 1.0 op_sel_hi:[1,0]
	v_readlane_b32 s51, v253, 7
	v_rcp_f32_e32 v154, v152
	s_nop 0
	v_mul_f32_e32 v147, v118, v154
	v_rcp_f32_e32 v154, v153
	s_nop 0
	v_mul_f32_e32 v152, v119, v154
	v_mov_b32_e32 v154, v152
	v_mul_f32_e32 v152, 0xbfb8aa3b, v120
	v_mul_f32_e32 v153, 0xbfb8aa3b, v121
	v_exp_f32_e32 v152, v152
	v_exp_f32_e32 v153, v153
	s_nop 0
	v_pk_add_f32 v[152:153], v[152:153], 1.0 op_sel_hi:[1,0]
	s_nop 0
	v_rcp_f32_e32 v156, v152
	s_nop 0
	v_mul_f32_e32 v155, v120, v156
	v_mov_b32_e32 v152, v155
	v_rcp_f32_e32 v156, v153
	s_mov_b64 s[2:3], 0
	v_mul_f32_e32 v155, v121, v156
	v_mov_b32_e32 v153, v155
	v_bfe_u32 v155, v153, 16, 1
	v_bfe_u32 v156, v152, 16, 1
	v_bfe_u32 v157, v154, 16, 1
	v_bfe_u32 v158, v147, 16, 1
	v_add3_u32 v147, v147, v158, s0
	v_add3_u32 v154, v154, v157, s0
	v_add3_u32 v152, v152, v156, s0
	v_add3_u32 v153, v153, v155, s0
	v_perm_b32 v153, v153, v152, s19
	v_perm_b32 v152, v154, v147, s19
	v_lshl_add_u64 v[154:155], s[48:49], 0, v[150:151]
	v_lshl_add_u64 v[154:155], v[154:155], 0, v[0:1]
	global_store_dwordx2 v[154:155], v[152:153], off offset:64

.LBB0_686:
	s_andn2_b64 vcc, exec, s[2:3]
	s_cbranch_vccnz .LBB0_688
	v_mul_f32_e32 v152, 0xbfb8aa3b, v118
	v_exp_f32_e32 v152, v152
	s_waitcnt vmcnt(1)
	v_sub_f32_e32 v147, 1.0, v134
	s_mov_b32 s14, 0x800000
	s_mov_b32 s24, 0x3f317217
	v_add_f32_e32 v152, 1.0, v152
	v_rcp_f32_e32 v154, v152
	s_mov_b32 s15, 0x7f800000
	v_readlane_b32 s48, v252, 16
	v_readlane_b32 s60, v252, 28
	v_mov_b32_e32 v153, v154
	v_mov_b32_e32 v152, v153
	v_fma_f32 v147, v152, v147, v134
	v_mul_f32_e32 v153, 0xbfb8aa3b, v119
	v_cmp_gt_f32_e32 vcc, s14, v147
	v_exp_f32_e32 v153, v153
	v_readlane_b32 s61, v252, 29
	v_cndmask_b32_e64 v152, 0, 32, vcc
	v_ldexp_f32 v147, v147, v152
	v_log_f32_e32 v147, v147
	v_add_f32_e32 v153, 1.0, v153
	v_rcp_f32_e32 v155, v153
	v_mul_f32_e32 v152, 0x3f317217, v147
	v_fma_f32 v152, v147, s24, -v152
	v_fmac_f32_e32 v152, 0x3377d1cf, v147
	v_fmac_f32_e32 v152, 0x3f317217, v147
	v_cmp_lt_f32_e64 s[4:5], |v147|, s15
	v_cndmask_b32_e64 v147, v147, v152, s[4:5]
	v_cndmask_b32_e32 v152, 0, v213, vcc
	v_mov_b32_e32 v154, v155
	v_sub_f32_e32 v147, v147, v152
	v_sub_f32_e32 v152, 1.0, v135
	v_mov_b32_e32 v153, v154
	v_fma_f32 v152, v153, v152, v135
	v_mul_f32_e32 v154, 0xbfb8aa3b, v120
	v_cmp_gt_f32_e32 vcc, s14, v152
	v_exp_f32_e32 v154, v154
	v_readlane_b32 s49, v252, 17
	v_cndmask_b32_e64 v153, 0, 32, vcc
	v_ldexp_f32 v152, v152, v153
	v_log_f32_e32 v152, v152
	v_add_f32_e32 v154, 1.0, v154
	v_rcp_f32_e32 v156, v154
	v_mul_f32_e32 v153, 0x3f317217, v152
	v_fma_f32 v153, v152, s24, -v153
	v_fmac_f32_e32 v153, 0x3377d1cf, v152
	v_fmac_f32_e32 v153, 0x3f317217, v152
	v_cmp_lt_f32_e64 s[4:5], |v152|, s15
	v_cndmask_b32_e64 v152, v152, v153, s[4:5]
	v_cndmask_b32_e32 v153, 0, v213, vcc
	v_mov_b32_e32 v155, v156
	v_sub_f32_e32 v152, v152, v153
	v_sub_f32_e32 v153, 1.0, v136
	v_mov_b32_e32 v154, v155
	v_fma_f32 v153, v154, v153, v136
	v_mul_f32_e32 v155, 0xbfb8aa3b, v121
	v_cmp_gt_f32_e32 vcc, s14, v153
	v_exp_f32_e32 v155, v155
	v_cvt_pk_f16_f32 v152, v147, v152
	v_cndmask_b32_e64 v154, 0, 32, vcc
	v_ldexp_f32 v153, v153, v154
	v_log_f32_e32 v153, v153
	v_add_f32_e32 v155, 1.0, v155
	v_rcp_f32_e32 v157, v155
	v_mul_f32_e32 v154, 0x3f317217, v153
	v_fma_f32 v154, v153, s24, -v154
	v_fmac_f32_e32 v154, 0x3377d1cf, v153
	v_fmac_f32_e32 v154, 0x3f317217, v153
	v_cmp_lt_f32_e64 s[4:5], |v153|, s15
	v_cndmask_b32_e64 v153, v153, v154, s[4:5]
	v_cndmask_b32_e32 v154, 0, v213, vcc
	v_mov_b32_e32 v156, v157
	v_sub_f32_e32 v153, v153, v154
	v_sub_f32_e32 v154, 1.0, v137
	v_mov_b32_e32 v155, v156
	v_fma_f32 v154, v155, v154, v137
	v_cmp_gt_f32_e32 vcc, s14, v154
	s_add_i32 s2, s34, -1
	s_mul_hi_i32 s3, s2, 0x2200000
	v_cndmask_b32_e64 v155, 0, 32, vcc
	v_ldexp_f32 v154, v154, v155
	v_log_f32_e32 v154, v154
	s_mul_i32 s2, s2, 0x2200000
	s_add_u32 s2, s60, s2
	s_addc_u32 s3, s61, s3
	v_mul_f32_e32 v155, 0x3f317217, v154
	v_fma_f32 v155, v154, s24, -v155
	v_fmac_f32_e32 v155, 0x3377d1cf, v154
	v_fmac_f32_e32 v155, 0x3f317217, v154
	v_cmp_lt_f32_e64 s[4:5], |v154|, s15
	v_readlane_b32 s50, v252, 18
	v_readlane_b32 s51, v252, 19
	v_cndmask_b32_e64 v154, v154, v155, s[4:5]
	v_cndmask_b32_e32 v155, 0, v213, vcc
	v_sub_f32_e32 v154, v154, v155
	v_cvt_pk_f16_f32 v153, v153, v154
	v_lshl_add_u64 v[154:155], s[2:3], 0, v[150:151]
	v_lshl_add_u64 v[154:155], v[154:155], 0, v[0:1]
	v_readlane_b32 s52, v252, 20
	v_readlane_b32 s53, v252, 21
	v_readlane_b32 s54, v252, 22
	v_readlane_b32 s55, v252, 23
	v_readlane_b32 s56, v252, 24
	v_readlane_b32 s57, v252, 25
	v_readlane_b32 s58, v252, 26
	v_readlane_b32 s59, v252, 27
	v_readlane_b32 s62, v252, 30
	v_readlane_b32 s63, v252, 31
	global_store_dwordx2 v[154:155], v[152:153], off offset:64

.LBB0_689:
	s_andn2_b64 vcc, exec, s[2:3]
	s_cbranch_vccnz .LBB0_691
	v_mul_f32_e32 v147, 0xbfb8aa3b, v118
	v_exp_f32_e32 v152, v147
	v_mul_f32_e32 v147, 0xbfb8aa3b, v119
	v_exp_f32_e32 v153, v147
	s_mov_b32 s4, 0x3db504f3
	v_pk_add_f32 v[152:153], v[152:153], 1.0 op_sel_hi:[1,0]
	s_nop 0
	v_rcp_f32_e32 v154, v153
	s_nop 0
	v_mul_f32_e32 v147, v119, v154
	v_mov_b32_e32 v153, v147
	v_rcp_f32_e32 v154, v152
	s_nop 0
	v_mul_f32_e32 v147, v118, v154
	v_mov_b32_e32 v152, v147
	v_mul_f32_e32 v147, 0xbfb8aa3b, v120
	v_exp_f32_e32 v154, v147
	v_mul_f32_e32 v147, 0xbfb8aa3b, v121
	v_exp_f32_e32 v155, v147
	v_pk_mul_f32 v[152:153], v[152:153], s[4:5] op_sel_hi:[1,0]
	v_pk_add_f32 v[154:155], v[154:155], 1.0 op_sel_hi:[1,0]
	s_nop 0
	v_rcp_f32_e32 v156, v155
	s_nop 0
	v_mul_f32_e32 v147, v121, v156
	v_mov_b32_e32 v155, v147
	v_rcp_f32_e32 v156, v154
	s_nop 0
	v_mul_f32_e32 v147, v120, v156
	v_mov_b32_e32 v154, v147
	v_pk_mul_f32 v[154:155], v[154:155], s[4:5] op_sel_hi:[1,0]
	v_bfe_u32 v157, v153, 16, 1
	v_bfe_u32 v147, v155, 16, 1
	v_bfe_u32 v156, v154, 16, 1
	v_bfe_u32 v158, v152, 16, 1
	v_add3_u32 v152, v152, v158, s0
	v_add3_u32 v157, v153, v157, s0
	v_add3_u32 v153, v154, v156, s0
	v_add3_u32 v147, v155, v147, s0
	v_perm_b32 v153, v147, v153, s19
	v_perm_b32 v152, v157, v152, s19
	v_lshl_add_u64 v[154:155], v[148:149], 0, v[0:1]
	global_store_dwordx2 v[154:155], v[152:153], off offset:64
.LBB0_691:
	s_and_b64 vcc, exec, s[40:41]
	s_mov_b64 s[2:3], -1
	s_cbranch_vccnz .LBB0_701
	s_cmp_lt_i32 s34, 3
	s_cbranch_scc1 .LBB0_698
	s_cmp_eq_u32 s34, 3
	s_cbranch_scc1 .LBB0_695
	v_mul_f32_e32 v147, 0xbfb8aa3b, v114
	v_exp_f32_e32 v152, v147
	v_mul_f32_e32 v147, 0xbfb8aa3b, v115
	v_exp_f32_e32 v153, v147
	v_readlane_b32 s48, v253, 4
	v_readlane_b32 s49, v253, 5
	v_readlane_b32 s50, v253, 6
	v_pk_add_f32 v[152:153], v[152:153], 1.0 op_sel_hi:[1,0]
	v_readlane_b32 s51, v253, 7
	v_rcp_f32_e32 v154, v152
	s_nop 0
	v_mul_f32_e32 v147, v114, v154
	v_rcp_f32_e32 v154, v153
	s_nop 0
	v_mul_f32_e32 v152, v115, v154
	v_mov_b32_e32 v154, v152
	v_mul_f32_e32 v152, 0xbfb8aa3b, v116
	v_mul_f32_e32 v153, 0xbfb8aa3b, v117
	v_exp_f32_e32 v152, v152
	v_exp_f32_e32 v153, v153
	s_nop 0
	v_pk_add_f32 v[152:153], v[152:153], 1.0 op_sel_hi:[1,0]
	s_nop 0
	v_rcp_f32_e32 v156, v152
	s_nop 0
	v_mul_f32_e32 v155, v116, v156
	v_mov_b32_e32 v152, v155
	v_rcp_f32_e32 v156, v153
	s_mov_b64 s[2:3], 0
	v_mul_f32_e32 v155, v117, v156
	v_mov_b32_e32 v153, v155
	v_bfe_u32 v155, v153, 16, 1
	v_bfe_u32 v156, v152, 16, 1
	v_bfe_u32 v157, v154, 16, 1
	v_bfe_u32 v158, v147, 16, 1
	v_add3_u32 v147, v147, v158, s0
	v_add3_u32 v154, v154, v157, s0
	v_add3_u32 v152, v152, v156, s0
	v_add3_u32 v153, v153, v155, s0
	v_perm_b32 v153, v153, v152, s19
	v_perm_b32 v152, v154, v147, s19
	v_lshl_add_u64 v[154:155], s[48:49], 0, v[150:151]
	v_lshl_add_u64 v[154:155], v[154:155], 0, v[0:1]
	global_store_dwordx2 v[154:155], v[152:153], off offset:96

.LBB0_698:
	s_andn2_b64 vcc, exec, s[2:3]
	s_cbranch_vccnz .LBB0_700
	v_mul_f32_e32 v152, 0xbfb8aa3b, v114
	v_exp_f32_e32 v152, v152
	s_waitcnt vmcnt(0)
	v_sub_f32_e32 v147, 1.0, v130
	s_mov_b32 s14, 0x800000
	s_mov_b32 s24, 0x3f317217
	v_add_f32_e32 v152, 1.0, v152
	v_rcp_f32_e32 v154, v152
	s_mov_b32 s15, 0x7f800000
	v_readlane_b32 s48, v252, 16
	v_readlane_b32 s60, v252, 28
	v_mov_b32_e32 v153, v154
	v_mov_b32_e32 v152, v153
	v_fma_f32 v147, v152, v147, v130
	v_mul_f32_e32 v153, 0xbfb8aa3b, v115
	v_cmp_gt_f32_e32 vcc, s14, v147
	v_exp_f32_e32 v153, v153
	v_readlane_b32 s61, v252, 29
	v_cndmask_b32_e64 v152, 0, 32, vcc
	v_ldexp_f32 v147, v147, v152
	v_log_f32_e32 v147, v147
	v_add_f32_e32 v153, 1.0, v153
	v_rcp_f32_e32 v155, v153
	v_mul_f32_e32 v152, 0x3f317217, v147
	v_fma_f32 v152, v147, s24, -v152
	v_fmac_f32_e32 v152, 0x3377d1cf, v147
	v_fmac_f32_e32 v152, 0x3f317217, v147
	v_cmp_lt_f32_e64 s[4:5], |v147|, s15
	v_cndmask_b32_e64 v147, v147, v152, s[4:5]
	v_cndmask_b32_e32 v152, 0, v213, vcc
	v_mov_b32_e32 v154, v155
	v_sub_f32_e32 v147, v147, v152
	v_sub_f32_e32 v152, 1.0, v131
	v_mov_b32_e32 v153, v154
	v_fma_f32 v152, v153, v152, v131
	v_mul_f32_e32 v154, 0xbfb8aa3b, v116
	v_cmp_gt_f32_e32 vcc, s14, v152
	v_exp_f32_e32 v154, v154
	v_readlane_b32 s49, v252, 17
	v_cndmask_b32_e64 v153, 0, 32, vcc
	v_ldexp_f32 v152, v152, v153
	v_log_f32_e32 v152, v152
	v_add_f32_e32 v154, 1.0, v154
	v_rcp_f32_e32 v156, v154
	v_mul_f32_e32 v153, 0x3f317217, v152
	v_fma_f32 v153, v152, s24, -v153
	v_fmac_f32_e32 v153, 0x3377d1cf, v152
	v_fmac_f32_e32 v153, 0x3f317217, v152
	v_cmp_lt_f32_e64 s[4:5], |v152|, s15
	v_cndmask_b32_e64 v152, v152, v153, s[4:5]
	v_cndmask_b32_e32 v153, 0, v213, vcc
	v_mov_b32_e32 v155, v156
	v_sub_f32_e32 v152, v152, v153
	v_sub_f32_e32 v153, 1.0, v132
	v_mov_b32_e32 v154, v155
	v_fma_f32 v153, v154, v153, v132
	v_mul_f32_e32 v155, 0xbfb8aa3b, v117
	v_cmp_gt_f32_e32 vcc, s14, v153
	v_exp_f32_e32 v155, v155
	v_cvt_pk_f16_f32 v152, v147, v152
	v_cndmask_b32_e64 v154, 0, 32, vcc
	v_ldexp_f32 v153, v153, v154
	v_log_f32_e32 v153, v153
	v_add_f32_e32 v155, 1.0, v155
	v_rcp_f32_e32 v157, v155
	v_mul_f32_e32 v154, 0x3f317217, v153
	v_fma_f32 v154, v153, s24, -v154
	v_fmac_f32_e32 v154, 0x3377d1cf, v153
	v_fmac_f32_e32 v154, 0x3f317217, v153
	v_cmp_lt_f32_e64 s[4:5], |v153|, s15
	v_cndmask_b32_e64 v153, v153, v154, s[4:5]
	v_cndmask_b32_e32 v154, 0, v213, vcc
	v_mov_b32_e32 v156, v157
	v_sub_f32_e32 v153, v153, v154
	v_sub_f32_e32 v154, 1.0, v133
	v_mov_b32_e32 v155, v156
	v_fma_f32 v154, v155, v154, v133
	v_cmp_gt_f32_e32 vcc, s14, v154
	s_add_i32 s2, s34, -1
	s_mul_hi_i32 s3, s2, 0x2200000
	v_cndmask_b32_e64 v155, 0, 32, vcc
	v_ldexp_f32 v154, v154, v155
	v_log_f32_e32 v154, v154
	s_mul_i32 s2, s2, 0x2200000
	s_add_u32 s2, s60, s2
	s_addc_u32 s3, s61, s3
	v_mul_f32_e32 v155, 0x3f317217, v154
	v_fma_f32 v155, v154, s24, -v155
	v_fmac_f32_e32 v155, 0x3377d1cf, v154
	v_fmac_f32_e32 v155, 0x3f317217, v154
	v_cmp_lt_f32_e64 s[4:5], |v154|, s15
	v_lshl_add_u64 v[150:151], s[2:3], 0, v[150:151]
	v_lshl_add_u64 v[150:151], v[150:151], 0, v[0:1]
	v_cndmask_b32_e64 v154, v154, v155, s[4:5]
	v_cndmask_b32_e32 v155, 0, v213, vcc
	v_sub_f32_e32 v154, v154, v155
	v_cvt_pk_f16_f32 v153, v153, v154
	v_readlane_b32 s50, v252, 18
	v_readlane_b32 s51, v252, 19
	v_readlane_b32 s52, v252, 20
	v_readlane_b32 s53, v252, 21
	v_readlane_b32 s54, v252, 22
	v_readlane_b32 s55, v252, 23
	v_readlane_b32 s56, v252, 24
	v_readlane_b32 s57, v252, 25
	v_readlane_b32 s58, v252, 26
	v_readlane_b32 s59, v252, 27
	v_readlane_b32 s62, v252, 30
	v_readlane_b32 s63, v252, 31
	global_store_dwordx2 v[150:151], v[152:153], off offset:96

.LBB0_701:
	s_andn2_b64 vcc, exec, s[2:3]
	s_cbranch_vccnz .LBB0_703
	v_mul_f32_e32 v147, 0xbfb8aa3b, v114
	v_exp_f32_e32 v150, v147
	v_mul_f32_e32 v147, 0xbfb8aa3b, v115
	v_exp_f32_e32 v151, v147
	s_mov_b32 s4, 0x3db504f3
	v_lshl_add_u64 v[148:149], v[148:149], 0, v[0:1]
	v_pk_add_f32 v[150:151], v[150:151], 1.0 op_sel_hi:[1,0]
	s_nop 0
	v_rcp_f32_e32 v152, v151
	s_nop 0
	v_mul_f32_e32 v147, v115, v152
	v_mov_b32_e32 v151, v147
	v_rcp_f32_e32 v152, v150
	s_nop 0
	v_mul_f32_e32 v147, v114, v152
	v_mov_b32_e32 v150, v147
	v_mul_f32_e32 v147, 0xbfb8aa3b, v116
	v_exp_f32_e32 v152, v147
	v_mul_f32_e32 v147, 0xbfb8aa3b, v117
	v_exp_f32_e32 v153, v147
	v_pk_mul_f32 v[150:151], v[150:151], s[4:5] op_sel_hi:[1,0]
	v_pk_add_f32 v[152:153], v[152:153], 1.0 op_sel_hi:[1,0]
	s_nop 0
	v_rcp_f32_e32 v154, v153
	s_nop 0
	v_mul_f32_e32 v147, v117, v154
	v_mov_b32_e32 v153, v147
	v_rcp_f32_e32 v154, v152
	s_nop 0
	v_mul_f32_e32 v147, v116, v154
	v_mov_b32_e32 v152, v147
	v_pk_mul_f32 v[152:153], v[152:153], s[4:5] op_sel_hi:[1,0]
	v_bfe_u32 v155, v151, 16, 1
	v_bfe_u32 v147, v153, 16, 1
	v_bfe_u32 v154, v152, 16, 1
	v_bfe_u32 v156, v150, 16, 1
	v_add3_u32 v150, v150, v156, s0
	v_add3_u32 v155, v151, v155, s0
	v_add3_u32 v151, v152, v154, s0
	v_add3_u32 v147, v153, v147, s0
	v_perm_b32 v151, v147, v151, s19
	v_perm_b32 v150, v155, v150, s19
	global_store_dwordx2 v[148:149], v[150:151], off offset:96
.LBB0_703:
	v_or_b32_e32 v148, 16, v146
	v_ashrrev_i32_e32 v149, 31, v148
	s_and_b64 vcc, exec, s[40:41]
	s_mov_b64 s[2:3], -1
	s_cbranch_vccnz .LBB0_713
	s_cmp_lt_i32 s34, 3
	s_cbranch_scc1 .LBB0_710
	s_cmp_eq_u32 s34, 3
	s_cbranch_scc1 .LBB0_707
	v_mul_f32_e32 v147, 0xbfb8aa3b, v110
	v_exp_f32_e32 v150, v147
	v_mul_f32_e32 v147, 0xbfb8aa3b, v111
	v_exp_f32_e32 v151, v147
	v_readlane_b32 s48, v253, 4
	v_readlane_b32 s49, v253, 5
	v_readlane_b32 s50, v253, 6
	v_pk_add_f32 v[150:151], v[150:151], 1.0 op_sel_hi:[1,0]
	v_readlane_b32 s51, v253, 7
	v_rcp_f32_e32 v152, v150
	s_nop 0
	v_mul_f32_e32 v147, v110, v152
	v_rcp_f32_e32 v152, v151
	s_nop 0
	v_mul_f32_e32 v150, v111, v152
	v_mov_b32_e32 v152, v150
	v_mul_f32_e32 v150, 0xbfb8aa3b, v112
	v_mul_f32_e32 v151, 0xbfb8aa3b, v113
	v_exp_f32_e32 v150, v150
	v_exp_f32_e32 v151, v151
	s_nop 0
	v_pk_add_f32 v[150:151], v[150:151], 1.0 op_sel_hi:[1,0]
	s_nop 0
	v_rcp_f32_e32 v154, v150
	s_nop 0
	v_mul_f32_e32 v153, v112, v154
	v_mov_b32_e32 v150, v153
	v_rcp_f32_e32 v154, v151
	s_mov_b64 s[2:3], 0
	v_mul_f32_e32 v153, v113, v154
	v_mov_b32_e32 v151, v153
	v_bfe_u32 v153, v151, 16, 1
	v_bfe_u32 v154, v150, 16, 1
	v_bfe_u32 v155, v152, 16, 1
	v_bfe_u32 v156, v147, 16, 1
	v_add3_u32 v147, v147, v156, s0
	v_add3_u32 v152, v152, v155, s0
	v_add3_u32 v150, v150, v154, s0
	v_add3_u32 v151, v151, v153, s0
	v_perm_b32 v151, v151, v150, s19
	v_perm_b32 v150, v152, v147, s19
	v_lshlrev_b64 v[152:153], 11, v[148:149]
	v_lshl_add_u64 v[152:153], s[48:49], 0, v[152:153]
	v_lshl_add_u64 v[152:153], v[152:153], 0, v[0:1]
	global_store_dwordx2 v[152:153], v[150:151], off

.LBB0_710:
	s_andn2_b64 vcc, exec, s[2:3]
	s_cbranch_vccnz .LBB0_712
	v_mul_f32_e32 v150, 0xbfb8aa3b, v110
	v_exp_f32_e32 v150, v150
	s_waitcnt vmcnt(3)
	v_sub_f32_e32 v147, 1.0, v142
	s_mov_b32 s14, 0x800000
	s_mov_b32 s24, 0x3f317217
	v_add_f32_e32 v150, 1.0, v150
	v_rcp_f32_e32 v152, v150
	s_mov_b32 s15, 0x7f800000
	v_readlane_b32 s48, v252, 16
	v_readlane_b32 s60, v252, 28
	v_mov_b32_e32 v151, v152
	v_mov_b32_e32 v150, v151
	v_fma_f32 v147, v150, v147, v142
	v_mul_f32_e32 v151, 0xbfb8aa3b, v111
	v_cmp_gt_f32_e32 vcc, s14, v147
	v_exp_f32_e32 v151, v151
	v_readlane_b32 s61, v252, 29
	v_cndmask_b32_e64 v150, 0, 32, vcc
	v_ldexp_f32 v147, v147, v150
	v_log_f32_e32 v147, v147
	v_add_f32_e32 v151, 1.0, v151
	v_rcp_f32_e32 v153, v151
	v_mul_f32_e32 v150, 0x3f317217, v147
	v_fma_f32 v150, v147, s24, -v150
	v_fmac_f32_e32 v150, 0x3377d1cf, v147
	v_fmac_f32_e32 v150, 0x3f317217, v147
	v_cmp_lt_f32_e64 s[4:5], |v147|, s15
	v_cndmask_b32_e64 v147, v147, v150, s[4:5]
	v_cndmask_b32_e32 v150, 0, v213, vcc
	v_mov_b32_e32 v152, v153
	v_sub_f32_e32 v147, v147, v150
	v_sub_f32_e32 v150, 1.0, v143
	v_mov_b32_e32 v151, v152
	v_fma_f32 v150, v151, v150, v143
	v_mul_f32_e32 v152, 0xbfb8aa3b, v112
	v_cmp_gt_f32_e32 vcc, s14, v150
	v_exp_f32_e32 v152, v152
	v_readlane_b32 s49, v252, 17
	v_cndmask_b32_e64 v151, 0, 32, vcc
	v_ldexp_f32 v150, v150, v151
	v_log_f32_e32 v150, v150
	v_add_f32_e32 v152, 1.0, v152
	v_rcp_f32_e32 v154, v152
	v_mul_f32_e32 v151, 0x3f317217, v150
	v_fma_f32 v151, v150, s24, -v151
	v_fmac_f32_e32 v151, 0x3377d1cf, v150
	v_fmac_f32_e32 v151, 0x3f317217, v150
	v_cmp_lt_f32_e64 s[4:5], |v150|, s15
	v_cndmask_b32_e64 v150, v150, v151, s[4:5]
	v_cndmask_b32_e32 v151, 0, v213, vcc
	v_mov_b32_e32 v153, v154
	v_sub_f32_e32 v150, v150, v151
	v_sub_f32_e32 v151, 1.0, v144
	v_mov_b32_e32 v152, v153
	v_fma_f32 v151, v152, v151, v144
	v_mul_f32_e32 v153, 0xbfb8aa3b, v113
	v_cmp_gt_f32_e32 vcc, s14, v151
	v_exp_f32_e32 v153, v153
	v_cvt_pk_f16_f32 v150, v147, v150
	v_cndmask_b32_e64 v152, 0, 32, vcc
	v_ldexp_f32 v151, v151, v152
	v_log_f32_e32 v151, v151
	v_add_f32_e32 v153, 1.0, v153
	v_rcp_f32_e32 v155, v153
	v_mul_f32_e32 v152, 0x3f317217, v151
	v_fma_f32 v152, v151, s24, -v152
	v_fmac_f32_e32 v152, 0x3377d1cf, v151
	v_fmac_f32_e32 v152, 0x3f317217, v151
	v_cmp_lt_f32_e64 s[4:5], |v151|, s15
	v_cndmask_b32_e64 v151, v151, v152, s[4:5]
	v_cndmask_b32_e32 v152, 0, v213, vcc
	v_mov_b32_e32 v154, v155
	v_sub_f32_e32 v151, v151, v152
	v_sub_f32_e32 v152, 1.0, v145
	v_mov_b32_e32 v153, v154
	v_fma_f32 v152, v153, v152, v145
	v_cmp_gt_f32_e32 vcc, s14, v152
	s_add_i32 s2, s34, -1
	s_mul_hi_i32 s3, s2, 0x2200000
	v_cndmask_b32_e64 v153, 0, 32, vcc
	v_ldexp_f32 v152, v152, v153
	v_log_f32_e32 v152, v152
	s_mul_i32 s2, s2, 0x2200000
	s_add_u32 s2, s60, s2
	s_addc_u32 s3, s61, s3
	v_mul_f32_e32 v153, 0x3f317217, v152
	v_fma_f32 v153, v152, s24, -v153
	v_fmac_f32_e32 v153, 0x3377d1cf, v152
	v_fmac_f32_e32 v153, 0x3f317217, v152
	v_cmp_lt_f32_e64 s[4:5], |v152|, s15
	v_readlane_b32 s50, v252, 18
	v_readlane_b32 s51, v252, 19
	v_cndmask_b32_e64 v152, v152, v153, s[4:5]
	v_cndmask_b32_e32 v153, 0, v213, vcc
	v_sub_f32_e32 v152, v152, v153
	v_cvt_pk_f16_f32 v151, v151, v152
	v_lshlrev_b64 v[152:153], 11, v[148:149]
	v_lshl_add_u64 v[152:153], s[2:3], 0, v[152:153]
	v_lshl_add_u64 v[152:153], v[152:153], 0, v[0:1]
	v_readlane_b32 s52, v252, 20
	v_readlane_b32 s53, v252, 21
	v_readlane_b32 s54, v252, 22
	v_readlane_b32 s55, v252, 23
	v_readlane_b32 s56, v252, 24
	v_readlane_b32 s57, v252, 25
	v_readlane_b32 s58, v252, 26
	v_readlane_b32 s59, v252, 27
	v_readlane_b32 s62, v252, 30
	v_readlane_b32 s63, v252, 31
	global_store_dwordx2 v[152:153], v[150:151], off

.LBB0_713:
	v_readlane_b32 s48, v252, 16
	v_lshlrev_b64 v[150:151], 11, v[148:149]
	v_readlane_b32 s58, v252, 26
	v_readlane_b32 s59, v252, 27
	s_andn2_b64 vcc, exec, s[2:3]
	v_readlane_b32 s49, v252, 17
	v_lshl_add_u64 v[148:149], s[58:59], 0, v[150:151]
	v_readlane_b32 s50, v252, 18
	v_readlane_b32 s51, v252, 19
	v_readlane_b32 s52, v252, 20
	v_readlane_b32 s53, v252, 21
	v_readlane_b32 s54, v252, 22
	v_readlane_b32 s55, v252, 23
	v_readlane_b32 s56, v252, 24
	v_readlane_b32 s57, v252, 25
	v_readlane_b32 s60, v252, 28
	v_readlane_b32 s61, v252, 29
	v_readlane_b32 s62, v252, 30
	v_readlane_b32 s63, v252, 31
	s_cbranch_vccnz .LBB0_715
	v_mul_f32_e32 v147, 0xbfb8aa3b, v110
	v_exp_f32_e32 v152, v147
	v_mul_f32_e32 v147, 0xbfb8aa3b, v111
	v_exp_f32_e32 v153, v147
	s_mov_b32 s4, 0x3db504f3
	v_pk_add_f32 v[152:153], v[152:153], 1.0 op_sel_hi:[1,0]
	s_nop 0
	v_rcp_f32_e32 v154, v153
	s_nop 0
	v_mul_f32_e32 v147, v111, v154
	v_mov_b32_e32 v153, v147
	v_rcp_f32_e32 v154, v152
	s_nop 0
	v_mul_f32_e32 v147, v110, v154
	v_mov_b32_e32 v152, v147
	v_mul_f32_e32 v147, 0xbfb8aa3b, v112
	v_exp_f32_e32 v154, v147
	v_mul_f32_e32 v147, 0xbfb8aa3b, v113
	v_exp_f32_e32 v155, v147
	v_pk_mul_f32 v[152:153], v[152:153], s[4:5] op_sel_hi:[1,0]
	v_pk_add_f32 v[154:155], v[154:155], 1.0 op_sel_hi:[1,0]
	s_nop 0
	v_rcp_f32_e32 v156, v155
	s_nop 0
	v_mul_f32_e32 v147, v113, v156
	v_mov_b32_e32 v155, v147
	v_rcp_f32_e32 v156, v154
	s_nop 0
	v_mul_f32_e32 v147, v112, v156
	v_mov_b32_e32 v154, v147
	v_pk_mul_f32 v[154:155], v[154:155], s[4:5] op_sel_hi:[1,0]
	v_bfe_u32 v157, v153, 16, 1
	v_bfe_u32 v147, v155, 16, 1
	v_bfe_u32 v156, v154, 16, 1
	v_bfe_u32 v158, v152, 16, 1
	v_add3_u32 v152, v152, v158, s0
	v_add3_u32 v157, v153, v157, s0
	v_add3_u32 v153, v154, v156, s0
	v_add3_u32 v147, v155, v147, s0
	v_perm_b32 v153, v147, v153, s19
	v_perm_b32 v152, v157, v152, s19
	v_lshl_add_u64 v[154:155], v[148:149], 0, v[0:1]
	global_store_dwordx2 v[154:155], v[152:153], off
.LBB0_715:
	s_and_b64 vcc, exec, s[40:41]
	s_mov_b64 s[2:3], -1
	s_cbranch_vccnz .LBB0_725
	s_cmp_lt_i32 s34, 3
	s_cbranch_scc1 .LBB0_722
	s_cmp_eq_u32 s34, 3
	s_cbranch_scc1 .LBB0_719
	v_mul_f32_e32 v147, 0xbfb8aa3b, v106
	v_exp_f32_e32 v152, v147
	v_mul_f32_e32 v147, 0xbfb8aa3b, v107
	v_exp_f32_e32 v153, v147
	v_readlane_b32 s48, v253, 4
	v_readlane_b32 s49, v253, 5
	v_readlane_b32 s50, v253, 6
	v_pk_add_f32 v[152:153], v[152:153], 1.0 op_sel_hi:[1,0]
	v_readlane_b32 s51, v253, 7
	v_rcp_f32_e32 v154, v152
	s_nop 0
	v_mul_f32_e32 v147, v106, v154
	v_rcp_f32_e32 v154, v153
	s_nop 0
	v_mul_f32_e32 v152, v107, v154
	v_mov_b32_e32 v154, v152
	v_mul_f32_e32 v152, 0xbfb8aa3b, v108
	v_mul_f32_e32 v153, 0xbfb8aa3b, v109
	v_exp_f32_e32 v152, v152
	v_exp_f32_e32 v153, v153
	s_nop 0
	v_pk_add_f32 v[152:153], v[152:153], 1.0 op_sel_hi:[1,0]
	s_nop 0
	v_rcp_f32_e32 v156, v152
	s_nop 0
	v_mul_f32_e32 v155, v108, v156
	v_mov_b32_e32 v152, v155
	v_rcp_f32_e32 v156, v153
	s_mov_b64 s[2:3], 0
	v_mul_f32_e32 v155, v109, v156
	v_mov_b32_e32 v153, v155
	v_bfe_u32 v155, v153, 16, 1
	v_bfe_u32 v156, v152, 16, 1
	v_bfe_u32 v157, v154, 16, 1
	v_bfe_u32 v158, v147, 16, 1
	v_add3_u32 v147, v147, v158, s0
	v_add3_u32 v154, v154, v157, s0
	v_add3_u32 v152, v152, v156, s0
	v_add3_u32 v153, v153, v155, s0
	v_perm_b32 v153, v153, v152, s19
	v_perm_b32 v152, v154, v147, s19
	v_lshl_add_u64 v[154:155], s[48:49], 0, v[150:151]
	v_lshl_add_u64 v[154:155], v[154:155], 0, v[0:1]
	global_store_dwordx2 v[154:155], v[152:153], off offset:32

.LBB0_722:
	s_andn2_b64 vcc, exec, s[2:3]
	s_cbranch_vccnz .LBB0_724
	v_mul_f32_e32 v152, 0xbfb8aa3b, v106
	v_exp_f32_e32 v152, v152
	s_waitcnt vmcnt(2)
	v_sub_f32_e32 v147, 1.0, v138
	s_mov_b32 s14, 0x800000
	s_mov_b32 s24, 0x3f317217
	v_add_f32_e32 v152, 1.0, v152
	v_rcp_f32_e32 v154, v152
	s_mov_b32 s15, 0x7f800000
	v_readlane_b32 s48, v252, 16
	v_readlane_b32 s60, v252, 28
	v_mov_b32_e32 v153, v154
	v_mov_b32_e32 v152, v153
	v_fma_f32 v147, v152, v147, v138
	v_mul_f32_e32 v153, 0xbfb8aa3b, v107
	v_cmp_gt_f32_e32 vcc, s14, v147
	v_exp_f32_e32 v153, v153
	v_readlane_b32 s61, v252, 29
	v_cndmask_b32_e64 v152, 0, 32, vcc
	v_ldexp_f32 v147, v147, v152
	v_log_f32_e32 v147, v147
	v_add_f32_e32 v153, 1.0, v153
	v_rcp_f32_e32 v155, v153
	v_mul_f32_e32 v152, 0x3f317217, v147
	v_fma_f32 v152, v147, s24, -v152
	v_fmac_f32_e32 v152, 0x3377d1cf, v147
	v_fmac_f32_e32 v152, 0x3f317217, v147
	v_cmp_lt_f32_e64 s[4:5], |v147|, s15
	v_cndmask_b32_e64 v147, v147, v152, s[4:5]
	v_cndmask_b32_e32 v152, 0, v213, vcc
	v_mov_b32_e32 v154, v155
	v_sub_f32_e32 v147, v147, v152
	v_sub_f32_e32 v152, 1.0, v139
	v_mov_b32_e32 v153, v154
	v_fma_f32 v152, v153, v152, v139
	v_mul_f32_e32 v154, 0xbfb8aa3b, v108
	v_cmp_gt_f32_e32 vcc, s14, v152
	v_exp_f32_e32 v154, v154
	v_readlane_b32 s49, v252, 17
	v_cndmask_b32_e64 v153, 0, 32, vcc
	v_ldexp_f32 v152, v152, v153
	v_log_f32_e32 v152, v152
	v_add_f32_e32 v154, 1.0, v154
	v_rcp_f32_e32 v156, v154
	v_mul_f32_e32 v153, 0x3f317217, v152
	v_fma_f32 v153, v152, s24, -v153
	v_fmac_f32_e32 v153, 0x3377d1cf, v152
	v_fmac_f32_e32 v153, 0x3f317217, v152
	v_cmp_lt_f32_e64 s[4:5], |v152|, s15
	v_cndmask_b32_e64 v152, v152, v153, s[4:5]
	v_cndmask_b32_e32 v153, 0, v213, vcc
	v_mov_b32_e32 v155, v156
	v_sub_f32_e32 v152, v152, v153
	v_sub_f32_e32 v153, 1.0, v140
	v_mov_b32_e32 v154, v155
	v_fma_f32 v153, v154, v153, v140
	v_mul_f32_e32 v155, 0xbfb8aa3b, v109
	v_cmp_gt_f32_e32 vcc, s14, v153
	v_exp_f32_e32 v155, v155
	v_cvt_pk_f16_f32 v152, v147, v152
	v_cndmask_b32_e64 v154, 0, 32, vcc
	v_ldexp_f32 v153, v153, v154
	v_log_f32_e32 v153, v153
	v_add_f32_e32 v155, 1.0, v155
	v_rcp_f32_e32 v157, v155
	v_mul_f32_e32 v154, 0x3f317217, v153
	v_fma_f32 v154, v153, s24, -v154
	v_fmac_f32_e32 v154, 0x3377d1cf, v153
	v_fmac_f32_e32 v154, 0x3f317217, v153
	v_cmp_lt_f32_e64 s[4:5], |v153|, s15
	v_cndmask_b32_e64 v153, v153, v154, s[4:5]
	v_cndmask_b32_e32 v154, 0, v213, vcc
	v_mov_b32_e32 v156, v157
	v_sub_f32_e32 v153, v153, v154
	v_sub_f32_e32 v154, 1.0, v141
	v_mov_b32_e32 v155, v156
	v_fma_f32 v154, v155, v154, v141
	v_cmp_gt_f32_e32 vcc, s14, v154
	s_add_i32 s2, s34, -1
	s_mul_hi_i32 s3, s2, 0x2200000
	v_cndmask_b32_e64 v155, 0, 32, vcc
	v_ldexp_f32 v154, v154, v155
	v_log_f32_e32 v154, v154
	s_mul_i32 s2, s2, 0x2200000
	s_add_u32 s2, s60, s2
	s_addc_u32 s3, s61, s3
	v_mul_f32_e32 v155, 0x3f317217, v154
	v_fma_f32 v155, v154, s24, -v155
	v_fmac_f32_e32 v155, 0x3377d1cf, v154
	v_fmac_f32_e32 v155, 0x3f317217, v154
	v_cmp_lt_f32_e64 s[4:5], |v154|, s15
	v_readlane_b32 s50, v252, 18
	v_readlane_b32 s51, v252, 19
	v_cndmask_b32_e64 v154, v154, v155, s[4:5]
	v_cndmask_b32_e32 v155, 0, v213, vcc
	v_sub_f32_e32 v154, v154, v155
	v_cvt_pk_f16_f32 v153, v153, v154
	v_lshl_add_u64 v[154:155], s[2:3], 0, v[150:151]
	v_lshl_add_u64 v[154:155], v[154:155], 0, v[0:1]
	v_readlane_b32 s52, v252, 20
	v_readlane_b32 s53, v252, 21
	v_readlane_b32 s54, v252, 22
	v_readlane_b32 s55, v252, 23
	v_readlane_b32 s56, v252, 24
	v_readlane_b32 s57, v252, 25
	v_readlane_b32 s58, v252, 26
	v_readlane_b32 s59, v252, 27
	v_readlane_b32 s62, v252, 30
	v_readlane_b32 s63, v252, 31
	global_store_dwordx2 v[154:155], v[152:153], off offset:32

.LBB0_725:
	s_andn2_b64 vcc, exec, s[2:3]
	s_cbranch_vccnz .LBB0_727
	v_mul_f32_e32 v147, 0xbfb8aa3b, v106
	v_exp_f32_e32 v152, v147
	v_mul_f32_e32 v147, 0xbfb8aa3b, v107
	v_exp_f32_e32 v153, v147
	s_mov_b32 s4, 0x3db504f3
	v_pk_add_f32 v[152:153], v[152:153], 1.0 op_sel_hi:[1,0]
	s_nop 0
	v_rcp_f32_e32 v154, v153
	s_nop 0
	v_mul_f32_e32 v147, v107, v154
	v_mov_b32_e32 v153, v147
	v_rcp_f32_e32 v154, v152
	s_nop 0
	v_mul_f32_e32 v147, v106, v154
	v_mov_b32_e32 v152, v147
	v_mul_f32_e32 v147, 0xbfb8aa3b, v108
	v_exp_f32_e32 v154, v147
	v_mul_f32_e32 v147, 0xbfb8aa3b, v109
	v_exp_f32_e32 v155, v147
	v_pk_mul_f32 v[152:153], v[152:153], s[4:5] op_sel_hi:[1,0]
	v_pk_add_f32 v[154:155], v[154:155], 1.0 op_sel_hi:[1,0]
	s_nop 0
	v_rcp_f32_e32 v156, v155
	s_nop 0
	v_mul_f32_e32 v147, v109, v156
	v_mov_b32_e32 v155, v147
	v_rcp_f32_e32 v156, v154
	s_nop 0
	v_mul_f32_e32 v147, v108, v156
	v_mov_b32_e32 v154, v147
	v_pk_mul_f32 v[154:155], v[154:155], s[4:5] op_sel_hi:[1,0]
	v_bfe_u32 v157, v153, 16, 1
	v_bfe_u32 v147, v155, 16, 1
	v_bfe_u32 v156, v154, 16, 1
	v_bfe_u32 v158, v152, 16, 1
	v_add3_u32 v152, v152, v158, s0
	v_add3_u32 v157, v153, v157, s0
	v_add3_u32 v153, v154, v156, s0
	v_add3_u32 v147, v155, v147, s0
	v_perm_b32 v153, v147, v153, s19
	v_perm_b32 v152, v157, v152, s19
	v_lshl_add_u64 v[154:155], v[148:149], 0, v[0:1]
	global_store_dwordx2 v[154:155], v[152:153], off offset:32
.LBB0_727:
	s_and_b64 vcc, exec, s[40:41]
	s_mov_b64 s[2:3], -1
	s_cbranch_vccnz .LBB0_737
	s_cmp_lt_i32 s34, 3
	s_cbranch_scc1 .LBB0_734
	s_cmp_eq_u32 s34, 3
	s_cbranch_scc1 .LBB0_731
	v_mul_f32_e32 v147, 0xbfb8aa3b, v102
	v_exp_f32_e32 v152, v147
	v_mul_f32_e32 v147, 0xbfb8aa3b, v103
	v_exp_f32_e32 v153, v147
	v_readlane_b32 s48, v253, 4
	v_readlane_b32 s49, v253, 5
	v_readlane_b32 s50, v253, 6
	v_pk_add_f32 v[152:153], v[152:153], 1.0 op_sel_hi:[1,0]
	v_readlane_b32 s51, v253, 7
	v_rcp_f32_e32 v154, v152
	s_nop 0
	v_mul_f32_e32 v147, v102, v154
	v_rcp_f32_e32 v154, v153
	s_nop 0
	v_mul_f32_e32 v152, v103, v154
	v_mov_b32_e32 v154, v152
	v_mul_f32_e32 v152, 0xbfb8aa3b, v104
	v_mul_f32_e32 v153, 0xbfb8aa3b, v105
	v_exp_f32_e32 v152, v152
	v_exp_f32_e32 v153, v153
	s_nop 0
	v_pk_add_f32 v[152:153], v[152:153], 1.0 op_sel_hi:[1,0]
	s_nop 0
	v_rcp_f32_e32 v156, v152
	s_nop 0
	v_mul_f32_e32 v155, v104, v156
	v_mov_b32_e32 v152, v155
	v_rcp_f32_e32 v156, v153
	s_mov_b64 s[2:3], 0
	v_mul_f32_e32 v155, v105, v156
	v_mov_b32_e32 v153, v155
	v_bfe_u32 v155, v153, 16, 1
	v_bfe_u32 v156, v152, 16, 1
	v_bfe_u32 v157, v154, 16, 1
	v_bfe_u32 v158, v147, 16, 1
	v_add3_u32 v147, v147, v158, s0
	v_add3_u32 v154, v154, v157, s0
	v_add3_u32 v152, v152, v156, s0
	v_add3_u32 v153, v153, v155, s0
	v_perm_b32 v153, v153, v152, s19
	v_perm_b32 v152, v154, v147, s19
	v_lshl_add_u64 v[154:155], s[48:49], 0, v[150:151]
	v_lshl_add_u64 v[154:155], v[154:155], 0, v[0:1]
	global_store_dwordx2 v[154:155], v[152:153], off offset:64

.LBB0_734:
	s_andn2_b64 vcc, exec, s[2:3]
	s_cbranch_vccnz .LBB0_736
	v_mul_f32_e32 v152, 0xbfb8aa3b, v102
	v_exp_f32_e32 v152, v152
	s_waitcnt vmcnt(1)
	v_sub_f32_e32 v147, 1.0, v134
	s_mov_b32 s14, 0x800000
	s_mov_b32 s24, 0x3f317217
	v_add_f32_e32 v152, 1.0, v152
	v_rcp_f32_e32 v154, v152
	s_mov_b32 s15, 0x7f800000
	v_readlane_b32 s48, v252, 16
	v_readlane_b32 s60, v252, 28
	v_mov_b32_e32 v153, v154
	v_mov_b32_e32 v152, v153
	v_fma_f32 v147, v152, v147, v134
	v_mul_f32_e32 v153, 0xbfb8aa3b, v103
	v_cmp_gt_f32_e32 vcc, s14, v147
	v_exp_f32_e32 v153, v153
	v_readlane_b32 s61, v252, 29
	v_cndmask_b32_e64 v152, 0, 32, vcc
	v_ldexp_f32 v147, v147, v152
	v_log_f32_e32 v147, v147
	v_add_f32_e32 v153, 1.0, v153
	v_rcp_f32_e32 v155, v153
	v_mul_f32_e32 v152, 0x3f317217, v147
	v_fma_f32 v152, v147, s24, -v152
	v_fmac_f32_e32 v152, 0x3377d1cf, v147
	v_fmac_f32_e32 v152, 0x3f317217, v147
	v_cmp_lt_f32_e64 s[4:5], |v147|, s15
	v_cndmask_b32_e64 v147, v147, v152, s[4:5]
	v_cndmask_b32_e32 v152, 0, v213, vcc
	v_mov_b32_e32 v154, v155
	v_sub_f32_e32 v147, v147, v152
	v_sub_f32_e32 v152, 1.0, v135
	v_mov_b32_e32 v153, v154
	v_fma_f32 v152, v153, v152, v135
	v_mul_f32_e32 v154, 0xbfb8aa3b, v104
	v_cmp_gt_f32_e32 vcc, s14, v152
	v_exp_f32_e32 v154, v154
	v_readlane_b32 s49, v252, 17
	v_cndmask_b32_e64 v153, 0, 32, vcc
	v_ldexp_f32 v152, v152, v153
	v_log_f32_e32 v152, v152
	v_add_f32_e32 v154, 1.0, v154
	v_rcp_f32_e32 v156, v154
	v_mul_f32_e32 v153, 0x3f317217, v152
	v_fma_f32 v153, v152, s24, -v153
	v_fmac_f32_e32 v153, 0x3377d1cf, v152
	v_fmac_f32_e32 v153, 0x3f317217, v152
	v_cmp_lt_f32_e64 s[4:5], |v152|, s15
	v_cndmask_b32_e64 v152, v152, v153, s[4:5]
	v_cndmask_b32_e32 v153, 0, v213, vcc
	v_mov_b32_e32 v155, v156
	v_sub_f32_e32 v152, v152, v153
	v_sub_f32_e32 v153, 1.0, v136
	v_mov_b32_e32 v154, v155
	v_fma_f32 v153, v154, v153, v136
	v_mul_f32_e32 v155, 0xbfb8aa3b, v105
	v_cmp_gt_f32_e32 vcc, s14, v153
	v_exp_f32_e32 v155, v155
	v_cvt_pk_f16_f32 v152, v147, v152
	v_cndmask_b32_e64 v154, 0, 32, vcc
	v_ldexp_f32 v153, v153, v154
	v_log_f32_e32 v153, v153
	v_add_f32_e32 v155, 1.0, v155
	v_rcp_f32_e32 v157, v155
	v_mul_f32_e32 v154, 0x3f317217, v153
	v_fma_f32 v154, v153, s24, -v154
	v_fmac_f32_e32 v154, 0x3377d1cf, v153
	v_fmac_f32_e32 v154, 0x3f317217, v153
	v_cmp_lt_f32_e64 s[4:5], |v153|, s15
	v_cndmask_b32_e64 v153, v153, v154, s[4:5]
	v_cndmask_b32_e32 v154, 0, v213, vcc
	v_mov_b32_e32 v156, v157
	v_sub_f32_e32 v153, v153, v154
	v_sub_f32_e32 v154, 1.0, v137
	v_mov_b32_e32 v155, v156
	v_fma_f32 v154, v155, v154, v137
	v_cmp_gt_f32_e32 vcc, s14, v154
	s_add_i32 s2, s34, -1
	s_mul_hi_i32 s3, s2, 0x2200000
	v_cndmask_b32_e64 v155, 0, 32, vcc
	v_ldexp_f32 v154, v154, v155
	v_log_f32_e32 v154, v154
	s_mul_i32 s2, s2, 0x2200000
	s_add_u32 s2, s60, s2
	s_addc_u32 s3, s61, s3
	v_mul_f32_e32 v155, 0x3f317217, v154
	v_fma_f32 v155, v154, s24, -v155
	v_fmac_f32_e32 v155, 0x3377d1cf, v154
	v_fmac_f32_e32 v155, 0x3f317217, v154
	v_cmp_lt_f32_e64 s[4:5], |v154|, s15
	v_readlane_b32 s50, v252, 18
	v_readlane_b32 s51, v252, 19
	v_cndmask_b32_e64 v154, v154, v155, s[4:5]
	v_cndmask_b32_e32 v155, 0, v213, vcc
	v_sub_f32_e32 v154, v154, v155
	v_cvt_pk_f16_f32 v153, v153, v154
	v_lshl_add_u64 v[154:155], s[2:3], 0, v[150:151]
	v_lshl_add_u64 v[154:155], v[154:155], 0, v[0:1]
	v_readlane_b32 s52, v252, 20
	v_readlane_b32 s53, v252, 21
	v_readlane_b32 s54, v252, 22
	v_readlane_b32 s55, v252, 23
	v_readlane_b32 s56, v252, 24
	v_readlane_b32 s57, v252, 25
	v_readlane_b32 s58, v252, 26
	v_readlane_b32 s59, v252, 27
	v_readlane_b32 s62, v252, 30
	v_readlane_b32 s63, v252, 31
	global_store_dwordx2 v[154:155], v[152:153], off offset:64

.LBB0_737:
	s_andn2_b64 vcc, exec, s[2:3]
	s_cbranch_vccnz .LBB0_739
	v_mul_f32_e32 v147, 0xbfb8aa3b, v102
	v_exp_f32_e32 v152, v147
	v_mul_f32_e32 v147, 0xbfb8aa3b, v103
	v_exp_f32_e32 v153, v147
	s_mov_b32 s4, 0x3db504f3
	v_pk_add_f32 v[152:153], v[152:153], 1.0 op_sel_hi:[1,0]
	s_nop 0
	v_rcp_f32_e32 v154, v153
	s_nop 0
	v_mul_f32_e32 v147, v103, v154
	v_mov_b32_e32 v153, v147
	v_rcp_f32_e32 v154, v152
	s_nop 0
	v_mul_f32_e32 v147, v102, v154
	v_mov_b32_e32 v152, v147
	v_mul_f32_e32 v147, 0xbfb8aa3b, v104
	v_exp_f32_e32 v154, v147
	v_mul_f32_e32 v147, 0xbfb8aa3b, v105
	v_exp_f32_e32 v155, v147
	v_pk_mul_f32 v[152:153], v[152:153], s[4:5] op_sel_hi:[1,0]
	v_pk_add_f32 v[154:155], v[154:155], 1.0 op_sel_hi:[1,0]
	s_nop 0
	v_rcp_f32_e32 v156, v155
	s_nop 0
	v_mul_f32_e32 v147, v105, v156
	v_mov_b32_e32 v155, v147
	v_rcp_f32_e32 v156, v154
	s_nop 0
	v_mul_f32_e32 v147, v104, v156
	v_mov_b32_e32 v154, v147
	v_pk_mul_f32 v[154:155], v[154:155], s[4:5] op_sel_hi:[1,0]
	v_bfe_u32 v157, v153, 16, 1
	v_bfe_u32 v147, v155, 16, 1
	v_bfe_u32 v156, v154, 16, 1
	v_bfe_u32 v158, v152, 16, 1
	v_add3_u32 v152, v152, v158, s0
	v_add3_u32 v157, v153, v157, s0
	v_add3_u32 v153, v154, v156, s0
	v_add3_u32 v147, v155, v147, s0
	v_perm_b32 v153, v147, v153, s19
	v_perm_b32 v152, v157, v152, s19
	v_lshl_add_u64 v[154:155], v[148:149], 0, v[0:1]
	global_store_dwordx2 v[154:155], v[152:153], off offset:64
.LBB0_739:
	s_and_b64 vcc, exec, s[40:41]
	s_mov_b64 s[2:3], -1
	s_cbranch_vccnz .LBB0_749
	s_cmp_lt_i32 s34, 3
	s_cbranch_scc1 .LBB0_746
	s_cmp_eq_u32 s34, 3
	s_cbranch_scc1 .LBB0_743
	v_mul_f32_e32 v147, 0xbfb8aa3b, v98
	v_exp_f32_e32 v152, v147
	v_mul_f32_e32 v147, 0xbfb8aa3b, v99
	v_exp_f32_e32 v153, v147
	v_readlane_b32 s48, v253, 4
	v_readlane_b32 s49, v253, 5
	v_readlane_b32 s50, v253, 6
	v_pk_add_f32 v[152:153], v[152:153], 1.0 op_sel_hi:[1,0]
	v_readlane_b32 s51, v253, 7
	v_rcp_f32_e32 v154, v152
	s_nop 0
	v_mul_f32_e32 v147, v98, v154
	v_rcp_f32_e32 v154, v153
	s_nop 0
	v_mul_f32_e32 v152, v99, v154
	v_mov_b32_e32 v154, v152
	v_mul_f32_e32 v152, 0xbfb8aa3b, v100
	v_mul_f32_e32 v153, 0xbfb8aa3b, v101
	v_exp_f32_e32 v152, v152
	v_exp_f32_e32 v153, v153
	s_nop 0
	v_pk_add_f32 v[152:153], v[152:153], 1.0 op_sel_hi:[1,0]
	s_nop 0
	v_rcp_f32_e32 v156, v152
	s_nop 0
	v_mul_f32_e32 v155, v100, v156
	v_mov_b32_e32 v152, v155
	v_rcp_f32_e32 v156, v153
	s_mov_b64 s[2:3], 0
	v_mul_f32_e32 v155, v101, v156
	v_mov_b32_e32 v153, v155
	v_bfe_u32 v155, v153, 16, 1
	v_bfe_u32 v156, v152, 16, 1
	v_bfe_u32 v157, v154, 16, 1
	v_bfe_u32 v158, v147, 16, 1
	v_add3_u32 v147, v147, v158, s0
	v_add3_u32 v154, v154, v157, s0
	v_add3_u32 v152, v152, v156, s0
	v_add3_u32 v153, v153, v155, s0
	v_perm_b32 v153, v153, v152, s19
	v_perm_b32 v152, v154, v147, s19
	v_lshl_add_u64 v[154:155], s[48:49], 0, v[150:151]
	v_lshl_add_u64 v[154:155], v[154:155], 0, v[0:1]
	global_store_dwordx2 v[154:155], v[152:153], off offset:96

.LBB0_746:
	s_andn2_b64 vcc, exec, s[2:3]
	s_cbranch_vccnz .LBB0_748
	v_mul_f32_e32 v152, 0xbfb8aa3b, v98
	v_exp_f32_e32 v152, v152
	s_waitcnt vmcnt(0)
	v_sub_f32_e32 v147, 1.0, v130
	s_mov_b32 s14, 0x800000
	s_mov_b32 s24, 0x3f317217
	v_add_f32_e32 v152, 1.0, v152
	v_rcp_f32_e32 v154, v152
	s_mov_b32 s15, 0x7f800000
	v_readlane_b32 s48, v252, 16
	v_readlane_b32 s60, v252, 28
	v_mov_b32_e32 v153, v154
	v_mov_b32_e32 v152, v153
	v_fma_f32 v147, v152, v147, v130
	v_mul_f32_e32 v153, 0xbfb8aa3b, v99
	v_cmp_gt_f32_e32 vcc, s14, v147
	v_exp_f32_e32 v153, v153
	v_readlane_b32 s61, v252, 29
	v_cndmask_b32_e64 v152, 0, 32, vcc
	v_ldexp_f32 v147, v147, v152
	v_log_f32_e32 v147, v147
	v_add_f32_e32 v153, 1.0, v153
	v_rcp_f32_e32 v155, v153
	v_mul_f32_e32 v152, 0x3f317217, v147
	v_fma_f32 v152, v147, s24, -v152
	v_fmac_f32_e32 v152, 0x3377d1cf, v147
	v_fmac_f32_e32 v152, 0x3f317217, v147
	v_cmp_lt_f32_e64 s[4:5], |v147|, s15
	v_cndmask_b32_e64 v147, v147, v152, s[4:5]
	v_cndmask_b32_e32 v152, 0, v213, vcc
	v_mov_b32_e32 v154, v155
	v_sub_f32_e32 v147, v147, v152
	v_sub_f32_e32 v152, 1.0, v131
	v_mov_b32_e32 v153, v154
	v_fma_f32 v152, v153, v152, v131
	v_mul_f32_e32 v154, 0xbfb8aa3b, v100
	v_cmp_gt_f32_e32 vcc, s14, v152
	v_exp_f32_e32 v154, v154
	v_readlane_b32 s49, v252, 17
	v_cndmask_b32_e64 v153, 0, 32, vcc
	v_ldexp_f32 v152, v152, v153
	v_log_f32_e32 v152, v152
	v_add_f32_e32 v154, 1.0, v154
	v_rcp_f32_e32 v156, v154
	v_mul_f32_e32 v153, 0x3f317217, v152
	v_fma_f32 v153, v152, s24, -v153
	v_fmac_f32_e32 v153, 0x3377d1cf, v152
	v_fmac_f32_e32 v153, 0x3f317217, v152
	v_cmp_lt_f32_e64 s[4:5], |v152|, s15
	v_cndmask_b32_e64 v152, v152, v153, s[4:5]
	v_cndmask_b32_e32 v153, 0, v213, vcc
	v_mov_b32_e32 v155, v156
	v_sub_f32_e32 v152, v152, v153
	v_sub_f32_e32 v153, 1.0, v132
	v_mov_b32_e32 v154, v155
	v_fma_f32 v153, v154, v153, v132
	v_mul_f32_e32 v155, 0xbfb8aa3b, v101
	v_cmp_gt_f32_e32 vcc, s14, v153
	v_exp_f32_e32 v155, v155
	v_cvt_pk_f16_f32 v152, v147, v152
	v_cndmask_b32_e64 v154, 0, 32, vcc
	v_ldexp_f32 v153, v153, v154
	v_log_f32_e32 v153, v153
	v_add_f32_e32 v155, 1.0, v155
	v_rcp_f32_e32 v157, v155
	v_mul_f32_e32 v154, 0x3f317217, v153
	v_fma_f32 v154, v153, s24, -v154
	v_fmac_f32_e32 v154, 0x3377d1cf, v153
	v_fmac_f32_e32 v154, 0x3f317217, v153
	v_cmp_lt_f32_e64 s[4:5], |v153|, s15
	v_cndmask_b32_e64 v153, v153, v154, s[4:5]
	v_cndmask_b32_e32 v154, 0, v213, vcc
	v_mov_b32_e32 v156, v157
	v_sub_f32_e32 v153, v153, v154
	v_sub_f32_e32 v154, 1.0, v133
	v_mov_b32_e32 v155, v156
	v_fma_f32 v154, v155, v154, v133
	v_cmp_gt_f32_e32 vcc, s14, v154
	s_add_i32 s2, s34, -1
	s_mul_hi_i32 s3, s2, 0x2200000
	v_cndmask_b32_e64 v155, 0, 32, vcc
	v_ldexp_f32 v154, v154, v155
	v_log_f32_e32 v154, v154
	s_mul_i32 s2, s2, 0x2200000
	s_add_u32 s2, s60, s2
	s_addc_u32 s3, s61, s3
	v_mul_f32_e32 v155, 0x3f317217, v154
	v_fma_f32 v155, v154, s24, -v155
	v_fmac_f32_e32 v155, 0x3377d1cf, v154
	v_fmac_f32_e32 v155, 0x3f317217, v154
	v_cmp_lt_f32_e64 s[4:5], |v154|, s15
	v_lshl_add_u64 v[150:151], s[2:3], 0, v[150:151]
	v_lshl_add_u64 v[150:151], v[150:151], 0, v[0:1]
	v_cndmask_b32_e64 v154, v154, v155, s[4:5]
	v_cndmask_b32_e32 v155, 0, v213, vcc
	v_sub_f32_e32 v154, v154, v155
	v_cvt_pk_f16_f32 v153, v153, v154
	v_readlane_b32 s50, v252, 18
	v_readlane_b32 s51, v252, 19
	v_readlane_b32 s52, v252, 20
	v_readlane_b32 s53, v252, 21
	v_readlane_b32 s54, v252, 22
	v_readlane_b32 s55, v252, 23
	v_readlane_b32 s56, v252, 24
	v_readlane_b32 s57, v252, 25
	v_readlane_b32 s58, v252, 26
	v_readlane_b32 s59, v252, 27
	v_readlane_b32 s62, v252, 30
	v_readlane_b32 s63, v252, 31
	global_store_dwordx2 v[150:151], v[152:153], off offset:96

.LBB0_749:
	s_andn2_b64 vcc, exec, s[2:3]
	s_cbranch_vccnz .LBB0_751
	v_mul_f32_e32 v147, 0xbfb8aa3b, v98
	v_exp_f32_e32 v150, v147
	v_mul_f32_e32 v147, 0xbfb8aa3b, v99
	v_exp_f32_e32 v151, v147
	s_mov_b32 s4, 0x3db504f3
	v_lshl_add_u64 v[148:149], v[148:149], 0, v[0:1]
	v_pk_add_f32 v[150:151], v[150:151], 1.0 op_sel_hi:[1,0]
	s_nop 0
	v_rcp_f32_e32 v152, v151
	s_nop 0
	v_mul_f32_e32 v147, v99, v152
	v_mov_b32_e32 v151, v147
	v_rcp_f32_e32 v152, v150
	s_nop 0
	v_mul_f32_e32 v147, v98, v152
	v_mov_b32_e32 v150, v147
	v_mul_f32_e32 v147, 0xbfb8aa3b, v100
	v_exp_f32_e32 v152, v147
	v_mul_f32_e32 v147, 0xbfb8aa3b, v101
	v_exp_f32_e32 v153, v147
	v_pk_mul_f32 v[150:151], v[150:151], s[4:5] op_sel_hi:[1,0]
	v_pk_add_f32 v[152:153], v[152:153], 1.0 op_sel_hi:[1,0]
	s_nop 0
	v_rcp_f32_e32 v154, v153
	s_nop 0
	v_mul_f32_e32 v147, v101, v154
	v_mov_b32_e32 v153, v147
	v_rcp_f32_e32 v154, v152
	s_nop 0
	v_mul_f32_e32 v147, v100, v154
	v_mov_b32_e32 v152, v147
	v_pk_mul_f32 v[152:153], v[152:153], s[4:5] op_sel_hi:[1,0]
	v_bfe_u32 v155, v151, 16, 1
	v_bfe_u32 v147, v153, 16, 1
	v_bfe_u32 v154, v152, 16, 1
	v_bfe_u32 v156, v150, 16, 1
	v_add3_u32 v150, v150, v156, s0
	v_add3_u32 v155, v151, v155, s0
	v_add3_u32 v151, v152, v154, s0
	v_add3_u32 v147, v153, v147, s0
	v_perm_b32 v151, v147, v151, s19
	v_perm_b32 v150, v155, v150, s19
	global_store_dwordx2 v[148:149], v[150:151], off offset:96
.LBB0_751:
	v_or_b32_e32 v148, 32, v146
	v_ashrrev_i32_e32 v149, 31, v148
	s_and_b64 vcc, exec, s[40:41]
	s_mov_b64 s[2:3], -1
	s_cbranch_vccnz .LBB0_761
	s_cmp_lt_i32 s34, 3
	s_cbranch_scc1 .LBB0_758
	s_cmp_eq_u32 s34, 3
	s_cbranch_scc1 .LBB0_755
	v_mul_f32_e32 v147, 0xbfb8aa3b, v94
	v_exp_f32_e32 v150, v147
	v_mul_f32_e32 v147, 0xbfb8aa3b, v95
	v_exp_f32_e32 v151, v147
	v_readlane_b32 s48, v253, 4
	v_readlane_b32 s49, v253, 5
	v_readlane_b32 s50, v253, 6
	v_pk_add_f32 v[150:151], v[150:151], 1.0 op_sel_hi:[1,0]
	v_readlane_b32 s51, v253, 7
	v_rcp_f32_e32 v152, v150
	s_nop 0
	v_mul_f32_e32 v147, v94, v152
	v_rcp_f32_e32 v152, v151
	s_nop 0
	v_mul_f32_e32 v150, v95, v152
	v_mov_b32_e32 v152, v150
	v_mul_f32_e32 v150, 0xbfb8aa3b, v96
	v_mul_f32_e32 v151, 0xbfb8aa3b, v97
	v_exp_f32_e32 v150, v150
	v_exp_f32_e32 v151, v151
	s_nop 0
	v_pk_add_f32 v[150:151], v[150:151], 1.0 op_sel_hi:[1,0]
	s_nop 0
	v_rcp_f32_e32 v154, v150
	s_nop 0
	v_mul_f32_e32 v153, v96, v154
	v_mov_b32_e32 v150, v153
	v_rcp_f32_e32 v154, v151
	s_mov_b64 s[2:3], 0
	v_mul_f32_e32 v153, v97, v154
	v_mov_b32_e32 v151, v153
	v_bfe_u32 v153, v151, 16, 1
	v_bfe_u32 v154, v150, 16, 1
	v_bfe_u32 v155, v152, 16, 1
	v_bfe_u32 v156, v147, 16, 1
	v_add3_u32 v147, v147, v156, s0
	v_add3_u32 v152, v152, v155, s0
	v_add3_u32 v150, v150, v154, s0
	v_add3_u32 v151, v151, v153, s0
	v_perm_b32 v151, v151, v150, s19
	v_perm_b32 v150, v152, v147, s19
	v_lshlrev_b64 v[152:153], 11, v[148:149]
	v_lshl_add_u64 v[152:153], s[48:49], 0, v[152:153]
	v_lshl_add_u64 v[152:153], v[152:153], 0, v[0:1]
	global_store_dwordx2 v[152:153], v[150:151], off

.LBB0_758:
	s_andn2_b64 vcc, exec, s[2:3]
	s_cbranch_vccnz .LBB0_760
	v_mul_f32_e32 v150, 0xbfb8aa3b, v94
	v_exp_f32_e32 v150, v150
	s_waitcnt vmcnt(3)
	v_sub_f32_e32 v147, 1.0, v142
	s_mov_b32 s14, 0x800000
	s_mov_b32 s24, 0x3f317217
	v_add_f32_e32 v150, 1.0, v150
	v_rcp_f32_e32 v152, v150
	s_mov_b32 s15, 0x7f800000
	v_readlane_b32 s48, v252, 16
	v_readlane_b32 s60, v252, 28
	v_mov_b32_e32 v151, v152
	v_mov_b32_e32 v150, v151
	v_fma_f32 v147, v150, v147, v142
	v_mul_f32_e32 v151, 0xbfb8aa3b, v95
	v_cmp_gt_f32_e32 vcc, s14, v147
	v_exp_f32_e32 v151, v151
	v_readlane_b32 s61, v252, 29
	v_cndmask_b32_e64 v150, 0, 32, vcc
	v_ldexp_f32 v147, v147, v150
	v_log_f32_e32 v147, v147
	v_add_f32_e32 v151, 1.0, v151
	v_rcp_f32_e32 v153, v151
	v_mul_f32_e32 v150, 0x3f317217, v147
	v_fma_f32 v150, v147, s24, -v150
	v_fmac_f32_e32 v150, 0x3377d1cf, v147
	v_fmac_f32_e32 v150, 0x3f317217, v147
	v_cmp_lt_f32_e64 s[4:5], |v147|, s15
	v_cndmask_b32_e64 v147, v147, v150, s[4:5]
	v_cndmask_b32_e32 v150, 0, v213, vcc
	v_mov_b32_e32 v152, v153
	v_sub_f32_e32 v147, v147, v150
	v_sub_f32_e32 v150, 1.0, v143
	v_mov_b32_e32 v151, v152
	v_fma_f32 v150, v151, v150, v143
	v_mul_f32_e32 v152, 0xbfb8aa3b, v96
	v_cmp_gt_f32_e32 vcc, s14, v150
	v_exp_f32_e32 v152, v152
	v_readlane_b32 s49, v252, 17
	v_cndmask_b32_e64 v151, 0, 32, vcc
	v_ldexp_f32 v150, v150, v151
	v_log_f32_e32 v150, v150
	v_add_f32_e32 v152, 1.0, v152
	v_rcp_f32_e32 v154, v152
	v_mul_f32_e32 v151, 0x3f317217, v150
	v_fma_f32 v151, v150, s24, -v151
	v_fmac_f32_e32 v151, 0x3377d1cf, v150
	v_fmac_f32_e32 v151, 0x3f317217, v150
	v_cmp_lt_f32_e64 s[4:5], |v150|, s15
	v_cndmask_b32_e64 v150, v150, v151, s[4:5]
	v_cndmask_b32_e32 v151, 0, v213, vcc
	v_mov_b32_e32 v153, v154
	v_sub_f32_e32 v150, v150, v151
	v_sub_f32_e32 v151, 1.0, v144
	v_mov_b32_e32 v152, v153
	v_fma_f32 v151, v152, v151, v144
	v_mul_f32_e32 v153, 0xbfb8aa3b, v97
	v_cmp_gt_f32_e32 vcc, s14, v151
	v_exp_f32_e32 v153, v153
	v_cvt_pk_f16_f32 v150, v147, v150
	v_cndmask_b32_e64 v152, 0, 32, vcc
	v_ldexp_f32 v151, v151, v152
	v_log_f32_e32 v151, v151
	v_add_f32_e32 v153, 1.0, v153
	v_rcp_f32_e32 v155, v153
	v_mul_f32_e32 v152, 0x3f317217, v151
	v_fma_f32 v152, v151, s24, -v152
	v_fmac_f32_e32 v152, 0x3377d1cf, v151
	v_fmac_f32_e32 v152, 0x3f317217, v151
	v_cmp_lt_f32_e64 s[4:5], |v151|, s15
	v_cndmask_b32_e64 v151, v151, v152, s[4:5]
	v_cndmask_b32_e32 v152, 0, v213, vcc
	v_mov_b32_e32 v154, v155
	v_sub_f32_e32 v151, v151, v152
	v_sub_f32_e32 v152, 1.0, v145
	v_mov_b32_e32 v153, v154
	v_fma_f32 v152, v153, v152, v145
	v_cmp_gt_f32_e32 vcc, s14, v152
	s_add_i32 s2, s34, -1
	s_mul_hi_i32 s3, s2, 0x2200000
	v_cndmask_b32_e64 v153, 0, 32, vcc
	v_ldexp_f32 v152, v152, v153
	v_log_f32_e32 v152, v152
	s_mul_i32 s2, s2, 0x2200000
	s_add_u32 s2, s60, s2
	s_addc_u32 s3, s61, s3
	v_mul_f32_e32 v153, 0x3f317217, v152
	v_fma_f32 v153, v152, s24, -v153
	v_fmac_f32_e32 v153, 0x3377d1cf, v152
	v_fmac_f32_e32 v153, 0x3f317217, v152
	v_cmp_lt_f32_e64 s[4:5], |v152|, s15
	v_readlane_b32 s50, v252, 18
	v_readlane_b32 s51, v252, 19
	v_cndmask_b32_e64 v152, v152, v153, s[4:5]
	v_cndmask_b32_e32 v153, 0, v213, vcc
	v_sub_f32_e32 v152, v152, v153
	v_cvt_pk_f16_f32 v151, v151, v152
	v_lshlrev_b64 v[152:153], 11, v[148:149]
	v_lshl_add_u64 v[152:153], s[2:3], 0, v[152:153]
	v_lshl_add_u64 v[152:153], v[152:153], 0, v[0:1]
	v_readlane_b32 s52, v252, 20
	v_readlane_b32 s53, v252, 21
	v_readlane_b32 s54, v252, 22
	v_readlane_b32 s55, v252, 23
	v_readlane_b32 s56, v252, 24
	v_readlane_b32 s57, v252, 25
	v_readlane_b32 s58, v252, 26
	v_readlane_b32 s59, v252, 27
	v_readlane_b32 s62, v252, 30
	v_readlane_b32 s63, v252, 31
	global_store_dwordx2 v[152:153], v[150:151], off

.LBB0_761:
	v_readlane_b32 s48, v252, 16
	v_lshlrev_b64 v[150:151], 11, v[148:149]
	v_readlane_b32 s58, v252, 26
	v_readlane_b32 s59, v252, 27
	s_andn2_b64 vcc, exec, s[2:3]
	v_readlane_b32 s49, v252, 17
	v_lshl_add_u64 v[148:149], s[58:59], 0, v[150:151]
	v_readlane_b32 s50, v252, 18
	v_readlane_b32 s51, v252, 19
	v_readlane_b32 s52, v252, 20
	v_readlane_b32 s53, v252, 21
	v_readlane_b32 s54, v252, 22
	v_readlane_b32 s55, v252, 23
	v_readlane_b32 s56, v252, 24
	v_readlane_b32 s57, v252, 25
	v_readlane_b32 s60, v252, 28
	v_readlane_b32 s61, v252, 29
	v_readlane_b32 s62, v252, 30
	v_readlane_b32 s63, v252, 31
	s_cbranch_vccnz .LBB0_763
	v_mul_f32_e32 v147, 0xbfb8aa3b, v94
	v_exp_f32_e32 v152, v147
	v_mul_f32_e32 v147, 0xbfb8aa3b, v95
	v_exp_f32_e32 v153, v147
	s_mov_b32 s4, 0x3db504f3
	v_pk_add_f32 v[152:153], v[152:153], 1.0 op_sel_hi:[1,0]
	s_nop 0
	v_rcp_f32_e32 v154, v153
	s_nop 0
	v_mul_f32_e32 v147, v95, v154
	v_mov_b32_e32 v153, v147
	v_rcp_f32_e32 v154, v152
	s_nop 0
	v_mul_f32_e32 v147, v94, v154
	v_mov_b32_e32 v152, v147
	v_mul_f32_e32 v147, 0xbfb8aa3b, v96
	v_exp_f32_e32 v154, v147
	v_mul_f32_e32 v147, 0xbfb8aa3b, v97
	v_exp_f32_e32 v155, v147
	v_pk_mul_f32 v[152:153], v[152:153], s[4:5] op_sel_hi:[1,0]
	v_pk_add_f32 v[154:155], v[154:155], 1.0 op_sel_hi:[1,0]
	s_nop 0
	v_rcp_f32_e32 v156, v155
	s_nop 0
	v_mul_f32_e32 v147, v97, v156
	v_mov_b32_e32 v155, v147
	v_rcp_f32_e32 v156, v154
	s_nop 0
	v_mul_f32_e32 v147, v96, v156
	v_mov_b32_e32 v154, v147
	v_pk_mul_f32 v[154:155], v[154:155], s[4:5] op_sel_hi:[1,0]
	v_bfe_u32 v157, v153, 16, 1
	v_bfe_u32 v147, v155, 16, 1
	v_bfe_u32 v156, v154, 16, 1
	v_bfe_u32 v158, v152, 16, 1
	v_add3_u32 v152, v152, v158, s0
	v_add3_u32 v157, v153, v157, s0
	v_add3_u32 v153, v154, v156, s0
	v_add3_u32 v147, v155, v147, s0
	v_perm_b32 v153, v147, v153, s19
	v_perm_b32 v152, v157, v152, s19
	v_lshl_add_u64 v[154:155], v[148:149], 0, v[0:1]
	global_store_dwordx2 v[154:155], v[152:153], off
.LBB0_763:
	s_and_b64 vcc, exec, s[40:41]
	s_mov_b64 s[2:3], -1
	s_cbranch_vccnz .LBB0_773
	s_cmp_lt_i32 s34, 3
	s_cbranch_scc1 .LBB0_770
	s_cmp_eq_u32 s34, 3
	s_cbranch_scc1 .LBB0_767
	v_mul_f32_e32 v147, 0xbfb8aa3b, v90
	v_exp_f32_e32 v152, v147
	v_mul_f32_e32 v147, 0xbfb8aa3b, v91
	v_exp_f32_e32 v153, v147
	v_readlane_b32 s48, v253, 4
	v_readlane_b32 s49, v253, 5
	v_readlane_b32 s50, v253, 6
	v_pk_add_f32 v[152:153], v[152:153], 1.0 op_sel_hi:[1,0]
	v_readlane_b32 s51, v253, 7
	v_rcp_f32_e32 v154, v152
	s_nop 0
	v_mul_f32_e32 v147, v90, v154
	v_rcp_f32_e32 v154, v153
	s_nop 0
	v_mul_f32_e32 v152, v91, v154
	v_mov_b32_e32 v154, v152
	v_mul_f32_e32 v152, 0xbfb8aa3b, v92
	v_mul_f32_e32 v153, 0xbfb8aa3b, v93
	v_exp_f32_e32 v152, v152
	v_exp_f32_e32 v153, v153
	s_nop 0
	v_pk_add_f32 v[152:153], v[152:153], 1.0 op_sel_hi:[1,0]
	s_nop 0
	v_rcp_f32_e32 v156, v152
	s_nop 0
	v_mul_f32_e32 v155, v92, v156
	v_mov_b32_e32 v152, v155
	v_rcp_f32_e32 v156, v153
	s_mov_b64 s[2:3], 0
	v_mul_f32_e32 v155, v93, v156
	v_mov_b32_e32 v153, v155
	v_bfe_u32 v155, v153, 16, 1
	v_bfe_u32 v156, v152, 16, 1
	v_bfe_u32 v157, v154, 16, 1
	v_bfe_u32 v158, v147, 16, 1
	v_add3_u32 v147, v147, v158, s0
	v_add3_u32 v154, v154, v157, s0
	v_add3_u32 v152, v152, v156, s0
	v_add3_u32 v153, v153, v155, s0
	v_perm_b32 v153, v153, v152, s19
	v_perm_b32 v152, v154, v147, s19
	v_lshl_add_u64 v[154:155], s[48:49], 0, v[150:151]
	v_lshl_add_u64 v[154:155], v[154:155], 0, v[0:1]
	global_store_dwordx2 v[154:155], v[152:153], off offset:32

.LBB0_770:
	s_andn2_b64 vcc, exec, s[2:3]
	s_cbranch_vccnz .LBB0_772
	v_mul_f32_e32 v152, 0xbfb8aa3b, v90
	v_exp_f32_e32 v152, v152
	s_waitcnt vmcnt(2)
	v_sub_f32_e32 v147, 1.0, v138
	s_mov_b32 s14, 0x800000
	s_mov_b32 s24, 0x3f317217
	v_add_f32_e32 v152, 1.0, v152
	v_rcp_f32_e32 v154, v152
	s_mov_b32 s15, 0x7f800000
	v_readlane_b32 s48, v252, 16
	v_readlane_b32 s60, v252, 28
	v_mov_b32_e32 v153, v154
	v_mov_b32_e32 v152, v153
	v_fma_f32 v147, v152, v147, v138
	v_mul_f32_e32 v153, 0xbfb8aa3b, v91
	v_cmp_gt_f32_e32 vcc, s14, v147
	v_exp_f32_e32 v153, v153
	v_readlane_b32 s61, v252, 29
	v_cndmask_b32_e64 v152, 0, 32, vcc
	v_ldexp_f32 v147, v147, v152
	v_log_f32_e32 v147, v147
	v_add_f32_e32 v153, 1.0, v153
	v_rcp_f32_e32 v155, v153
	v_mul_f32_e32 v152, 0x3f317217, v147
	v_fma_f32 v152, v147, s24, -v152
	v_fmac_f32_e32 v152, 0x3377d1cf, v147
	v_fmac_f32_e32 v152, 0x3f317217, v147
	v_cmp_lt_f32_e64 s[4:5], |v147|, s15
	v_cndmask_b32_e64 v147, v147, v152, s[4:5]
	v_cndmask_b32_e32 v152, 0, v213, vcc
	v_mov_b32_e32 v154, v155
	v_sub_f32_e32 v147, v147, v152
	v_sub_f32_e32 v152, 1.0, v139
	v_mov_b32_e32 v153, v154
	v_fma_f32 v152, v153, v152, v139
	v_mul_f32_e32 v154, 0xbfb8aa3b, v92
	v_cmp_gt_f32_e32 vcc, s14, v152
	v_exp_f32_e32 v154, v154
	v_readlane_b32 s49, v252, 17
	v_cndmask_b32_e64 v153, 0, 32, vcc
	v_ldexp_f32 v152, v152, v153
	v_log_f32_e32 v152, v152
	v_add_f32_e32 v154, 1.0, v154
	v_rcp_f32_e32 v156, v154
	v_mul_f32_e32 v153, 0x3f317217, v152
	v_fma_f32 v153, v152, s24, -v153
	v_fmac_f32_e32 v153, 0x3377d1cf, v152
	v_fmac_f32_e32 v153, 0x3f317217, v152
	v_cmp_lt_f32_e64 s[4:5], |v152|, s15
	v_cndmask_b32_e64 v152, v152, v153, s[4:5]
	v_cndmask_b32_e32 v153, 0, v213, vcc
	v_mov_b32_e32 v155, v156
	v_sub_f32_e32 v152, v152, v153
	v_sub_f32_e32 v153, 1.0, v140
	v_mov_b32_e32 v154, v155
	v_fma_f32 v153, v154, v153, v140
	v_mul_f32_e32 v155, 0xbfb8aa3b, v93
	v_cmp_gt_f32_e32 vcc, s14, v153
	v_exp_f32_e32 v155, v155
	v_cvt_pk_f16_f32 v152, v147, v152
	v_cndmask_b32_e64 v154, 0, 32, vcc
	v_ldexp_f32 v153, v153, v154
	v_log_f32_e32 v153, v153
	v_add_f32_e32 v155, 1.0, v155
	v_rcp_f32_e32 v157, v155
	v_mul_f32_e32 v154, 0x3f317217, v153
	v_fma_f32 v154, v153, s24, -v154
	v_fmac_f32_e32 v154, 0x3377d1cf, v153
	v_fmac_f32_e32 v154, 0x3f317217, v153
	v_cmp_lt_f32_e64 s[4:5], |v153|, s15
	v_cndmask_b32_e64 v153, v153, v154, s[4:5]
	v_cndmask_b32_e32 v154, 0, v213, vcc
	v_mov_b32_e32 v156, v157
	v_sub_f32_e32 v153, v153, v154
	v_sub_f32_e32 v154, 1.0, v141
	v_mov_b32_e32 v155, v156
	v_fma_f32 v154, v155, v154, v141
	v_cmp_gt_f32_e32 vcc, s14, v154
	s_add_i32 s2, s34, -1
	s_mul_hi_i32 s3, s2, 0x2200000
	v_cndmask_b32_e64 v155, 0, 32, vcc
	v_ldexp_f32 v154, v154, v155
	v_log_f32_e32 v154, v154
	s_mul_i32 s2, s2, 0x2200000
	s_add_u32 s2, s60, s2
	s_addc_u32 s3, s61, s3
	v_mul_f32_e32 v155, 0x3f317217, v154
	v_fma_f32 v155, v154, s24, -v155
	v_fmac_f32_e32 v155, 0x3377d1cf, v154
	v_fmac_f32_e32 v155, 0x3f317217, v154
	v_cmp_lt_f32_e64 s[4:5], |v154|, s15
	v_readlane_b32 s50, v252, 18
	v_readlane_b32 s51, v252, 19
	v_cndmask_b32_e64 v154, v154, v155, s[4:5]
	v_cndmask_b32_e32 v155, 0, v213, vcc
	v_sub_f32_e32 v154, v154, v155
	v_cvt_pk_f16_f32 v153, v153, v154
	v_lshl_add_u64 v[154:155], s[2:3], 0, v[150:151]
	v_lshl_add_u64 v[154:155], v[154:155], 0, v[0:1]
	v_readlane_b32 s52, v252, 20
	v_readlane_b32 s53, v252, 21
	v_readlane_b32 s54, v252, 22
	v_readlane_b32 s55, v252, 23
	v_readlane_b32 s56, v252, 24
	v_readlane_b32 s57, v252, 25
	v_readlane_b32 s58, v252, 26
	v_readlane_b32 s59, v252, 27
	v_readlane_b32 s62, v252, 30
	v_readlane_b32 s63, v252, 31
	global_store_dwordx2 v[154:155], v[152:153], off offset:32

.LBB0_773:
	s_andn2_b64 vcc, exec, s[2:3]
	s_cbranch_vccnz .LBB0_775
	v_mul_f32_e32 v147, 0xbfb8aa3b, v90
	v_exp_f32_e32 v152, v147
	v_mul_f32_e32 v147, 0xbfb8aa3b, v91
	v_exp_f32_e32 v153, v147
	s_mov_b32 s4, 0x3db504f3
	v_pk_add_f32 v[152:153], v[152:153], 1.0 op_sel_hi:[1,0]
	s_nop 0
	v_rcp_f32_e32 v154, v153
	s_nop 0
	v_mul_f32_e32 v147, v91, v154
	v_mov_b32_e32 v153, v147
	v_rcp_f32_e32 v154, v152
	s_nop 0
	v_mul_f32_e32 v147, v90, v154
	v_mov_b32_e32 v152, v147
	v_mul_f32_e32 v147, 0xbfb8aa3b, v92
	v_exp_f32_e32 v154, v147
	v_mul_f32_e32 v147, 0xbfb8aa3b, v93
	v_exp_f32_e32 v155, v147
	v_pk_mul_f32 v[152:153], v[152:153], s[4:5] op_sel_hi:[1,0]
	v_pk_add_f32 v[154:155], v[154:155], 1.0 op_sel_hi:[1,0]
	s_nop 0
	v_rcp_f32_e32 v156, v155
	s_nop 0
	v_mul_f32_e32 v147, v93, v156
	v_mov_b32_e32 v155, v147
	v_rcp_f32_e32 v156, v154
	s_nop 0
	v_mul_f32_e32 v147, v92, v156
	v_mov_b32_e32 v154, v147
	v_pk_mul_f32 v[154:155], v[154:155], s[4:5] op_sel_hi:[1,0]
	v_bfe_u32 v157, v153, 16, 1
	v_bfe_u32 v147, v155, 16, 1
	v_bfe_u32 v156, v154, 16, 1
	v_bfe_u32 v158, v152, 16, 1
	v_add3_u32 v152, v152, v158, s0
	v_add3_u32 v157, v153, v157, s0
	v_add3_u32 v153, v154, v156, s0
	v_add3_u32 v147, v155, v147, s0
	v_perm_b32 v153, v147, v153, s19
	v_perm_b32 v152, v157, v152, s19
	v_lshl_add_u64 v[154:155], v[148:149], 0, v[0:1]
	global_store_dwordx2 v[154:155], v[152:153], off offset:32
.LBB0_775:
	s_and_b64 vcc, exec, s[40:41]
	s_mov_b64 s[2:3], -1
	s_cbranch_vccnz .LBB0_785
	s_cmp_lt_i32 s34, 3
	s_cbranch_scc1 .LBB0_782
	s_cmp_eq_u32 s34, 3
	s_cbranch_scc1 .LBB0_779
	v_mul_f32_e32 v147, 0xbfb8aa3b, v86
	v_exp_f32_e32 v152, v147
	v_mul_f32_e32 v147, 0xbfb8aa3b, v87
	v_exp_f32_e32 v153, v147
	v_readlane_b32 s48, v253, 4
	v_readlane_b32 s49, v253, 5
	v_readlane_b32 s50, v253, 6
	v_pk_add_f32 v[152:153], v[152:153], 1.0 op_sel_hi:[1,0]
	v_readlane_b32 s51, v253, 7
	v_rcp_f32_e32 v154, v152
	s_nop 0
	v_mul_f32_e32 v147, v86, v154
	v_rcp_f32_e32 v154, v153
	s_nop 0
	v_mul_f32_e32 v152, v87, v154
	v_mov_b32_e32 v154, v152
	v_mul_f32_e32 v152, 0xbfb8aa3b, v88
	v_mul_f32_e32 v153, 0xbfb8aa3b, v89
	v_exp_f32_e32 v152, v152
	v_exp_f32_e32 v153, v153
	s_nop 0
	v_pk_add_f32 v[152:153], v[152:153], 1.0 op_sel_hi:[1,0]
	s_nop 0
	v_rcp_f32_e32 v156, v152
	s_nop 0
	v_mul_f32_e32 v155, v88, v156
	v_mov_b32_e32 v152, v155
	v_rcp_f32_e32 v156, v153
	s_mov_b64 s[2:3], 0
	v_mul_f32_e32 v155, v89, v156
	v_mov_b32_e32 v153, v155
	v_bfe_u32 v155, v153, 16, 1
	v_bfe_u32 v156, v152, 16, 1
	v_bfe_u32 v157, v154, 16, 1
	v_bfe_u32 v158, v147, 16, 1
	v_add3_u32 v147, v147, v158, s0
	v_add3_u32 v154, v154, v157, s0
	v_add3_u32 v152, v152, v156, s0
	v_add3_u32 v153, v153, v155, s0
	v_perm_b32 v153, v153, v152, s19
	v_perm_b32 v152, v154, v147, s19
	v_lshl_add_u64 v[154:155], s[48:49], 0, v[150:151]
	v_lshl_add_u64 v[154:155], v[154:155], 0, v[0:1]
	global_store_dwordx2 v[154:155], v[152:153], off offset:64

.LBB0_782:
	s_andn2_b64 vcc, exec, s[2:3]
	s_cbranch_vccnz .LBB0_784
	v_mul_f32_e32 v152, 0xbfb8aa3b, v86
	v_exp_f32_e32 v152, v152
	s_waitcnt vmcnt(1)
	v_sub_f32_e32 v147, 1.0, v134
	s_mov_b32 s14, 0x800000
	s_mov_b32 s24, 0x3f317217
	v_add_f32_e32 v152, 1.0, v152
	v_rcp_f32_e32 v154, v152
	s_mov_b32 s15, 0x7f800000
	v_readlane_b32 s48, v252, 16
	v_readlane_b32 s60, v252, 28
	v_mov_b32_e32 v153, v154
	v_mov_b32_e32 v152, v153
	v_fma_f32 v147, v152, v147, v134
	v_mul_f32_e32 v153, 0xbfb8aa3b, v87
	v_cmp_gt_f32_e32 vcc, s14, v147
	v_exp_f32_e32 v153, v153
	v_readlane_b32 s61, v252, 29
	v_cndmask_b32_e64 v152, 0, 32, vcc
	v_ldexp_f32 v147, v147, v152
	v_log_f32_e32 v147, v147
	v_add_f32_e32 v153, 1.0, v153
	v_rcp_f32_e32 v155, v153
	v_mul_f32_e32 v152, 0x3f317217, v147
	v_fma_f32 v152, v147, s24, -v152
	v_fmac_f32_e32 v152, 0x3377d1cf, v147
	v_fmac_f32_e32 v152, 0x3f317217, v147
	v_cmp_lt_f32_e64 s[4:5], |v147|, s15
	v_cndmask_b32_e64 v147, v147, v152, s[4:5]
	v_cndmask_b32_e32 v152, 0, v213, vcc
	v_mov_b32_e32 v154, v155
	v_sub_f32_e32 v147, v147, v152
	v_sub_f32_e32 v152, 1.0, v135
	v_mov_b32_e32 v153, v154
	v_fma_f32 v152, v153, v152, v135
	v_mul_f32_e32 v154, 0xbfb8aa3b, v88
	v_cmp_gt_f32_e32 vcc, s14, v152
	v_exp_f32_e32 v154, v154
	v_readlane_b32 s49, v252, 17
	v_cndmask_b32_e64 v153, 0, 32, vcc
	v_ldexp_f32 v152, v152, v153
	v_log_f32_e32 v152, v152
	v_add_f32_e32 v154, 1.0, v154
	v_rcp_f32_e32 v156, v154
	v_mul_f32_e32 v153, 0x3f317217, v152
	v_fma_f32 v153, v152, s24, -v153
	v_fmac_f32_e32 v153, 0x3377d1cf, v152
	v_fmac_f32_e32 v153, 0x3f317217, v152
	v_cmp_lt_f32_e64 s[4:5], |v152|, s15
	v_cndmask_b32_e64 v152, v152, v153, s[4:5]
	v_cndmask_b32_e32 v153, 0, v213, vcc
	v_mov_b32_e32 v155, v156
	v_sub_f32_e32 v152, v152, v153
	v_sub_f32_e32 v153, 1.0, v136
	v_mov_b32_e32 v154, v155
	v_fma_f32 v153, v154, v153, v136
	v_mul_f32_e32 v155, 0xbfb8aa3b, v89
	v_cmp_gt_f32_e32 vcc, s14, v153
	v_exp_f32_e32 v155, v155
	v_cvt_pk_f16_f32 v152, v147, v152
	v_cndmask_b32_e64 v154, 0, 32, vcc
	v_ldexp_f32 v153, v153, v154
	v_log_f32_e32 v153, v153
	v_add_f32_e32 v155, 1.0, v155
	v_rcp_f32_e32 v157, v155
	v_mul_f32_e32 v154, 0x3f317217, v153
	v_fma_f32 v154, v153, s24, -v154
	v_fmac_f32_e32 v154, 0x3377d1cf, v153
	v_fmac_f32_e32 v154, 0x3f317217, v153
	v_cmp_lt_f32_e64 s[4:5], |v153|, s15
	v_cndmask_b32_e64 v153, v153, v154, s[4:5]
	v_cndmask_b32_e32 v154, 0, v213, vcc
	v_mov_b32_e32 v156, v157
	v_sub_f32_e32 v153, v153, v154
	v_sub_f32_e32 v154, 1.0, v137
	v_mov_b32_e32 v155, v156
	v_fma_f32 v154, v155, v154, v137
	v_cmp_gt_f32_e32 vcc, s14, v154
	s_add_i32 s2, s34, -1
	s_mul_hi_i32 s3, s2, 0x2200000
	v_cndmask_b32_e64 v155, 0, 32, vcc
	v_ldexp_f32 v154, v154, v155
	v_log_f32_e32 v154, v154
	s_mul_i32 s2, s2, 0x2200000
	s_add_u32 s2, s60, s2
	s_addc_u32 s3, s61, s3
	v_mul_f32_e32 v155, 0x3f317217, v154
	v_fma_f32 v155, v154, s24, -v155
	v_fmac_f32_e32 v155, 0x3377d1cf, v154
	v_fmac_f32_e32 v155, 0x3f317217, v154
	v_cmp_lt_f32_e64 s[4:5], |v154|, s15
	v_readlane_b32 s50, v252, 18
	v_readlane_b32 s51, v252, 19
	v_cndmask_b32_e64 v154, v154, v155, s[4:5]
	v_cndmask_b32_e32 v155, 0, v213, vcc
	v_sub_f32_e32 v154, v154, v155
	v_cvt_pk_f16_f32 v153, v153, v154
	v_lshl_add_u64 v[154:155], s[2:3], 0, v[150:151]
	v_lshl_add_u64 v[154:155], v[154:155], 0, v[0:1]
	v_readlane_b32 s52, v252, 20
	v_readlane_b32 s53, v252, 21
	v_readlane_b32 s54, v252, 22
	v_readlane_b32 s55, v252, 23
	v_readlane_b32 s56, v252, 24
	v_readlane_b32 s57, v252, 25
	v_readlane_b32 s58, v252, 26
	v_readlane_b32 s59, v252, 27
	v_readlane_b32 s62, v252, 30
	v_readlane_b32 s63, v252, 31
	global_store_dwordx2 v[154:155], v[152:153], off offset:64

.LBB0_785:
	s_andn2_b64 vcc, exec, s[2:3]
	s_cbranch_vccnz .LBB0_787
	v_mul_f32_e32 v147, 0xbfb8aa3b, v86
	v_exp_f32_e32 v152, v147
	v_mul_f32_e32 v147, 0xbfb8aa3b, v87
	v_exp_f32_e32 v153, v147
	s_mov_b32 s4, 0x3db504f3
	v_pk_add_f32 v[152:153], v[152:153], 1.0 op_sel_hi:[1,0]
	s_nop 0
	v_rcp_f32_e32 v154, v153
	s_nop 0
	v_mul_f32_e32 v147, v87, v154
	v_mov_b32_e32 v153, v147
	v_rcp_f32_e32 v154, v152
	s_nop 0
	v_mul_f32_e32 v147, v86, v154
	v_mov_b32_e32 v152, v147
	v_mul_f32_e32 v147, 0xbfb8aa3b, v88
	v_exp_f32_e32 v154, v147
	v_mul_f32_e32 v147, 0xbfb8aa3b, v89
	v_exp_f32_e32 v155, v147
	v_pk_mul_f32 v[152:153], v[152:153], s[4:5] op_sel_hi:[1,0]
	v_pk_add_f32 v[154:155], v[154:155], 1.0 op_sel_hi:[1,0]
	s_nop 0
	v_rcp_f32_e32 v156, v155
	s_nop 0
	v_mul_f32_e32 v147, v89, v156
	v_mov_b32_e32 v155, v147
	v_rcp_f32_e32 v156, v154
	s_nop 0
	v_mul_f32_e32 v147, v88, v156
	v_mov_b32_e32 v154, v147
	v_pk_mul_f32 v[154:155], v[154:155], s[4:5] op_sel_hi:[1,0]
	v_bfe_u32 v157, v153, 16, 1
	v_bfe_u32 v147, v155, 16, 1
	v_bfe_u32 v156, v154, 16, 1
	v_bfe_u32 v158, v152, 16, 1
	v_add3_u32 v152, v152, v158, s0
	v_add3_u32 v157, v153, v157, s0
	v_add3_u32 v153, v154, v156, s0
	v_add3_u32 v147, v155, v147, s0
	v_perm_b32 v153, v147, v153, s19
	v_perm_b32 v152, v157, v152, s19
	v_lshl_add_u64 v[154:155], v[148:149], 0, v[0:1]
	global_store_dwordx2 v[154:155], v[152:153], off offset:64
.LBB0_787:
	s_and_b64 vcc, exec, s[40:41]
	s_mov_b64 s[2:3], -1
	s_cbranch_vccnz .LBB0_797
	s_cmp_lt_i32 s34, 3
	s_cbranch_scc1 .LBB0_794
	s_cmp_eq_u32 s34, 3
	s_cbranch_scc1 .LBB0_791
	v_mul_f32_e32 v147, 0xbfb8aa3b, v82
	v_exp_f32_e32 v152, v147
	v_mul_f32_e32 v147, 0xbfb8aa3b, v83
	v_exp_f32_e32 v153, v147
	v_readlane_b32 s48, v253, 4
	v_readlane_b32 s49, v253, 5
	v_readlane_b32 s50, v253, 6
	v_pk_add_f32 v[152:153], v[152:153], 1.0 op_sel_hi:[1,0]
	v_readlane_b32 s51, v253, 7
	v_rcp_f32_e32 v154, v152
	s_nop 0
	v_mul_f32_e32 v147, v82, v154
	v_rcp_f32_e32 v154, v153
	s_nop 0
	v_mul_f32_e32 v152, v83, v154
	v_mov_b32_e32 v154, v152
	v_mul_f32_e32 v152, 0xbfb8aa3b, v84
	v_mul_f32_e32 v153, 0xbfb8aa3b, v85
	v_exp_f32_e32 v152, v152
	v_exp_f32_e32 v153, v153
	s_nop 0
	v_pk_add_f32 v[152:153], v[152:153], 1.0 op_sel_hi:[1,0]
	s_nop 0
	v_rcp_f32_e32 v156, v152
	s_nop 0
	v_mul_f32_e32 v155, v84, v156
	v_mov_b32_e32 v152, v155
	v_rcp_f32_e32 v156, v153
	s_mov_b64 s[2:3], 0
	v_mul_f32_e32 v155, v85, v156
	v_mov_b32_e32 v153, v155
	v_bfe_u32 v155, v153, 16, 1
	v_bfe_u32 v156, v152, 16, 1
	v_bfe_u32 v157, v154, 16, 1
	v_bfe_u32 v158, v147, 16, 1
	v_add3_u32 v147, v147, v158, s0
	v_add3_u32 v154, v154, v157, s0
	v_add3_u32 v152, v152, v156, s0
	v_add3_u32 v153, v153, v155, s0
	v_perm_b32 v153, v153, v152, s19
	v_perm_b32 v152, v154, v147, s19
	v_lshl_add_u64 v[154:155], s[48:49], 0, v[150:151]
	v_lshl_add_u64 v[154:155], v[154:155], 0, v[0:1]
	global_store_dwordx2 v[154:155], v[152:153], off offset:96

.LBB0_794:
	s_andn2_b64 vcc, exec, s[2:3]
	s_cbranch_vccnz .LBB0_796
	v_mul_f32_e32 v152, 0xbfb8aa3b, v82
	v_exp_f32_e32 v152, v152
	s_waitcnt vmcnt(0)
	v_sub_f32_e32 v147, 1.0, v130
	s_mov_b32 s14, 0x800000
	s_mov_b32 s24, 0x3f317217
	v_add_f32_e32 v152, 1.0, v152
	v_rcp_f32_e32 v154, v152
	s_mov_b32 s15, 0x7f800000
	v_readlane_b32 s48, v252, 16
	v_readlane_b32 s60, v252, 28
	v_mov_b32_e32 v153, v154
	v_mov_b32_e32 v152, v153
	v_fma_f32 v147, v152, v147, v130
	v_mul_f32_e32 v153, 0xbfb8aa3b, v83
	v_cmp_gt_f32_e32 vcc, s14, v147
	v_exp_f32_e32 v153, v153
	v_readlane_b32 s61, v252, 29
	v_cndmask_b32_e64 v152, 0, 32, vcc
	v_ldexp_f32 v147, v147, v152
	v_log_f32_e32 v147, v147
	v_add_f32_e32 v153, 1.0, v153
	v_rcp_f32_e32 v155, v153
	v_mul_f32_e32 v152, 0x3f317217, v147
	v_fma_f32 v152, v147, s24, -v152
	v_fmac_f32_e32 v152, 0x3377d1cf, v147
	v_fmac_f32_e32 v152, 0x3f317217, v147
	v_cmp_lt_f32_e64 s[4:5], |v147|, s15
	v_cndmask_b32_e64 v147, v147, v152, s[4:5]
	v_cndmask_b32_e32 v152, 0, v213, vcc
	v_mov_b32_e32 v154, v155
	v_sub_f32_e32 v147, v147, v152
	v_sub_f32_e32 v152, 1.0, v131
	v_mov_b32_e32 v153, v154
	v_fma_f32 v152, v153, v152, v131
	v_mul_f32_e32 v154, 0xbfb8aa3b, v84
	v_cmp_gt_f32_e32 vcc, s14, v152
	v_exp_f32_e32 v154, v154
	v_readlane_b32 s49, v252, 17
	v_cndmask_b32_e64 v153, 0, 32, vcc
	v_ldexp_f32 v152, v152, v153
	v_log_f32_e32 v152, v152
	v_add_f32_e32 v154, 1.0, v154
	v_rcp_f32_e32 v156, v154
	v_mul_f32_e32 v153, 0x3f317217, v152
	v_fma_f32 v153, v152, s24, -v153
	v_fmac_f32_e32 v153, 0x3377d1cf, v152
	v_fmac_f32_e32 v153, 0x3f317217, v152
	v_cmp_lt_f32_e64 s[4:5], |v152|, s15
	v_cndmask_b32_e64 v152, v152, v153, s[4:5]
	v_cndmask_b32_e32 v153, 0, v213, vcc
	v_mov_b32_e32 v155, v156
	v_sub_f32_e32 v152, v152, v153
	v_sub_f32_e32 v153, 1.0, v132
	v_mov_b32_e32 v154, v155
	v_fma_f32 v153, v154, v153, v132
	v_mul_f32_e32 v155, 0xbfb8aa3b, v85
	v_cmp_gt_f32_e32 vcc, s14, v153
	v_exp_f32_e32 v155, v155
	v_cvt_pk_f16_f32 v152, v147, v152
	v_cndmask_b32_e64 v154, 0, 32, vcc
	v_ldexp_f32 v153, v153, v154
	v_log_f32_e32 v153, v153
	v_add_f32_e32 v155, 1.0, v155
	v_rcp_f32_e32 v157, v155
	v_mul_f32_e32 v154, 0x3f317217, v153
	v_fma_f32 v154, v153, s24, -v154
	v_fmac_f32_e32 v154, 0x3377d1cf, v153
	v_fmac_f32_e32 v154, 0x3f317217, v153
	v_cmp_lt_f32_e64 s[4:5], |v153|, s15
	v_cndmask_b32_e64 v153, v153, v154, s[4:5]
	v_cndmask_b32_e32 v154, 0, v213, vcc
	v_mov_b32_e32 v156, v157
	v_sub_f32_e32 v153, v153, v154
	v_sub_f32_e32 v154, 1.0, v133
	v_mov_b32_e32 v155, v156
	v_fma_f32 v154, v155, v154, v133
	v_cmp_gt_f32_e32 vcc, s14, v154
	s_add_i32 s2, s34, -1
	s_mul_hi_i32 s3, s2, 0x2200000
	v_cndmask_b32_e64 v155, 0, 32, vcc
	v_ldexp_f32 v154, v154, v155
	v_log_f32_e32 v154, v154
	s_mul_i32 s2, s2, 0x2200000
	s_add_u32 s2, s60, s2
	s_addc_u32 s3, s61, s3
	v_mul_f32_e32 v155, 0x3f317217, v154
	v_fma_f32 v155, v154, s24, -v155
	v_fmac_f32_e32 v155, 0x3377d1cf, v154
	v_fmac_f32_e32 v155, 0x3f317217, v154
	v_cmp_lt_f32_e64 s[4:5], |v154|, s15
	v_lshl_add_u64 v[150:151], s[2:3], 0, v[150:151]
	v_lshl_add_u64 v[150:151], v[150:151], 0, v[0:1]
	v_cndmask_b32_e64 v154, v154, v155, s[4:5]
	v_cndmask_b32_e32 v155, 0, v213, vcc
	v_sub_f32_e32 v154, v154, v155
	v_cvt_pk_f16_f32 v153, v153, v154
	v_readlane_b32 s50, v252, 18
	v_readlane_b32 s51, v252, 19
	v_readlane_b32 s52, v252, 20
	v_readlane_b32 s53, v252, 21
	v_readlane_b32 s54, v252, 22
	v_readlane_b32 s55, v252, 23
	v_readlane_b32 s56, v252, 24
	v_readlane_b32 s57, v252, 25
	v_readlane_b32 s58, v252, 26
	v_readlane_b32 s59, v252, 27
	v_readlane_b32 s62, v252, 30
	v_readlane_b32 s63, v252, 31
	global_store_dwordx2 v[150:151], v[152:153], off offset:96

.LBB0_797:
	s_andn2_b64 vcc, exec, s[2:3]
	s_cbranch_vccnz .LBB0_799
	v_mul_f32_e32 v147, 0xbfb8aa3b, v82
	v_exp_f32_e32 v150, v147
	v_mul_f32_e32 v147, 0xbfb8aa3b, v83
	v_exp_f32_e32 v151, v147
	s_mov_b32 s4, 0x3db504f3
	v_lshl_add_u64 v[148:149], v[148:149], 0, v[0:1]
	v_pk_add_f32 v[150:151], v[150:151], 1.0 op_sel_hi:[1,0]
	s_nop 0
	v_rcp_f32_e32 v152, v151
	s_nop 0
	v_mul_f32_e32 v147, v83, v152
	v_mov_b32_e32 v151, v147
	v_rcp_f32_e32 v152, v150
	s_nop 0
	v_mul_f32_e32 v147, v82, v152
	v_mov_b32_e32 v150, v147
	v_mul_f32_e32 v147, 0xbfb8aa3b, v84
	v_exp_f32_e32 v152, v147
	v_mul_f32_e32 v147, 0xbfb8aa3b, v85
	v_exp_f32_e32 v153, v147
	v_pk_mul_f32 v[150:151], v[150:151], s[4:5] op_sel_hi:[1,0]
	v_pk_add_f32 v[152:153], v[152:153], 1.0 op_sel_hi:[1,0]
	s_nop 0
	v_rcp_f32_e32 v154, v153
	s_nop 0
	v_mul_f32_e32 v147, v85, v154
	v_mov_b32_e32 v153, v147
	v_rcp_f32_e32 v154, v152
	s_nop 0
	v_mul_f32_e32 v147, v84, v154
	v_mov_b32_e32 v152, v147
	v_pk_mul_f32 v[152:153], v[152:153], s[4:5] op_sel_hi:[1,0]
	v_bfe_u32 v155, v151, 16, 1
	v_bfe_u32 v147, v153, 16, 1
	v_bfe_u32 v154, v152, 16, 1
	v_bfe_u32 v156, v150, 16, 1
	v_add3_u32 v150, v150, v156, s0
	v_add3_u32 v155, v151, v155, s0
	v_add3_u32 v151, v152, v154, s0
	v_add3_u32 v147, v153, v147, s0
	v_perm_b32 v151, v147, v151, s19
	v_perm_b32 v150, v155, v150, s19
	global_store_dwordx2 v[148:149], v[150:151], off offset:96
.LBB0_799:
	v_or_b32_e32 v148, 48, v146
	v_ashrrev_i32_e32 v149, 31, v148
	s_and_b64 vcc, exec, s[40:41]
	s_mov_b64 s[2:3], -1
	s_cbranch_vccnz .LBB0_809
	s_cmp_lt_i32 s34, 3
	s_cbranch_scc1 .LBB0_806
	s_cmp_eq_u32 s34, 3
	s_cbranch_scc1 .LBB0_803
	v_mul_f32_e32 v147, 0xbfb8aa3b, v78
	v_exp_f32_e32 v150, v147
	v_mul_f32_e32 v147, 0xbfb8aa3b, v79
	v_exp_f32_e32 v151, v147
	v_readlane_b32 s48, v253, 4
	v_readlane_b32 s49, v253, 5
	v_readlane_b32 s50, v253, 6
	v_pk_add_f32 v[150:151], v[150:151], 1.0 op_sel_hi:[1,0]
	v_readlane_b32 s51, v253, 7
	v_rcp_f32_e32 v152, v150
	s_nop 0
	v_mul_f32_e32 v147, v78, v152
	v_rcp_f32_e32 v152, v151
	s_nop 0
	v_mul_f32_e32 v150, v79, v152
	v_mov_b32_e32 v152, v150
	v_mul_f32_e32 v150, 0xbfb8aa3b, v80
	v_mul_f32_e32 v151, 0xbfb8aa3b, v81
	v_exp_f32_e32 v150, v150
	v_exp_f32_e32 v151, v151
	s_nop 0
	v_pk_add_f32 v[150:151], v[150:151], 1.0 op_sel_hi:[1,0]
	s_nop 0
	v_rcp_f32_e32 v154, v150
	s_nop 0
	v_mul_f32_e32 v153, v80, v154
	v_mov_b32_e32 v150, v153
	v_rcp_f32_e32 v154, v151
	s_mov_b64 s[2:3], 0
	v_mul_f32_e32 v153, v81, v154
	v_mov_b32_e32 v151, v153
	v_bfe_u32 v153, v151, 16, 1
	v_bfe_u32 v154, v150, 16, 1
	v_bfe_u32 v155, v152, 16, 1
	v_bfe_u32 v156, v147, 16, 1
	v_add3_u32 v147, v147, v156, s0
	v_add3_u32 v152, v152, v155, s0
	v_add3_u32 v150, v150, v154, s0
	v_add3_u32 v151, v151, v153, s0
	v_perm_b32 v151, v151, v150, s19
	v_perm_b32 v150, v152, v147, s19
	v_lshlrev_b64 v[152:153], 11, v[148:149]
	v_lshl_add_u64 v[152:153], s[48:49], 0, v[152:153]
	v_lshl_add_u64 v[152:153], v[152:153], 0, v[0:1]
	global_store_dwordx2 v[152:153], v[150:151], off

.LBB0_806:
	s_andn2_b64 vcc, exec, s[2:3]
	s_cbranch_vccnz .LBB0_808
	v_mul_f32_e32 v150, 0xbfb8aa3b, v78
	v_exp_f32_e32 v150, v150
	s_waitcnt vmcnt(3)
	v_sub_f32_e32 v147, 1.0, v142
	s_mov_b32 s14, 0x800000
	s_mov_b32 s24, 0x3f317217
	v_add_f32_e32 v150, 1.0, v150
	v_rcp_f32_e32 v152, v150
	s_mov_b32 s15, 0x7f800000
	v_readlane_b32 s48, v252, 16
	v_readlane_b32 s60, v252, 28
	v_mov_b32_e32 v151, v152
	v_mov_b32_e32 v150, v151
	v_fma_f32 v147, v150, v147, v142
	v_mul_f32_e32 v151, 0xbfb8aa3b, v79
	v_cmp_gt_f32_e32 vcc, s14, v147
	v_exp_f32_e32 v151, v151
	v_readlane_b32 s61, v252, 29
	v_cndmask_b32_e64 v150, 0, 32, vcc
	v_ldexp_f32 v147, v147, v150
	v_log_f32_e32 v147, v147
	v_add_f32_e32 v151, 1.0, v151
	v_rcp_f32_e32 v153, v151
	v_mul_f32_e32 v150, 0x3f317217, v147
	v_fma_f32 v150, v147, s24, -v150
	v_fmac_f32_e32 v150, 0x3377d1cf, v147
	v_fmac_f32_e32 v150, 0x3f317217, v147
	v_cmp_lt_f32_e64 s[4:5], |v147|, s15
	v_cndmask_b32_e64 v147, v147, v150, s[4:5]
	v_cndmask_b32_e32 v150, 0, v213, vcc
	v_mov_b32_e32 v152, v153
	v_sub_f32_e32 v147, v147, v150
	v_sub_f32_e32 v150, 1.0, v143
	v_mov_b32_e32 v151, v152
	v_fma_f32 v150, v151, v150, v143
	v_mul_f32_e32 v152, 0xbfb8aa3b, v80
	v_cmp_gt_f32_e32 vcc, s14, v150
	v_exp_f32_e32 v152, v152
	v_readlane_b32 s49, v252, 17
	v_cndmask_b32_e64 v151, 0, 32, vcc
	v_ldexp_f32 v150, v150, v151
	v_log_f32_e32 v150, v150
	v_add_f32_e32 v152, 1.0, v152
	v_rcp_f32_e32 v154, v152
	v_mul_f32_e32 v151, 0x3f317217, v150
	v_fma_f32 v151, v150, s24, -v151
	v_fmac_f32_e32 v151, 0x3377d1cf, v150
	v_fmac_f32_e32 v151, 0x3f317217, v150
	v_cmp_lt_f32_e64 s[4:5], |v150|, s15
	v_cndmask_b32_e64 v150, v150, v151, s[4:5]
	v_cndmask_b32_e32 v151, 0, v213, vcc
	v_mov_b32_e32 v153, v154
	v_sub_f32_e32 v150, v150, v151
	v_sub_f32_e32 v151, 1.0, v144
	v_mov_b32_e32 v152, v153
	v_fma_f32 v151, v152, v151, v144
	v_mul_f32_e32 v153, 0xbfb8aa3b, v81
	v_cmp_gt_f32_e32 vcc, s14, v151
	v_exp_f32_e32 v153, v153
	v_cvt_pk_f16_f32 v150, v147, v150
	v_cndmask_b32_e64 v152, 0, 32, vcc
	v_ldexp_f32 v151, v151, v152
	v_log_f32_e32 v151, v151
	v_add_f32_e32 v153, 1.0, v153
	v_rcp_f32_e32 v155, v153
	v_mul_f32_e32 v152, 0x3f317217, v151
	v_fma_f32 v152, v151, s24, -v152
	v_fmac_f32_e32 v152, 0x3377d1cf, v151
	v_fmac_f32_e32 v152, 0x3f317217, v151
	v_cmp_lt_f32_e64 s[4:5], |v151|, s15
	v_cndmask_b32_e64 v151, v151, v152, s[4:5]
	v_cndmask_b32_e32 v152, 0, v213, vcc
	v_mov_b32_e32 v154, v155
	v_sub_f32_e32 v151, v151, v152
	v_sub_f32_e32 v152, 1.0, v145
	v_mov_b32_e32 v153, v154
	v_fma_f32 v152, v153, v152, v145
	v_cmp_gt_f32_e32 vcc, s14, v152
	s_add_i32 s2, s34, -1
	s_mul_hi_i32 s3, s2, 0x2200000
	v_cndmask_b32_e64 v153, 0, 32, vcc
	v_ldexp_f32 v152, v152, v153
	v_log_f32_e32 v152, v152
	s_mul_i32 s2, s2, 0x2200000
	s_add_u32 s2, s60, s2
	s_addc_u32 s3, s61, s3
	v_mul_f32_e32 v153, 0x3f317217, v152
	v_fma_f32 v153, v152, s24, -v153
	v_fmac_f32_e32 v153, 0x3377d1cf, v152
	v_fmac_f32_e32 v153, 0x3f317217, v152
	v_cmp_lt_f32_e64 s[4:5], |v152|, s15
	v_readlane_b32 s50, v252, 18
	v_readlane_b32 s51, v252, 19
	v_cndmask_b32_e64 v152, v152, v153, s[4:5]
	v_cndmask_b32_e32 v153, 0, v213, vcc
	v_sub_f32_e32 v152, v152, v153
	v_cvt_pk_f16_f32 v151, v151, v152
	v_lshlrev_b64 v[152:153], 11, v[148:149]
	v_lshl_add_u64 v[152:153], s[2:3], 0, v[152:153]
	v_lshl_add_u64 v[152:153], v[152:153], 0, v[0:1]
	v_readlane_b32 s52, v252, 20
	v_readlane_b32 s53, v252, 21
	v_readlane_b32 s54, v252, 22
	v_readlane_b32 s55, v252, 23
	v_readlane_b32 s56, v252, 24
	v_readlane_b32 s57, v252, 25
	v_readlane_b32 s58, v252, 26
	v_readlane_b32 s59, v252, 27
	v_readlane_b32 s62, v252, 30
	v_readlane_b32 s63, v252, 31
	global_store_dwordx2 v[152:153], v[150:151], off

.LBB0_809:
	v_readlane_b32 s48, v252, 16
	v_lshlrev_b64 v[150:151], 11, v[148:149]
	v_readlane_b32 s58, v252, 26
	v_readlane_b32 s59, v252, 27
	s_andn2_b64 vcc, exec, s[2:3]
	v_readlane_b32 s49, v252, 17
	v_lshl_add_u64 v[148:149], s[58:59], 0, v[150:151]
	v_readlane_b32 s50, v252, 18
	v_readlane_b32 s51, v252, 19
	v_readlane_b32 s52, v252, 20
	v_readlane_b32 s53, v252, 21
	v_readlane_b32 s54, v252, 22
	v_readlane_b32 s55, v252, 23
	v_readlane_b32 s56, v252, 24
	v_readlane_b32 s57, v252, 25
	v_readlane_b32 s60, v252, 28
	v_readlane_b32 s61, v252, 29
	v_readlane_b32 s62, v252, 30
	v_readlane_b32 s63, v252, 31
	s_cbranch_vccnz .LBB0_811
	v_mul_f32_e32 v147, 0xbfb8aa3b, v78
	v_exp_f32_e32 v152, v147
	v_mul_f32_e32 v147, 0xbfb8aa3b, v79
	v_exp_f32_e32 v153, v147
	s_mov_b32 s4, 0x3db504f3
	v_pk_add_f32 v[152:153], v[152:153], 1.0 op_sel_hi:[1,0]
	s_nop 0
	v_rcp_f32_e32 v154, v153
	s_nop 0
	v_mul_f32_e32 v147, v79, v154
	v_mov_b32_e32 v153, v147
	v_rcp_f32_e32 v154, v152
	s_nop 0
	v_mul_f32_e32 v147, v78, v154
	v_mov_b32_e32 v152, v147
	v_mul_f32_e32 v147, 0xbfb8aa3b, v80
	v_exp_f32_e32 v154, v147
	v_mul_f32_e32 v147, 0xbfb8aa3b, v81
	v_exp_f32_e32 v155, v147
	v_pk_mul_f32 v[152:153], v[152:153], s[4:5] op_sel_hi:[1,0]
	v_pk_add_f32 v[154:155], v[154:155], 1.0 op_sel_hi:[1,0]
	s_nop 0
	v_rcp_f32_e32 v156, v155
	s_nop 0
	v_mul_f32_e32 v147, v81, v156
	v_mov_b32_e32 v155, v147
	v_rcp_f32_e32 v156, v154
	s_nop 0
	v_mul_f32_e32 v147, v80, v156
	v_mov_b32_e32 v154, v147
	v_pk_mul_f32 v[154:155], v[154:155], s[4:5] op_sel_hi:[1,0]
	v_bfe_u32 v157, v153, 16, 1
	v_bfe_u32 v147, v155, 16, 1
	v_bfe_u32 v156, v154, 16, 1
	v_bfe_u32 v158, v152, 16, 1
	v_add3_u32 v152, v152, v158, s0
	v_add3_u32 v157, v153, v157, s0
	v_add3_u32 v153, v154, v156, s0
	v_add3_u32 v147, v155, v147, s0
	v_perm_b32 v153, v147, v153, s19
	v_perm_b32 v152, v157, v152, s19
	v_lshl_add_u64 v[154:155], v[148:149], 0, v[0:1]
	global_store_dwordx2 v[154:155], v[152:153], off
.LBB0_811:
	s_and_b64 vcc, exec, s[40:41]
	s_mov_b64 s[2:3], -1
	s_cbranch_vccnz .LBB0_821
	s_cmp_lt_i32 s34, 3
	s_cbranch_scc1 .LBB0_818
	s_cmp_eq_u32 s34, 3
	s_cbranch_scc1 .LBB0_815
	v_mul_f32_e32 v147, 0xbfb8aa3b, v74
	v_exp_f32_e32 v152, v147
	v_mul_f32_e32 v147, 0xbfb8aa3b, v75
	v_exp_f32_e32 v153, v147
	v_readlane_b32 s48, v253, 4
	v_readlane_b32 s49, v253, 5
	v_readlane_b32 s50, v253, 6
	v_pk_add_f32 v[152:153], v[152:153], 1.0 op_sel_hi:[1,0]
	v_readlane_b32 s51, v253, 7
	v_rcp_f32_e32 v154, v152
	s_nop 0
	v_mul_f32_e32 v147, v74, v154
	v_rcp_f32_e32 v154, v153
	s_nop 0
	v_mul_f32_e32 v152, v75, v154
	v_mov_b32_e32 v154, v152
	v_mul_f32_e32 v152, 0xbfb8aa3b, v76
	v_mul_f32_e32 v153, 0xbfb8aa3b, v77
	v_exp_f32_e32 v152, v152
	v_exp_f32_e32 v153, v153
	s_nop 0
	v_pk_add_f32 v[152:153], v[152:153], 1.0 op_sel_hi:[1,0]
	s_nop 0
	v_rcp_f32_e32 v156, v152
	s_nop 0
	v_mul_f32_e32 v155, v76, v156
	v_mov_b32_e32 v152, v155
	v_rcp_f32_e32 v156, v153
	s_mov_b64 s[2:3], 0
	v_mul_f32_e32 v155, v77, v156
	v_mov_b32_e32 v153, v155
	v_bfe_u32 v155, v153, 16, 1
	v_bfe_u32 v156, v152, 16, 1
	v_bfe_u32 v157, v154, 16, 1
	v_bfe_u32 v158, v147, 16, 1
	v_add3_u32 v147, v147, v158, s0
	v_add3_u32 v154, v154, v157, s0
	v_add3_u32 v152, v152, v156, s0
	v_add3_u32 v153, v153, v155, s0
	v_perm_b32 v153, v153, v152, s19
	v_perm_b32 v152, v154, v147, s19
	v_lshl_add_u64 v[154:155], s[48:49], 0, v[150:151]
	v_lshl_add_u64 v[154:155], v[154:155], 0, v[0:1]
	global_store_dwordx2 v[154:155], v[152:153], off offset:32

.LBB0_818:
	s_andn2_b64 vcc, exec, s[2:3]
	s_cbranch_vccnz .LBB0_820
	v_mul_f32_e32 v152, 0xbfb8aa3b, v74
	v_exp_f32_e32 v152, v152
	s_waitcnt vmcnt(2)
	v_sub_f32_e32 v147, 1.0, v138
	s_mov_b32 s14, 0x800000
	s_mov_b32 s24, 0x3f317217
	v_add_f32_e32 v152, 1.0, v152
	v_rcp_f32_e32 v154, v152
	s_mov_b32 s15, 0x7f800000
	v_readlane_b32 s48, v252, 16
	v_readlane_b32 s60, v252, 28
	v_mov_b32_e32 v153, v154
	v_mov_b32_e32 v152, v153
	v_fma_f32 v147, v152, v147, v138
	v_mul_f32_e32 v153, 0xbfb8aa3b, v75
	v_cmp_gt_f32_e32 vcc, s14, v147
	v_exp_f32_e32 v153, v153
	v_readlane_b32 s61, v252, 29
	v_cndmask_b32_e64 v152, 0, 32, vcc
	v_ldexp_f32 v147, v147, v152
	v_log_f32_e32 v147, v147
	v_add_f32_e32 v153, 1.0, v153
	v_rcp_f32_e32 v155, v153
	v_mul_f32_e32 v152, 0x3f317217, v147
	v_fma_f32 v152, v147, s24, -v152
	v_fmac_f32_e32 v152, 0x3377d1cf, v147
	v_fmac_f32_e32 v152, 0x3f317217, v147
	v_cmp_lt_f32_e64 s[4:5], |v147|, s15
	v_cndmask_b32_e64 v147, v147, v152, s[4:5]
	v_cndmask_b32_e32 v152, 0, v213, vcc
	v_mov_b32_e32 v154, v155
	v_sub_f32_e32 v147, v147, v152
	v_sub_f32_e32 v152, 1.0, v139
	v_mov_b32_e32 v153, v154
	v_fma_f32 v152, v153, v152, v139
	v_mul_f32_e32 v154, 0xbfb8aa3b, v76
	v_cmp_gt_f32_e32 vcc, s14, v152
	v_exp_f32_e32 v154, v154
	v_readlane_b32 s49, v252, 17
	v_cndmask_b32_e64 v153, 0, 32, vcc
	v_ldexp_f32 v152, v152, v153
	v_log_f32_e32 v152, v152
	v_add_f32_e32 v154, 1.0, v154
	v_rcp_f32_e32 v156, v154
	v_mul_f32_e32 v153, 0x3f317217, v152
	v_fma_f32 v153, v152, s24, -v153
	v_fmac_f32_e32 v153, 0x3377d1cf, v152
	v_fmac_f32_e32 v153, 0x3f317217, v152
	v_cmp_lt_f32_e64 s[4:5], |v152|, s15
	v_cndmask_b32_e64 v152, v152, v153, s[4:5]
	v_cndmask_b32_e32 v153, 0, v213, vcc
	v_mov_b32_e32 v155, v156
	v_sub_f32_e32 v152, v152, v153
	v_sub_f32_e32 v153, 1.0, v140
	v_mov_b32_e32 v154, v155
	v_fma_f32 v153, v154, v153, v140
	v_mul_f32_e32 v155, 0xbfb8aa3b, v77
	v_cmp_gt_f32_e32 vcc, s14, v153
	v_exp_f32_e32 v155, v155
	v_cvt_pk_f16_f32 v152, v147, v152
	v_cndmask_b32_e64 v154, 0, 32, vcc
	v_ldexp_f32 v153, v153, v154
	v_log_f32_e32 v153, v153
	v_add_f32_e32 v155, 1.0, v155
	v_rcp_f32_e32 v157, v155
	v_mul_f32_e32 v154, 0x3f317217, v153
	v_fma_f32 v154, v153, s24, -v154
	v_fmac_f32_e32 v154, 0x3377d1cf, v153
	v_fmac_f32_e32 v154, 0x3f317217, v153
	v_cmp_lt_f32_e64 s[4:5], |v153|, s15
	v_cndmask_b32_e64 v153, v153, v154, s[4:5]
	v_cndmask_b32_e32 v154, 0, v213, vcc
	v_mov_b32_e32 v156, v157
	v_sub_f32_e32 v153, v153, v154
	v_sub_f32_e32 v154, 1.0, v141
	v_mov_b32_e32 v155, v156
	v_fma_f32 v154, v155, v154, v141
	v_cmp_gt_f32_e32 vcc, s14, v154
	s_add_i32 s2, s34, -1
	s_mul_hi_i32 s3, s2, 0x2200000
	v_cndmask_b32_e64 v155, 0, 32, vcc
	v_ldexp_f32 v154, v154, v155
	v_log_f32_e32 v154, v154
	s_mul_i32 s2, s2, 0x2200000
	s_add_u32 s2, s60, s2
	s_addc_u32 s3, s61, s3
	v_mul_f32_e32 v155, 0x3f317217, v154
	v_fma_f32 v155, v154, s24, -v155
	v_fmac_f32_e32 v155, 0x3377d1cf, v154
	v_fmac_f32_e32 v155, 0x3f317217, v154
	v_cmp_lt_f32_e64 s[4:5], |v154|, s15
	v_readlane_b32 s50, v252, 18
	v_readlane_b32 s51, v252, 19
	v_cndmask_b32_e64 v154, v154, v155, s[4:5]
	v_cndmask_b32_e32 v155, 0, v213, vcc
	v_sub_f32_e32 v154, v154, v155
	v_cvt_pk_f16_f32 v153, v153, v154
	v_lshl_add_u64 v[154:155], s[2:3], 0, v[150:151]
	v_lshl_add_u64 v[154:155], v[154:155], 0, v[0:1]
	v_readlane_b32 s52, v252, 20
	v_readlane_b32 s53, v252, 21
	v_readlane_b32 s54, v252, 22
	v_readlane_b32 s55, v252, 23
	v_readlane_b32 s56, v252, 24
	v_readlane_b32 s57, v252, 25
	v_readlane_b32 s58, v252, 26
	v_readlane_b32 s59, v252, 27
	v_readlane_b32 s62, v252, 30
	v_readlane_b32 s63, v252, 31
	global_store_dwordx2 v[154:155], v[152:153], off offset:32

.LBB0_821:
	s_andn2_b64 vcc, exec, s[2:3]
	s_cbranch_vccnz .LBB0_823
	v_mul_f32_e32 v147, 0xbfb8aa3b, v74
	v_exp_f32_e32 v152, v147
	v_mul_f32_e32 v147, 0xbfb8aa3b, v75
	v_exp_f32_e32 v153, v147
	s_mov_b32 s4, 0x3db504f3
	v_pk_add_f32 v[152:153], v[152:153], 1.0 op_sel_hi:[1,0]
	s_nop 0
	v_rcp_f32_e32 v154, v153
	s_nop 0
	v_mul_f32_e32 v147, v75, v154
	v_mov_b32_e32 v153, v147
	v_rcp_f32_e32 v154, v152
	s_nop 0
	v_mul_f32_e32 v147, v74, v154
	v_mov_b32_e32 v152, v147
	v_mul_f32_e32 v147, 0xbfb8aa3b, v76
	v_exp_f32_e32 v154, v147
	v_mul_f32_e32 v147, 0xbfb8aa3b, v77
	v_exp_f32_e32 v155, v147
	v_pk_mul_f32 v[152:153], v[152:153], s[4:5] op_sel_hi:[1,0]
	v_pk_add_f32 v[154:155], v[154:155], 1.0 op_sel_hi:[1,0]
	s_nop 0
	v_rcp_f32_e32 v156, v155
	s_nop 0
	v_mul_f32_e32 v147, v77, v156
	v_mov_b32_e32 v155, v147
	v_rcp_f32_e32 v156, v154
	s_nop 0
	v_mul_f32_e32 v147, v76, v156
	v_mov_b32_e32 v154, v147
	v_pk_mul_f32 v[154:155], v[154:155], s[4:5] op_sel_hi:[1,0]
	v_bfe_u32 v157, v153, 16, 1
	v_bfe_u32 v147, v155, 16, 1
	v_bfe_u32 v156, v154, 16, 1
	v_bfe_u32 v158, v152, 16, 1
	v_add3_u32 v152, v152, v158, s0
	v_add3_u32 v157, v153, v157, s0
	v_add3_u32 v153, v154, v156, s0
	v_add3_u32 v147, v155, v147, s0
	v_perm_b32 v153, v147, v153, s19
	v_perm_b32 v152, v157, v152, s19
	v_lshl_add_u64 v[154:155], v[148:149], 0, v[0:1]
	global_store_dwordx2 v[154:155], v[152:153], off offset:32
.LBB0_823:
	s_and_b64 vcc, exec, s[40:41]
	s_mov_b64 s[2:3], -1
	s_cbranch_vccnz .LBB0_833
	s_cmp_lt_i32 s34, 3
	s_cbranch_scc1 .LBB0_830
	s_cmp_eq_u32 s34, 3
	s_cbranch_scc1 .LBB0_827
	v_mul_f32_e32 v147, 0xbfb8aa3b, v70
	v_exp_f32_e32 v152, v147
	v_mul_f32_e32 v147, 0xbfb8aa3b, v71
	v_exp_f32_e32 v153, v147
	v_readlane_b32 s48, v253, 4
	v_readlane_b32 s49, v253, 5
	v_readlane_b32 s50, v253, 6
	v_pk_add_f32 v[152:153], v[152:153], 1.0 op_sel_hi:[1,0]
	v_readlane_b32 s51, v253, 7
	v_rcp_f32_e32 v154, v152
	s_nop 0
	v_mul_f32_e32 v147, v70, v154
	v_rcp_f32_e32 v154, v153
	s_nop 0
	v_mul_f32_e32 v152, v71, v154
	v_mov_b32_e32 v154, v152
	v_mul_f32_e32 v152, 0xbfb8aa3b, v72
	v_mul_f32_e32 v153, 0xbfb8aa3b, v73
	v_exp_f32_e32 v152, v152
	v_exp_f32_e32 v153, v153
	s_nop 0
	v_pk_add_f32 v[152:153], v[152:153], 1.0 op_sel_hi:[1,0]
	s_nop 0
	v_rcp_f32_e32 v156, v152
	s_nop 0
	v_mul_f32_e32 v155, v72, v156
	v_mov_b32_e32 v152, v155
	v_rcp_f32_e32 v156, v153
	s_mov_b64 s[2:3], 0
	v_mul_f32_e32 v155, v73, v156
	v_mov_b32_e32 v153, v155
	v_bfe_u32 v155, v153, 16, 1
	v_bfe_u32 v156, v152, 16, 1
	v_bfe_u32 v157, v154, 16, 1
	v_bfe_u32 v158, v147, 16, 1
	v_add3_u32 v147, v147, v158, s0
	v_add3_u32 v154, v154, v157, s0
	v_add3_u32 v152, v152, v156, s0
	v_add3_u32 v153, v153, v155, s0
	v_perm_b32 v153, v153, v152, s19
	v_perm_b32 v152, v154, v147, s19
	v_lshl_add_u64 v[154:155], s[48:49], 0, v[150:151]
	v_lshl_add_u64 v[154:155], v[154:155], 0, v[0:1]
	global_store_dwordx2 v[154:155], v[152:153], off offset:64

.LBB0_830:
	s_andn2_b64 vcc, exec, s[2:3]
	s_cbranch_vccnz .LBB0_832
	v_mul_f32_e32 v152, 0xbfb8aa3b, v70
	v_exp_f32_e32 v152, v152
	s_waitcnt vmcnt(1)
	v_sub_f32_e32 v147, 1.0, v134
	s_mov_b32 s14, 0x800000
	s_mov_b32 s24, 0x3f317217
	v_add_f32_e32 v152, 1.0, v152
	v_rcp_f32_e32 v154, v152
	s_mov_b32 s15, 0x7f800000
	v_readlane_b32 s48, v252, 16
	v_readlane_b32 s60, v252, 28
	v_mov_b32_e32 v153, v154
	v_mov_b32_e32 v152, v153
	v_fma_f32 v147, v152, v147, v134
	v_mul_f32_e32 v153, 0xbfb8aa3b, v71
	v_cmp_gt_f32_e32 vcc, s14, v147
	v_exp_f32_e32 v153, v153
	v_readlane_b32 s61, v252, 29
	v_cndmask_b32_e64 v152, 0, 32, vcc
	v_ldexp_f32 v147, v147, v152
	v_log_f32_e32 v147, v147
	v_add_f32_e32 v153, 1.0, v153
	v_rcp_f32_e32 v155, v153
	v_mul_f32_e32 v152, 0x3f317217, v147
	v_fma_f32 v152, v147, s24, -v152
	v_fmac_f32_e32 v152, 0x3377d1cf, v147
	v_fmac_f32_e32 v152, 0x3f317217, v147
	v_cmp_lt_f32_e64 s[4:5], |v147|, s15
	v_cndmask_b32_e64 v147, v147, v152, s[4:5]
	v_cndmask_b32_e32 v152, 0, v213, vcc
	v_mov_b32_e32 v154, v155
	v_sub_f32_e32 v147, v147, v152
	v_sub_f32_e32 v152, 1.0, v135
	v_mov_b32_e32 v153, v154
	v_fma_f32 v152, v153, v152, v135
	v_mul_f32_e32 v154, 0xbfb8aa3b, v72
	v_cmp_gt_f32_e32 vcc, s14, v152
	v_exp_f32_e32 v154, v154
	v_readlane_b32 s49, v252, 17
	v_cndmask_b32_e64 v153, 0, 32, vcc
	v_ldexp_f32 v152, v152, v153
	v_log_f32_e32 v152, v152
	v_add_f32_e32 v154, 1.0, v154
	v_rcp_f32_e32 v156, v154
	v_mul_f32_e32 v153, 0x3f317217, v152
	v_fma_f32 v153, v152, s24, -v153
	v_fmac_f32_e32 v153, 0x3377d1cf, v152
	v_fmac_f32_e32 v153, 0x3f317217, v152
	v_cmp_lt_f32_e64 s[4:5], |v152|, s15
	v_cndmask_b32_e64 v152, v152, v153, s[4:5]
	v_cndmask_b32_e32 v153, 0, v213, vcc
	v_mov_b32_e32 v155, v156
	v_sub_f32_e32 v152, v152, v153
	v_sub_f32_e32 v153, 1.0, v136
	v_mov_b32_e32 v154, v155
	v_fma_f32 v153, v154, v153, v136
	v_mul_f32_e32 v155, 0xbfb8aa3b, v73
	v_cmp_gt_f32_e32 vcc, s14, v153
	v_exp_f32_e32 v155, v155
	v_cvt_pk_f16_f32 v152, v147, v152
	v_cndmask_b32_e64 v154, 0, 32, vcc
	v_ldexp_f32 v153, v153, v154
	v_log_f32_e32 v153, v153
	v_add_f32_e32 v155, 1.0, v155
	v_rcp_f32_e32 v157, v155
	v_mul_f32_e32 v154, 0x3f317217, v153
	v_fma_f32 v154, v153, s24, -v154
	v_fmac_f32_e32 v154, 0x3377d1cf, v153
	v_fmac_f32_e32 v154, 0x3f317217, v153
	v_cmp_lt_f32_e64 s[4:5], |v153|, s15
	v_cndmask_b32_e64 v153, v153, v154, s[4:5]
	v_cndmask_b32_e32 v154, 0, v213, vcc
	v_mov_b32_e32 v156, v157
	v_sub_f32_e32 v153, v153, v154
	v_sub_f32_e32 v154, 1.0, v137
	v_mov_b32_e32 v155, v156
	v_fma_f32 v154, v155, v154, v137
	v_cmp_gt_f32_e32 vcc, s14, v154
	s_add_i32 s2, s34, -1
	s_mul_hi_i32 s3, s2, 0x2200000
	v_cndmask_b32_e64 v155, 0, 32, vcc
	v_ldexp_f32 v154, v154, v155
	v_log_f32_e32 v154, v154
	s_mul_i32 s2, s2, 0x2200000
	s_add_u32 s2, s60, s2
	s_addc_u32 s3, s61, s3
	v_mul_f32_e32 v155, 0x3f317217, v154
	v_fma_f32 v155, v154, s24, -v155
	v_fmac_f32_e32 v155, 0x3377d1cf, v154
	v_fmac_f32_e32 v155, 0x3f317217, v154
	v_cmp_lt_f32_e64 s[4:5], |v154|, s15
	v_readlane_b32 s50, v252, 18
	v_readlane_b32 s51, v252, 19
	v_cndmask_b32_e64 v154, v154, v155, s[4:5]
	v_cndmask_b32_e32 v155, 0, v213, vcc
	v_sub_f32_e32 v154, v154, v155
	v_cvt_pk_f16_f32 v153, v153, v154
	v_lshl_add_u64 v[154:155], s[2:3], 0, v[150:151]
	v_lshl_add_u64 v[154:155], v[154:155], 0, v[0:1]
	v_readlane_b32 s52, v252, 20
	v_readlane_b32 s53, v252, 21
	v_readlane_b32 s54, v252, 22
	v_readlane_b32 s55, v252, 23
	v_readlane_b32 s56, v252, 24
	v_readlane_b32 s57, v252, 25
	v_readlane_b32 s58, v252, 26
	v_readlane_b32 s59, v252, 27
	v_readlane_b32 s62, v252, 30
	v_readlane_b32 s63, v252, 31
	global_store_dwordx2 v[154:155], v[152:153], off offset:64

.LBB0_833:
	s_andn2_b64 vcc, exec, s[2:3]
	s_cbranch_vccnz .LBB0_835
	v_mul_f32_e32 v147, 0xbfb8aa3b, v70
	v_exp_f32_e32 v152, v147
	v_mul_f32_e32 v147, 0xbfb8aa3b, v71
	v_exp_f32_e32 v153, v147
	s_mov_b32 s4, 0x3db504f3
	v_pk_add_f32 v[152:153], v[152:153], 1.0 op_sel_hi:[1,0]
	s_nop 0
	v_rcp_f32_e32 v154, v153
	s_nop 0
	v_mul_f32_e32 v147, v71, v154
	v_mov_b32_e32 v153, v147
	v_rcp_f32_e32 v154, v152
	s_nop 0
	v_mul_f32_e32 v147, v70, v154
	v_mov_b32_e32 v152, v147
	v_mul_f32_e32 v147, 0xbfb8aa3b, v72
	v_exp_f32_e32 v154, v147
	v_mul_f32_e32 v147, 0xbfb8aa3b, v73
	v_exp_f32_e32 v155, v147
	v_pk_mul_f32 v[152:153], v[152:153], s[4:5] op_sel_hi:[1,0]
	v_pk_add_f32 v[154:155], v[154:155], 1.0 op_sel_hi:[1,0]
	s_nop 0
	v_rcp_f32_e32 v156, v155
	s_nop 0
	v_mul_f32_e32 v147, v73, v156
	v_mov_b32_e32 v155, v147
	v_rcp_f32_e32 v156, v154
	s_nop 0
	v_mul_f32_e32 v147, v72, v156
	v_mov_b32_e32 v154, v147
	v_pk_mul_f32 v[154:155], v[154:155], s[4:5] op_sel_hi:[1,0]
	v_bfe_u32 v157, v153, 16, 1
	v_bfe_u32 v147, v155, 16, 1
	v_bfe_u32 v156, v154, 16, 1
	v_bfe_u32 v158, v152, 16, 1
	v_add3_u32 v152, v152, v158, s0
	v_add3_u32 v157, v153, v157, s0
	v_add3_u32 v153, v154, v156, s0
	v_add3_u32 v147, v155, v147, s0
	v_perm_b32 v153, v147, v153, s19
	v_perm_b32 v152, v157, v152, s19
	v_lshl_add_u64 v[154:155], v[148:149], 0, v[0:1]
	global_store_dwordx2 v[154:155], v[152:153], off offset:64
.LBB0_835:
	s_and_b64 vcc, exec, s[40:41]
	s_mov_b64 s[2:3], -1
	s_cbranch_vccnz .LBB0_845
	s_cmp_lt_i32 s34, 3
	s_cbranch_scc1 .LBB0_842
	s_cmp_eq_u32 s34, 3
	s_cbranch_scc1 .LBB0_839
	v_mul_f32_e32 v147, 0xbfb8aa3b, v66
	v_exp_f32_e32 v152, v147
	v_mul_f32_e32 v147, 0xbfb8aa3b, v67
	v_exp_f32_e32 v153, v147
	v_readlane_b32 s48, v253, 4
	v_readlane_b32 s49, v253, 5
	v_readlane_b32 s50, v253, 6
	v_pk_add_f32 v[152:153], v[152:153], 1.0 op_sel_hi:[1,0]
	v_readlane_b32 s51, v253, 7
	v_rcp_f32_e32 v154, v152
	s_nop 0
	v_mul_f32_e32 v147, v66, v154
	v_rcp_f32_e32 v154, v153
	s_nop 0
	v_mul_f32_e32 v152, v67, v154
	v_mov_b32_e32 v154, v152
	v_mul_f32_e32 v152, 0xbfb8aa3b, v68
	v_mul_f32_e32 v153, 0xbfb8aa3b, v69
	v_exp_f32_e32 v152, v152
	v_exp_f32_e32 v153, v153
	s_nop 0
	v_pk_add_f32 v[152:153], v[152:153], 1.0 op_sel_hi:[1,0]
	s_nop 0
	v_rcp_f32_e32 v156, v152
	s_nop 0
	v_mul_f32_e32 v155, v68, v156
	v_mov_b32_e32 v152, v155
	v_rcp_f32_e32 v156, v153
	s_mov_b64 s[2:3], 0
	v_mul_f32_e32 v155, v69, v156
	v_mov_b32_e32 v153, v155
	v_bfe_u32 v155, v153, 16, 1
	v_bfe_u32 v156, v152, 16, 1
	v_bfe_u32 v157, v154, 16, 1
	v_bfe_u32 v158, v147, 16, 1
	v_add3_u32 v147, v147, v158, s0
	v_add3_u32 v154, v154, v157, s0
	v_add3_u32 v152, v152, v156, s0
	v_add3_u32 v153, v153, v155, s0
	v_perm_b32 v153, v153, v152, s19
	v_perm_b32 v152, v154, v147, s19
	v_lshl_add_u64 v[154:155], s[48:49], 0, v[150:151]
	v_lshl_add_u64 v[154:155], v[154:155], 0, v[0:1]
	global_store_dwordx2 v[154:155], v[152:153], off offset:96

.LBB0_842:
	s_andn2_b64 vcc, exec, s[2:3]
	s_cbranch_vccnz .LBB0_844
	v_mul_f32_e32 v152, 0xbfb8aa3b, v66
	v_exp_f32_e32 v152, v152
	s_waitcnt vmcnt(0)
	v_sub_f32_e32 v147, 1.0, v130
	s_mov_b32 s14, 0x800000
	s_mov_b32 s24, 0x3f317217
	v_add_f32_e32 v152, 1.0, v152
	v_rcp_f32_e32 v154, v152
	s_mov_b32 s15, 0x7f800000
	v_readlane_b32 s48, v252, 16
	v_readlane_b32 s60, v252, 28
	v_mov_b32_e32 v153, v154
	v_mov_b32_e32 v152, v153
	v_fma_f32 v147, v152, v147, v130
	v_mul_f32_e32 v153, 0xbfb8aa3b, v67
	v_cmp_gt_f32_e32 vcc, s14, v147
	v_exp_f32_e32 v153, v153
	v_readlane_b32 s61, v252, 29
	v_cndmask_b32_e64 v152, 0, 32, vcc
	v_ldexp_f32 v147, v147, v152
	v_log_f32_e32 v147, v147
	v_add_f32_e32 v153, 1.0, v153
	v_rcp_f32_e32 v155, v153
	v_mul_f32_e32 v152, 0x3f317217, v147
	v_fma_f32 v152, v147, s24, -v152
	v_fmac_f32_e32 v152, 0x3377d1cf, v147
	v_fmac_f32_e32 v152, 0x3f317217, v147
	v_cmp_lt_f32_e64 s[4:5], |v147|, s15
	v_cndmask_b32_e64 v147, v147, v152, s[4:5]
	v_cndmask_b32_e32 v152, 0, v213, vcc
	v_mov_b32_e32 v154, v155
	v_sub_f32_e32 v147, v147, v152
	v_sub_f32_e32 v152, 1.0, v131
	v_mov_b32_e32 v153, v154
	v_fma_f32 v152, v153, v152, v131
	v_mul_f32_e32 v154, 0xbfb8aa3b, v68
	v_cmp_gt_f32_e32 vcc, s14, v152
	v_exp_f32_e32 v154, v154
	v_readlane_b32 s49, v252, 17
	v_cndmask_b32_e64 v153, 0, 32, vcc
	v_ldexp_f32 v152, v152, v153
	v_log_f32_e32 v152, v152
	v_add_f32_e32 v154, 1.0, v154
	v_rcp_f32_e32 v156, v154
	v_mul_f32_e32 v153, 0x3f317217, v152
	v_fma_f32 v153, v152, s24, -v153
	v_fmac_f32_e32 v153, 0x3377d1cf, v152
	v_fmac_f32_e32 v153, 0x3f317217, v152
	v_cmp_lt_f32_e64 s[4:5], |v152|, s15
	v_cndmask_b32_e64 v152, v152, v153, s[4:5]
	v_cndmask_b32_e32 v153, 0, v213, vcc
	v_mov_b32_e32 v155, v156
	v_sub_f32_e32 v152, v152, v153
	v_sub_f32_e32 v153, 1.0, v132
	v_mov_b32_e32 v154, v155
	v_fma_f32 v153, v154, v153, v132
	v_mul_f32_e32 v155, 0xbfb8aa3b, v69
	v_cmp_gt_f32_e32 vcc, s14, v153
	v_exp_f32_e32 v155, v155
	v_cvt_pk_f16_f32 v152, v147, v152
	v_cndmask_b32_e64 v154, 0, 32, vcc
	v_ldexp_f32 v153, v153, v154
	v_log_f32_e32 v153, v153
	v_add_f32_e32 v155, 1.0, v155
	v_rcp_f32_e32 v157, v155
	v_mul_f32_e32 v154, 0x3f317217, v153
	v_fma_f32 v154, v153, s24, -v154
	v_fmac_f32_e32 v154, 0x3377d1cf, v153
	v_fmac_f32_e32 v154, 0x3f317217, v153
	v_cmp_lt_f32_e64 s[4:5], |v153|, s15
	v_cndmask_b32_e64 v153, v153, v154, s[4:5]
	v_cndmask_b32_e32 v154, 0, v213, vcc
	v_mov_b32_e32 v156, v157
	v_sub_f32_e32 v153, v153, v154
	v_sub_f32_e32 v154, 1.0, v133
	v_mov_b32_e32 v155, v156
	v_fma_f32 v154, v155, v154, v133
	v_cmp_gt_f32_e32 vcc, s14, v154
	s_add_i32 s2, s34, -1
	s_mul_hi_i32 s3, s2, 0x2200000
	v_cndmask_b32_e64 v155, 0, 32, vcc
	v_ldexp_f32 v154, v154, v155
	v_log_f32_e32 v154, v154
	s_mul_i32 s2, s2, 0x2200000
	s_add_u32 s2, s60, s2
	s_addc_u32 s3, s61, s3
	v_mul_f32_e32 v155, 0x3f317217, v154
	v_fma_f32 v155, v154, s24, -v155
	v_fmac_f32_e32 v155, 0x3377d1cf, v154
	v_fmac_f32_e32 v155, 0x3f317217, v154
	v_cmp_lt_f32_e64 s[4:5], |v154|, s15
	v_lshl_add_u64 v[150:151], s[2:3], 0, v[150:151]
	v_lshl_add_u64 v[150:151], v[150:151], 0, v[0:1]
	v_cndmask_b32_e64 v154, v154, v155, s[4:5]
	v_cndmask_b32_e32 v155, 0, v213, vcc
	v_sub_f32_e32 v154, v154, v155
	v_cvt_pk_f16_f32 v153, v153, v154
	v_readlane_b32 s50, v252, 18
	v_readlane_b32 s51, v252, 19
	v_readlane_b32 s52, v252, 20
	v_readlane_b32 s53, v252, 21
	v_readlane_b32 s54, v252, 22
	v_readlane_b32 s55, v252, 23
	v_readlane_b32 s56, v252, 24
	v_readlane_b32 s57, v252, 25
	v_readlane_b32 s58, v252, 26
	v_readlane_b32 s59, v252, 27
	v_readlane_b32 s62, v252, 30
	v_readlane_b32 s63, v252, 31
	global_store_dwordx2 v[150:151], v[152:153], off offset:96

.LBB0_845:
	s_andn2_b64 vcc, exec, s[2:3]
	s_cbranch_vccnz .LBB0_847
	v_mul_f32_e32 v147, 0xbfb8aa3b, v66
	v_exp_f32_e32 v150, v147
	v_mul_f32_e32 v147, 0xbfb8aa3b, v67
	v_exp_f32_e32 v151, v147
	s_mov_b32 s4, 0x3db504f3
	v_lshl_add_u64 v[148:149], v[148:149], 0, v[0:1]
	v_pk_add_f32 v[150:151], v[150:151], 1.0 op_sel_hi:[1,0]
	s_nop 0
	v_rcp_f32_e32 v152, v151
	s_nop 0
	v_mul_f32_e32 v147, v67, v152
	v_mov_b32_e32 v151, v147
	v_rcp_f32_e32 v152, v150
	s_nop 0
	v_mul_f32_e32 v147, v66, v152
	v_mov_b32_e32 v150, v147
	v_mul_f32_e32 v147, 0xbfb8aa3b, v68
	v_exp_f32_e32 v152, v147
	v_mul_f32_e32 v147, 0xbfb8aa3b, v69
	v_exp_f32_e32 v153, v147
	v_pk_mul_f32 v[150:151], v[150:151], s[4:5] op_sel_hi:[1,0]
	v_pk_add_f32 v[152:153], v[152:153], 1.0 op_sel_hi:[1,0]
	s_nop 0
	v_rcp_f32_e32 v154, v153
	s_nop 0
	v_mul_f32_e32 v147, v69, v154
	v_mov_b32_e32 v153, v147
	v_rcp_f32_e32 v154, v152
	s_nop 0
	v_mul_f32_e32 v147, v68, v154
	v_mov_b32_e32 v152, v147
	v_pk_mul_f32 v[152:153], v[152:153], s[4:5] op_sel_hi:[1,0]
	v_bfe_u32 v155, v151, 16, 1
	v_bfe_u32 v147, v153, 16, 1
	v_bfe_u32 v154, v152, 16, 1
	v_bfe_u32 v156, v150, 16, 1
	v_add3_u32 v150, v150, v156, s0
	v_add3_u32 v155, v151, v155, s0
	v_add3_u32 v151, v152, v154, s0
	v_add3_u32 v147, v153, v147, s0
	v_perm_b32 v151, v147, v151, s19
	v_perm_b32 v150, v155, v150, s19
	global_store_dwordx2 v[148:149], v[150:151], off offset:96
.LBB0_847:
	v_or_b32_e32 v148, 64, v146
	v_ashrrev_i32_e32 v149, 31, v148
	s_and_b64 vcc, exec, s[40:41]
	s_mov_b64 s[2:3], -1
	s_cbranch_vccnz .LBB0_857
	s_cmp_lt_i32 s34, 3
	s_cbranch_scc1 .LBB0_854
	s_cmp_eq_u32 s34, 3
	s_cbranch_scc1 .LBB0_851
	v_mul_f32_e32 v147, 0xbfb8aa3b, v62
	v_exp_f32_e32 v150, v147
	v_mul_f32_e32 v147, 0xbfb8aa3b, v63
	v_exp_f32_e32 v151, v147
	v_readlane_b32 s48, v253, 4
	v_readlane_b32 s49, v253, 5
	v_readlane_b32 s50, v253, 6
	v_pk_add_f32 v[150:151], v[150:151], 1.0 op_sel_hi:[1,0]
	v_readlane_b32 s51, v253, 7
	v_rcp_f32_e32 v152, v150
	s_nop 0
	v_mul_f32_e32 v147, v62, v152
	v_rcp_f32_e32 v152, v151
	s_nop 0
	v_mul_f32_e32 v150, v63, v152
	v_mov_b32_e32 v152, v150
	v_mul_f32_e32 v150, 0xbfb8aa3b, v64
	v_mul_f32_e32 v151, 0xbfb8aa3b, v65
	v_exp_f32_e32 v150, v150
	v_exp_f32_e32 v151, v151
	s_nop 0
	v_pk_add_f32 v[150:151], v[150:151], 1.0 op_sel_hi:[1,0]
	s_nop 0
	v_rcp_f32_e32 v154, v150
	s_nop 0
	v_mul_f32_e32 v153, v64, v154
	v_mov_b32_e32 v150, v153
	v_rcp_f32_e32 v154, v151
	s_mov_b64 s[2:3], 0
	v_mul_f32_e32 v153, v65, v154
	v_mov_b32_e32 v151, v153
	v_bfe_u32 v153, v151, 16, 1
	v_bfe_u32 v154, v150, 16, 1
	v_bfe_u32 v155, v152, 16, 1
	v_bfe_u32 v156, v147, 16, 1
	v_add3_u32 v147, v147, v156, s0
	v_add3_u32 v152, v152, v155, s0
	v_add3_u32 v150, v150, v154, s0
	v_add3_u32 v151, v151, v153, s0
	v_perm_b32 v151, v151, v150, s19
	v_perm_b32 v150, v152, v147, s19
	v_lshlrev_b64 v[152:153], 11, v[148:149]
	v_lshl_add_u64 v[152:153], s[48:49], 0, v[152:153]
	v_lshl_add_u64 v[152:153], v[152:153], 0, v[0:1]
	global_store_dwordx2 v[152:153], v[150:151], off

.LBB0_854:
	s_andn2_b64 vcc, exec, s[2:3]
	s_cbranch_vccnz .LBB0_856
	v_mul_f32_e32 v150, 0xbfb8aa3b, v62
	v_exp_f32_e32 v150, v150
	s_waitcnt vmcnt(3)
	v_sub_f32_e32 v147, 1.0, v142
	s_mov_b32 s14, 0x800000
	s_mov_b32 s24, 0x3f317217
	v_add_f32_e32 v150, 1.0, v150
	v_rcp_f32_e32 v152, v150
	s_mov_b32 s15, 0x7f800000
	v_readlane_b32 s48, v252, 16
	v_readlane_b32 s60, v252, 28
	v_mov_b32_e32 v151, v152
	v_mov_b32_e32 v150, v151
	v_fma_f32 v147, v150, v147, v142
	v_mul_f32_e32 v151, 0xbfb8aa3b, v63
	v_cmp_gt_f32_e32 vcc, s14, v147
	v_exp_f32_e32 v151, v151
	v_readlane_b32 s61, v252, 29
	v_cndmask_b32_e64 v150, 0, 32, vcc
	v_ldexp_f32 v147, v147, v150
	v_log_f32_e32 v147, v147
	v_add_f32_e32 v151, 1.0, v151
	v_rcp_f32_e32 v153, v151
	v_mul_f32_e32 v150, 0x3f317217, v147
	v_fma_f32 v150, v147, s24, -v150
	v_fmac_f32_e32 v150, 0x3377d1cf, v147
	v_fmac_f32_e32 v150, 0x3f317217, v147
	v_cmp_lt_f32_e64 s[4:5], |v147|, s15
	v_cndmask_b32_e64 v147, v147, v150, s[4:5]
	v_cndmask_b32_e32 v150, 0, v213, vcc
	v_mov_b32_e32 v152, v153
	v_sub_f32_e32 v147, v147, v150
	v_sub_f32_e32 v150, 1.0, v143
	v_mov_b32_e32 v151, v152
	v_fma_f32 v150, v151, v150, v143
	v_mul_f32_e32 v152, 0xbfb8aa3b, v64
	v_cmp_gt_f32_e32 vcc, s14, v150
	v_exp_f32_e32 v152, v152
	v_readlane_b32 s49, v252, 17
	v_cndmask_b32_e64 v151, 0, 32, vcc
	v_ldexp_f32 v150, v150, v151
	v_log_f32_e32 v150, v150
	v_add_f32_e32 v152, 1.0, v152
	v_rcp_f32_e32 v154, v152
	v_mul_f32_e32 v151, 0x3f317217, v150
	v_fma_f32 v151, v150, s24, -v151
	v_fmac_f32_e32 v151, 0x3377d1cf, v150
	v_fmac_f32_e32 v151, 0x3f317217, v150
	v_cmp_lt_f32_e64 s[4:5], |v150|, s15
	v_cndmask_b32_e64 v150, v150, v151, s[4:5]
	v_cndmask_b32_e32 v151, 0, v213, vcc
	v_mov_b32_e32 v153, v154
	v_sub_f32_e32 v150, v150, v151
	v_sub_f32_e32 v151, 1.0, v144
	v_mov_b32_e32 v152, v153
	v_fma_f32 v151, v152, v151, v144
	v_mul_f32_e32 v153, 0xbfb8aa3b, v65
	v_cmp_gt_f32_e32 vcc, s14, v151
	v_exp_f32_e32 v153, v153
	v_cvt_pk_f16_f32 v150, v147, v150
	v_cndmask_b32_e64 v152, 0, 32, vcc
	v_ldexp_f32 v151, v151, v152
	v_log_f32_e32 v151, v151
	v_add_f32_e32 v153, 1.0, v153
	v_rcp_f32_e32 v155, v153
	v_mul_f32_e32 v152, 0x3f317217, v151
	v_fma_f32 v152, v151, s24, -v152
	v_fmac_f32_e32 v152, 0x3377d1cf, v151
	v_fmac_f32_e32 v152, 0x3f317217, v151
	v_cmp_lt_f32_e64 s[4:5], |v151|, s15
	v_cndmask_b32_e64 v151, v151, v152, s[4:5]
	v_cndmask_b32_e32 v152, 0, v213, vcc
	v_mov_b32_e32 v154, v155
	v_sub_f32_e32 v151, v151, v152
	v_sub_f32_e32 v152, 1.0, v145
	v_mov_b32_e32 v153, v154
	v_fma_f32 v152, v153, v152, v145
	v_cmp_gt_f32_e32 vcc, s14, v152
	s_add_i32 s2, s34, -1
	s_mul_hi_i32 s3, s2, 0x2200000
	v_cndmask_b32_e64 v153, 0, 32, vcc
	v_ldexp_f32 v152, v152, v153
	v_log_f32_e32 v152, v152
	s_mul_i32 s2, s2, 0x2200000
	s_add_u32 s2, s60, s2
	s_addc_u32 s3, s61, s3
	v_mul_f32_e32 v153, 0x3f317217, v152
	v_fma_f32 v153, v152, s24, -v153
	v_fmac_f32_e32 v153, 0x3377d1cf, v152
	v_fmac_f32_e32 v153, 0x3f317217, v152
	v_cmp_lt_f32_e64 s[4:5], |v152|, s15
	v_readlane_b32 s50, v252, 18
	v_readlane_b32 s51, v252, 19
	v_cndmask_b32_e64 v152, v152, v153, s[4:5]
	v_cndmask_b32_e32 v153, 0, v213, vcc
	v_sub_f32_e32 v152, v152, v153
	v_cvt_pk_f16_f32 v151, v151, v152
	v_lshlrev_b64 v[152:153], 11, v[148:149]
	v_lshl_add_u64 v[152:153], s[2:3], 0, v[152:153]
	v_lshl_add_u64 v[152:153], v[152:153], 0, v[0:1]
	v_readlane_b32 s52, v252, 20
	v_readlane_b32 s53, v252, 21
	v_readlane_b32 s54, v252, 22
	v_readlane_b32 s55, v252, 23
	v_readlane_b32 s56, v252, 24
	v_readlane_b32 s57, v252, 25
	v_readlane_b32 s58, v252, 26
	v_readlane_b32 s59, v252, 27
	v_readlane_b32 s62, v252, 30
	v_readlane_b32 s63, v252, 31
	global_store_dwordx2 v[152:153], v[150:151], off

.LBB0_857:
	v_readlane_b32 s48, v252, 16
	v_lshlrev_b64 v[150:151], 11, v[148:149]
	v_readlane_b32 s58, v252, 26
	v_readlane_b32 s59, v252, 27
	s_andn2_b64 vcc, exec, s[2:3]
	v_readlane_b32 s49, v252, 17
	v_lshl_add_u64 v[148:149], s[58:59], 0, v[150:151]
	v_readlane_b32 s50, v252, 18
	v_readlane_b32 s51, v252, 19
	v_readlane_b32 s52, v252, 20
	v_readlane_b32 s53, v252, 21
	v_readlane_b32 s54, v252, 22
	v_readlane_b32 s55, v252, 23
	v_readlane_b32 s56, v252, 24
	v_readlane_b32 s57, v252, 25
	v_readlane_b32 s60, v252, 28
	v_readlane_b32 s61, v252, 29
	v_readlane_b32 s62, v252, 30
	v_readlane_b32 s63, v252, 31
	s_cbranch_vccnz .LBB0_859
	v_mul_f32_e32 v147, 0xbfb8aa3b, v62
	v_exp_f32_e32 v152, v147
	v_mul_f32_e32 v147, 0xbfb8aa3b, v63
	v_exp_f32_e32 v153, v147
	s_mov_b32 s4, 0x3db504f3
	v_pk_add_f32 v[152:153], v[152:153], 1.0 op_sel_hi:[1,0]
	s_nop 0
	v_rcp_f32_e32 v154, v153
	s_nop 0
	v_mul_f32_e32 v147, v63, v154
	v_mov_b32_e32 v153, v147
	v_rcp_f32_e32 v154, v152
	s_nop 0
	v_mul_f32_e32 v147, v62, v154
	v_mov_b32_e32 v152, v147
	v_mul_f32_e32 v147, 0xbfb8aa3b, v64
	v_exp_f32_e32 v154, v147
	v_mul_f32_e32 v147, 0xbfb8aa3b, v65
	v_exp_f32_e32 v155, v147
	v_pk_mul_f32 v[152:153], v[152:153], s[4:5] op_sel_hi:[1,0]
	v_pk_add_f32 v[154:155], v[154:155], 1.0 op_sel_hi:[1,0]
	s_nop 0
	v_rcp_f32_e32 v156, v155
	s_nop 0
	v_mul_f32_e32 v147, v65, v156
	v_mov_b32_e32 v155, v147
	v_rcp_f32_e32 v156, v154
	s_nop 0
	v_mul_f32_e32 v147, v64, v156
	v_mov_b32_e32 v154, v147
	v_pk_mul_f32 v[154:155], v[154:155], s[4:5] op_sel_hi:[1,0]
	v_bfe_u32 v157, v153, 16, 1
	v_bfe_u32 v147, v155, 16, 1
	v_bfe_u32 v156, v154, 16, 1
	v_bfe_u32 v158, v152, 16, 1
	v_add3_u32 v152, v152, v158, s0
	v_add3_u32 v157, v153, v157, s0
	v_add3_u32 v153, v154, v156, s0
	v_add3_u32 v147, v155, v147, s0
	v_perm_b32 v153, v147, v153, s19
	v_perm_b32 v152, v157, v152, s19
	v_lshl_add_u64 v[154:155], v[148:149], 0, v[0:1]
	global_store_dwordx2 v[154:155], v[152:153], off
.LBB0_859:
	s_and_b64 vcc, exec, s[40:41]
	s_mov_b64 s[2:3], -1
	s_cbranch_vccnz .LBB0_869
	s_cmp_lt_i32 s34, 3
	s_cbranch_scc1 .LBB0_866
	s_cmp_eq_u32 s34, 3
	s_cbranch_scc1 .LBB0_863
	v_mul_f32_e32 v147, 0xbfb8aa3b, v58
	v_exp_f32_e32 v152, v147
	v_mul_f32_e32 v147, 0xbfb8aa3b, v59
	v_exp_f32_e32 v153, v147
	v_readlane_b32 s48, v253, 4
	v_readlane_b32 s49, v253, 5
	v_readlane_b32 s50, v253, 6
	v_pk_add_f32 v[152:153], v[152:153], 1.0 op_sel_hi:[1,0]
	v_readlane_b32 s51, v253, 7
	v_rcp_f32_e32 v154, v152
	s_nop 0
	v_mul_f32_e32 v147, v58, v154
	v_rcp_f32_e32 v154, v153
	s_nop 0
	v_mul_f32_e32 v152, v59, v154
	v_mov_b32_e32 v154, v152
	v_mul_f32_e32 v152, 0xbfb8aa3b, v60
	v_mul_f32_e32 v153, 0xbfb8aa3b, v61
	v_exp_f32_e32 v152, v152
	v_exp_f32_e32 v153, v153
	s_nop 0
	v_pk_add_f32 v[152:153], v[152:153], 1.0 op_sel_hi:[1,0]
	s_nop 0
	v_rcp_f32_e32 v156, v152
	s_nop 0
	v_mul_f32_e32 v155, v60, v156
	v_mov_b32_e32 v152, v155
	v_rcp_f32_e32 v156, v153
	s_mov_b64 s[2:3], 0
	v_mul_f32_e32 v155, v61, v156
	v_mov_b32_e32 v153, v155
	v_bfe_u32 v155, v153, 16, 1
	v_bfe_u32 v156, v152, 16, 1
	v_bfe_u32 v157, v154, 16, 1
	v_bfe_u32 v158, v147, 16, 1
	v_add3_u32 v147, v147, v158, s0
	v_add3_u32 v154, v154, v157, s0
	v_add3_u32 v152, v152, v156, s0
	v_add3_u32 v153, v153, v155, s0
	v_perm_b32 v153, v153, v152, s19
	v_perm_b32 v152, v154, v147, s19
	v_lshl_add_u64 v[154:155], s[48:49], 0, v[150:151]
	v_lshl_add_u64 v[154:155], v[154:155], 0, v[0:1]
	global_store_dwordx2 v[154:155], v[152:153], off offset:32

.LBB0_866:
	s_andn2_b64 vcc, exec, s[2:3]
	s_cbranch_vccnz .LBB0_868
	v_mul_f32_e32 v152, 0xbfb8aa3b, v58
	v_exp_f32_e32 v152, v152
	s_waitcnt vmcnt(2)
	v_sub_f32_e32 v147, 1.0, v138
	s_mov_b32 s14, 0x800000
	s_mov_b32 s24, 0x3f317217
	v_add_f32_e32 v152, 1.0, v152
	v_rcp_f32_e32 v154, v152
	s_mov_b32 s15, 0x7f800000
	v_readlane_b32 s48, v252, 16
	v_readlane_b32 s60, v252, 28
	v_mov_b32_e32 v153, v154
	v_mov_b32_e32 v152, v153
	v_fma_f32 v147, v152, v147, v138
	v_mul_f32_e32 v153, 0xbfb8aa3b, v59
	v_cmp_gt_f32_e32 vcc, s14, v147
	v_exp_f32_e32 v153, v153
	v_readlane_b32 s61, v252, 29
	v_cndmask_b32_e64 v152, 0, 32, vcc
	v_ldexp_f32 v147, v147, v152
	v_log_f32_e32 v147, v147
	v_add_f32_e32 v153, 1.0, v153
	v_rcp_f32_e32 v155, v153
	v_mul_f32_e32 v152, 0x3f317217, v147
	v_fma_f32 v152, v147, s24, -v152
	v_fmac_f32_e32 v152, 0x3377d1cf, v147
	v_fmac_f32_e32 v152, 0x3f317217, v147
	v_cmp_lt_f32_e64 s[4:5], |v147|, s15
	v_cndmask_b32_e64 v147, v147, v152, s[4:5]
	v_cndmask_b32_e32 v152, 0, v213, vcc
	v_mov_b32_e32 v154, v155
	v_sub_f32_e32 v147, v147, v152
	v_sub_f32_e32 v152, 1.0, v139
	v_mov_b32_e32 v153, v154
	v_fma_f32 v152, v153, v152, v139
	v_mul_f32_e32 v154, 0xbfb8aa3b, v60
	v_cmp_gt_f32_e32 vcc, s14, v152
	v_exp_f32_e32 v154, v154
	v_readlane_b32 s49, v252, 17
	v_cndmask_b32_e64 v153, 0, 32, vcc
	v_ldexp_f32 v152, v152, v153
	v_log_f32_e32 v152, v152
	v_add_f32_e32 v154, 1.0, v154
	v_rcp_f32_e32 v156, v154
	v_mul_f32_e32 v153, 0x3f317217, v152
	v_fma_f32 v153, v152, s24, -v153
	v_fmac_f32_e32 v153, 0x3377d1cf, v152
	v_fmac_f32_e32 v153, 0x3f317217, v152
	v_cmp_lt_f32_e64 s[4:5], |v152|, s15
	v_cndmask_b32_e64 v152, v152, v153, s[4:5]
	v_cndmask_b32_e32 v153, 0, v213, vcc
	v_mov_b32_e32 v155, v156
	v_sub_f32_e32 v152, v152, v153
	v_sub_f32_e32 v153, 1.0, v140
	v_mov_b32_e32 v154, v155
	v_fma_f32 v153, v154, v153, v140
	v_mul_f32_e32 v155, 0xbfb8aa3b, v61
	v_cmp_gt_f32_e32 vcc, s14, v153
	v_exp_f32_e32 v155, v155
	v_cvt_pk_f16_f32 v152, v147, v152
	v_cndmask_b32_e64 v154, 0, 32, vcc
	v_ldexp_f32 v153, v153, v154
	v_log_f32_e32 v153, v153
	v_add_f32_e32 v155, 1.0, v155
	v_rcp_f32_e32 v157, v155
	v_mul_f32_e32 v154, 0x3f317217, v153
	v_fma_f32 v154, v153, s24, -v154
	v_fmac_f32_e32 v154, 0x3377d1cf, v153
	v_fmac_f32_e32 v154, 0x3f317217, v153
	v_cmp_lt_f32_e64 s[4:5], |v153|, s15
	v_cndmask_b32_e64 v153, v153, v154, s[4:5]
	v_cndmask_b32_e32 v154, 0, v213, vcc
	v_mov_b32_e32 v156, v157
	v_sub_f32_e32 v153, v153, v154
	v_sub_f32_e32 v154, 1.0, v141
	v_mov_b32_e32 v155, v156
	v_fma_f32 v154, v155, v154, v141
	v_cmp_gt_f32_e32 vcc, s14, v154
	s_add_i32 s2, s34, -1
	s_mul_hi_i32 s3, s2, 0x2200000
	v_cndmask_b32_e64 v155, 0, 32, vcc
	v_ldexp_f32 v154, v154, v155
	v_log_f32_e32 v154, v154
	s_mul_i32 s2, s2, 0x2200000
	s_add_u32 s2, s60, s2
	s_addc_u32 s3, s61, s3
	v_mul_f32_e32 v155, 0x3f317217, v154
	v_fma_f32 v155, v154, s24, -v155
	v_fmac_f32_e32 v155, 0x3377d1cf, v154
	v_fmac_f32_e32 v155, 0x3f317217, v154
	v_cmp_lt_f32_e64 s[4:5], |v154|, s15
	v_readlane_b32 s50, v252, 18
	v_readlane_b32 s51, v252, 19
	v_cndmask_b32_e64 v154, v154, v155, s[4:5]
	v_cndmask_b32_e32 v155, 0, v213, vcc
	v_sub_f32_e32 v154, v154, v155
	v_cvt_pk_f16_f32 v153, v153, v154
	v_lshl_add_u64 v[154:155], s[2:3], 0, v[150:151]
	v_lshl_add_u64 v[154:155], v[154:155], 0, v[0:1]
	v_readlane_b32 s52, v252, 20
	v_readlane_b32 s53, v252, 21
	v_readlane_b32 s54, v252, 22
	v_readlane_b32 s55, v252, 23
	v_readlane_b32 s56, v252, 24
	v_readlane_b32 s57, v252, 25
	v_readlane_b32 s58, v252, 26
	v_readlane_b32 s59, v252, 27
	v_readlane_b32 s62, v252, 30
	v_readlane_b32 s63, v252, 31
	global_store_dwordx2 v[154:155], v[152:153], off offset:32

.LBB0_869:
	s_andn2_b64 vcc, exec, s[2:3]
	s_cbranch_vccnz .LBB0_871
	v_mul_f32_e32 v147, 0xbfb8aa3b, v58
	v_exp_f32_e32 v152, v147
	v_mul_f32_e32 v147, 0xbfb8aa3b, v59
	v_exp_f32_e32 v153, v147
	s_mov_b32 s4, 0x3db504f3
	v_pk_add_f32 v[152:153], v[152:153], 1.0 op_sel_hi:[1,0]
	s_nop 0
	v_rcp_f32_e32 v154, v153
	s_nop 0
	v_mul_f32_e32 v147, v59, v154
	v_mov_b32_e32 v153, v147
	v_rcp_f32_e32 v154, v152
	s_nop 0
	v_mul_f32_e32 v147, v58, v154
	v_mov_b32_e32 v152, v147
	v_mul_f32_e32 v147, 0xbfb8aa3b, v60
	v_exp_f32_e32 v154, v147
	v_mul_f32_e32 v147, 0xbfb8aa3b, v61
	v_exp_f32_e32 v155, v147
	v_pk_mul_f32 v[152:153], v[152:153], s[4:5] op_sel_hi:[1,0]
	v_pk_add_f32 v[154:155], v[154:155], 1.0 op_sel_hi:[1,0]
	s_nop 0
	v_rcp_f32_e32 v156, v155
	s_nop 0
	v_mul_f32_e32 v147, v61, v156
	v_mov_b32_e32 v155, v147
	v_rcp_f32_e32 v156, v154
	s_nop 0
	v_mul_f32_e32 v147, v60, v156
	v_mov_b32_e32 v154, v147
	v_pk_mul_f32 v[154:155], v[154:155], s[4:5] op_sel_hi:[1,0]
	v_bfe_u32 v157, v153, 16, 1
	v_bfe_u32 v147, v155, 16, 1
	v_bfe_u32 v156, v154, 16, 1
	v_bfe_u32 v158, v152, 16, 1
	v_add3_u32 v152, v152, v158, s0
	v_add3_u32 v157, v153, v157, s0
	v_add3_u32 v153, v154, v156, s0
	v_add3_u32 v147, v155, v147, s0
	v_perm_b32 v153, v147, v153, s19
	v_perm_b32 v152, v157, v152, s19
	v_lshl_add_u64 v[154:155], v[148:149], 0, v[0:1]
	global_store_dwordx2 v[154:155], v[152:153], off offset:32
.LBB0_871:
	s_and_b64 vcc, exec, s[40:41]
	s_mov_b64 s[2:3], -1
	s_cbranch_vccnz .LBB0_881
	s_cmp_lt_i32 s34, 3
	s_cbranch_scc1 .LBB0_878
	s_cmp_eq_u32 s34, 3
	s_cbranch_scc1 .LBB0_875
	v_mul_f32_e32 v147, 0xbfb8aa3b, v54
	v_exp_f32_e32 v152, v147
	v_mul_f32_e32 v147, 0xbfb8aa3b, v55
	v_exp_f32_e32 v153, v147
	v_readlane_b32 s48, v253, 4
	v_readlane_b32 s49, v253, 5
	v_readlane_b32 s50, v253, 6
	v_pk_add_f32 v[152:153], v[152:153], 1.0 op_sel_hi:[1,0]
	v_readlane_b32 s51, v253, 7
	v_rcp_f32_e32 v154, v152
	s_nop 0
	v_mul_f32_e32 v147, v54, v154
	v_rcp_f32_e32 v154, v153
	s_nop 0
	v_mul_f32_e32 v152, v55, v154
	v_mov_b32_e32 v154, v152
	v_mul_f32_e32 v152, 0xbfb8aa3b, v56
	v_mul_f32_e32 v153, 0xbfb8aa3b, v57
	v_exp_f32_e32 v152, v152
	v_exp_f32_e32 v153, v153
	s_nop 0
	v_pk_add_f32 v[152:153], v[152:153], 1.0 op_sel_hi:[1,0]
	s_nop 0
	v_rcp_f32_e32 v156, v152
	s_nop 0
	v_mul_f32_e32 v155, v56, v156
	v_mov_b32_e32 v152, v155
	v_rcp_f32_e32 v156, v153
	s_mov_b64 s[2:3], 0
	v_mul_f32_e32 v155, v57, v156
	v_mov_b32_e32 v153, v155
	v_bfe_u32 v155, v153, 16, 1
	v_bfe_u32 v156, v152, 16, 1
	v_bfe_u32 v157, v154, 16, 1
	v_bfe_u32 v158, v147, 16, 1
	v_add3_u32 v147, v147, v158, s0
	v_add3_u32 v154, v154, v157, s0
	v_add3_u32 v152, v152, v156, s0
	v_add3_u32 v153, v153, v155, s0
	v_perm_b32 v153, v153, v152, s19
	v_perm_b32 v152, v154, v147, s19
	v_lshl_add_u64 v[154:155], s[48:49], 0, v[150:151]
	v_lshl_add_u64 v[154:155], v[154:155], 0, v[0:1]
	global_store_dwordx2 v[154:155], v[152:153], off offset:64

.LBB0_878:
	s_andn2_b64 vcc, exec, s[2:3]
	s_cbranch_vccnz .LBB0_880
	v_mul_f32_e32 v152, 0xbfb8aa3b, v54
	v_exp_f32_e32 v152, v152
	s_waitcnt vmcnt(1)
	v_sub_f32_e32 v147, 1.0, v134
	s_mov_b32 s14, 0x800000
	s_mov_b32 s24, 0x3f317217
	v_add_f32_e32 v152, 1.0, v152
	v_rcp_f32_e32 v154, v152
	s_mov_b32 s15, 0x7f800000
	v_readlane_b32 s48, v252, 16
	v_readlane_b32 s60, v252, 28
	v_mov_b32_e32 v153, v154
	v_mov_b32_e32 v152, v153
	v_fma_f32 v147, v152, v147, v134
	v_mul_f32_e32 v153, 0xbfb8aa3b, v55
	v_cmp_gt_f32_e32 vcc, s14, v147
	v_exp_f32_e32 v153, v153
	v_readlane_b32 s61, v252, 29
	v_cndmask_b32_e64 v152, 0, 32, vcc
	v_ldexp_f32 v147, v147, v152
	v_log_f32_e32 v147, v147
	v_add_f32_e32 v153, 1.0, v153
	v_rcp_f32_e32 v155, v153
	v_mul_f32_e32 v152, 0x3f317217, v147
	v_fma_f32 v152, v147, s24, -v152
	v_fmac_f32_e32 v152, 0x3377d1cf, v147
	v_fmac_f32_e32 v152, 0x3f317217, v147
	v_cmp_lt_f32_e64 s[4:5], |v147|, s15
	v_cndmask_b32_e64 v147, v147, v152, s[4:5]
	v_cndmask_b32_e32 v152, 0, v213, vcc
	v_mov_b32_e32 v154, v155
	v_sub_f32_e32 v147, v147, v152
	v_sub_f32_e32 v152, 1.0, v135
	v_mov_b32_e32 v153, v154
	v_fma_f32 v152, v153, v152, v135
	v_mul_f32_e32 v154, 0xbfb8aa3b, v56
	v_cmp_gt_f32_e32 vcc, s14, v152
	v_exp_f32_e32 v154, v154
	v_readlane_b32 s49, v252, 17
	v_cndmask_b32_e64 v153, 0, 32, vcc
	v_ldexp_f32 v152, v152, v153
	v_log_f32_e32 v152, v152
	v_add_f32_e32 v154, 1.0, v154
	v_rcp_f32_e32 v156, v154
	v_mul_f32_e32 v153, 0x3f317217, v152
	v_fma_f32 v153, v152, s24, -v153
	v_fmac_f32_e32 v153, 0x3377d1cf, v152
	v_fmac_f32_e32 v153, 0x3f317217, v152
	v_cmp_lt_f32_e64 s[4:5], |v152|, s15
	v_cndmask_b32_e64 v152, v152, v153, s[4:5]
	v_cndmask_b32_e32 v153, 0, v213, vcc
	v_mov_b32_e32 v155, v156
	v_sub_f32_e32 v152, v152, v153
	v_sub_f32_e32 v153, 1.0, v136
	v_mov_b32_e32 v154, v155
	v_fma_f32 v153, v154, v153, v136
	v_mul_f32_e32 v155, 0xbfb8aa3b, v57
	v_cmp_gt_f32_e32 vcc, s14, v153
	v_exp_f32_e32 v155, v155
	v_cvt_pk_f16_f32 v152, v147, v152
	v_cndmask_b32_e64 v154, 0, 32, vcc
	v_ldexp_f32 v153, v153, v154
	v_log_f32_e32 v153, v153
	v_add_f32_e32 v155, 1.0, v155
	v_rcp_f32_e32 v157, v155
	v_mul_f32_e32 v154, 0x3f317217, v153
	v_fma_f32 v154, v153, s24, -v154
	v_fmac_f32_e32 v154, 0x3377d1cf, v153
	v_fmac_f32_e32 v154, 0x3f317217, v153
	v_cmp_lt_f32_e64 s[4:5], |v153|, s15
	v_cndmask_b32_e64 v153, v153, v154, s[4:5]
	v_cndmask_b32_e32 v154, 0, v213, vcc
	v_mov_b32_e32 v156, v157
	v_sub_f32_e32 v153, v153, v154
	v_sub_f32_e32 v154, 1.0, v137
	v_mov_b32_e32 v155, v156
	v_fma_f32 v154, v155, v154, v137
	v_cmp_gt_f32_e32 vcc, s14, v154
	s_add_i32 s2, s34, -1
	s_mul_hi_i32 s3, s2, 0x2200000
	v_cndmask_b32_e64 v155, 0, 32, vcc
	v_ldexp_f32 v154, v154, v155
	v_log_f32_e32 v154, v154
	s_mul_i32 s2, s2, 0x2200000
	s_add_u32 s2, s60, s2
	s_addc_u32 s3, s61, s3
	v_mul_f32_e32 v155, 0x3f317217, v154
	v_fma_f32 v155, v154, s24, -v155
	v_fmac_f32_e32 v155, 0x3377d1cf, v154
	v_fmac_f32_e32 v155, 0x3f317217, v154
	v_cmp_lt_f32_e64 s[4:5], |v154|, s15
	v_readlane_b32 s50, v252, 18
	v_readlane_b32 s51, v252, 19
	v_cndmask_b32_e64 v154, v154, v155, s[4:5]
	v_cndmask_b32_e32 v155, 0, v213, vcc
	v_sub_f32_e32 v154, v154, v155
	v_cvt_pk_f16_f32 v153, v153, v154
	v_lshl_add_u64 v[154:155], s[2:3], 0, v[150:151]
	v_lshl_add_u64 v[154:155], v[154:155], 0, v[0:1]
	v_readlane_b32 s52, v252, 20
	v_readlane_b32 s53, v252, 21
	v_readlane_b32 s54, v252, 22
	v_readlane_b32 s55, v252, 23
	v_readlane_b32 s56, v252, 24
	v_readlane_b32 s57, v252, 25
	v_readlane_b32 s58, v252, 26
	v_readlane_b32 s59, v252, 27
	v_readlane_b32 s62, v252, 30
	v_readlane_b32 s63, v252, 31
	global_store_dwordx2 v[154:155], v[152:153], off offset:64

.LBB0_881:
	s_andn2_b64 vcc, exec, s[2:3]
	s_cbranch_vccnz .LBB0_883
	v_mul_f32_e32 v147, 0xbfb8aa3b, v54
	v_exp_f32_e32 v152, v147
	v_mul_f32_e32 v147, 0xbfb8aa3b, v55
	v_exp_f32_e32 v153, v147
	s_mov_b32 s4, 0x3db504f3
	v_pk_add_f32 v[152:153], v[152:153], 1.0 op_sel_hi:[1,0]
	s_nop 0
	v_rcp_f32_e32 v154, v153
	s_nop 0
	v_mul_f32_e32 v147, v55, v154
	v_mov_b32_e32 v153, v147
	v_rcp_f32_e32 v154, v152
	s_nop 0
	v_mul_f32_e32 v147, v54, v154
	v_mov_b32_e32 v152, v147
	v_mul_f32_e32 v147, 0xbfb8aa3b, v56
	v_exp_f32_e32 v154, v147
	v_mul_f32_e32 v147, 0xbfb8aa3b, v57
	v_exp_f32_e32 v155, v147
	v_pk_mul_f32 v[152:153], v[152:153], s[4:5] op_sel_hi:[1,0]
	v_pk_add_f32 v[154:155], v[154:155], 1.0 op_sel_hi:[1,0]
	s_nop 0
	v_rcp_f32_e32 v156, v155
	s_nop 0
	v_mul_f32_e32 v147, v57, v156
	v_mov_b32_e32 v155, v147
	v_rcp_f32_e32 v156, v154
	s_nop 0
	v_mul_f32_e32 v147, v56, v156
	v_mov_b32_e32 v154, v147
	v_pk_mul_f32 v[154:155], v[154:155], s[4:5] op_sel_hi:[1,0]
	v_bfe_u32 v157, v153, 16, 1
	v_bfe_u32 v147, v155, 16, 1
	v_bfe_u32 v156, v154, 16, 1
	v_bfe_u32 v158, v152, 16, 1
	v_add3_u32 v152, v152, v158, s0
	v_add3_u32 v157, v153, v157, s0
	v_add3_u32 v153, v154, v156, s0
	v_add3_u32 v147, v155, v147, s0
	v_perm_b32 v153, v147, v153, s19
	v_perm_b32 v152, v157, v152, s19
	v_lshl_add_u64 v[154:155], v[148:149], 0, v[0:1]
	global_store_dwordx2 v[154:155], v[152:153], off offset:64
.LBB0_883:
	s_and_b64 vcc, exec, s[40:41]
	s_mov_b64 s[2:3], -1
	s_cbranch_vccnz .LBB0_893
	s_cmp_lt_i32 s34, 3
	s_cbranch_scc1 .LBB0_890
	s_cmp_eq_u32 s34, 3
	s_cbranch_scc1 .LBB0_887
	v_mul_f32_e32 v147, 0xbfb8aa3b, v50
	v_exp_f32_e32 v152, v147
	v_mul_f32_e32 v147, 0xbfb8aa3b, v51
	v_exp_f32_e32 v153, v147
	v_readlane_b32 s48, v253, 4
	v_readlane_b32 s49, v253, 5
	v_readlane_b32 s50, v253, 6
	v_pk_add_f32 v[152:153], v[152:153], 1.0 op_sel_hi:[1,0]
	v_readlane_b32 s51, v253, 7
	v_rcp_f32_e32 v154, v152
	s_nop 0
	v_mul_f32_e32 v147, v50, v154
	v_rcp_f32_e32 v154, v153
	s_nop 0
	v_mul_f32_e32 v152, v51, v154
	v_mov_b32_e32 v154, v152
	v_mul_f32_e32 v152, 0xbfb8aa3b, v52
	v_mul_f32_e32 v153, 0xbfb8aa3b, v53
	v_exp_f32_e32 v152, v152
	v_exp_f32_e32 v153, v153
	s_nop 0
	v_pk_add_f32 v[152:153], v[152:153], 1.0 op_sel_hi:[1,0]
	s_nop 0
	v_rcp_f32_e32 v156, v152
	s_nop 0
	v_mul_f32_e32 v155, v52, v156
	v_mov_b32_e32 v152, v155
	v_rcp_f32_e32 v156, v153
	s_mov_b64 s[2:3], 0
	v_mul_f32_e32 v155, v53, v156
	v_mov_b32_e32 v153, v155
	v_bfe_u32 v155, v153, 16, 1
	v_bfe_u32 v156, v152, 16, 1
	v_bfe_u32 v157, v154, 16, 1
	v_bfe_u32 v158, v147, 16, 1
	v_add3_u32 v147, v147, v158, s0
	v_add3_u32 v154, v154, v157, s0
	v_add3_u32 v152, v152, v156, s0
	v_add3_u32 v153, v153, v155, s0
	v_perm_b32 v153, v153, v152, s19
	v_perm_b32 v152, v154, v147, s19
	v_lshl_add_u64 v[154:155], s[48:49], 0, v[150:151]
	v_lshl_add_u64 v[154:155], v[154:155], 0, v[0:1]
	global_store_dwordx2 v[154:155], v[152:153], off offset:96

.LBB0_890:
	s_andn2_b64 vcc, exec, s[2:3]
	s_cbranch_vccnz .LBB0_892
	v_mul_f32_e32 v152, 0xbfb8aa3b, v50
	v_exp_f32_e32 v152, v152
	s_waitcnt vmcnt(0)
	v_sub_f32_e32 v147, 1.0, v130
	s_mov_b32 s14, 0x800000
	s_mov_b32 s24, 0x3f317217
	v_add_f32_e32 v152, 1.0, v152
	v_rcp_f32_e32 v154, v152
	s_mov_b32 s15, 0x7f800000
	v_readlane_b32 s48, v252, 16
	v_readlane_b32 s60, v252, 28
	v_mov_b32_e32 v153, v154
	v_mov_b32_e32 v152, v153
	v_fma_f32 v147, v152, v147, v130
	v_mul_f32_e32 v153, 0xbfb8aa3b, v51
	v_cmp_gt_f32_e32 vcc, s14, v147
	v_exp_f32_e32 v153, v153
	v_readlane_b32 s61, v252, 29
	v_cndmask_b32_e64 v152, 0, 32, vcc
	v_ldexp_f32 v147, v147, v152
	v_log_f32_e32 v147, v147
	v_add_f32_e32 v153, 1.0, v153
	v_rcp_f32_e32 v155, v153
	v_mul_f32_e32 v152, 0x3f317217, v147
	v_fma_f32 v152, v147, s24, -v152
	v_fmac_f32_e32 v152, 0x3377d1cf, v147
	v_fmac_f32_e32 v152, 0x3f317217, v147
	v_cmp_lt_f32_e64 s[4:5], |v147|, s15
	v_cndmask_b32_e64 v147, v147, v152, s[4:5]
	v_cndmask_b32_e32 v152, 0, v213, vcc
	v_mov_b32_e32 v154, v155
	v_sub_f32_e32 v147, v147, v152
	v_sub_f32_e32 v152, 1.0, v131
	v_mov_b32_e32 v153, v154
	v_fma_f32 v152, v153, v152, v131
	v_mul_f32_e32 v154, 0xbfb8aa3b, v52
	v_cmp_gt_f32_e32 vcc, s14, v152
	v_exp_f32_e32 v154, v154
	v_readlane_b32 s49, v252, 17
	v_cndmask_b32_e64 v153, 0, 32, vcc
	v_ldexp_f32 v152, v152, v153
	v_log_f32_e32 v152, v152
	v_add_f32_e32 v154, 1.0, v154
	v_rcp_f32_e32 v156, v154
	v_mul_f32_e32 v153, 0x3f317217, v152
	v_fma_f32 v153, v152, s24, -v153
	v_fmac_f32_e32 v153, 0x3377d1cf, v152
	v_fmac_f32_e32 v153, 0x3f317217, v152
	v_cmp_lt_f32_e64 s[4:5], |v152|, s15
	v_cndmask_b32_e64 v152, v152, v153, s[4:5]
	v_cndmask_b32_e32 v153, 0, v213, vcc
	v_mov_b32_e32 v155, v156
	v_sub_f32_e32 v152, v152, v153
	v_sub_f32_e32 v153, 1.0, v132
	v_mov_b32_e32 v154, v155
	v_fma_f32 v153, v154, v153, v132
	v_mul_f32_e32 v155, 0xbfb8aa3b, v53
	v_cmp_gt_f32_e32 vcc, s14, v153
	v_exp_f32_e32 v155, v155
	v_cvt_pk_f16_f32 v152, v147, v152
	v_cndmask_b32_e64 v154, 0, 32, vcc
	v_ldexp_f32 v153, v153, v154
	v_log_f32_e32 v153, v153
	v_add_f32_e32 v155, 1.0, v155
	v_rcp_f32_e32 v157, v155
	v_mul_f32_e32 v154, 0x3f317217, v153
	v_fma_f32 v154, v153, s24, -v154
	v_fmac_f32_e32 v154, 0x3377d1cf, v153
	v_fmac_f32_e32 v154, 0x3f317217, v153
	v_cmp_lt_f32_e64 s[4:5], |v153|, s15
	v_cndmask_b32_e64 v153, v153, v154, s[4:5]
	v_cndmask_b32_e32 v154, 0, v213, vcc
	v_mov_b32_e32 v156, v157
	v_sub_f32_e32 v153, v153, v154
	v_sub_f32_e32 v154, 1.0, v133
	v_mov_b32_e32 v155, v156
	v_fma_f32 v154, v155, v154, v133
	v_cmp_gt_f32_e32 vcc, s14, v154
	s_add_i32 s2, s34, -1
	s_mul_hi_i32 s3, s2, 0x2200000
	v_cndmask_b32_e64 v155, 0, 32, vcc
	v_ldexp_f32 v154, v154, v155
	v_log_f32_e32 v154, v154
	s_mul_i32 s2, s2, 0x2200000
	s_add_u32 s2, s60, s2
	s_addc_u32 s3, s61, s3
	v_mul_f32_e32 v155, 0x3f317217, v154
	v_fma_f32 v155, v154, s24, -v155
	v_fmac_f32_e32 v155, 0x3377d1cf, v154
	v_fmac_f32_e32 v155, 0x3f317217, v154
	v_cmp_lt_f32_e64 s[4:5], |v154|, s15
	v_lshl_add_u64 v[150:151], s[2:3], 0, v[150:151]
	v_lshl_add_u64 v[150:151], v[150:151], 0, v[0:1]
	v_cndmask_b32_e64 v154, v154, v155, s[4:5]
	v_cndmask_b32_e32 v155, 0, v213, vcc
	v_sub_f32_e32 v154, v154, v155
	v_cvt_pk_f16_f32 v153, v153, v154
	v_readlane_b32 s50, v252, 18
	v_readlane_b32 s51, v252, 19
	v_readlane_b32 s52, v252, 20
	v_readlane_b32 s53, v252, 21
	v_readlane_b32 s54, v252, 22
	v_readlane_b32 s55, v252, 23
	v_readlane_b32 s56, v252, 24
	v_readlane_b32 s57, v252, 25
	v_readlane_b32 s58, v252, 26
	v_readlane_b32 s59, v252, 27
	v_readlane_b32 s62, v252, 30
	v_readlane_b32 s63, v252, 31
	global_store_dwordx2 v[150:151], v[152:153], off offset:96

.LBB0_893:
	s_andn2_b64 vcc, exec, s[2:3]
	s_cbranch_vccnz .LBB0_895
	v_mul_f32_e32 v147, 0xbfb8aa3b, v50
	v_exp_f32_e32 v150, v147
	v_mul_f32_e32 v147, 0xbfb8aa3b, v51
	v_exp_f32_e32 v151, v147
	s_mov_b32 s4, 0x3db504f3
	v_lshl_add_u64 v[148:149], v[148:149], 0, v[0:1]
	v_pk_add_f32 v[150:151], v[150:151], 1.0 op_sel_hi:[1,0]
	s_nop 0
	v_rcp_f32_e32 v152, v151
	s_nop 0
	v_mul_f32_e32 v147, v51, v152
	v_mov_b32_e32 v151, v147
	v_rcp_f32_e32 v152, v150
	s_nop 0
	v_mul_f32_e32 v147, v50, v152
	v_mov_b32_e32 v150, v147
	v_mul_f32_e32 v147, 0xbfb8aa3b, v52
	v_exp_f32_e32 v152, v147
	v_mul_f32_e32 v147, 0xbfb8aa3b, v53
	v_exp_f32_e32 v153, v147
	v_pk_mul_f32 v[150:151], v[150:151], s[4:5] op_sel_hi:[1,0]
	v_pk_add_f32 v[152:153], v[152:153], 1.0 op_sel_hi:[1,0]
	s_nop 0
	v_rcp_f32_e32 v154, v153
	s_nop 0
	v_mul_f32_e32 v147, v53, v154
	v_mov_b32_e32 v153, v147
	v_rcp_f32_e32 v154, v152
	s_nop 0
	v_mul_f32_e32 v147, v52, v154
	v_mov_b32_e32 v152, v147
	v_pk_mul_f32 v[152:153], v[152:153], s[4:5] op_sel_hi:[1,0]
	v_bfe_u32 v155, v151, 16, 1
	v_bfe_u32 v147, v153, 16, 1
	v_bfe_u32 v154, v152, 16, 1
	v_bfe_u32 v156, v150, 16, 1
	v_add3_u32 v150, v150, v156, s0
	v_add3_u32 v155, v151, v155, s0
	v_add3_u32 v151, v152, v154, s0
	v_add3_u32 v147, v153, v147, s0
	v_perm_b32 v151, v147, v151, s19
	v_perm_b32 v150, v155, v150, s19
	global_store_dwordx2 v[148:149], v[150:151], off offset:96
.LBB0_895:
	v_or_b32_e32 v148, 0x50, v146
	v_ashrrev_i32_e32 v149, 31, v148
	s_and_b64 vcc, exec, s[40:41]
	s_mov_b64 s[2:3], -1
	s_cbranch_vccnz .LBB0_905
	s_cmp_lt_i32 s34, 3
	s_cbranch_scc1 .LBB0_902
	s_cmp_eq_u32 s34, 3
	s_cbranch_scc1 .LBB0_899
	v_mul_f32_e32 v147, 0xbfb8aa3b, v46
	v_exp_f32_e32 v150, v147
	v_mul_f32_e32 v147, 0xbfb8aa3b, v47
	v_exp_f32_e32 v151, v147
	v_readlane_b32 s48, v253, 4
	v_readlane_b32 s49, v253, 5
	v_readlane_b32 s50, v253, 6
	v_pk_add_f32 v[150:151], v[150:151], 1.0 op_sel_hi:[1,0]
	v_readlane_b32 s51, v253, 7
	v_rcp_f32_e32 v152, v150
	s_nop 0
	v_mul_f32_e32 v147, v46, v152
	v_rcp_f32_e32 v152, v151
	s_nop 0
	v_mul_f32_e32 v150, v47, v152
	v_mov_b32_e32 v152, v150
	v_mul_f32_e32 v150, 0xbfb8aa3b, v48
	v_mul_f32_e32 v151, 0xbfb8aa3b, v49
	v_exp_f32_e32 v150, v150
	v_exp_f32_e32 v151, v151
	s_nop 0
	v_pk_add_f32 v[150:151], v[150:151], 1.0 op_sel_hi:[1,0]
	s_nop 0
	v_rcp_f32_e32 v154, v150
	s_nop 0
	v_mul_f32_e32 v153, v48, v154
	v_mov_b32_e32 v150, v153
	v_rcp_f32_e32 v154, v151
	s_mov_b64 s[2:3], 0
	v_mul_f32_e32 v153, v49, v154
	v_mov_b32_e32 v151, v153
	v_bfe_u32 v153, v151, 16, 1
	v_bfe_u32 v154, v150, 16, 1
	v_bfe_u32 v155, v152, 16, 1
	v_bfe_u32 v156, v147, 16, 1
	v_add3_u32 v147, v147, v156, s0
	v_add3_u32 v152, v152, v155, s0
	v_add3_u32 v150, v150, v154, s0
	v_add3_u32 v151, v151, v153, s0
	v_perm_b32 v151, v151, v150, s19
	v_perm_b32 v150, v152, v147, s19
	v_lshlrev_b64 v[152:153], 11, v[148:149]
	v_lshl_add_u64 v[152:153], s[48:49], 0, v[152:153]
	v_lshl_add_u64 v[152:153], v[152:153], 0, v[0:1]
	global_store_dwordx2 v[152:153], v[150:151], off

.LBB0_902:
	s_andn2_b64 vcc, exec, s[2:3]
	s_cbranch_vccnz .LBB0_904
	v_mul_f32_e32 v150, 0xbfb8aa3b, v46
	v_exp_f32_e32 v150, v150
	s_waitcnt vmcnt(3)
	v_sub_f32_e32 v147, 1.0, v142
	s_mov_b32 s14, 0x800000
	s_mov_b32 s24, 0x3f317217
	v_add_f32_e32 v150, 1.0, v150
	v_rcp_f32_e32 v152, v150
	s_mov_b32 s15, 0x7f800000
	v_readlane_b32 s48, v252, 16
	v_readlane_b32 s60, v252, 28
	v_mov_b32_e32 v151, v152
	v_mov_b32_e32 v150, v151
	v_fma_f32 v147, v150, v147, v142
	v_mul_f32_e32 v151, 0xbfb8aa3b, v47
	v_cmp_gt_f32_e32 vcc, s14, v147
	v_exp_f32_e32 v151, v151
	v_readlane_b32 s61, v252, 29
	v_cndmask_b32_e64 v150, 0, 32, vcc
	v_ldexp_f32 v147, v147, v150
	v_log_f32_e32 v147, v147
	v_add_f32_e32 v151, 1.0, v151
	v_rcp_f32_e32 v153, v151
	v_mul_f32_e32 v150, 0x3f317217, v147
	v_fma_f32 v150, v147, s24, -v150
	v_fmac_f32_e32 v150, 0x3377d1cf, v147
	v_fmac_f32_e32 v150, 0x3f317217, v147
	v_cmp_lt_f32_e64 s[4:5], |v147|, s15
	v_cndmask_b32_e64 v147, v147, v150, s[4:5]
	v_cndmask_b32_e32 v150, 0, v213, vcc
	v_mov_b32_e32 v152, v153
	v_sub_f32_e32 v147, v147, v150
	v_sub_f32_e32 v150, 1.0, v143
	v_mov_b32_e32 v151, v152
	v_fma_f32 v150, v151, v150, v143
	v_mul_f32_e32 v152, 0xbfb8aa3b, v48
	v_cmp_gt_f32_e32 vcc, s14, v150
	v_exp_f32_e32 v152, v152
	v_readlane_b32 s49, v252, 17
	v_cndmask_b32_e64 v151, 0, 32, vcc
	v_ldexp_f32 v150, v150, v151
	v_log_f32_e32 v150, v150
	v_add_f32_e32 v152, 1.0, v152
	v_rcp_f32_e32 v154, v152
	v_mul_f32_e32 v151, 0x3f317217, v150
	v_fma_f32 v151, v150, s24, -v151
	v_fmac_f32_e32 v151, 0x3377d1cf, v150
	v_fmac_f32_e32 v151, 0x3f317217, v150
	v_cmp_lt_f32_e64 s[4:5], |v150|, s15
	v_cndmask_b32_e64 v150, v150, v151, s[4:5]
	v_cndmask_b32_e32 v151, 0, v213, vcc
	v_mov_b32_e32 v153, v154
	v_sub_f32_e32 v150, v150, v151
	v_sub_f32_e32 v151, 1.0, v144
	v_mov_b32_e32 v152, v153
	v_fma_f32 v151, v152, v151, v144
	v_mul_f32_e32 v153, 0xbfb8aa3b, v49
	v_cmp_gt_f32_e32 vcc, s14, v151
	v_exp_f32_e32 v153, v153
	v_cvt_pk_f16_f32 v150, v147, v150
	v_cndmask_b32_e64 v152, 0, 32, vcc
	v_ldexp_f32 v151, v151, v152
	v_log_f32_e32 v151, v151
	v_add_f32_e32 v153, 1.0, v153
	v_rcp_f32_e32 v155, v153
	v_mul_f32_e32 v152, 0x3f317217, v151
	v_fma_f32 v152, v151, s24, -v152
	v_fmac_f32_e32 v152, 0x3377d1cf, v151
	v_fmac_f32_e32 v152, 0x3f317217, v151
	v_cmp_lt_f32_e64 s[4:5], |v151|, s15
	v_cndmask_b32_e64 v151, v151, v152, s[4:5]
	v_cndmask_b32_e32 v152, 0, v213, vcc
	v_mov_b32_e32 v154, v155
	v_sub_f32_e32 v151, v151, v152
	v_sub_f32_e32 v152, 1.0, v145
	v_mov_b32_e32 v153, v154
	v_fma_f32 v152, v153, v152, v145
	v_cmp_gt_f32_e32 vcc, s14, v152
	s_add_i32 s2, s34, -1
	s_mul_hi_i32 s3, s2, 0x2200000
	v_cndmask_b32_e64 v153, 0, 32, vcc
	v_ldexp_f32 v152, v152, v153
	v_log_f32_e32 v152, v152
	s_mul_i32 s2, s2, 0x2200000
	s_add_u32 s2, s60, s2
	s_addc_u32 s3, s61, s3
	v_mul_f32_e32 v153, 0x3f317217, v152
	v_fma_f32 v153, v152, s24, -v153
	v_fmac_f32_e32 v153, 0x3377d1cf, v152
	v_fmac_f32_e32 v153, 0x3f317217, v152
	v_cmp_lt_f32_e64 s[4:5], |v152|, s15
	v_readlane_b32 s50, v252, 18
	v_readlane_b32 s51, v252, 19
	v_cndmask_b32_e64 v152, v152, v153, s[4:5]
	v_cndmask_b32_e32 v153, 0, v213, vcc
	v_sub_f32_e32 v152, v152, v153
	v_cvt_pk_f16_f32 v151, v151, v152
	v_lshlrev_b64 v[152:153], 11, v[148:149]
	v_lshl_add_u64 v[152:153], s[2:3], 0, v[152:153]
	v_lshl_add_u64 v[152:153], v[152:153], 0, v[0:1]
	v_readlane_b32 s52, v252, 20
	v_readlane_b32 s53, v252, 21
	v_readlane_b32 s54, v252, 22
	v_readlane_b32 s55, v252, 23
	v_readlane_b32 s56, v252, 24
	v_readlane_b32 s57, v252, 25
	v_readlane_b32 s58, v252, 26
	v_readlane_b32 s59, v252, 27
	v_readlane_b32 s62, v252, 30
	v_readlane_b32 s63, v252, 31
	global_store_dwordx2 v[152:153], v[150:151], off

.LBB0_905:
	v_readlane_b32 s48, v252, 16
	v_lshlrev_b64 v[150:151], 11, v[148:149]
	v_readlane_b32 s58, v252, 26
	v_readlane_b32 s59, v252, 27
	s_andn2_b64 vcc, exec, s[2:3]
	v_readlane_b32 s49, v252, 17
	v_lshl_add_u64 v[148:149], s[58:59], 0, v[150:151]
	v_readlane_b32 s50, v252, 18
	v_readlane_b32 s51, v252, 19
	v_readlane_b32 s52, v252, 20
	v_readlane_b32 s53, v252, 21
	v_readlane_b32 s54, v252, 22
	v_readlane_b32 s55, v252, 23
	v_readlane_b32 s56, v252, 24
	v_readlane_b32 s57, v252, 25
	v_readlane_b32 s60, v252, 28
	v_readlane_b32 s61, v252, 29
	v_readlane_b32 s62, v252, 30
	v_readlane_b32 s63, v252, 31
	s_cbranch_vccnz .LBB0_907
	v_mul_f32_e32 v147, 0xbfb8aa3b, v46
	v_exp_f32_e32 v152, v147
	v_mul_f32_e32 v147, 0xbfb8aa3b, v47
	v_exp_f32_e32 v153, v147
	s_mov_b32 s4, 0x3db504f3
	v_pk_add_f32 v[152:153], v[152:153], 1.0 op_sel_hi:[1,0]
	s_nop 0
	v_rcp_f32_e32 v154, v153
	s_nop 0
	v_mul_f32_e32 v147, v47, v154
	v_mov_b32_e32 v153, v147
	v_rcp_f32_e32 v154, v152
	s_nop 0
	v_mul_f32_e32 v147, v46, v154
	v_mov_b32_e32 v152, v147
	v_mul_f32_e32 v147, 0xbfb8aa3b, v48
	v_exp_f32_e32 v154, v147
	v_mul_f32_e32 v147, 0xbfb8aa3b, v49
	v_exp_f32_e32 v155, v147
	v_pk_mul_f32 v[152:153], v[152:153], s[4:5] op_sel_hi:[1,0]
	v_pk_add_f32 v[154:155], v[154:155], 1.0 op_sel_hi:[1,0]
	s_nop 0
	v_rcp_f32_e32 v156, v155
	s_nop 0
	v_mul_f32_e32 v147, v49, v156
	v_mov_b32_e32 v155, v147
	v_rcp_f32_e32 v156, v154
	s_nop 0
	v_mul_f32_e32 v147, v48, v156
	v_mov_b32_e32 v154, v147
	v_pk_mul_f32 v[154:155], v[154:155], s[4:5] op_sel_hi:[1,0]
	v_bfe_u32 v157, v153, 16, 1
	v_bfe_u32 v147, v155, 16, 1
	v_bfe_u32 v156, v154, 16, 1
	v_bfe_u32 v158, v152, 16, 1
	v_add3_u32 v152, v152, v158, s0
	v_add3_u32 v157, v153, v157, s0
	v_add3_u32 v153, v154, v156, s0
	v_add3_u32 v147, v155, v147, s0
	v_perm_b32 v153, v147, v153, s19
	v_perm_b32 v152, v157, v152, s19
	v_lshl_add_u64 v[154:155], v[148:149], 0, v[0:1]
	global_store_dwordx2 v[154:155], v[152:153], off
.LBB0_907:
	s_and_b64 vcc, exec, s[40:41]
	s_mov_b64 s[2:3], -1
	s_cbranch_vccnz .LBB0_917
	s_cmp_lt_i32 s34, 3
	s_cbranch_scc1 .LBB0_914
	s_cmp_eq_u32 s34, 3
	s_cbranch_scc1 .LBB0_911
	v_mul_f32_e32 v147, 0xbfb8aa3b, v42
	v_exp_f32_e32 v152, v147
	v_mul_f32_e32 v147, 0xbfb8aa3b, v43
	v_exp_f32_e32 v153, v147
	v_readlane_b32 s48, v253, 4
	v_readlane_b32 s49, v253, 5
	v_readlane_b32 s50, v253, 6
	v_pk_add_f32 v[152:153], v[152:153], 1.0 op_sel_hi:[1,0]
	v_readlane_b32 s51, v253, 7
	v_rcp_f32_e32 v154, v152
	s_nop 0
	v_mul_f32_e32 v147, v42, v154
	v_rcp_f32_e32 v154, v153
	s_nop 0
	v_mul_f32_e32 v152, v43, v154
	v_mov_b32_e32 v154, v152
	v_mul_f32_e32 v152, 0xbfb8aa3b, v44
	v_mul_f32_e32 v153, 0xbfb8aa3b, v45
	v_exp_f32_e32 v152, v152
	v_exp_f32_e32 v153, v153
	s_nop 0
	v_pk_add_f32 v[152:153], v[152:153], 1.0 op_sel_hi:[1,0]
	s_nop 0
	v_rcp_f32_e32 v156, v152
	s_nop 0
	v_mul_f32_e32 v155, v44, v156
	v_mov_b32_e32 v152, v155
	v_rcp_f32_e32 v156, v153
	s_mov_b64 s[2:3], 0
	v_mul_f32_e32 v155, v45, v156
	v_mov_b32_e32 v153, v155
	v_bfe_u32 v155, v153, 16, 1
	v_bfe_u32 v156, v152, 16, 1
	v_bfe_u32 v157, v154, 16, 1
	v_bfe_u32 v158, v147, 16, 1
	v_add3_u32 v147, v147, v158, s0
	v_add3_u32 v154, v154, v157, s0
	v_add3_u32 v152, v152, v156, s0
	v_add3_u32 v153, v153, v155, s0
	v_perm_b32 v153, v153, v152, s19
	v_perm_b32 v152, v154, v147, s19
	v_lshl_add_u64 v[154:155], s[48:49], 0, v[150:151]
	v_lshl_add_u64 v[154:155], v[154:155], 0, v[0:1]
	global_store_dwordx2 v[154:155], v[152:153], off offset:32

.LBB0_914:
	s_andn2_b64 vcc, exec, s[2:3]
	s_cbranch_vccnz .LBB0_916
	v_mul_f32_e32 v152, 0xbfb8aa3b, v42
	v_exp_f32_e32 v152, v152
	s_waitcnt vmcnt(2)
	v_sub_f32_e32 v147, 1.0, v138
	s_mov_b32 s14, 0x800000
	s_mov_b32 s24, 0x3f317217
	v_add_f32_e32 v152, 1.0, v152
	v_rcp_f32_e32 v154, v152
	s_mov_b32 s15, 0x7f800000
	v_readlane_b32 s48, v252, 16
	v_readlane_b32 s60, v252, 28
	v_mov_b32_e32 v153, v154
	v_mov_b32_e32 v152, v153
	v_fma_f32 v147, v152, v147, v138
	v_mul_f32_e32 v153, 0xbfb8aa3b, v43
	v_cmp_gt_f32_e32 vcc, s14, v147
	v_exp_f32_e32 v153, v153
	v_readlane_b32 s61, v252, 29
	v_cndmask_b32_e64 v152, 0, 32, vcc
	v_ldexp_f32 v147, v147, v152
	v_log_f32_e32 v147, v147
	v_add_f32_e32 v153, 1.0, v153
	v_rcp_f32_e32 v155, v153
	v_mul_f32_e32 v152, 0x3f317217, v147
	v_fma_f32 v152, v147, s24, -v152
	v_fmac_f32_e32 v152, 0x3377d1cf, v147
	v_fmac_f32_e32 v152, 0x3f317217, v147
	v_cmp_lt_f32_e64 s[4:5], |v147|, s15
	v_cndmask_b32_e64 v147, v147, v152, s[4:5]
	v_cndmask_b32_e32 v152, 0, v213, vcc
	v_mov_b32_e32 v154, v155
	v_sub_f32_e32 v147, v147, v152
	v_sub_f32_e32 v152, 1.0, v139
	v_mov_b32_e32 v153, v154
	v_fma_f32 v152, v153, v152, v139
	v_mul_f32_e32 v154, 0xbfb8aa3b, v44
	v_cmp_gt_f32_e32 vcc, s14, v152
	v_exp_f32_e32 v154, v154
	v_readlane_b32 s49, v252, 17
	v_cndmask_b32_e64 v153, 0, 32, vcc
	v_ldexp_f32 v152, v152, v153
	v_log_f32_e32 v152, v152
	v_add_f32_e32 v154, 1.0, v154
	v_rcp_f32_e32 v156, v154
	v_mul_f32_e32 v153, 0x3f317217, v152
	v_fma_f32 v153, v152, s24, -v153
	v_fmac_f32_e32 v153, 0x3377d1cf, v152
	v_fmac_f32_e32 v153, 0x3f317217, v152
	v_cmp_lt_f32_e64 s[4:5], |v152|, s15
	v_cndmask_b32_e64 v152, v152, v153, s[4:5]
	v_cndmask_b32_e32 v153, 0, v213, vcc
	v_mov_b32_e32 v155, v156
	v_sub_f32_e32 v152, v152, v153
	v_sub_f32_e32 v153, 1.0, v140
	v_mov_b32_e32 v154, v155
	v_fma_f32 v153, v154, v153, v140
	v_mul_f32_e32 v155, 0xbfb8aa3b, v45
	v_cmp_gt_f32_e32 vcc, s14, v153
	v_exp_f32_e32 v155, v155
	v_cvt_pk_f16_f32 v152, v147, v152
	v_cndmask_b32_e64 v154, 0, 32, vcc
	v_ldexp_f32 v153, v153, v154
	v_log_f32_e32 v153, v153
	v_add_f32_e32 v155, 1.0, v155
	v_rcp_f32_e32 v157, v155
	v_mul_f32_e32 v154, 0x3f317217, v153
	v_fma_f32 v154, v153, s24, -v154
	v_fmac_f32_e32 v154, 0x3377d1cf, v153
	v_fmac_f32_e32 v154, 0x3f317217, v153
	v_cmp_lt_f32_e64 s[4:5], |v153|, s15
	v_cndmask_b32_e64 v153, v153, v154, s[4:5]
	v_cndmask_b32_e32 v154, 0, v213, vcc
	v_mov_b32_e32 v156, v157
	v_sub_f32_e32 v153, v153, v154
	v_sub_f32_e32 v154, 1.0, v141
	v_mov_b32_e32 v155, v156
	v_fma_f32 v154, v155, v154, v141
	v_cmp_gt_f32_e32 vcc, s14, v154
	s_add_i32 s2, s34, -1
	s_mul_hi_i32 s3, s2, 0x2200000
	v_cndmask_b32_e64 v155, 0, 32, vcc
	v_ldexp_f32 v154, v154, v155
	v_log_f32_e32 v154, v154
	s_mul_i32 s2, s2, 0x2200000
	s_add_u32 s2, s60, s2
	s_addc_u32 s3, s61, s3
	v_mul_f32_e32 v155, 0x3f317217, v154
	v_fma_f32 v155, v154, s24, -v155
	v_fmac_f32_e32 v155, 0x3377d1cf, v154
	v_fmac_f32_e32 v155, 0x3f317217, v154
	v_cmp_lt_f32_e64 s[4:5], |v154|, s15
	v_readlane_b32 s50, v252, 18
	v_readlane_b32 s51, v252, 19
	v_cndmask_b32_e64 v154, v154, v155, s[4:5]
	v_cndmask_b32_e32 v155, 0, v213, vcc
	v_sub_f32_e32 v154, v154, v155
	v_cvt_pk_f16_f32 v153, v153, v154
	v_lshl_add_u64 v[154:155], s[2:3], 0, v[150:151]
	v_lshl_add_u64 v[154:155], v[154:155], 0, v[0:1]
	v_readlane_b32 s52, v252, 20
	v_readlane_b32 s53, v252, 21
	v_readlane_b32 s54, v252, 22
	v_readlane_b32 s55, v252, 23
	v_readlane_b32 s56, v252, 24
	v_readlane_b32 s57, v252, 25
	v_readlane_b32 s58, v252, 26
	v_readlane_b32 s59, v252, 27
	v_readlane_b32 s62, v252, 30
	v_readlane_b32 s63, v252, 31
	global_store_dwordx2 v[154:155], v[152:153], off offset:32

.LBB0_917:
	s_andn2_b64 vcc, exec, s[2:3]
	s_cbranch_vccnz .LBB0_919
	v_mul_f32_e32 v147, 0xbfb8aa3b, v42
	v_exp_f32_e32 v152, v147
	v_mul_f32_e32 v147, 0xbfb8aa3b, v43
	v_exp_f32_e32 v153, v147
	s_mov_b32 s4, 0x3db504f3
	v_pk_add_f32 v[152:153], v[152:153], 1.0 op_sel_hi:[1,0]
	s_nop 0
	v_rcp_f32_e32 v154, v153
	s_nop 0
	v_mul_f32_e32 v147, v43, v154
	v_mov_b32_e32 v153, v147
	v_rcp_f32_e32 v154, v152
	s_nop 0
	v_mul_f32_e32 v147, v42, v154
	v_mov_b32_e32 v152, v147
	v_mul_f32_e32 v147, 0xbfb8aa3b, v44
	v_exp_f32_e32 v154, v147
	v_mul_f32_e32 v147, 0xbfb8aa3b, v45
	v_exp_f32_e32 v155, v147
	v_pk_mul_f32 v[152:153], v[152:153], s[4:5] op_sel_hi:[1,0]
	v_pk_add_f32 v[154:155], v[154:155], 1.0 op_sel_hi:[1,0]
	s_nop 0
	v_rcp_f32_e32 v156, v155
	s_nop 0
	v_mul_f32_e32 v147, v45, v156
	v_mov_b32_e32 v155, v147
	v_rcp_f32_e32 v156, v154
	s_nop 0
	v_mul_f32_e32 v147, v44, v156
	v_mov_b32_e32 v154, v147
	v_pk_mul_f32 v[154:155], v[154:155], s[4:5] op_sel_hi:[1,0]
	v_bfe_u32 v157, v153, 16, 1
	v_bfe_u32 v147, v155, 16, 1
	v_bfe_u32 v156, v154, 16, 1
	v_bfe_u32 v158, v152, 16, 1
	v_add3_u32 v152, v152, v158, s0
	v_add3_u32 v157, v153, v157, s0
	v_add3_u32 v153, v154, v156, s0
	v_add3_u32 v147, v155, v147, s0
	v_perm_b32 v153, v147, v153, s19
	v_perm_b32 v152, v157, v152, s19
	v_lshl_add_u64 v[154:155], v[148:149], 0, v[0:1]
	global_store_dwordx2 v[154:155], v[152:153], off offset:32
.LBB0_919:
	s_and_b64 vcc, exec, s[40:41]
	s_mov_b64 s[2:3], -1
	s_cbranch_vccnz .LBB0_929
	s_cmp_lt_i32 s34, 3
	s_cbranch_scc1 .LBB0_926
	s_cmp_eq_u32 s34, 3
	s_cbranch_scc1 .LBB0_923
	v_mul_f32_e32 v147, 0xbfb8aa3b, v34
	v_exp_f32_e32 v152, v147
	v_mul_f32_e32 v147, 0xbfb8aa3b, v35
	v_exp_f32_e32 v153, v147
	v_readlane_b32 s48, v253, 4
	v_readlane_b32 s49, v253, 5
	v_readlane_b32 s50, v253, 6
	v_pk_add_f32 v[152:153], v[152:153], 1.0 op_sel_hi:[1,0]
	v_readlane_b32 s51, v253, 7
	v_rcp_f32_e32 v154, v152
	s_nop 0
	v_mul_f32_e32 v147, v34, v154
	v_rcp_f32_e32 v154, v153
	s_nop 0
	v_mul_f32_e32 v152, v35, v154
	v_mov_b32_e32 v154, v152
	v_mul_f32_e32 v152, 0xbfb8aa3b, v36
	v_mul_f32_e32 v153, 0xbfb8aa3b, v37
	v_exp_f32_e32 v152, v152
	v_exp_f32_e32 v153, v153
	s_nop 0
	v_pk_add_f32 v[152:153], v[152:153], 1.0 op_sel_hi:[1,0]
	s_nop 0
	v_rcp_f32_e32 v156, v152
	s_nop 0
	v_mul_f32_e32 v155, v36, v156
	v_mov_b32_e32 v152, v155
	v_rcp_f32_e32 v156, v153
	s_mov_b64 s[2:3], 0
	v_mul_f32_e32 v155, v37, v156
	v_mov_b32_e32 v153, v155
	v_bfe_u32 v155, v153, 16, 1
	v_bfe_u32 v156, v152, 16, 1
	v_bfe_u32 v157, v154, 16, 1
	v_bfe_u32 v158, v147, 16, 1
	v_add3_u32 v147, v147, v158, s0
	v_add3_u32 v154, v154, v157, s0
	v_add3_u32 v152, v152, v156, s0
	v_add3_u32 v153, v153, v155, s0
	v_perm_b32 v153, v153, v152, s19
	v_perm_b32 v152, v154, v147, s19
	v_lshl_add_u64 v[154:155], s[48:49], 0, v[150:151]
	v_lshl_add_u64 v[154:155], v[154:155], 0, v[0:1]
	global_store_dwordx2 v[154:155], v[152:153], off offset:64

.LBB0_926:
	s_andn2_b64 vcc, exec, s[2:3]
	s_cbranch_vccnz .LBB0_928
	v_mul_f32_e32 v152, 0xbfb8aa3b, v34
	v_exp_f32_e32 v152, v152
	s_waitcnt vmcnt(1)
	v_sub_f32_e32 v147, 1.0, v134
	s_mov_b32 s14, 0x800000
	s_mov_b32 s24, 0x3f317217
	v_add_f32_e32 v152, 1.0, v152
	v_rcp_f32_e32 v154, v152
	s_mov_b32 s15, 0x7f800000
	v_readlane_b32 s48, v252, 16
	v_readlane_b32 s60, v252, 28
	v_mov_b32_e32 v153, v154
	v_mov_b32_e32 v152, v153
	v_fma_f32 v147, v152, v147, v134
	v_mul_f32_e32 v153, 0xbfb8aa3b, v35
	v_cmp_gt_f32_e32 vcc, s14, v147
	v_exp_f32_e32 v153, v153
	v_readlane_b32 s61, v252, 29
	v_cndmask_b32_e64 v152, 0, 32, vcc
	v_ldexp_f32 v147, v147, v152
	v_log_f32_e32 v147, v147
	v_add_f32_e32 v153, 1.0, v153
	v_rcp_f32_e32 v155, v153
	v_mul_f32_e32 v152, 0x3f317217, v147
	v_fma_f32 v152, v147, s24, -v152
	v_fmac_f32_e32 v152, 0x3377d1cf, v147
	v_fmac_f32_e32 v152, 0x3f317217, v147
	v_cmp_lt_f32_e64 s[4:5], |v147|, s15
	v_cndmask_b32_e64 v147, v147, v152, s[4:5]
	v_cndmask_b32_e32 v152, 0, v213, vcc
	v_mov_b32_e32 v154, v155
	v_sub_f32_e32 v147, v147, v152
	v_sub_f32_e32 v152, 1.0, v135
	v_mov_b32_e32 v153, v154
	v_fma_f32 v152, v153, v152, v135
	v_mul_f32_e32 v154, 0xbfb8aa3b, v36
	v_cmp_gt_f32_e32 vcc, s14, v152
	v_exp_f32_e32 v154, v154
	v_readlane_b32 s49, v252, 17
	v_cndmask_b32_e64 v153, 0, 32, vcc
	v_ldexp_f32 v152, v152, v153
	v_log_f32_e32 v152, v152
	v_add_f32_e32 v154, 1.0, v154
	v_rcp_f32_e32 v156, v154
	v_mul_f32_e32 v153, 0x3f317217, v152
	v_fma_f32 v153, v152, s24, -v153
	v_fmac_f32_e32 v153, 0x3377d1cf, v152
	v_fmac_f32_e32 v153, 0x3f317217, v152
	v_cmp_lt_f32_e64 s[4:5], |v152|, s15
	v_cndmask_b32_e64 v152, v152, v153, s[4:5]
	v_cndmask_b32_e32 v153, 0, v213, vcc
	v_mov_b32_e32 v155, v156
	v_sub_f32_e32 v152, v152, v153
	v_sub_f32_e32 v153, 1.0, v136
	v_mov_b32_e32 v154, v155
	v_fma_f32 v153, v154, v153, v136
	v_mul_f32_e32 v155, 0xbfb8aa3b, v37
	v_cmp_gt_f32_e32 vcc, s14, v153
	v_exp_f32_e32 v155, v155
	v_cvt_pk_f16_f32 v152, v147, v152
	v_cndmask_b32_e64 v154, 0, 32, vcc
	v_ldexp_f32 v153, v153, v154
	v_log_f32_e32 v153, v153
	v_add_f32_e32 v155, 1.0, v155
	v_rcp_f32_e32 v157, v155
	v_mul_f32_e32 v154, 0x3f317217, v153
	v_fma_f32 v154, v153, s24, -v154
	v_fmac_f32_e32 v154, 0x3377d1cf, v153
	v_fmac_f32_e32 v154, 0x3f317217, v153
	v_cmp_lt_f32_e64 s[4:5], |v153|, s15
	v_cndmask_b32_e64 v153, v153, v154, s[4:5]
	v_cndmask_b32_e32 v154, 0, v213, vcc
	v_mov_b32_e32 v156, v157
	v_sub_f32_e32 v153, v153, v154
	v_sub_f32_e32 v154, 1.0, v137
	v_mov_b32_e32 v155, v156
	v_fma_f32 v154, v155, v154, v137
	v_cmp_gt_f32_e32 vcc, s14, v154
	s_add_i32 s2, s34, -1
	s_mul_hi_i32 s3, s2, 0x2200000
	v_cndmask_b32_e64 v155, 0, 32, vcc
	v_ldexp_f32 v154, v154, v155
	v_log_f32_e32 v154, v154
	s_mul_i32 s2, s2, 0x2200000
	s_add_u32 s2, s60, s2
	s_addc_u32 s3, s61, s3
	v_mul_f32_e32 v155, 0x3f317217, v154
	v_fma_f32 v155, v154, s24, -v155
	v_fmac_f32_e32 v155, 0x3377d1cf, v154
	v_fmac_f32_e32 v155, 0x3f317217, v154
	v_cmp_lt_f32_e64 s[4:5], |v154|, s15
	v_readlane_b32 s50, v252, 18
	v_readlane_b32 s51, v252, 19
	v_cndmask_b32_e64 v154, v154, v155, s[4:5]
	v_cndmask_b32_e32 v155, 0, v213, vcc
	v_sub_f32_e32 v154, v154, v155
	v_cvt_pk_f16_f32 v153, v153, v154
	v_lshl_add_u64 v[154:155], s[2:3], 0, v[150:151]
	v_lshl_add_u64 v[154:155], v[154:155], 0, v[0:1]
	v_readlane_b32 s52, v252, 20
	v_readlane_b32 s53, v252, 21
	v_readlane_b32 s54, v252, 22
	v_readlane_b32 s55, v252, 23
	v_readlane_b32 s56, v252, 24
	v_readlane_b32 s57, v252, 25
	v_readlane_b32 s58, v252, 26
	v_readlane_b32 s59, v252, 27
	v_readlane_b32 s62, v252, 30
	v_readlane_b32 s63, v252, 31
	global_store_dwordx2 v[154:155], v[152:153], off offset:64

.LBB0_929:
	s_andn2_b64 vcc, exec, s[2:3]
	s_cbranch_vccnz .LBB0_931
	v_mul_f32_e32 v147, 0xbfb8aa3b, v34
	v_exp_f32_e32 v152, v147
	v_mul_f32_e32 v147, 0xbfb8aa3b, v35
	v_exp_f32_e32 v153, v147
	s_mov_b32 s4, 0x3db504f3
	v_pk_add_f32 v[152:153], v[152:153], 1.0 op_sel_hi:[1,0]
	s_nop 0
	v_rcp_f32_e32 v154, v153
	s_nop 0
	v_mul_f32_e32 v147, v35, v154
	v_mov_b32_e32 v153, v147
	v_rcp_f32_e32 v154, v152
	s_nop 0
	v_mul_f32_e32 v147, v34, v154
	v_mov_b32_e32 v152, v147
	v_mul_f32_e32 v147, 0xbfb8aa3b, v36
	v_exp_f32_e32 v154, v147
	v_mul_f32_e32 v147, 0xbfb8aa3b, v37
	v_exp_f32_e32 v155, v147
	v_pk_mul_f32 v[152:153], v[152:153], s[4:5] op_sel_hi:[1,0]
	v_pk_add_f32 v[154:155], v[154:155], 1.0 op_sel_hi:[1,0]
	s_nop 0
	v_rcp_f32_e32 v156, v155
	s_nop 0
	v_mul_f32_e32 v147, v37, v156
	v_mov_b32_e32 v155, v147
	v_rcp_f32_e32 v156, v154
	s_nop 0
	v_mul_f32_e32 v147, v36, v156
	v_mov_b32_e32 v154, v147
	v_pk_mul_f32 v[154:155], v[154:155], s[4:5] op_sel_hi:[1,0]
	v_bfe_u32 v157, v153, 16, 1
	v_bfe_u32 v147, v155, 16, 1
	v_bfe_u32 v156, v154, 16, 1
	v_bfe_u32 v158, v152, 16, 1
	v_add3_u32 v152, v152, v158, s0
	v_add3_u32 v157, v153, v157, s0
	v_add3_u32 v153, v154, v156, s0
	v_add3_u32 v147, v155, v147, s0
	v_perm_b32 v153, v147, v153, s19
	v_perm_b32 v152, v157, v152, s19
	v_lshl_add_u64 v[154:155], v[148:149], 0, v[0:1]
	global_store_dwordx2 v[154:155], v[152:153], off offset:64
.LBB0_931:
	s_and_b64 vcc, exec, s[40:41]
	s_mov_b64 s[2:3], -1
	s_cbranch_vccnz .LBB0_941
	s_cmp_lt_i32 s34, 3
	s_cbranch_scc1 .LBB0_938
	s_cmp_eq_u32 s34, 3
	s_cbranch_scc1 .LBB0_935
	v_mul_f32_e32 v147, 0xbfb8aa3b, v30
	v_exp_f32_e32 v152, v147
	v_mul_f32_e32 v147, 0xbfb8aa3b, v31
	v_exp_f32_e32 v153, v147
	v_readlane_b32 s48, v253, 4
	v_readlane_b32 s49, v253, 5
	v_readlane_b32 s50, v253, 6
	v_pk_add_f32 v[152:153], v[152:153], 1.0 op_sel_hi:[1,0]
	v_readlane_b32 s51, v253, 7
	v_rcp_f32_e32 v154, v152
	s_nop 0
	v_mul_f32_e32 v147, v30, v154
	v_rcp_f32_e32 v154, v153
	s_nop 0
	v_mul_f32_e32 v152, v31, v154
	v_mov_b32_e32 v154, v152
	v_mul_f32_e32 v152, 0xbfb8aa3b, v32
	v_mul_f32_e32 v153, 0xbfb8aa3b, v33
	v_exp_f32_e32 v152, v152
	v_exp_f32_e32 v153, v153
	s_nop 0
	v_pk_add_f32 v[152:153], v[152:153], 1.0 op_sel_hi:[1,0]
	s_nop 0
	v_rcp_f32_e32 v156, v152
	s_nop 0
	v_mul_f32_e32 v155, v32, v156
	v_mov_b32_e32 v152, v155
	v_rcp_f32_e32 v156, v153
	s_mov_b64 s[2:3], 0
	v_mul_f32_e32 v155, v33, v156
	v_mov_b32_e32 v153, v155
	v_bfe_u32 v155, v153, 16, 1
	v_bfe_u32 v156, v152, 16, 1
	v_bfe_u32 v157, v154, 16, 1
	v_bfe_u32 v158, v147, 16, 1
	v_add3_u32 v147, v147, v158, s0
	v_add3_u32 v154, v154, v157, s0
	v_add3_u32 v152, v152, v156, s0
	v_add3_u32 v153, v153, v155, s0
	v_perm_b32 v153, v153, v152, s19
	v_perm_b32 v152, v154, v147, s19
	v_lshl_add_u64 v[154:155], s[48:49], 0, v[150:151]
	v_lshl_add_u64 v[154:155], v[154:155], 0, v[0:1]
	global_store_dwordx2 v[154:155], v[152:153], off offset:96

.LBB0_938:
	s_andn2_b64 vcc, exec, s[2:3]
	s_cbranch_vccnz .LBB0_940
	v_mul_f32_e32 v152, 0xbfb8aa3b, v30
	v_exp_f32_e32 v152, v152
	s_waitcnt vmcnt(0)
	v_sub_f32_e32 v147, 1.0, v130
	s_mov_b32 s14, 0x800000
	s_mov_b32 s24, 0x3f317217
	v_add_f32_e32 v152, 1.0, v152
	v_rcp_f32_e32 v154, v152
	s_mov_b32 s15, 0x7f800000
	v_readlane_b32 s48, v252, 16
	v_readlane_b32 s60, v252, 28
	v_mov_b32_e32 v153, v154
	v_mov_b32_e32 v152, v153
	v_fma_f32 v147, v152, v147, v130
	v_mul_f32_e32 v153, 0xbfb8aa3b, v31
	v_cmp_gt_f32_e32 vcc, s14, v147
	v_exp_f32_e32 v153, v153
	v_readlane_b32 s61, v252, 29
	v_cndmask_b32_e64 v152, 0, 32, vcc
	v_ldexp_f32 v147, v147, v152
	v_log_f32_e32 v147, v147
	v_add_f32_e32 v153, 1.0, v153
	v_rcp_f32_e32 v155, v153
	v_mul_f32_e32 v152, 0x3f317217, v147
	v_fma_f32 v152, v147, s24, -v152
	v_fmac_f32_e32 v152, 0x3377d1cf, v147
	v_fmac_f32_e32 v152, 0x3f317217, v147
	v_cmp_lt_f32_e64 s[4:5], |v147|, s15
	v_cndmask_b32_e64 v147, v147, v152, s[4:5]
	v_cndmask_b32_e32 v152, 0, v213, vcc
	v_mov_b32_e32 v154, v155
	v_sub_f32_e32 v147, v147, v152
	v_sub_f32_e32 v152, 1.0, v131
	v_mov_b32_e32 v153, v154
	v_fma_f32 v152, v153, v152, v131
	v_mul_f32_e32 v154, 0xbfb8aa3b, v32
	v_cmp_gt_f32_e32 vcc, s14, v152
	v_exp_f32_e32 v154, v154
	v_readlane_b32 s49, v252, 17
	v_cndmask_b32_e64 v153, 0, 32, vcc
	v_ldexp_f32 v152, v152, v153
	v_log_f32_e32 v152, v152
	v_add_f32_e32 v154, 1.0, v154
	v_rcp_f32_e32 v156, v154
	v_mul_f32_e32 v153, 0x3f317217, v152
	v_fma_f32 v153, v152, s24, -v153
	v_fmac_f32_e32 v153, 0x3377d1cf, v152
	v_fmac_f32_e32 v153, 0x3f317217, v152
	v_cmp_lt_f32_e64 s[4:5], |v152|, s15
	v_cndmask_b32_e64 v152, v152, v153, s[4:5]
	v_cndmask_b32_e32 v153, 0, v213, vcc
	v_mov_b32_e32 v155, v156
	v_sub_f32_e32 v152, v152, v153
	v_sub_f32_e32 v153, 1.0, v132
	v_mov_b32_e32 v154, v155
	v_fma_f32 v153, v154, v153, v132
	v_mul_f32_e32 v155, 0xbfb8aa3b, v33
	v_cmp_gt_f32_e32 vcc, s14, v153
	v_exp_f32_e32 v155, v155
	v_cvt_pk_f16_f32 v152, v147, v152
	v_cndmask_b32_e64 v154, 0, 32, vcc
	v_ldexp_f32 v153, v153, v154
	v_log_f32_e32 v153, v153
	v_add_f32_e32 v155, 1.0, v155
	v_rcp_f32_e32 v157, v155
	v_mul_f32_e32 v154, 0x3f317217, v153
	v_fma_f32 v154, v153, s24, -v154
	v_fmac_f32_e32 v154, 0x3377d1cf, v153
	v_fmac_f32_e32 v154, 0x3f317217, v153
	v_cmp_lt_f32_e64 s[4:5], |v153|, s15
	v_cndmask_b32_e64 v153, v153, v154, s[4:5]
	v_cndmask_b32_e32 v154, 0, v213, vcc
	v_mov_b32_e32 v156, v157
	v_sub_f32_e32 v153, v153, v154
	v_sub_f32_e32 v154, 1.0, v133
	v_mov_b32_e32 v155, v156
	v_fma_f32 v154, v155, v154, v133
	v_cmp_gt_f32_e32 vcc, s14, v154
	s_add_i32 s2, s34, -1
	s_mul_hi_i32 s3, s2, 0x2200000
	v_cndmask_b32_e64 v155, 0, 32, vcc
	v_ldexp_f32 v154, v154, v155
	v_log_f32_e32 v154, v154
	s_mul_i32 s2, s2, 0x2200000
	s_add_u32 s2, s60, s2
	s_addc_u32 s3, s61, s3
	v_mul_f32_e32 v155, 0x3f317217, v154
	v_fma_f32 v155, v154, s24, -v155
	v_fmac_f32_e32 v155, 0x3377d1cf, v154
	v_fmac_f32_e32 v155, 0x3f317217, v154
	v_cmp_lt_f32_e64 s[4:5], |v154|, s15
	v_lshl_add_u64 v[150:151], s[2:3], 0, v[150:151]
	v_lshl_add_u64 v[150:151], v[150:151], 0, v[0:1]
	v_cndmask_b32_e64 v154, v154, v155, s[4:5]
	v_cndmask_b32_e32 v155, 0, v213, vcc
	v_sub_f32_e32 v154, v154, v155
	v_cvt_pk_f16_f32 v153, v153, v154
	v_readlane_b32 s50, v252, 18
	v_readlane_b32 s51, v252, 19
	v_readlane_b32 s52, v252, 20
	v_readlane_b32 s53, v252, 21
	v_readlane_b32 s54, v252, 22
	v_readlane_b32 s55, v252, 23
	v_readlane_b32 s56, v252, 24
	v_readlane_b32 s57, v252, 25
	v_readlane_b32 s58, v252, 26
	v_readlane_b32 s59, v252, 27
	v_readlane_b32 s62, v252, 30
	v_readlane_b32 s63, v252, 31
	global_store_dwordx2 v[150:151], v[152:153], off offset:96

.LBB0_941:
	s_andn2_b64 vcc, exec, s[2:3]
	s_cbranch_vccnz .LBB0_943
	v_mul_f32_e32 v147, 0xbfb8aa3b, v30
	v_exp_f32_e32 v150, v147
	v_mul_f32_e32 v147, 0xbfb8aa3b, v31
	v_exp_f32_e32 v151, v147
	s_mov_b32 s4, 0x3db504f3
	v_lshl_add_u64 v[148:149], v[148:149], 0, v[0:1]
	v_pk_add_f32 v[150:151], v[150:151], 1.0 op_sel_hi:[1,0]
	s_nop 0
	v_rcp_f32_e32 v152, v151
	s_nop 0
	v_mul_f32_e32 v147, v31, v152
	v_mov_b32_e32 v151, v147
	v_rcp_f32_e32 v152, v150
	s_nop 0
	v_mul_f32_e32 v147, v30, v152
	v_mov_b32_e32 v150, v147
	v_mul_f32_e32 v147, 0xbfb8aa3b, v32
	v_exp_f32_e32 v152, v147
	v_mul_f32_e32 v147, 0xbfb8aa3b, v33
	v_exp_f32_e32 v153, v147
	v_pk_mul_f32 v[150:151], v[150:151], s[4:5] op_sel_hi:[1,0]
	v_pk_add_f32 v[152:153], v[152:153], 1.0 op_sel_hi:[1,0]
	s_nop 0
	v_rcp_f32_e32 v154, v153
	s_nop 0
	v_mul_f32_e32 v147, v33, v154
	v_mov_b32_e32 v153, v147
	v_rcp_f32_e32 v154, v152
	s_nop 0
	v_mul_f32_e32 v147, v32, v154
	v_mov_b32_e32 v152, v147
	v_pk_mul_f32 v[152:153], v[152:153], s[4:5] op_sel_hi:[1,0]
	v_bfe_u32 v155, v151, 16, 1
	v_bfe_u32 v147, v153, 16, 1
	v_bfe_u32 v154, v152, 16, 1
	v_bfe_u32 v156, v150, 16, 1
	v_add3_u32 v150, v150, v156, s0
	v_add3_u32 v155, v151, v155, s0
	v_add3_u32 v151, v152, v154, s0
	v_add3_u32 v147, v153, v147, s0
	v_perm_b32 v151, v147, v151, s19
	v_perm_b32 v150, v155, v150, s19
	global_store_dwordx2 v[148:149], v[150:151], off offset:96
.LBB0_943:
	v_or_b32_e32 v148, 0x60, v146
	v_ashrrev_i32_e32 v149, 31, v148
	s_and_b64 vcc, exec, s[40:41]
	s_mov_b64 s[2:3], -1
	s_cbranch_vccnz .LBB0_953
	s_cmp_lt_i32 s34, 3
	s_cbranch_scc1 .LBB0_950
	s_cmp_eq_u32 s34, 3
	s_cbranch_scc1 .LBB0_947
	v_mul_f32_e32 v147, 0xbfb8aa3b, v38
	v_exp_f32_e32 v150, v147
	v_mul_f32_e32 v147, 0xbfb8aa3b, v39
	v_exp_f32_e32 v151, v147
	v_readlane_b32 s48, v253, 4
	v_readlane_b32 s49, v253, 5
	v_readlane_b32 s50, v253, 6
	v_pk_add_f32 v[150:151], v[150:151], 1.0 op_sel_hi:[1,0]
	v_readlane_b32 s51, v253, 7
	v_rcp_f32_e32 v152, v150
	s_nop 0
	v_mul_f32_e32 v147, v38, v152
	v_rcp_f32_e32 v152, v151
	s_nop 0
	v_mul_f32_e32 v150, v39, v152
	v_mov_b32_e32 v152, v150
	v_mul_f32_e32 v150, 0xbfb8aa3b, v40
	v_mul_f32_e32 v151, 0xbfb8aa3b, v41
	v_exp_f32_e32 v150, v150
	v_exp_f32_e32 v151, v151
	s_nop 0
	v_pk_add_f32 v[150:151], v[150:151], 1.0 op_sel_hi:[1,0]
	s_nop 0
	v_rcp_f32_e32 v154, v150
	s_nop 0
	v_mul_f32_e32 v153, v40, v154
	v_mov_b32_e32 v150, v153
	v_rcp_f32_e32 v154, v151
	s_mov_b64 s[2:3], 0
	v_mul_f32_e32 v153, v41, v154
	v_mov_b32_e32 v151, v153
	v_bfe_u32 v153, v151, 16, 1
	v_bfe_u32 v154, v150, 16, 1
	v_bfe_u32 v155, v152, 16, 1
	v_bfe_u32 v156, v147, 16, 1
	v_add3_u32 v147, v147, v156, s0
	v_add3_u32 v152, v152, v155, s0
	v_add3_u32 v150, v150, v154, s0
	v_add3_u32 v151, v151, v153, s0
	v_perm_b32 v151, v151, v150, s19
	v_perm_b32 v150, v152, v147, s19
	v_lshlrev_b64 v[152:153], 11, v[148:149]
	v_lshl_add_u64 v[152:153], s[48:49], 0, v[152:153]
	v_lshl_add_u64 v[152:153], v[152:153], 0, v[0:1]
	global_store_dwordx2 v[152:153], v[150:151], off

.LBB0_950:
	s_andn2_b64 vcc, exec, s[2:3]
	s_cbranch_vccnz .LBB0_952
	v_mul_f32_e32 v150, 0xbfb8aa3b, v38
	v_exp_f32_e32 v150, v150
	s_waitcnt vmcnt(3)
	v_sub_f32_e32 v147, 1.0, v142
	s_mov_b32 s14, 0x800000
	s_mov_b32 s24, 0x3f317217
	v_add_f32_e32 v150, 1.0, v150
	v_rcp_f32_e32 v152, v150
	s_mov_b32 s15, 0x7f800000
	v_readlane_b32 s48, v252, 16
	v_readlane_b32 s60, v252, 28
	v_mov_b32_e32 v151, v152
	v_mov_b32_e32 v150, v151
	v_fma_f32 v147, v150, v147, v142
	v_mul_f32_e32 v151, 0xbfb8aa3b, v39
	v_cmp_gt_f32_e32 vcc, s14, v147
	v_exp_f32_e32 v151, v151
	v_readlane_b32 s61, v252, 29
	v_cndmask_b32_e64 v150, 0, 32, vcc
	v_ldexp_f32 v147, v147, v150
	v_log_f32_e32 v147, v147
	v_add_f32_e32 v151, 1.0, v151
	v_rcp_f32_e32 v153, v151
	v_mul_f32_e32 v150, 0x3f317217, v147
	v_fma_f32 v150, v147, s24, -v150
	v_fmac_f32_e32 v150, 0x3377d1cf, v147
	v_fmac_f32_e32 v150, 0x3f317217, v147
	v_cmp_lt_f32_e64 s[4:5], |v147|, s15
	v_cndmask_b32_e64 v147, v147, v150, s[4:5]
	v_cndmask_b32_e32 v150, 0, v213, vcc
	v_mov_b32_e32 v152, v153
	v_sub_f32_e32 v147, v147, v150
	v_sub_f32_e32 v150, 1.0, v143
	v_mov_b32_e32 v151, v152
	v_fma_f32 v150, v151, v150, v143
	v_mul_f32_e32 v152, 0xbfb8aa3b, v40
	v_cmp_gt_f32_e32 vcc, s14, v150
	v_exp_f32_e32 v152, v152
	v_readlane_b32 s49, v252, 17
	v_cndmask_b32_e64 v151, 0, 32, vcc
	v_ldexp_f32 v150, v150, v151
	v_log_f32_e32 v150, v150
	v_add_f32_e32 v152, 1.0, v152
	v_rcp_f32_e32 v154, v152
	v_mul_f32_e32 v151, 0x3f317217, v150
	v_fma_f32 v151, v150, s24, -v151
	v_fmac_f32_e32 v151, 0x3377d1cf, v150
	v_fmac_f32_e32 v151, 0x3f317217, v150
	v_cmp_lt_f32_e64 s[4:5], |v150|, s15
	v_cndmask_b32_e64 v150, v150, v151, s[4:5]
	v_cndmask_b32_e32 v151, 0, v213, vcc
	v_mov_b32_e32 v153, v154
	v_sub_f32_e32 v150, v150, v151
	v_sub_f32_e32 v151, 1.0, v144
	v_mov_b32_e32 v152, v153
	v_fma_f32 v151, v152, v151, v144
	v_mul_f32_e32 v153, 0xbfb8aa3b, v41
	v_cmp_gt_f32_e32 vcc, s14, v151
	v_exp_f32_e32 v153, v153
	v_cvt_pk_f16_f32 v150, v147, v150
	v_cndmask_b32_e64 v152, 0, 32, vcc
	v_ldexp_f32 v151, v151, v152
	v_log_f32_e32 v151, v151
	v_add_f32_e32 v153, 1.0, v153
	v_rcp_f32_e32 v155, v153
	v_mul_f32_e32 v152, 0x3f317217, v151
	v_fma_f32 v152, v151, s24, -v152
	v_fmac_f32_e32 v152, 0x3377d1cf, v151
	v_fmac_f32_e32 v152, 0x3f317217, v151
	v_cmp_lt_f32_e64 s[4:5], |v151|, s15
	v_cndmask_b32_e64 v151, v151, v152, s[4:5]
	v_cndmask_b32_e32 v152, 0, v213, vcc
	v_mov_b32_e32 v154, v155
	v_sub_f32_e32 v151, v151, v152
	v_sub_f32_e32 v152, 1.0, v145
	v_mov_b32_e32 v153, v154
	v_fma_f32 v152, v153, v152, v145
	v_cmp_gt_f32_e32 vcc, s14, v152
	s_add_i32 s2, s34, -1
	s_mul_hi_i32 s3, s2, 0x2200000
	v_cndmask_b32_e64 v153, 0, 32, vcc
	v_ldexp_f32 v152, v152, v153
	v_log_f32_e32 v152, v152
	s_mul_i32 s2, s2, 0x2200000
	s_add_u32 s2, s60, s2
	s_addc_u32 s3, s61, s3
	v_mul_f32_e32 v153, 0x3f317217, v152
	v_fma_f32 v153, v152, s24, -v153
	v_fmac_f32_e32 v153, 0x3377d1cf, v152
	v_fmac_f32_e32 v153, 0x3f317217, v152
	v_cmp_lt_f32_e64 s[4:5], |v152|, s15
	v_readlane_b32 s50, v252, 18
	v_readlane_b32 s51, v252, 19
	v_cndmask_b32_e64 v152, v152, v153, s[4:5]
	v_cndmask_b32_e32 v153, 0, v213, vcc
	v_sub_f32_e32 v152, v152, v153
	v_cvt_pk_f16_f32 v151, v151, v152
	v_lshlrev_b64 v[152:153], 11, v[148:149]
	v_lshl_add_u64 v[152:153], s[2:3], 0, v[152:153]
	v_lshl_add_u64 v[152:153], v[152:153], 0, v[0:1]
	v_readlane_b32 s52, v252, 20
	v_readlane_b32 s53, v252, 21
	v_readlane_b32 s54, v252, 22
	v_readlane_b32 s55, v252, 23
	v_readlane_b32 s56, v252, 24
	v_readlane_b32 s57, v252, 25
	v_readlane_b32 s58, v252, 26
	v_readlane_b32 s59, v252, 27
	v_readlane_b32 s62, v252, 30
	v_readlane_b32 s63, v252, 31
	global_store_dwordx2 v[152:153], v[150:151], off

.LBB0_953:
	v_readlane_b32 s48, v252, 16
	v_lshlrev_b64 v[150:151], 11, v[148:149]
	v_readlane_b32 s58, v252, 26
	v_readlane_b32 s59, v252, 27
	s_andn2_b64 vcc, exec, s[2:3]
	v_readlane_b32 s49, v252, 17
	v_lshl_add_u64 v[148:149], s[58:59], 0, v[150:151]
	v_readlane_b32 s50, v252, 18
	v_readlane_b32 s51, v252, 19
	v_readlane_b32 s52, v252, 20
	v_readlane_b32 s53, v252, 21
	v_readlane_b32 s54, v252, 22
	v_readlane_b32 s55, v252, 23
	v_readlane_b32 s56, v252, 24
	v_readlane_b32 s57, v252, 25
	v_readlane_b32 s60, v252, 28
	v_readlane_b32 s61, v252, 29
	v_readlane_b32 s62, v252, 30
	v_readlane_b32 s63, v252, 31
	s_cbranch_vccnz .LBB0_955
	v_mul_f32_e32 v147, 0xbfb8aa3b, v38
	v_exp_f32_e32 v152, v147
	v_mul_f32_e32 v147, 0xbfb8aa3b, v39
	v_exp_f32_e32 v153, v147
	s_mov_b32 s4, 0x3db504f3
	v_pk_add_f32 v[152:153], v[152:153], 1.0 op_sel_hi:[1,0]
	s_nop 0
	v_rcp_f32_e32 v154, v153
	s_nop 0
	v_mul_f32_e32 v147, v39, v154
	v_mov_b32_e32 v153, v147
	v_rcp_f32_e32 v154, v152
	s_nop 0
	v_mul_f32_e32 v147, v38, v154
	v_mov_b32_e32 v152, v147
	v_mul_f32_e32 v147, 0xbfb8aa3b, v40
	v_exp_f32_e32 v154, v147
	v_mul_f32_e32 v147, 0xbfb8aa3b, v41
	v_exp_f32_e32 v155, v147
	v_pk_mul_f32 v[152:153], v[152:153], s[4:5] op_sel_hi:[1,0]
	v_pk_add_f32 v[154:155], v[154:155], 1.0 op_sel_hi:[1,0]
	s_nop 0
	v_rcp_f32_e32 v156, v155
	s_nop 0
	v_mul_f32_e32 v147, v41, v156
	v_mov_b32_e32 v155, v147
	v_rcp_f32_e32 v156, v154
	s_nop 0
	v_mul_f32_e32 v147, v40, v156
	v_mov_b32_e32 v154, v147
	v_pk_mul_f32 v[154:155], v[154:155], s[4:5] op_sel_hi:[1,0]
	v_bfe_u32 v157, v153, 16, 1
	v_bfe_u32 v147, v155, 16, 1
	v_bfe_u32 v156, v154, 16, 1
	v_bfe_u32 v158, v152, 16, 1
	v_add3_u32 v152, v152, v158, s0
	v_add3_u32 v157, v153, v157, s0
	v_add3_u32 v153, v154, v156, s0
	v_add3_u32 v147, v155, v147, s0
	v_perm_b32 v153, v147, v153, s19
	v_perm_b32 v152, v157, v152, s19
	v_lshl_add_u64 v[154:155], v[148:149], 0, v[0:1]
	global_store_dwordx2 v[154:155], v[152:153], off
.LBB0_955:
	s_and_b64 vcc, exec, s[40:41]
	s_mov_b64 s[2:3], -1
	s_cbranch_vccnz .LBB0_965
	s_cmp_lt_i32 s34, 3
	s_cbranch_scc1 .LBB0_962
	s_cmp_eq_u32 s34, 3
	s_cbranch_scc1 .LBB0_959
	v_mul_f32_e32 v147, 0xbfb8aa3b, v26
	v_exp_f32_e32 v152, v147
	v_mul_f32_e32 v147, 0xbfb8aa3b, v27
	v_exp_f32_e32 v153, v147
	v_readlane_b32 s48, v253, 4
	v_readlane_b32 s49, v253, 5
	v_readlane_b32 s50, v253, 6
	v_pk_add_f32 v[152:153], v[152:153], 1.0 op_sel_hi:[1,0]
	v_readlane_b32 s51, v253, 7
	v_rcp_f32_e32 v154, v152
	s_nop 0
	v_mul_f32_e32 v147, v26, v154
	v_rcp_f32_e32 v154, v153
	s_nop 0
	v_mul_f32_e32 v152, v27, v154
	v_mov_b32_e32 v154, v152
	v_mul_f32_e32 v152, 0xbfb8aa3b, v28
	v_mul_f32_e32 v153, 0xbfb8aa3b, v29
	v_exp_f32_e32 v152, v152
	v_exp_f32_e32 v153, v153
	s_nop 0
	v_pk_add_f32 v[152:153], v[152:153], 1.0 op_sel_hi:[1,0]
	s_nop 0
	v_rcp_f32_e32 v156, v152
	s_nop 0
	v_mul_f32_e32 v155, v28, v156
	v_mov_b32_e32 v152, v155
	v_rcp_f32_e32 v156, v153
	s_mov_b64 s[2:3], 0
	v_mul_f32_e32 v155, v29, v156
	v_mov_b32_e32 v153, v155
	v_bfe_u32 v155, v153, 16, 1
	v_bfe_u32 v156, v152, 16, 1
	v_bfe_u32 v157, v154, 16, 1
	v_bfe_u32 v158, v147, 16, 1
	v_add3_u32 v147, v147, v158, s0
	v_add3_u32 v154, v154, v157, s0
	v_add3_u32 v152, v152, v156, s0
	v_add3_u32 v153, v153, v155, s0
	v_perm_b32 v153, v153, v152, s19
	v_perm_b32 v152, v154, v147, s19
	v_lshl_add_u64 v[154:155], s[48:49], 0, v[150:151]
	v_lshl_add_u64 v[154:155], v[154:155], 0, v[0:1]
	global_store_dwordx2 v[154:155], v[152:153], off offset:32

.LBB0_962:
	s_andn2_b64 vcc, exec, s[2:3]
	s_cbranch_vccnz .LBB0_964
	v_mul_f32_e32 v152, 0xbfb8aa3b, v26
	v_exp_f32_e32 v152, v152
	s_waitcnt vmcnt(2)
	v_sub_f32_e32 v147, 1.0, v138
	s_mov_b32 s14, 0x800000
	s_mov_b32 s24, 0x3f317217
	v_add_f32_e32 v152, 1.0, v152
	v_rcp_f32_e32 v154, v152
	s_mov_b32 s15, 0x7f800000
	v_readlane_b32 s48, v252, 16
	v_readlane_b32 s60, v252, 28
	v_mov_b32_e32 v153, v154
	v_mov_b32_e32 v152, v153
	v_fma_f32 v147, v152, v147, v138
	v_mul_f32_e32 v153, 0xbfb8aa3b, v27
	v_cmp_gt_f32_e32 vcc, s14, v147
	v_exp_f32_e32 v153, v153
	v_readlane_b32 s61, v252, 29
	v_cndmask_b32_e64 v152, 0, 32, vcc
	v_ldexp_f32 v147, v147, v152
	v_log_f32_e32 v147, v147
	v_add_f32_e32 v153, 1.0, v153
	v_rcp_f32_e32 v155, v153
	v_mul_f32_e32 v152, 0x3f317217, v147
	v_fma_f32 v152, v147, s24, -v152
	v_fmac_f32_e32 v152, 0x3377d1cf, v147
	v_fmac_f32_e32 v152, 0x3f317217, v147
	v_cmp_lt_f32_e64 s[4:5], |v147|, s15
	v_cndmask_b32_e64 v147, v147, v152, s[4:5]
	v_cndmask_b32_e32 v152, 0, v213, vcc
	v_mov_b32_e32 v154, v155
	v_sub_f32_e32 v147, v147, v152
	v_sub_f32_e32 v152, 1.0, v139
	v_mov_b32_e32 v153, v154
	v_fma_f32 v152, v153, v152, v139
	v_mul_f32_e32 v154, 0xbfb8aa3b, v28
	v_cmp_gt_f32_e32 vcc, s14, v152
	v_exp_f32_e32 v154, v154
	v_readlane_b32 s49, v252, 17
	v_cndmask_b32_e64 v153, 0, 32, vcc
	v_ldexp_f32 v152, v152, v153
	v_log_f32_e32 v152, v152
	v_add_f32_e32 v154, 1.0, v154
	v_rcp_f32_e32 v156, v154
	v_mul_f32_e32 v153, 0x3f317217, v152
	v_fma_f32 v153, v152, s24, -v153
	v_fmac_f32_e32 v153, 0x3377d1cf, v152
	v_fmac_f32_e32 v153, 0x3f317217, v152
	v_cmp_lt_f32_e64 s[4:5], |v152|, s15
	v_cndmask_b32_e64 v152, v152, v153, s[4:5]
	v_cndmask_b32_e32 v153, 0, v213, vcc
	v_mov_b32_e32 v155, v156
	v_sub_f32_e32 v152, v152, v153
	v_sub_f32_e32 v153, 1.0, v140
	v_mov_b32_e32 v154, v155
	v_fma_f32 v153, v154, v153, v140
	v_mul_f32_e32 v155, 0xbfb8aa3b, v29
	v_cmp_gt_f32_e32 vcc, s14, v153
	v_exp_f32_e32 v155, v155
	v_cvt_pk_f16_f32 v152, v147, v152
	v_cndmask_b32_e64 v154, 0, 32, vcc
	v_ldexp_f32 v153, v153, v154
	v_log_f32_e32 v153, v153
	v_add_f32_e32 v155, 1.0, v155
	v_rcp_f32_e32 v157, v155
	v_mul_f32_e32 v154, 0x3f317217, v153
	v_fma_f32 v154, v153, s24, -v154
	v_fmac_f32_e32 v154, 0x3377d1cf, v153
	v_fmac_f32_e32 v154, 0x3f317217, v153
	v_cmp_lt_f32_e64 s[4:5], |v153|, s15
	v_cndmask_b32_e64 v153, v153, v154, s[4:5]
	v_cndmask_b32_e32 v154, 0, v213, vcc
	v_mov_b32_e32 v156, v157
	v_sub_f32_e32 v153, v153, v154
	v_sub_f32_e32 v154, 1.0, v141
	v_mov_b32_e32 v155, v156
	v_fma_f32 v154, v155, v154, v141
	v_cmp_gt_f32_e32 vcc, s14, v154
	s_add_i32 s2, s34, -1
	s_mul_hi_i32 s3, s2, 0x2200000
	v_cndmask_b32_e64 v155, 0, 32, vcc
	v_ldexp_f32 v154, v154, v155
	v_log_f32_e32 v154, v154
	s_mul_i32 s2, s2, 0x2200000
	s_add_u32 s2, s60, s2
	s_addc_u32 s3, s61, s3
	v_mul_f32_e32 v155, 0x3f317217, v154
	v_fma_f32 v155, v154, s24, -v155
	v_fmac_f32_e32 v155, 0x3377d1cf, v154
	v_fmac_f32_e32 v155, 0x3f317217, v154
	v_cmp_lt_f32_e64 s[4:5], |v154|, s15
	v_readlane_b32 s50, v252, 18
	v_readlane_b32 s51, v252, 19
	v_cndmask_b32_e64 v154, v154, v155, s[4:5]
	v_cndmask_b32_e32 v155, 0, v213, vcc
	v_sub_f32_e32 v154, v154, v155
	v_cvt_pk_f16_f32 v153, v153, v154
	v_lshl_add_u64 v[154:155], s[2:3], 0, v[150:151]
	v_lshl_add_u64 v[154:155], v[154:155], 0, v[0:1]
	v_readlane_b32 s52, v252, 20
	v_readlane_b32 s53, v252, 21
	v_readlane_b32 s54, v252, 22
	v_readlane_b32 s55, v252, 23
	v_readlane_b32 s56, v252, 24
	v_readlane_b32 s57, v252, 25
	v_readlane_b32 s58, v252, 26
	v_readlane_b32 s59, v252, 27
	v_readlane_b32 s62, v252, 30
	v_readlane_b32 s63, v252, 31
	global_store_dwordx2 v[154:155], v[152:153], off offset:32

.LBB0_965:
	s_andn2_b64 vcc, exec, s[2:3]
	s_cbranch_vccnz .LBB0_967
	v_mul_f32_e32 v147, 0xbfb8aa3b, v26
	v_exp_f32_e32 v152, v147
	v_mul_f32_e32 v147, 0xbfb8aa3b, v27
	v_exp_f32_e32 v153, v147
	s_mov_b32 s4, 0x3db504f3
	v_pk_add_f32 v[152:153], v[152:153], 1.0 op_sel_hi:[1,0]
	s_nop 0
	v_rcp_f32_e32 v154, v153
	s_nop 0
	v_mul_f32_e32 v147, v27, v154
	v_mov_b32_e32 v153, v147
	v_rcp_f32_e32 v154, v152
	s_nop 0
	v_mul_f32_e32 v147, v26, v154
	v_mov_b32_e32 v152, v147
	v_mul_f32_e32 v147, 0xbfb8aa3b, v28
	v_exp_f32_e32 v154, v147
	v_mul_f32_e32 v147, 0xbfb8aa3b, v29
	v_exp_f32_e32 v155, v147
	v_pk_mul_f32 v[152:153], v[152:153], s[4:5] op_sel_hi:[1,0]
	v_pk_add_f32 v[154:155], v[154:155], 1.0 op_sel_hi:[1,0]
	s_nop 0
	v_rcp_f32_e32 v156, v155
	s_nop 0
	v_mul_f32_e32 v147, v29, v156
	v_mov_b32_e32 v155, v147
	v_rcp_f32_e32 v156, v154
	s_nop 0
	v_mul_f32_e32 v147, v28, v156
	v_mov_b32_e32 v154, v147
	v_pk_mul_f32 v[154:155], v[154:155], s[4:5] op_sel_hi:[1,0]
	v_bfe_u32 v157, v153, 16, 1
	v_bfe_u32 v147, v155, 16, 1
	v_bfe_u32 v156, v154, 16, 1
	v_bfe_u32 v158, v152, 16, 1
	v_add3_u32 v152, v152, v158, s0
	v_add3_u32 v157, v153, v157, s0
	v_add3_u32 v153, v154, v156, s0
	v_add3_u32 v147, v155, v147, s0
	v_perm_b32 v153, v147, v153, s19
	v_perm_b32 v152, v157, v152, s19
	v_lshl_add_u64 v[154:155], v[148:149], 0, v[0:1]
	global_store_dwordx2 v[154:155], v[152:153], off offset:32
.LBB0_967:
	s_and_b64 vcc, exec, s[40:41]
	s_mov_b64 s[2:3], -1
	s_cbranch_vccnz .LBB0_977
	s_cmp_lt_i32 s34, 3
	s_cbranch_scc1 .LBB0_974
	s_cmp_eq_u32 s34, 3
	s_cbranch_scc1 .LBB0_971
	v_mul_f32_e32 v147, 0xbfb8aa3b, v22
	v_exp_f32_e32 v152, v147
	v_mul_f32_e32 v147, 0xbfb8aa3b, v23
	v_exp_f32_e32 v153, v147
	v_readlane_b32 s48, v253, 4
	v_readlane_b32 s49, v253, 5
	v_readlane_b32 s50, v253, 6
	v_pk_add_f32 v[152:153], v[152:153], 1.0 op_sel_hi:[1,0]
	v_readlane_b32 s51, v253, 7
	v_rcp_f32_e32 v154, v152
	s_nop 0
	v_mul_f32_e32 v147, v22, v154
	v_rcp_f32_e32 v154, v153
	s_nop 0
	v_mul_f32_e32 v152, v23, v154
	v_mov_b32_e32 v154, v152
	v_mul_f32_e32 v152, 0xbfb8aa3b, v24
	v_mul_f32_e32 v153, 0xbfb8aa3b, v25
	v_exp_f32_e32 v152, v152
	v_exp_f32_e32 v153, v153
	s_nop 0
	v_pk_add_f32 v[152:153], v[152:153], 1.0 op_sel_hi:[1,0]
	s_nop 0
	v_rcp_f32_e32 v156, v152
	s_nop 0
	v_mul_f32_e32 v155, v24, v156
	v_mov_b32_e32 v152, v155
	v_rcp_f32_e32 v156, v153
	s_mov_b64 s[2:3], 0
	v_mul_f32_e32 v155, v25, v156
	v_mov_b32_e32 v153, v155
	v_bfe_u32 v155, v153, 16, 1
	v_bfe_u32 v156, v152, 16, 1
	v_bfe_u32 v157, v154, 16, 1
	v_bfe_u32 v158, v147, 16, 1
	v_add3_u32 v147, v147, v158, s0
	v_add3_u32 v154, v154, v157, s0
	v_add3_u32 v152, v152, v156, s0
	v_add3_u32 v153, v153, v155, s0
	v_perm_b32 v153, v153, v152, s19
	v_perm_b32 v152, v154, v147, s19
	v_lshl_add_u64 v[154:155], s[48:49], 0, v[150:151]
	v_lshl_add_u64 v[154:155], v[154:155], 0, v[0:1]
	global_store_dwordx2 v[154:155], v[152:153], off offset:64

.LBB0_974:
	s_andn2_b64 vcc, exec, s[2:3]
	s_cbranch_vccnz .LBB0_976
	v_mul_f32_e32 v152, 0xbfb8aa3b, v22
	v_exp_f32_e32 v152, v152
	s_waitcnt vmcnt(1)
	v_sub_f32_e32 v147, 1.0, v134
	s_mov_b32 s14, 0x800000
	s_mov_b32 s24, 0x3f317217
	v_add_f32_e32 v152, 1.0, v152
	v_rcp_f32_e32 v154, v152
	s_mov_b32 s15, 0x7f800000
	v_readlane_b32 s48, v252, 16
	v_readlane_b32 s60, v252, 28
	v_mov_b32_e32 v153, v154
	v_mov_b32_e32 v152, v153
	v_fma_f32 v147, v152, v147, v134
	v_mul_f32_e32 v153, 0xbfb8aa3b, v23
	v_cmp_gt_f32_e32 vcc, s14, v147
	v_exp_f32_e32 v153, v153
	v_readlane_b32 s61, v252, 29
	v_cndmask_b32_e64 v152, 0, 32, vcc
	v_ldexp_f32 v147, v147, v152
	v_log_f32_e32 v147, v147
	v_add_f32_e32 v153, 1.0, v153
	v_rcp_f32_e32 v155, v153
	v_mul_f32_e32 v152, 0x3f317217, v147
	v_fma_f32 v152, v147, s24, -v152
	v_fmac_f32_e32 v152, 0x3377d1cf, v147
	v_fmac_f32_e32 v152, 0x3f317217, v147
	v_cmp_lt_f32_e64 s[4:5], |v147|, s15
	v_cndmask_b32_e64 v147, v147, v152, s[4:5]
	v_cndmask_b32_e32 v152, 0, v213, vcc
	v_mov_b32_e32 v154, v155
	v_sub_f32_e32 v147, v147, v152
	v_sub_f32_e32 v152, 1.0, v135
	v_mov_b32_e32 v153, v154
	v_fma_f32 v152, v153, v152, v135
	v_mul_f32_e32 v154, 0xbfb8aa3b, v24
	v_cmp_gt_f32_e32 vcc, s14, v152
	v_exp_f32_e32 v154, v154
	v_readlane_b32 s49, v252, 17
	v_cndmask_b32_e64 v153, 0, 32, vcc
	v_ldexp_f32 v152, v152, v153
	v_log_f32_e32 v152, v152
	v_add_f32_e32 v154, 1.0, v154
	v_rcp_f32_e32 v156, v154
	v_mul_f32_e32 v153, 0x3f317217, v152
	v_fma_f32 v153, v152, s24, -v153
	v_fmac_f32_e32 v153, 0x3377d1cf, v152
	v_fmac_f32_e32 v153, 0x3f317217, v152
	v_cmp_lt_f32_e64 s[4:5], |v152|, s15
	v_cndmask_b32_e64 v152, v152, v153, s[4:5]
	v_cndmask_b32_e32 v153, 0, v213, vcc
	v_mov_b32_e32 v155, v156
	v_sub_f32_e32 v152, v152, v153
	v_sub_f32_e32 v153, 1.0, v136
	v_mov_b32_e32 v154, v155
	v_fma_f32 v153, v154, v153, v136
	v_mul_f32_e32 v155, 0xbfb8aa3b, v25
	v_cmp_gt_f32_e32 vcc, s14, v153
	v_exp_f32_e32 v155, v155
	v_cvt_pk_f16_f32 v152, v147, v152
	v_cndmask_b32_e64 v154, 0, 32, vcc
	v_ldexp_f32 v153, v153, v154
	v_log_f32_e32 v153, v153
	v_add_f32_e32 v155, 1.0, v155
	v_rcp_f32_e32 v157, v155
	v_mul_f32_e32 v154, 0x3f317217, v153
	v_fma_f32 v154, v153, s24, -v154
	v_fmac_f32_e32 v154, 0x3377d1cf, v153
	v_fmac_f32_e32 v154, 0x3f317217, v153
	v_cmp_lt_f32_e64 s[4:5], |v153|, s15
	v_cndmask_b32_e64 v153, v153, v154, s[4:5]
	v_cndmask_b32_e32 v154, 0, v213, vcc
	v_mov_b32_e32 v156, v157
	v_sub_f32_e32 v153, v153, v154
	v_sub_f32_e32 v154, 1.0, v137
	v_mov_b32_e32 v155, v156
	v_fma_f32 v154, v155, v154, v137
	v_cmp_gt_f32_e32 vcc, s14, v154
	s_add_i32 s2, s34, -1
	s_mul_hi_i32 s3, s2, 0x2200000
	v_cndmask_b32_e64 v155, 0, 32, vcc
	v_ldexp_f32 v154, v154, v155
	v_log_f32_e32 v154, v154
	s_mul_i32 s2, s2, 0x2200000
	s_add_u32 s2, s60, s2
	s_addc_u32 s3, s61, s3
	v_mul_f32_e32 v155, 0x3f317217, v154
	v_fma_f32 v155, v154, s24, -v155
	v_fmac_f32_e32 v155, 0x3377d1cf, v154
	v_fmac_f32_e32 v155, 0x3f317217, v154
	v_cmp_lt_f32_e64 s[4:5], |v154|, s15
	v_readlane_b32 s50, v252, 18
	v_readlane_b32 s51, v252, 19
	v_cndmask_b32_e64 v154, v154, v155, s[4:5]
	v_cndmask_b32_e32 v155, 0, v213, vcc
	v_sub_f32_e32 v154, v154, v155
	v_cvt_pk_f16_f32 v153, v153, v154
	v_lshl_add_u64 v[154:155], s[2:3], 0, v[150:151]
	v_lshl_add_u64 v[154:155], v[154:155], 0, v[0:1]
	v_readlane_b32 s52, v252, 20
	v_readlane_b32 s53, v252, 21
	v_readlane_b32 s54, v252, 22
	v_readlane_b32 s55, v252, 23
	v_readlane_b32 s56, v252, 24
	v_readlane_b32 s57, v252, 25
	v_readlane_b32 s58, v252, 26
	v_readlane_b32 s59, v252, 27
	v_readlane_b32 s62, v252, 30
	v_readlane_b32 s63, v252, 31
	global_store_dwordx2 v[154:155], v[152:153], off offset:64

.LBB0_977:
	s_andn2_b64 vcc, exec, s[2:3]
	s_cbranch_vccnz .LBB0_979
	v_mul_f32_e32 v147, 0xbfb8aa3b, v22
	v_exp_f32_e32 v152, v147
	v_mul_f32_e32 v147, 0xbfb8aa3b, v23
	v_exp_f32_e32 v153, v147
	s_mov_b32 s4, 0x3db504f3
	v_pk_add_f32 v[152:153], v[152:153], 1.0 op_sel_hi:[1,0]
	s_nop 0
	v_rcp_f32_e32 v154, v153
	s_nop 0
	v_mul_f32_e32 v147, v23, v154
	v_mov_b32_e32 v153, v147
	v_rcp_f32_e32 v154, v152
	s_nop 0
	v_mul_f32_e32 v147, v22, v154
	v_mov_b32_e32 v152, v147
	v_mul_f32_e32 v147, 0xbfb8aa3b, v24
	v_exp_f32_e32 v154, v147
	v_mul_f32_e32 v147, 0xbfb8aa3b, v25
	v_exp_f32_e32 v155, v147
	v_pk_mul_f32 v[152:153], v[152:153], s[4:5] op_sel_hi:[1,0]
	v_pk_add_f32 v[154:155], v[154:155], 1.0 op_sel_hi:[1,0]
	s_nop 0
	v_rcp_f32_e32 v156, v155
	s_nop 0
	v_mul_f32_e32 v147, v25, v156
	v_mov_b32_e32 v155, v147
	v_rcp_f32_e32 v156, v154
	s_nop 0
	v_mul_f32_e32 v147, v24, v156
	v_mov_b32_e32 v154, v147
	v_pk_mul_f32 v[154:155], v[154:155], s[4:5] op_sel_hi:[1,0]
	v_bfe_u32 v157, v153, 16, 1
	v_bfe_u32 v147, v155, 16, 1
	v_bfe_u32 v156, v154, 16, 1
	v_bfe_u32 v158, v152, 16, 1
	v_add3_u32 v152, v152, v158, s0
	v_add3_u32 v157, v153, v157, s0
	v_add3_u32 v153, v154, v156, s0
	v_add3_u32 v147, v155, v147, s0
	v_perm_b32 v153, v147, v153, s19
	v_perm_b32 v152, v157, v152, s19
	v_lshl_add_u64 v[154:155], v[148:149], 0, v[0:1]
	global_store_dwordx2 v[154:155], v[152:153], off offset:64
.LBB0_979:
	s_and_b64 vcc, exec, s[40:41]
	s_mov_b64 s[2:3], -1
	s_cbranch_vccnz .LBB0_989
	s_cmp_lt_i32 s34, 3
	s_cbranch_scc1 .LBB0_986
	s_cmp_eq_u32 s34, 3
	s_cbranch_scc1 .LBB0_983
	v_mul_f32_e32 v147, 0xbfb8aa3b, v18
	v_exp_f32_e32 v152, v147
	v_mul_f32_e32 v147, 0xbfb8aa3b, v19
	v_exp_f32_e32 v153, v147
	v_readlane_b32 s48, v253, 4
	v_readlane_b32 s49, v253, 5
	v_readlane_b32 s50, v253, 6
	v_pk_add_f32 v[152:153], v[152:153], 1.0 op_sel_hi:[1,0]
	v_readlane_b32 s51, v253, 7
	v_rcp_f32_e32 v154, v152
	s_nop 0
	v_mul_f32_e32 v147, v18, v154
	v_rcp_f32_e32 v154, v153
	s_nop 0
	v_mul_f32_e32 v152, v19, v154
	v_mov_b32_e32 v154, v152
	v_mul_f32_e32 v152, 0xbfb8aa3b, v20
	v_mul_f32_e32 v153, 0xbfb8aa3b, v21
	v_exp_f32_e32 v152, v152
	v_exp_f32_e32 v153, v153
	s_nop 0
	v_pk_add_f32 v[152:153], v[152:153], 1.0 op_sel_hi:[1,0]
	s_nop 0
	v_rcp_f32_e32 v156, v152
	s_nop 0
	v_mul_f32_e32 v155, v20, v156
	v_mov_b32_e32 v152, v155
	v_rcp_f32_e32 v156, v153
	s_mov_b64 s[2:3], 0
	v_mul_f32_e32 v155, v21, v156
	v_mov_b32_e32 v153, v155
	v_bfe_u32 v155, v153, 16, 1
	v_bfe_u32 v156, v152, 16, 1
	v_bfe_u32 v157, v154, 16, 1
	v_bfe_u32 v158, v147, 16, 1
	v_add3_u32 v147, v147, v158, s0
	v_add3_u32 v154, v154, v157, s0
	v_add3_u32 v152, v152, v156, s0
	v_add3_u32 v153, v153, v155, s0
	v_perm_b32 v153, v153, v152, s19
	v_perm_b32 v152, v154, v147, s19
	v_lshl_add_u64 v[154:155], s[48:49], 0, v[150:151]
	v_lshl_add_u64 v[154:155], v[154:155], 0, v[0:1]
	global_store_dwordx2 v[154:155], v[152:153], off offset:96

.LBB0_986:
	s_andn2_b64 vcc, exec, s[2:3]
	s_cbranch_vccnz .LBB0_988
	v_mul_f32_e32 v152, 0xbfb8aa3b, v18
	v_exp_f32_e32 v152, v152
	s_waitcnt vmcnt(0)
	v_sub_f32_e32 v147, 1.0, v130
	s_mov_b32 s14, 0x800000
	s_mov_b32 s24, 0x3f317217
	v_add_f32_e32 v152, 1.0, v152
	v_rcp_f32_e32 v154, v152
	s_mov_b32 s15, 0x7f800000
	v_readlane_b32 s48, v252, 16
	v_readlane_b32 s60, v252, 28
	v_mov_b32_e32 v153, v154
	v_mov_b32_e32 v152, v153
	v_fma_f32 v147, v152, v147, v130
	v_mul_f32_e32 v153, 0xbfb8aa3b, v19
	v_cmp_gt_f32_e32 vcc, s14, v147
	v_exp_f32_e32 v153, v153
	v_readlane_b32 s61, v252, 29
	v_cndmask_b32_e64 v152, 0, 32, vcc
	v_ldexp_f32 v147, v147, v152
	v_log_f32_e32 v147, v147
	v_add_f32_e32 v153, 1.0, v153
	v_rcp_f32_e32 v155, v153
	v_mul_f32_e32 v152, 0x3f317217, v147
	v_fma_f32 v152, v147, s24, -v152
	v_fmac_f32_e32 v152, 0x3377d1cf, v147
	v_fmac_f32_e32 v152, 0x3f317217, v147
	v_cmp_lt_f32_e64 s[4:5], |v147|, s15
	v_cndmask_b32_e64 v147, v147, v152, s[4:5]
	v_cndmask_b32_e32 v152, 0, v213, vcc
	v_mov_b32_e32 v154, v155
	v_sub_f32_e32 v147, v147, v152
	v_sub_f32_e32 v152, 1.0, v131
	v_mov_b32_e32 v153, v154
	v_fma_f32 v152, v153, v152, v131
	v_mul_f32_e32 v154, 0xbfb8aa3b, v20
	v_cmp_gt_f32_e32 vcc, s14, v152
	v_exp_f32_e32 v154, v154
	v_readlane_b32 s49, v252, 17
	v_cndmask_b32_e64 v153, 0, 32, vcc
	v_ldexp_f32 v152, v152, v153
	v_log_f32_e32 v152, v152
	v_add_f32_e32 v154, 1.0, v154
	v_rcp_f32_e32 v156, v154
	v_mul_f32_e32 v153, 0x3f317217, v152
	v_fma_f32 v153, v152, s24, -v153
	v_fmac_f32_e32 v153, 0x3377d1cf, v152
	v_fmac_f32_e32 v153, 0x3f317217, v152
	v_cmp_lt_f32_e64 s[4:5], |v152|, s15
	v_cndmask_b32_e64 v152, v152, v153, s[4:5]
	v_cndmask_b32_e32 v153, 0, v213, vcc
	v_mov_b32_e32 v155, v156
	v_sub_f32_e32 v152, v152, v153
	v_sub_f32_e32 v153, 1.0, v132
	v_mov_b32_e32 v154, v155
	v_fma_f32 v153, v154, v153, v132
	v_mul_f32_e32 v155, 0xbfb8aa3b, v21
	v_cmp_gt_f32_e32 vcc, s14, v153
	v_exp_f32_e32 v155, v155
	v_cvt_pk_f16_f32 v152, v147, v152
	v_cndmask_b32_e64 v154, 0, 32, vcc
	v_ldexp_f32 v153, v153, v154
	v_log_f32_e32 v153, v153
	v_add_f32_e32 v155, 1.0, v155
	v_rcp_f32_e32 v157, v155
	v_mul_f32_e32 v154, 0x3f317217, v153
	v_fma_f32 v154, v153, s24, -v154
	v_fmac_f32_e32 v154, 0x3377d1cf, v153
	v_fmac_f32_e32 v154, 0x3f317217, v153
	v_cmp_lt_f32_e64 s[4:5], |v153|, s15
	v_cndmask_b32_e64 v153, v153, v154, s[4:5]
	v_cndmask_b32_e32 v154, 0, v213, vcc
	v_mov_b32_e32 v156, v157
	v_sub_f32_e32 v153, v153, v154
	v_sub_f32_e32 v154, 1.0, v133
	v_mov_b32_e32 v155, v156
	v_fma_f32 v154, v155, v154, v133
	v_cmp_gt_f32_e32 vcc, s14, v154
	s_add_i32 s2, s34, -1
	s_mul_hi_i32 s3, s2, 0x2200000
	v_cndmask_b32_e64 v155, 0, 32, vcc
	v_ldexp_f32 v154, v154, v155
	v_log_f32_e32 v154, v154
	s_mul_i32 s2, s2, 0x2200000
	s_add_u32 s2, s60, s2
	s_addc_u32 s3, s61, s3
	v_mul_f32_e32 v155, 0x3f317217, v154
	v_fma_f32 v155, v154, s24, -v155
	v_fmac_f32_e32 v155, 0x3377d1cf, v154
	v_fmac_f32_e32 v155, 0x3f317217, v154
	v_cmp_lt_f32_e64 s[4:5], |v154|, s15
	v_lshl_add_u64 v[150:151], s[2:3], 0, v[150:151]
	v_lshl_add_u64 v[150:151], v[150:151], 0, v[0:1]
	v_cndmask_b32_e64 v154, v154, v155, s[4:5]
	v_cndmask_b32_e32 v155, 0, v213, vcc
	v_sub_f32_e32 v154, v154, v155
	v_cvt_pk_f16_f32 v153, v153, v154
	v_readlane_b32 s50, v252, 18
	v_readlane_b32 s51, v252, 19
	v_readlane_b32 s52, v252, 20
	v_readlane_b32 s53, v252, 21
	v_readlane_b32 s54, v252, 22
	v_readlane_b32 s55, v252, 23
	v_readlane_b32 s56, v252, 24
	v_readlane_b32 s57, v252, 25
	v_readlane_b32 s58, v252, 26
	v_readlane_b32 s59, v252, 27
	v_readlane_b32 s62, v252, 30
	v_readlane_b32 s63, v252, 31
	global_store_dwordx2 v[150:151], v[152:153], off offset:96

.LBB0_989:
	s_andn2_b64 vcc, exec, s[2:3]
	s_cbranch_vccnz .LBB0_991
	v_mul_f32_e32 v147, 0xbfb8aa3b, v18
	v_exp_f32_e32 v150, v147
	v_mul_f32_e32 v147, 0xbfb8aa3b, v19
	v_exp_f32_e32 v151, v147
	s_mov_b32 s4, 0x3db504f3
	v_lshl_add_u64 v[148:149], v[148:149], 0, v[0:1]
	v_pk_add_f32 v[150:151], v[150:151], 1.0 op_sel_hi:[1,0]
	s_nop 0
	v_rcp_f32_e32 v152, v151
	s_nop 0
	v_mul_f32_e32 v147, v19, v152
	v_mov_b32_e32 v151, v147
	v_rcp_f32_e32 v152, v150
	s_nop 0
	v_mul_f32_e32 v147, v18, v152
	v_mov_b32_e32 v150, v147
	v_mul_f32_e32 v147, 0xbfb8aa3b, v20
	v_exp_f32_e32 v152, v147
	v_mul_f32_e32 v147, 0xbfb8aa3b, v21
	v_exp_f32_e32 v153, v147
	v_pk_mul_f32 v[150:151], v[150:151], s[4:5] op_sel_hi:[1,0]
	v_pk_add_f32 v[152:153], v[152:153], 1.0 op_sel_hi:[1,0]
	s_nop 0
	v_rcp_f32_e32 v154, v153
	s_nop 0
	v_mul_f32_e32 v147, v21, v154
	v_mov_b32_e32 v153, v147
	v_rcp_f32_e32 v154, v152
	s_nop 0
	v_mul_f32_e32 v147, v20, v154
	v_mov_b32_e32 v152, v147
	v_pk_mul_f32 v[152:153], v[152:153], s[4:5] op_sel_hi:[1,0]
	v_bfe_u32 v155, v151, 16, 1
	v_bfe_u32 v147, v153, 16, 1
	v_bfe_u32 v154, v152, 16, 1
	v_bfe_u32 v156, v150, 16, 1
	v_add3_u32 v150, v150, v156, s0
	v_add3_u32 v155, v151, v155, s0
	v_add3_u32 v151, v152, v154, s0
	v_add3_u32 v147, v153, v147, s0
	v_perm_b32 v151, v147, v151, s19
	v_perm_b32 v150, v155, v150, s19
	global_store_dwordx2 v[148:149], v[150:151], off offset:96
.LBB0_991:
	v_or_b32_e32 v146, 0x70, v146
	v_ashrrev_i32_e32 v147, 31, v146
	s_and_b64 vcc, exec, s[40:41]
	s_mov_b64 s[2:3], -1
	s_cbranch_vccnz .LBB0_1001
	s_cmp_lt_i32 s34, 3
	s_cbranch_scc1 .LBB0_998
	s_cmp_eq_u32 s34, 3
	s_cbranch_scc1 .LBB0_995
	v_mul_f32_e32 v148, 0xbfb8aa3b, v14
	v_mul_f32_e32 v149, 0xbfb8aa3b, v15
	v_exp_f32_e32 v148, v148
	v_exp_f32_e32 v149, v149
	v_readlane_b32 s48, v253, 4
	v_readlane_b32 s49, v253, 5
	v_readlane_b32 s50, v253, 6
	v_pk_add_f32 v[148:149], v[148:149], 1.0 op_sel_hi:[1,0]
	v_readlane_b32 s51, v253, 7
	v_rcp_f32_e32 v151, v148
	s_nop 0
	v_mul_f32_e32 v150, v14, v151
	v_rcp_f32_e32 v151, v149
	s_nop 0
	v_mul_f32_e32 v148, v15, v151
	v_mov_b32_e32 v151, v148
	v_mul_f32_e32 v148, 0xbfb8aa3b, v16
	v_mul_f32_e32 v149, 0xbfb8aa3b, v17
	v_exp_f32_e32 v148, v148
	v_exp_f32_e32 v149, v149
	s_nop 0
	v_pk_add_f32 v[148:149], v[148:149], 1.0 op_sel_hi:[1,0]
	s_nop 0
	v_rcp_f32_e32 v153, v148
	s_nop 0
	v_mul_f32_e32 v152, v16, v153
	v_mov_b32_e32 v148, v152
	v_rcp_f32_e32 v153, v149
	s_mov_b64 s[2:3], 0
	v_mul_f32_e32 v152, v17, v153
	v_mov_b32_e32 v149, v152
	v_bfe_u32 v152, v149, 16, 1
	v_bfe_u32 v153, v148, 16, 1
	v_bfe_u32 v154, v151, 16, 1
	v_bfe_u32 v155, v150, 16, 1
	v_add3_u32 v150, v150, v155, s0
	v_add3_u32 v151, v151, v154, s0
	v_add3_u32 v148, v148, v153, s0
	v_add3_u32 v149, v149, v152, s0
	v_perm_b32 v149, v149, v148, s19
	v_perm_b32 v148, v151, v150, s19
	v_lshlrev_b64 v[150:151], 11, v[146:147]
	v_lshl_add_u64 v[150:151], s[48:49], 0, v[150:151]
	v_lshl_add_u64 v[150:151], v[150:151], 0, v[0:1]
	global_store_dwordx2 v[150:151], v[148:149], off

.LBB0_998:
	s_andn2_b64 vcc, exec, s[2:3]
	s_cbranch_vccnz .LBB0_1000
	v_mul_f32_e32 v149, 0xbfb8aa3b, v14
	v_exp_f32_e32 v149, v149
	s_waitcnt vmcnt(3)
	v_sub_f32_e32 v148, 1.0, v142
	s_mov_b32 s14, 0x800000
	s_mov_b32 s24, 0x3f317217
	v_add_f32_e32 v149, 1.0, v149
	v_rcp_f32_e32 v151, v149
	s_mov_b32 s15, 0x7f800000
	v_readlane_b32 s48, v252, 16
	v_readlane_b32 s60, v252, 28
	v_mov_b32_e32 v150, v151
	v_mov_b32_e32 v149, v150
	v_fma_f32 v142, v149, v148, v142
	v_mul_f32_e32 v149, 0xbfb8aa3b, v15
	v_cmp_gt_f32_e32 vcc, s14, v142
	v_exp_f32_e32 v149, v149
	v_readlane_b32 s61, v252, 29
	v_cndmask_b32_e64 v148, 0, 32, vcc
	v_ldexp_f32 v142, v142, v148
	v_log_f32_e32 v142, v142
	v_add_f32_e32 v149, 1.0, v149
	v_rcp_f32_e32 v151, v149
	v_mul_f32_e32 v148, 0x3f317217, v142
	v_fma_f32 v148, v142, s24, -v148
	v_fmac_f32_e32 v148, 0x3377d1cf, v142
	v_fmac_f32_e32 v148, 0x3f317217, v142
	v_cmp_lt_f32_e64 s[4:5], |v142|, s15
	v_cndmask_b32_e64 v142, v142, v148, s[4:5]
	v_cndmask_b32_e32 v148, 0, v213, vcc
	v_mov_b32_e32 v150, v151
	v_sub_f32_e32 v142, v142, v148
	v_sub_f32_e32 v148, 1.0, v143
	v_mov_b32_e32 v149, v150
	v_fma_f32 v143, v149, v148, v143
	v_mul_f32_e32 v149, 0xbfb8aa3b, v16
	v_cmp_gt_f32_e32 vcc, s14, v143
	v_exp_f32_e32 v149, v149
	v_readlane_b32 s49, v252, 17
	v_cndmask_b32_e64 v148, 0, 32, vcc
	v_ldexp_f32 v143, v143, v148
	v_log_f32_e32 v143, v143
	v_add_f32_e32 v149, 1.0, v149
	v_rcp_f32_e32 v151, v149
	v_mul_f32_e32 v148, 0x3f317217, v143
	v_fma_f32 v148, v143, s24, -v148
	v_fmac_f32_e32 v148, 0x3377d1cf, v143
	v_fmac_f32_e32 v148, 0x3f317217, v143
	v_cmp_lt_f32_e64 s[4:5], |v143|, s15
	v_cndmask_b32_e64 v143, v143, v148, s[4:5]
	v_cndmask_b32_e32 v148, 0, v213, vcc
	v_mov_b32_e32 v150, v151
	v_sub_f32_e32 v148, v143, v148
	v_sub_f32_e32 v143, 1.0, v144
	v_mov_b32_e32 v149, v150
	v_fma_f32 v143, v149, v143, v144
	v_mul_f32_e32 v149, 0xbfb8aa3b, v17
	v_cmp_gt_f32_e32 vcc, s14, v143
	v_exp_f32_e32 v149, v149
	v_cvt_pk_f16_f32 v142, v142, v148
	v_cndmask_b32_e64 v144, 0, 32, vcc
	v_ldexp_f32 v143, v143, v144
	v_log_f32_e32 v143, v143
	v_add_f32_e32 v149, 1.0, v149
	v_rcp_f32_e32 v151, v149
	v_mul_f32_e32 v144, 0x3f317217, v143
	v_fma_f32 v144, v143, s24, -v144
	v_fmac_f32_e32 v144, 0x3377d1cf, v143
	v_fmac_f32_e32 v144, 0x3f317217, v143
	v_cmp_lt_f32_e64 s[4:5], |v143|, s15
	v_cndmask_b32_e64 v143, v143, v144, s[4:5]
	v_cndmask_b32_e32 v144, 0, v213, vcc
	v_mov_b32_e32 v150, v151
	v_sub_f32_e32 v143, v143, v144
	v_sub_f32_e32 v144, 1.0, v145
	v_mov_b32_e32 v149, v150
	v_fmac_f32_e32 v145, v149, v144
	v_cmp_gt_f32_e32 vcc, s14, v145
	s_add_i32 s2, s34, -1
	s_mul_hi_i32 s3, s2, 0x2200000
	v_cndmask_b32_e64 v144, 0, 32, vcc
	v_ldexp_f32 v144, v145, v144
	v_log_f32_e32 v144, v144
	s_mul_i32 s2, s2, 0x2200000
	s_add_u32 s2, s60, s2
	s_addc_u32 s3, s61, s3
	v_mul_f32_e32 v145, 0x3f317217, v144
	v_fma_f32 v145, v144, s24, -v145
	v_fmac_f32_e32 v145, 0x3377d1cf, v144
	v_fmac_f32_e32 v145, 0x3f317217, v144
	v_cmp_lt_f32_e64 s[4:5], |v144|, s15
	v_readlane_b32 s50, v252, 18
	v_readlane_b32 s51, v252, 19
	v_cndmask_b32_e64 v144, v144, v145, s[4:5]
	v_cndmask_b32_e32 v145, 0, v213, vcc
	v_sub_f32_e32 v144, v144, v145
	v_cvt_pk_f16_f32 v143, v143, v144
	v_lshlrev_b64 v[144:145], 11, v[146:147]
	v_lshl_add_u64 v[144:145], s[2:3], 0, v[144:145]
	v_lshl_add_u64 v[144:145], v[144:145], 0, v[0:1]
	v_readlane_b32 s52, v252, 20
	v_readlane_b32 s53, v252, 21
	v_readlane_b32 s54, v252, 22
	v_readlane_b32 s55, v252, 23
	v_readlane_b32 s56, v252, 24
	v_readlane_b32 s57, v252, 25
	v_readlane_b32 s58, v252, 26
	v_readlane_b32 s59, v252, 27
	v_readlane_b32 s62, v252, 30
	v_readlane_b32 s63, v252, 31
	global_store_dwordx2 v[144:145], v[142:143], off

.LBB0_1001:
	v_readlane_b32 s48, v252, 16
	s_waitcnt vmcnt(3)
	v_lshlrev_b64 v[144:145], 11, v[146:147]
	v_readlane_b32 s58, v252, 26
	v_readlane_b32 s59, v252, 27
	s_andn2_b64 vcc, exec, s[2:3]
	v_readlane_b32 s49, v252, 17
	v_lshl_add_u64 v[142:143], s[58:59], 0, v[144:145]
	v_readlane_b32 s50, v252, 18
	v_readlane_b32 s51, v252, 19
	v_readlane_b32 s52, v252, 20
	v_readlane_b32 s53, v252, 21
	v_readlane_b32 s54, v252, 22
	v_readlane_b32 s55, v252, 23
	v_readlane_b32 s56, v252, 24
	v_readlane_b32 s57, v252, 25
	v_readlane_b32 s60, v252, 28
	v_readlane_b32 s61, v252, 29
	v_readlane_b32 s62, v252, 30
	v_readlane_b32 s63, v252, 31
	s_cbranch_vccnz .LBB0_1003
	v_mul_f32_e32 v146, 0xbfb8aa3b, v14
	v_mul_f32_e32 v147, 0xbfb8aa3b, v15
	v_exp_f32_e32 v146, v146
	v_exp_f32_e32 v147, v147
	s_mov_b32 s4, 0x3db504f3
	v_pk_add_f32 v[146:147], v[146:147], 1.0 op_sel_hi:[1,0]
	s_nop 0
	v_rcp_f32_e32 v149, v147
	s_nop 0
	v_mul_f32_e32 v148, v15, v149
	v_mov_b32_e32 v147, v148
	v_rcp_f32_e32 v149, v146
	s_nop 0
	v_mul_f32_e32 v148, v14, v149
	v_mov_b32_e32 v146, v148
	v_mul_f32_e32 v148, 0xbfb8aa3b, v16
	v_mul_f32_e32 v149, 0xbfb8aa3b, v17
	v_exp_f32_e32 v148, v148
	v_exp_f32_e32 v149, v149
	v_pk_mul_f32 v[146:147], v[146:147], s[4:5] op_sel_hi:[1,0]
	v_pk_add_f32 v[148:149], v[148:149], 1.0 op_sel_hi:[1,0]
	s_nop 0
	v_rcp_f32_e32 v151, v149
	s_nop 0
	v_mul_f32_e32 v150, v17, v151
	v_mov_b32_e32 v149, v150
	v_rcp_f32_e32 v151, v148
	s_nop 0
	v_mul_f32_e32 v150, v16, v151
	v_mov_b32_e32 v148, v150
	v_pk_mul_f32 v[148:149], v[148:149], s[4:5] op_sel_hi:[1,0]
	v_bfe_u32 v152, v147, 16, 1
	v_bfe_u32 v150, v149, 16, 1
	v_bfe_u32 v151, v148, 16, 1
	v_bfe_u32 v153, v146, 16, 1
	v_add3_u32 v146, v146, v153, s0
	v_add3_u32 v152, v147, v152, s0
	v_add3_u32 v147, v148, v151, s0
	v_add3_u32 v148, v149, v150, s0
	v_perm_b32 v147, v148, v147, s19
	v_perm_b32 v146, v152, v146, s19
	v_lshl_add_u64 v[148:149], v[142:143], 0, v[0:1]
	global_store_dwordx2 v[148:149], v[146:147], off
.LBB0_1003:
	s_and_b64 vcc, exec, s[40:41]
	s_mov_b64 s[2:3], -1
	s_cbranch_vccnz .LBB0_1013
	s_cmp_lt_i32 s34, 3
	s_cbranch_scc1 .LBB0_1010
	s_cmp_eq_u32 s34, 3
	s_cbranch_scc1 .LBB0_1007
	v_mul_f32_e32 v146, 0xbfb8aa3b, v10
	v_mul_f32_e32 v147, 0xbfb8aa3b, v11
	v_exp_f32_e32 v146, v146
	v_exp_f32_e32 v147, v147
	v_readlane_b32 s48, v253, 4
	v_readlane_b32 s49, v253, 5
	v_readlane_b32 s50, v253, 6
	v_pk_add_f32 v[146:147], v[146:147], 1.0 op_sel_hi:[1,0]
	v_readlane_b32 s51, v253, 7
	v_rcp_f32_e32 v149, v146
	s_nop 0
	v_mul_f32_e32 v148, v10, v149
	v_rcp_f32_e32 v149, v147
	s_nop 0
	v_mul_f32_e32 v146, v11, v149
	v_mov_b32_e32 v149, v146
	v_mul_f32_e32 v146, 0xbfb8aa3b, v12
	v_mul_f32_e32 v147, 0xbfb8aa3b, v13
	v_exp_f32_e32 v146, v146
	v_exp_f32_e32 v147, v147
	s_nop 0
	v_pk_add_f32 v[146:147], v[146:147], 1.0 op_sel_hi:[1,0]
	s_nop 0
	v_rcp_f32_e32 v151, v146
	s_nop 0
	v_mul_f32_e32 v150, v12, v151
	v_mov_b32_e32 v146, v150
	v_rcp_f32_e32 v151, v147
	s_mov_b64 s[2:3], 0
	v_mul_f32_e32 v150, v13, v151
	v_mov_b32_e32 v147, v150
	v_bfe_u32 v150, v147, 16, 1
	v_bfe_u32 v151, v146, 16, 1
	v_bfe_u32 v152, v149, 16, 1
	v_bfe_u32 v153, v148, 16, 1
	v_add3_u32 v148, v148, v153, s0
	v_add3_u32 v149, v149, v152, s0
	v_add3_u32 v146, v146, v151, s0
	v_add3_u32 v147, v147, v150, s0
	v_perm_b32 v147, v147, v146, s19
	v_perm_b32 v146, v149, v148, s19
	v_lshl_add_u64 v[148:149], s[48:49], 0, v[144:145]
	v_lshl_add_u64 v[148:149], v[148:149], 0, v[0:1]
	global_store_dwordx2 v[148:149], v[146:147], off offset:32

.LBB0_1010:
	s_andn2_b64 vcc, exec, s[2:3]
	s_cbranch_vccnz .LBB0_1012
	v_mul_f32_e32 v147, 0xbfb8aa3b, v10
	v_exp_f32_e32 v147, v147
	s_waitcnt vmcnt(2)
	v_sub_f32_e32 v146, 1.0, v138
	s_mov_b32 s14, 0x800000
	s_mov_b32 s24, 0x3f317217
	v_add_f32_e32 v147, 1.0, v147
	v_rcp_f32_e32 v149, v147
	s_mov_b32 s15, 0x7f800000
	v_readlane_b32 s48, v252, 16
	v_readlane_b32 s60, v252, 28
	v_mov_b32_e32 v148, v149
	v_mov_b32_e32 v147, v148
	v_fma_f32 v138, v147, v146, v138
	v_mul_f32_e32 v147, 0xbfb8aa3b, v11
	v_cmp_gt_f32_e32 vcc, s14, v138
	v_exp_f32_e32 v147, v147
	v_readlane_b32 s61, v252, 29
	v_cndmask_b32_e64 v146, 0, 32, vcc
	v_ldexp_f32 v138, v138, v146
	v_log_f32_e32 v138, v138
	v_add_f32_e32 v147, 1.0, v147
	v_rcp_f32_e32 v149, v147
	v_mul_f32_e32 v146, 0x3f317217, v138
	v_fma_f32 v146, v138, s24, -v146
	v_fmac_f32_e32 v146, 0x3377d1cf, v138
	v_fmac_f32_e32 v146, 0x3f317217, v138
	v_cmp_lt_f32_e64 s[4:5], |v138|, s15
	v_cndmask_b32_e64 v138, v138, v146, s[4:5]
	v_cndmask_b32_e32 v146, 0, v213, vcc
	v_mov_b32_e32 v148, v149
	v_sub_f32_e32 v138, v138, v146
	v_sub_f32_e32 v146, 1.0, v139
	v_mov_b32_e32 v147, v148
	v_fma_f32 v139, v147, v146, v139
	v_mul_f32_e32 v147, 0xbfb8aa3b, v12
	v_cmp_gt_f32_e32 vcc, s14, v139
	v_exp_f32_e32 v147, v147
	v_readlane_b32 s49, v252, 17
	v_cndmask_b32_e64 v146, 0, 32, vcc
	v_ldexp_f32 v139, v139, v146
	v_log_f32_e32 v139, v139
	v_add_f32_e32 v147, 1.0, v147
	v_rcp_f32_e32 v149, v147
	v_mul_f32_e32 v146, 0x3f317217, v139
	v_fma_f32 v146, v139, s24, -v146
	v_fmac_f32_e32 v146, 0x3377d1cf, v139
	v_fmac_f32_e32 v146, 0x3f317217, v139
	v_cmp_lt_f32_e64 s[4:5], |v139|, s15
	v_cndmask_b32_e64 v139, v139, v146, s[4:5]
	v_cndmask_b32_e32 v146, 0, v213, vcc
	v_mov_b32_e32 v148, v149
	v_sub_f32_e32 v146, v139, v146
	v_sub_f32_e32 v139, 1.0, v140
	v_mov_b32_e32 v147, v148
	v_fma_f32 v139, v147, v139, v140
	v_mul_f32_e32 v147, 0xbfb8aa3b, v13
	v_cmp_gt_f32_e32 vcc, s14, v139
	v_exp_f32_e32 v147, v147
	v_cvt_pk_f16_f32 v138, v138, v146
	v_cndmask_b32_e64 v140, 0, 32, vcc
	v_ldexp_f32 v139, v139, v140
	v_log_f32_e32 v139, v139
	v_add_f32_e32 v147, 1.0, v147
	v_rcp_f32_e32 v149, v147
	v_mul_f32_e32 v140, 0x3f317217, v139
	v_fma_f32 v140, v139, s24, -v140
	v_fmac_f32_e32 v140, 0x3377d1cf, v139
	v_fmac_f32_e32 v140, 0x3f317217, v139
	v_cmp_lt_f32_e64 s[4:5], |v139|, s15
	v_cndmask_b32_e64 v139, v139, v140, s[4:5]
	v_cndmask_b32_e32 v140, 0, v213, vcc
	v_mov_b32_e32 v148, v149
	v_sub_f32_e32 v139, v139, v140
	v_sub_f32_e32 v140, 1.0, v141
	v_mov_b32_e32 v147, v148
	v_fmac_f32_e32 v141, v147, v140
	v_cmp_gt_f32_e32 vcc, s14, v141
	s_add_i32 s2, s34, -1
	s_mul_hi_i32 s3, s2, 0x2200000
	v_cndmask_b32_e64 v140, 0, 32, vcc
	v_ldexp_f32 v140, v141, v140
	v_log_f32_e32 v140, v140
	s_mul_i32 s2, s2, 0x2200000
	s_add_u32 s2, s60, s2
	s_addc_u32 s3, s61, s3
	v_mul_f32_e32 v141, 0x3f317217, v140
	v_fma_f32 v141, v140, s24, -v141
	v_fmac_f32_e32 v141, 0x3377d1cf, v140
	v_fmac_f32_e32 v141, 0x3f317217, v140
	v_cmp_lt_f32_e64 s[4:5], |v140|, s15
	v_readlane_b32 s50, v252, 18
	v_readlane_b32 s51, v252, 19
	v_cndmask_b32_e64 v140, v140, v141, s[4:5]
	v_cndmask_b32_e32 v141, 0, v213, vcc
	v_sub_f32_e32 v140, v140, v141
	v_cvt_pk_f16_f32 v139, v139, v140
	v_lshl_add_u64 v[140:141], s[2:3], 0, v[144:145]
	v_lshl_add_u64 v[140:141], v[140:141], 0, v[0:1]
	v_readlane_b32 s52, v252, 20
	v_readlane_b32 s53, v252, 21
	v_readlane_b32 s54, v252, 22
	v_readlane_b32 s55, v252, 23
	v_readlane_b32 s56, v252, 24
	v_readlane_b32 s57, v252, 25
	v_readlane_b32 s58, v252, 26
	v_readlane_b32 s59, v252, 27
	v_readlane_b32 s62, v252, 30
	v_readlane_b32 s63, v252, 31
	global_store_dwordx2 v[140:141], v[138:139], off offset:32

.LBB0_1013:
	s_andn2_b64 vcc, exec, s[2:3]
	s_cbranch_vccnz .LBB0_1015
	s_waitcnt vmcnt(2)
	v_mul_f32_e32 v138, 0xbfb8aa3b, v10
	v_mul_f32_e32 v139, 0xbfb8aa3b, v11
	v_exp_f32_e32 v138, v138
	v_exp_f32_e32 v139, v139
	s_mov_b32 s4, 0x3db504f3
	v_pk_add_f32 v[138:139], v[138:139], 1.0 op_sel_hi:[1,0]
	s_nop 0
	v_rcp_f32_e32 v141, v139
	s_nop 0
	v_mul_f32_e32 v140, v11, v141
	v_mov_b32_e32 v139, v140
	v_rcp_f32_e32 v141, v138
	s_nop 0
	v_mul_f32_e32 v140, v10, v141
	v_mov_b32_e32 v138, v140
	v_mul_f32_e32 v140, 0xbfb8aa3b, v12
	v_mul_f32_e32 v141, 0xbfb8aa3b, v13
	v_exp_f32_e32 v140, v140
	v_exp_f32_e32 v141, v141
	v_pk_mul_f32 v[138:139], v[138:139], s[4:5] op_sel_hi:[1,0]
	v_pk_add_f32 v[140:141], v[140:141], 1.0 op_sel_hi:[1,0]
	s_nop 0
	v_rcp_f32_e32 v147, v141
	s_nop 0
	v_mul_f32_e32 v146, v13, v147
	v_mov_b32_e32 v141, v146
	v_rcp_f32_e32 v147, v140
	s_nop 0
	v_mul_f32_e32 v146, v12, v147
	v_mov_b32_e32 v140, v146
	v_pk_mul_f32 v[140:141], v[140:141], s[4:5] op_sel_hi:[1,0]
	v_bfe_u32 v148, v139, 16, 1
	v_bfe_u32 v146, v141, 16, 1
	v_bfe_u32 v147, v140, 16, 1
	v_bfe_u32 v149, v138, 16, 1
	v_add3_u32 v138, v138, v149, s0
	v_add3_u32 v148, v139, v148, s0
	v_add3_u32 v139, v140, v147, s0
	v_add3_u32 v140, v141, v146, s0
	v_perm_b32 v139, v140, v139, s19
	v_perm_b32 v138, v148, v138, s19
	v_lshl_add_u64 v[140:141], v[142:143], 0, v[0:1]
	global_store_dwordx2 v[140:141], v[138:139], off offset:32
.LBB0_1015:
	s_and_b64 vcc, exec, s[40:41]
	s_mov_b64 s[2:3], -1
	s_cbranch_vccnz .LBB0_1025
	s_cmp_lt_i32 s34, 3
	s_cbranch_scc1 .LBB0_1022
	s_cmp_eq_u32 s34, 3
	s_cbranch_scc1 .LBB0_1019
	s_waitcnt vmcnt(2)
	v_mul_f32_e32 v138, 0xbfb8aa3b, v6
	v_mul_f32_e32 v139, 0xbfb8aa3b, v7
	v_exp_f32_e32 v138, v138
	v_exp_f32_e32 v139, v139
	v_readlane_b32 s48, v253, 4
	v_readlane_b32 s49, v253, 5
	v_readlane_b32 s50, v253, 6
	v_pk_add_f32 v[138:139], v[138:139], 1.0 op_sel_hi:[1,0]
	v_readlane_b32 s51, v253, 7
	v_rcp_f32_e32 v141, v138
	s_nop 0
	v_mul_f32_e32 v140, v6, v141
	v_rcp_f32_e32 v141, v139
	s_nop 0
	v_mul_f32_e32 v138, v7, v141
	v_mov_b32_e32 v141, v138
	v_mul_f32_e32 v138, 0xbfb8aa3b, v8
	v_mul_f32_e32 v139, 0xbfb8aa3b, v9
	v_exp_f32_e32 v138, v138
	v_exp_f32_e32 v139, v139
	s_nop 0
	v_pk_add_f32 v[138:139], v[138:139], 1.0 op_sel_hi:[1,0]
	s_nop 0
	v_rcp_f32_e32 v147, v138
	s_nop 0
	v_mul_f32_e32 v146, v8, v147
	v_mov_b32_e32 v138, v146
	v_rcp_f32_e32 v147, v139
	s_mov_b64 s[2:3], 0
	v_mul_f32_e32 v146, v9, v147
	v_mov_b32_e32 v139, v146
	v_bfe_u32 v146, v139, 16, 1
	v_bfe_u32 v147, v138, 16, 1
	v_bfe_u32 v148, v141, 16, 1
	v_bfe_u32 v149, v140, 16, 1
	v_add3_u32 v140, v140, v149, s0
	v_add3_u32 v141, v141, v148, s0
	v_add3_u32 v138, v138, v147, s0
	v_add3_u32 v139, v139, v146, s0
	v_perm_b32 v139, v139, v138, s19
	v_perm_b32 v138, v141, v140, s19
	v_lshl_add_u64 v[140:141], s[48:49], 0, v[144:145]
	v_lshl_add_u64 v[140:141], v[140:141], 0, v[0:1]
	global_store_dwordx2 v[140:141], v[138:139], off offset:64

.LBB0_1022:
	s_andn2_b64 vcc, exec, s[2:3]
	s_cbranch_vccnz .LBB0_1024
	s_waitcnt vmcnt(2)
	v_mul_f32_e32 v139, 0xbfb8aa3b, v6
	v_exp_f32_e32 v139, v139
	s_waitcnt vmcnt(1)
	v_sub_f32_e32 v138, 1.0, v134
	s_mov_b32 s14, 0x800000
	s_mov_b32 s24, 0x3f317217
	v_add_f32_e32 v139, 1.0, v139
	v_rcp_f32_e32 v141, v139
	s_mov_b32 s15, 0x7f800000
	v_readlane_b32 s48, v252, 16
	v_readlane_b32 s60, v252, 28
	v_mov_b32_e32 v140, v141
	v_mov_b32_e32 v139, v140
	v_fma_f32 v134, v139, v138, v134
	v_mul_f32_e32 v139, 0xbfb8aa3b, v7
	v_cmp_gt_f32_e32 vcc, s14, v134
	v_exp_f32_e32 v139, v139
	v_readlane_b32 s61, v252, 29
	v_cndmask_b32_e64 v138, 0, 32, vcc
	v_ldexp_f32 v134, v134, v138
	v_log_f32_e32 v134, v134
	v_add_f32_e32 v139, 1.0, v139
	v_rcp_f32_e32 v141, v139
	v_mul_f32_e32 v138, 0x3f317217, v134
	v_fma_f32 v138, v134, s24, -v138
	v_fmac_f32_e32 v138, 0x3377d1cf, v134
	v_fmac_f32_e32 v138, 0x3f317217, v134
	v_cmp_lt_f32_e64 s[4:5], |v134|, s15
	v_cndmask_b32_e64 v134, v134, v138, s[4:5]
	v_cndmask_b32_e32 v138, 0, v213, vcc
	v_mov_b32_e32 v140, v141
	v_sub_f32_e32 v134, v134, v138
	v_sub_f32_e32 v138, 1.0, v135
	v_mov_b32_e32 v139, v140
	v_fma_f32 v135, v139, v138, v135
	v_mul_f32_e32 v139, 0xbfb8aa3b, v8
	v_cmp_gt_f32_e32 vcc, s14, v135
	v_exp_f32_e32 v139, v139
	v_readlane_b32 s49, v252, 17
	v_cndmask_b32_e64 v138, 0, 32, vcc
	v_ldexp_f32 v135, v135, v138
	v_log_f32_e32 v135, v135
	v_add_f32_e32 v139, 1.0, v139
	v_rcp_f32_e32 v141, v139
	v_mul_f32_e32 v138, 0x3f317217, v135
	v_fma_f32 v138, v135, s24, -v138
	v_fmac_f32_e32 v138, 0x3377d1cf, v135
	v_fmac_f32_e32 v138, 0x3f317217, v135
	v_cmp_lt_f32_e64 s[4:5], |v135|, s15
	v_cndmask_b32_e64 v135, v135, v138, s[4:5]
	v_cndmask_b32_e32 v138, 0, v213, vcc
	v_mov_b32_e32 v140, v141
	v_sub_f32_e32 v138, v135, v138
	v_sub_f32_e32 v135, 1.0, v136
	v_mov_b32_e32 v139, v140
	v_fma_f32 v135, v139, v135, v136
	v_mul_f32_e32 v139, 0xbfb8aa3b, v9
	v_cmp_gt_f32_e32 vcc, s14, v135
	v_exp_f32_e32 v139, v139
	v_cvt_pk_f16_f32 v134, v134, v138
	v_cndmask_b32_e64 v136, 0, 32, vcc
	v_ldexp_f32 v135, v135, v136
	v_log_f32_e32 v135, v135
	v_add_f32_e32 v139, 1.0, v139
	v_rcp_f32_e32 v141, v139
	v_mul_f32_e32 v136, 0x3f317217, v135
	v_fma_f32 v136, v135, s24, -v136
	v_fmac_f32_e32 v136, 0x3377d1cf, v135
	v_fmac_f32_e32 v136, 0x3f317217, v135
	v_cmp_lt_f32_e64 s[4:5], |v135|, s15
	v_cndmask_b32_e64 v135, v135, v136, s[4:5]
	v_cndmask_b32_e32 v136, 0, v213, vcc
	v_mov_b32_e32 v140, v141
	v_sub_f32_e32 v135, v135, v136
	v_sub_f32_e32 v136, 1.0, v137
	v_mov_b32_e32 v139, v140
	v_fmac_f32_e32 v137, v139, v136
	v_cmp_gt_f32_e32 vcc, s14, v137
	s_add_i32 s2, s34, -1
	s_mul_hi_i32 s3, s2, 0x2200000
	v_cndmask_b32_e64 v136, 0, 32, vcc
	v_ldexp_f32 v136, v137, v136
	v_log_f32_e32 v136, v136
	s_mul_i32 s2, s2, 0x2200000
	s_add_u32 s2, s60, s2
	s_addc_u32 s3, s61, s3
	v_mul_f32_e32 v137, 0x3f317217, v136
	v_fma_f32 v137, v136, s24, -v137
	v_fmac_f32_e32 v137, 0x3377d1cf, v136
	v_fmac_f32_e32 v137, 0x3f317217, v136
	v_cmp_lt_f32_e64 s[4:5], |v136|, s15
	v_readlane_b32 s50, v252, 18
	v_readlane_b32 s51, v252, 19
	v_cndmask_b32_e64 v136, v136, v137, s[4:5]
	v_cndmask_b32_e32 v137, 0, v213, vcc
	v_sub_f32_e32 v136, v136, v137
	v_cvt_pk_f16_f32 v135, v135, v136
	v_lshl_add_u64 v[136:137], s[2:3], 0, v[144:145]
	v_lshl_add_u64 v[136:137], v[136:137], 0, v[0:1]
	v_readlane_b32 s52, v252, 20
	v_readlane_b32 s53, v252, 21
	v_readlane_b32 s54, v252, 22
	v_readlane_b32 s55, v252, 23
	v_readlane_b32 s56, v252, 24
	v_readlane_b32 s57, v252, 25
	v_readlane_b32 s58, v252, 26
	v_readlane_b32 s59, v252, 27
	v_readlane_b32 s62, v252, 30
	v_readlane_b32 s63, v252, 31
	global_store_dwordx2 v[136:137], v[134:135], off offset:64

.LBB0_1025:
	s_andn2_b64 vcc, exec, s[2:3]
	s_cbranch_vccnz .LBB0_1027
	s_waitcnt vmcnt(1)
	v_mul_f32_e32 v134, 0xbfb8aa3b, v6
	v_mul_f32_e32 v135, 0xbfb8aa3b, v7
	v_exp_f32_e32 v134, v134
	v_exp_f32_e32 v135, v135
	s_mov_b32 s4, 0x3db504f3
	v_pk_add_f32 v[134:135], v[134:135], 1.0 op_sel_hi:[1,0]
	s_nop 0
	v_rcp_f32_e32 v137, v135
	s_nop 0
	v_mul_f32_e32 v136, v7, v137
	v_mov_b32_e32 v135, v136
	v_rcp_f32_e32 v137, v134
	s_nop 0
	v_mul_f32_e32 v136, v6, v137
	v_mov_b32_e32 v134, v136
	v_mul_f32_e32 v136, 0xbfb8aa3b, v8
	v_mul_f32_e32 v137, 0xbfb8aa3b, v9
	v_exp_f32_e32 v136, v136
	v_exp_f32_e32 v137, v137
	v_pk_mul_f32 v[134:135], v[134:135], s[4:5] op_sel_hi:[1,0]
	v_pk_add_f32 v[136:137], v[136:137], 1.0 op_sel_hi:[1,0]
	s_nop 0
	v_rcp_f32_e32 v139, v137
	s_nop 0
	v_mul_f32_e32 v138, v9, v139
	v_mov_b32_e32 v137, v138
	v_rcp_f32_e32 v139, v136
	s_nop 0
	v_mul_f32_e32 v138, v8, v139
	v_mov_b32_e32 v136, v138
	v_pk_mul_f32 v[136:137], v[136:137], s[4:5] op_sel_hi:[1,0]
	v_bfe_u32 v140, v135, 16, 1
	v_bfe_u32 v138, v137, 16, 1
	v_bfe_u32 v139, v136, 16, 1
	v_bfe_u32 v141, v134, 16, 1
	v_add3_u32 v134, v134, v141, s0
	v_add3_u32 v140, v135, v140, s0
	v_add3_u32 v135, v136, v139, s0
	v_add3_u32 v136, v137, v138, s0
	v_perm_b32 v135, v136, v135, s19
	v_perm_b32 v134, v140, v134, s19
	v_lshl_add_u64 v[136:137], v[142:143], 0, v[0:1]
	global_store_dwordx2 v[136:137], v[134:135], off offset:64
.LBB0_1027:
	s_and_b64 vcc, exec, s[40:41]
	s_mov_b64 s[2:3], -1
	s_cbranch_vccnz .LBB0_1037
	s_cmp_lt_i32 s34, 3
	s_cbranch_scc1 .LBB0_1034
	s_cmp_eq_u32 s34, 3
	s_cbranch_scc1 .LBB0_1031
	s_waitcnt vmcnt(1)
	v_mul_f32_e32 v134, 0xbfb8aa3b, v2
	v_mul_f32_e32 v135, 0xbfb8aa3b, v3
	v_exp_f32_e32 v134, v134
	v_exp_f32_e32 v135, v135
	v_readlane_b32 s48, v253, 4
	v_readlane_b32 s49, v253, 5
	v_readlane_b32 s50, v253, 6
	v_pk_add_f32 v[134:135], v[134:135], 1.0 op_sel_hi:[1,0]
	v_readlane_b32 s51, v253, 7
	v_rcp_f32_e32 v137, v134
	s_nop 0
	v_mul_f32_e32 v136, v2, v137
	v_rcp_f32_e32 v137, v135
	s_nop 0
	v_mul_f32_e32 v134, v3, v137
	v_mov_b32_e32 v137, v134
	v_mul_f32_e32 v134, 0xbfb8aa3b, v4
	v_mul_f32_e32 v135, 0xbfb8aa3b, v5
	v_exp_f32_e32 v134, v134
	v_exp_f32_e32 v135, v135
	s_nop 0
	v_pk_add_f32 v[134:135], v[134:135], 1.0 op_sel_hi:[1,0]
	s_nop 0
	v_rcp_f32_e32 v139, v134
	s_nop 0
	v_mul_f32_e32 v138, v4, v139
	v_mov_b32_e32 v134, v138
	v_rcp_f32_e32 v139, v135
	s_mov_b64 s[2:3], 0
	v_mul_f32_e32 v138, v5, v139
	v_mov_b32_e32 v135, v138
	v_bfe_u32 v138, v135, 16, 1
	v_bfe_u32 v139, v134, 16, 1
	v_bfe_u32 v140, v137, 16, 1
	v_bfe_u32 v141, v136, 16, 1
	v_add3_u32 v136, v136, v141, s0
	v_add3_u32 v137, v137, v140, s0
	v_add3_u32 v134, v134, v139, s0
	v_add3_u32 v135, v135, v138, s0
	v_perm_b32 v135, v135, v134, s19
	v_perm_b32 v134, v137, v136, s19
	v_lshl_add_u64 v[136:137], s[48:49], 0, v[144:145]
	v_lshl_add_u64 v[136:137], v[136:137], 0, v[0:1]
	global_store_dwordx2 v[136:137], v[134:135], off offset:96

.LBB0_1034:
	s_andn2_b64 vcc, exec, s[2:3]
	s_cbranch_vccnz .LBB0_1036
	s_waitcnt vmcnt(1)
	v_mul_f32_e32 v135, 0xbfb8aa3b, v2
	v_exp_f32_e32 v135, v135
	s_waitcnt vmcnt(0)
	v_sub_f32_e32 v134, 1.0, v130
	s_mov_b32 s14, 0x800000
	s_mov_b32 s24, 0x3f317217
	v_add_f32_e32 v135, 1.0, v135
	v_rcp_f32_e32 v137, v135
	s_mov_b32 s15, 0x7f800000
	v_readlane_b32 s48, v252, 16
	v_readlane_b32 s60, v252, 28
	v_mov_b32_e32 v136, v137
	v_mov_b32_e32 v135, v136
	v_fma_f32 v130, v135, v134, v130
	v_mul_f32_e32 v135, 0xbfb8aa3b, v3
	v_cmp_gt_f32_e32 vcc, s14, v130
	v_exp_f32_e32 v135, v135
	v_readlane_b32 s61, v252, 29
	v_cndmask_b32_e64 v134, 0, 32, vcc
	v_ldexp_f32 v130, v130, v134
	v_log_f32_e32 v130, v130
	v_add_f32_e32 v135, 1.0, v135
	v_rcp_f32_e32 v137, v135
	v_mul_f32_e32 v134, 0x3f317217, v130
	v_fma_f32 v134, v130, s24, -v134
	v_fmac_f32_e32 v134, 0x3377d1cf, v130
	v_fmac_f32_e32 v134, 0x3f317217, v130
	v_cmp_lt_f32_e64 s[4:5], |v130|, s15
	v_cndmask_b32_e64 v130, v130, v134, s[4:5]
	v_cndmask_b32_e32 v134, 0, v213, vcc
	v_mov_b32_e32 v136, v137
	v_sub_f32_e32 v130, v130, v134
	v_sub_f32_e32 v134, 1.0, v131
	v_mov_b32_e32 v135, v136
	v_fma_f32 v131, v135, v134, v131
	v_mul_f32_e32 v135, 0xbfb8aa3b, v4
	v_cmp_gt_f32_e32 vcc, s14, v131
	v_exp_f32_e32 v135, v135
	v_readlane_b32 s49, v252, 17
	v_cndmask_b32_e64 v134, 0, 32, vcc
	v_ldexp_f32 v131, v131, v134
	v_log_f32_e32 v131, v131
	v_add_f32_e32 v135, 1.0, v135
	v_rcp_f32_e32 v137, v135
	v_mul_f32_e32 v134, 0x3f317217, v131
	v_fma_f32 v134, v131, s24, -v134
	v_fmac_f32_e32 v134, 0x3377d1cf, v131
	v_fmac_f32_e32 v134, 0x3f317217, v131
	v_cmp_lt_f32_e64 s[4:5], |v131|, s15
	v_cndmask_b32_e64 v131, v131, v134, s[4:5]
	v_cndmask_b32_e32 v134, 0, v213, vcc
	v_mov_b32_e32 v136, v137
	v_sub_f32_e32 v134, v131, v134
	v_sub_f32_e32 v131, 1.0, v132
	v_mov_b32_e32 v135, v136
	v_fma_f32 v131, v135, v131, v132
	v_mul_f32_e32 v135, 0xbfb8aa3b, v5
	v_cmp_gt_f32_e32 vcc, s14, v131
	v_exp_f32_e32 v135, v135
	v_cvt_pk_f16_f32 v130, v130, v134
	v_cndmask_b32_e64 v132, 0, 32, vcc
	v_ldexp_f32 v131, v131, v132
	v_log_f32_e32 v131, v131
	v_add_f32_e32 v135, 1.0, v135
	v_rcp_f32_e32 v137, v135
	v_mul_f32_e32 v132, 0x3f317217, v131
	v_fma_f32 v132, v131, s24, -v132
	v_fmac_f32_e32 v132, 0x3377d1cf, v131
	v_fmac_f32_e32 v132, 0x3f317217, v131
	v_cmp_lt_f32_e64 s[4:5], |v131|, s15
	v_cndmask_b32_e64 v131, v131, v132, s[4:5]
	v_cndmask_b32_e32 v132, 0, v213, vcc
	v_mov_b32_e32 v136, v137
	v_sub_f32_e32 v131, v131, v132
	v_sub_f32_e32 v132, 1.0, v133
	v_mov_b32_e32 v135, v136
	v_fmac_f32_e32 v133, v135, v132
	v_cmp_gt_f32_e32 vcc, s14, v133
	s_add_i32 s2, s34, -1
	s_mul_hi_i32 s3, s2, 0x2200000
	v_cndmask_b32_e64 v132, 0, 32, vcc
	v_ldexp_f32 v132, v133, v132
	v_log_f32_e32 v132, v132
	s_mul_i32 s2, s2, 0x2200000
	s_add_u32 s2, s60, s2
	s_addc_u32 s3, s61, s3
	v_mul_f32_e32 v133, 0x3f317217, v132
	v_fma_f32 v133, v132, s24, -v133
	v_fmac_f32_e32 v133, 0x3377d1cf, v132
	v_fmac_f32_e32 v133, 0x3f317217, v132
	v_cmp_lt_f32_e64 s[4:5], |v132|, s15
	v_readlane_b32 s50, v252, 18
	v_readlane_b32 s51, v252, 19
	v_cndmask_b32_e64 v132, v132, v133, s[4:5]
	v_cndmask_b32_e32 v133, 0, v213, vcc
	v_sub_f32_e32 v132, v132, v133
	v_cvt_pk_f16_f32 v131, v131, v132
	v_lshl_add_u64 v[132:133], s[2:3], 0, v[144:145]
	v_lshl_add_u64 v[132:133], v[132:133], 0, v[0:1]
	v_readlane_b32 s52, v252, 20
	v_readlane_b32 s53, v252, 21
	v_readlane_b32 s54, v252, 22
	v_readlane_b32 s55, v252, 23
	v_readlane_b32 s56, v252, 24
	v_readlane_b32 s57, v252, 25
	v_readlane_b32 s58, v252, 26
	v_readlane_b32 s59, v252, 27
	v_readlane_b32 s62, v252, 30
	v_readlane_b32 s63, v252, 31
	global_store_dwordx2 v[132:133], v[130:131], off offset:96

.LBB0_1037:
	s_andn2_b64 vcc, exec, s[2:3]
	s_cbranch_vccnz .LBB0_1039
	s_waitcnt vmcnt(0)
	v_mul_f32_e32 v130, 0xbfb8aa3b, v2
	v_mul_f32_e32 v131, 0xbfb8aa3b, v3
	v_exp_f32_e32 v130, v130
	v_exp_f32_e32 v131, v131
	s_mov_b32 s4, 0x3db504f3
	v_pk_add_f32 v[130:131], v[130:131], 1.0 op_sel_hi:[1,0]
	s_nop 0
	v_rcp_f32_e32 v133, v131
	s_nop 0
	v_mul_f32_e32 v132, v3, v133
	v_mov_b32_e32 v131, v132
	v_rcp_f32_e32 v133, v130
	s_nop 0
	v_mul_f32_e32 v132, v2, v133
	v_mov_b32_e32 v130, v132
	v_mul_f32_e32 v132, 0xbfb8aa3b, v4
	v_mul_f32_e32 v133, 0xbfb8aa3b, v5
	v_exp_f32_e32 v132, v132
	v_exp_f32_e32 v133, v133
	v_pk_mul_f32 v[130:131], v[130:131], s[4:5] op_sel_hi:[1,0]
	v_pk_add_f32 v[132:133], v[132:133], 1.0 op_sel_hi:[1,0]
	s_nop 0
	v_rcp_f32_e32 v135, v133
	s_nop 0
	v_mul_f32_e32 v134, v5, v135
	v_mov_b32_e32 v133, v134
	v_rcp_f32_e32 v135, v132
	s_nop 0
	v_mul_f32_e32 v134, v4, v135
	v_mov_b32_e32 v132, v134
	v_pk_mul_f32 v[132:133], v[132:133], s[4:5] op_sel_hi:[1,0]
	v_bfe_u32 v136, v131, 16, 1
	v_bfe_u32 v134, v133, 16, 1
	v_bfe_u32 v135, v132, 16, 1
	v_bfe_u32 v137, v130, 16, 1
	v_add3_u32 v130, v130, v137, s0
	v_add3_u32 v136, v131, v136, s0
	v_add3_u32 v131, v132, v135, s0
	v_add3_u32 v132, v133, v134, s0
	v_perm_b32 v131, v132, v131, s19
	v_perm_b32 v130, v136, v130, s19
	v_lshl_add_u64 v[132:133], v[142:143], 0, v[0:1]
	global_store_dwordx2 v[132:133], v[130:131], off offset:96

.LBB0_1041:
	s_andn2_b64 vcc, exec, s[2:3]
	s_cbranch_vccnz .LBB0_1046
	s_cmp_gt_i32 s44, 4
	s_mov_b64 s[2:3], -1
	s_cbranch_scc0 .LBB0_1044
	s_mul_hi_i32 s3, s45, 0x78787879
	s_lshr_b32 s4, s3, 31
	s_ashr_i32 s3, s3, 11
	s_add_i32 s3, s3, s4
	s_mul_i32 s4, s3, 0xffffef00
	s_add_i32 s4, s4, s45
	s_cmpk_gt_i32 s4, 0xff
	s_mul_i32 s2, s28, 9
	s_cselect_b32 s3, s3, 8
	s_add_i32 s2, s3, s2
	v_readlane_b32 s48, v254, 55
	s_mul_hi_i32 s3, s2, 0x6000
	s_mulk_i32 s2, 0x6000
	v_readlane_b32 s56, v254, 63
	v_readlane_b32 s57, v255, 0
	s_add_u32 s4, s56, s2
	s_mul_i32 s34, s29, 0xc00
	s_addc_u32 s5, s57, s3
	s_lshl_b64 s[2:3], s[34:35], 2
	s_add_u32 s4, s4, s2
	s_addc_u32 s5, s5, s3
	s_lshl_b32 s2, s47, 7
	s_ashr_i32 s3, s2, 31
	s_lshl_b64 s[2:3], s[2:3], 2
	s_add_u32 s4, s4, s2
	s_addc_u32 s5, s5, s3
	v_lshlrev_b32_e32 v0, 7, v174
	s_waitcnt vmcnt(0)
	v_lshl_add_u64 v[130:131], s[4:5], 0, v[0:1]
	v_lshlrev_b32_e32 v138, 4, v223
	v_mov_b32_e32 v139, v1
	v_readlane_b32 s52, v254, 59
	v_lshl_add_u64 v[130:131], v[130:131], 0, v[138:139]
	s_mov_b64 s[4:5], 0x2000
	v_readlane_b32 s53, v254, 60
	v_lshl_add_u64 v[134:135], v[130:131], 0, s[4:5]
	s_add_u32 s4, s52, s2
	v_add_u32_e32 v140, s45, v225
	s_addc_u32 s5, s53, s3
	v_lshl_add_u64 v[132:133], s[4:5], 0, v[0:1]
	v_ashrrev_i32_e32 v141, 31, v140
	v_lshl_add_u64 v[142:143], v[132:133], 0, v[138:139]
	v_lshlrev_b64 v[132:133], 12, v[140:141]
	v_lshl_add_u64 v[182:183], v[142:143], 0, v[132:133]
	v_lshl_add_u64 v[132:133], s[52:53], 0, v[132:133]
	v_lshl_add_u64 v[132:133], v[132:133], 0, s[2:3]
	v_lshl_add_u64 v[132:133], v[132:133], 0, v[0:1]
	v_lshl_add_u64 v[174:175], v[132:133], 0, v[138:139]
	v_mul_f32_e32 v132, 0xbfb8aa3b, v114
	v_exp_f32_e32 v180, v132
	v_mul_f32_e32 v132, 0xbfb8aa3b, v115
	v_exp_f32_e32 v181, v132
	v_mul_f32_e32 v132, 0xbfb8aa3b, v116
	v_exp_f32_e32 v178, v132
	v_mul_f32_e32 v132, 0xbfb8aa3b, v117
	v_exp_f32_e32 v179, v132
	v_mul_f32_e32 v132, 0xbfb8aa3b, v102
	v_or_b32_e32 v136, 16, v140
	v_exp_f32_e32 v176, v132
	v_mul_f32_e32 v132, 0xbfb8aa3b, v103
	v_ashrrev_i32_e32 v137, 31, v136
	v_exp_f32_e32 v177, v132
	v_mul_f32_e32 v132, 0xbfb8aa3b, v104
	v_lshlrev_b64 v[136:137], 12, v[136:137]
	v_exp_f32_e32 v172, v132
	v_mul_f32_e32 v132, 0xbfb8aa3b, v105
	v_exp_f32_e32 v173, v132
	v_lshl_add_u64 v[132:133], s[52:53], 0, v[136:137]
	v_lshl_add_u64 v[132:133], v[132:133], 0, s[2:3]
	v_lshl_add_u64 v[132:133], v[132:133], 0, v[0:1]
	v_lshl_add_u64 v[164:165], v[132:133], 0, v[138:139]
	v_mul_f32_e32 v132, 0xbfb8aa3b, v98
	v_exp_f32_e32 v168, v132
	v_mul_f32_e32 v132, 0xbfb8aa3b, v99
	v_exp_f32_e32 v169, v132
	v_mul_f32_e32 v132, 0xbfb8aa3b, v100
	v_exp_f32_e32 v166, v132
	v_mul_f32_e32 v132, 0xbfb8aa3b, v101
	v_exp_f32_e32 v167, v132
	v_or_b32_e32 v132, 32, v140
	v_ashrrev_i32_e32 v133, 31, v132
	v_lshlrev_b64 v[160:161], 12, v[132:133]
	v_or_b32_e32 v132, 48, v140
	v_ashrrev_i32_e32 v133, 31, v132
	v_lshlrev_b64 v[158:159], 12, v[132:133]
	v_mul_f32_e32 v132, 0xbfb8aa3b, v86
	v_exp_f32_e32 v156, v132
	v_mul_f32_e32 v132, 0xbfb8aa3b, v87
	v_exp_f32_e32 v157, v132
	v_mul_f32_e32 v132, 0xbfb8aa3b, v6
	v_mul_f32_e32 v133, 0xbfb8aa3b, v7
	v_exp_f32_e32 v132, v132
	v_exp_f32_e32 v133, v133
	v_mul_f32_e32 v141, 0xbfb8aa3b, v118
	v_exp_f32_e32 v186, v141
	v_mul_f32_e32 v141, 0xbfb8aa3b, v119
	v_exp_f32_e32 v187, v141
	v_mul_f32_e32 v141, 0xbfb8aa3b, v120
	v_exp_f32_e32 v184, v141
	v_mul_f32_e32 v141, 0xbfb8aa3b, v121
	v_pk_add_f32 v[144:145], v[132:133], 1.0 op_sel_hi:[1,0]
	v_exp_f32_e32 v185, v141
	v_rcp_f32_e32 v146, v145
	v_add_co_u32_e32 v130, vcc, s25, v130
	v_lshl_add_u64 v[170:171], v[142:143], 0, v[136:137]
	s_nop 0
	v_addc_co_u32_e32 v131, vcc, 0, v131, vcc
	v_rcp_f32_e32 v150, v144
	v_mul_f32_e32 v136, 0xbfb8aa3b, v8
	v_mul_f32_e32 v137, 0xbfb8aa3b, v9
	v_exp_f32_e32 v136, v136
	v_exp_f32_e32 v137, v137
	v_mov_b32_e32 v141, v146
	v_pk_add_f32 v[146:147], v[136:137], 1.0 op_sel_hi:[1,0]
	v_rcp_f32_e32 v137, v147
	v_mov_b32_e32 v226, v150
	global_load_dwordx4 v[130:133], v[130:131], off
	v_pk_add_f32 v[236:237], v[186:187], 1.0 op_sel_hi:[1,0]
	v_rcp_f32_e32 v151, v146
	v_mov_b32_e32 v227, v137
	v_mul_f32_e32 v136, 0xbfb8aa3b, v2
	v_mul_f32_e32 v137, 0xbfb8aa3b, v3
	v_exp_f32_e32 v136, v136
	v_exp_f32_e32 v137, v137
	v_mov_b32_e32 v228, v151
	v_mul_f32_e32 v148, 0xbfb8aa3b, v4
	v_exp_f32_e32 v150, v148
	v_pk_add_f32 v[148:149], v[136:137], 1.0 op_sel_hi:[1,0]
	v_mul_f32_e32 v136, 0xbfb8aa3b, v5
	v_rcp_f32_e32 v230, v149
	v_exp_f32_e32 v151, v136
	global_load_dwordx4 v[200:203], v[182:183], off
	v_rcp_f32_e32 v234, v148
	v_mov_b32_e32 v229, v230
	v_pk_add_f32 v[150:151], v[150:151], 1.0 op_sel_hi:[1,0]
	v_rcp_f32_e32 v235, v151
	v_mov_b32_e32 v230, v234
	global_load_dwordx4 v[134:137], v[134:135], off offset:64
	v_rcp_f32_e32 v238, v150
	v_mov_b32_e32 v231, v235
	v_pk_add_f32 v[184:185], v[184:185], 1.0 op_sel_hi:[1,0]
	v_rcp_f32_e32 v235, v237
	v_mov_b32_e32 v186, v238
	v_mov_b32_e32 v187, v235
	global_load_dwordx4 v[232:235], v[182:183], off offset:64
	v_rcp_f32_e32 v239, v236
	v_mov_b32_e32 v237, v187
	v_rcp_f32_e32 v238, v185
	v_mov_b32_e32 v182, v239
	v_mov_b32_e32 v236, v182
	s_waitcnt vmcnt(3)
	v_pk_mul_f32 v[182:183], v[126:127], v[130:131]
	v_pk_add_f32 v[178:179], v[178:179], 1.0 op_sel_hi:[1,0]
	v_pk_add_f32 v[172:173], v[172:173], 1.0 op_sel_hi:[1,0]
	v_pk_add_f32 v[168:169], v[168:169], 1.0 op_sel_hi:[1,0]
	v_lshl_add_u64 v[154:155], v[142:143], 0, v[160:161]
	v_lshl_add_u64 v[160:161], s[52:53], 0, v[160:161]
	v_lshl_add_u64 v[160:161], v[160:161], 0, s[2:3]
	s_waitcnt vmcnt(2)
	v_pk_fma_f32 v[182:183], v[236:237], v[182:183], v[200:201]
	v_rcp_f32_e32 v236, v184
	v_mov_b32_e32 v187, v238
	v_mov_b32_e32 v185, v187
	v_lshl_add_u64 v[160:161], v[160:161], 0, v[0:1]
	v_mov_b32_e32 v187, v236
	v_pk_add_f32 v[200:201], v[180:181], 1.0 op_sel_hi:[1,0]
	v_mov_b32_e32 v184, v187
	v_rcp_f32_e32 v236, v201
	v_pk_mul_f32 v[180:181], v[128:129], v[132:133]
	v_lshl_add_u64 v[152:153], v[142:143], 0, v[158:159]
	v_pk_fma_f32 v[184:185], v[184:185], v[180:181], v[202:203]
	global_store_dwordx4 v[174:175], v[182:185], off
	v_lshl_add_u64 v[158:159], s[52:53], 0, v[158:159]
	v_lshl_add_u64 v[158:159], v[158:159], 0, s[2:3]
	v_rcp_f32_e32 v187, v200
	v_mov_b32_e32 v180, v236
	v_mov_b32_e32 v185, v180
	global_load_dwordx4 v[180:183], v[170:171], off
	v_mov_b32_e32 v184, v187
	v_rcp_f32_e32 v202, v179
	s_waitcnt vmcnt(3)
	v_pk_mul_f32 v[200:201], v[122:123], v[134:135]
	v_lshl_add_u64 v[158:159], v[158:159], 0, v[0:1]
	s_waitcnt vmcnt(2)
	v_pk_fma_f32 v[200:201], v[184:185], v[200:201], v[232:233]
	v_rcp_f32_e32 v203, v178
	v_mov_b32_e32 v184, v202
	v_mov_b32_e32 v179, v184
	v_mov_b32_e32 v150, v186
	v_mov_b32_e32 v184, v203
	v_mov_b32_e32 v178, v184
	v_pk_add_f32 v[184:185], v[176:177], 1.0 op_sel_hi:[1,0]
	v_pk_mul_f32 v[176:177], v[124:125], v[136:137]
	v_rcp_f32_e32 v232, v185
	v_pk_fma_f32 v[202:203], v[178:179], v[176:177], v[234:235]
	global_store_dwordx4 v[174:175], v[200:203], off offset:64
	v_mov_b32_e32 v174, v232
	v_mov_b32_e32 v179, v174
	global_load_dwordx4 v[174:177], v[170:171], off offset:64
	v_rcp_f32_e32 v187, v184
	v_pk_add_f32 v[234:235], v[156:157], 1.0 op_sel_hi:[1,0]
	v_mov_b32_e32 v151, v231
	v_mov_b32_e32 v170, v187
	v_rcp_f32_e32 v187, v173
	v_mov_b32_e32 v178, v170
	v_pk_mul_f32 v[170:171], v[110:111], v[130:131]
	v_rcp_f32_e32 v237, v234
	s_waitcnt vmcnt(2)
	v_pk_fma_f32 v[170:171], v[178:179], v[170:171], v[180:181]
	v_rcp_f32_e32 v181, v172
	v_mov_b32_e32 v178, v187
	v_mov_b32_e32 v173, v178
	v_mov_b32_e32 v178, v181
	v_rcp_f32_e32 v181, v169
	v_mov_b32_e32 v172, v178
	v_pk_mul_f32 v[178:179], v[112:113], v[132:133]
	v_pk_fma_f32 v[172:173], v[172:173], v[178:179], v[182:183]
	global_store_dwordx4 v[164:165], v[170:173], off
	v_rcp_f32_e32 v200, v235
	v_readlane_b32 s49, v254, 56
	v_rcp_f32_e32 v173, v168
	v_mov_b32_e32 v170, v181
	v_mov_b32_e32 v169, v170
	v_mov_b32_e32 v172, v173
	v_pk_add_f32 v[170:171], v[166:167], 1.0 op_sel_hi:[1,0]
	v_mov_b32_e32 v168, v172
	v_rcp_f32_e32 v178, v171
	v_pk_mul_f32 v[166:167], v[106:107], v[134:135]
	s_waitcnt vmcnt(1)
	v_pk_fma_f32 v[166:167], v[168:169], v[166:167], v[174:175]
	v_rcp_f32_e32 v173, v170
	v_mov_b32_e32 v168, v178
	v_mov_b32_e32 v169, v168
	v_mov_b32_e32 v168, v173
	v_pk_mul_f32 v[170:171], v[108:109], v[136:137]
	v_pk_fma_f32 v[168:169], v[168:169], v[170:171], v[176:177]
	global_store_dwordx4 v[164:165], v[166:169], off offset:64
	global_load_dwordx4 v[180:183], v[154:155], off
	v_mov_b32_e32 v187, v200
	global_load_dwordx4 v[200:203], v[154:155], off offset:64
	v_mul_f32_e32 v164, 0xbfb8aa3b, v88
	v_mov_b32_e32 v235, v187
	v_exp_f32_e32 v184, v164
	v_mul_f32_e32 v164, 0xbfb8aa3b, v89
	v_exp_f32_e32 v185, v164
	v_mov_b32_e32 v187, v237
	v_pk_add_f32 v[154:155], v[184:185], 1.0 op_sel_hi:[1,0]
	v_mov_b32_e32 v234, v187
	v_rcp_f32_e32 v237, v155
	v_pk_mul_f32 v[184:185], v[94:95], v[130:131]
	v_lshl_add_u64 v[174:175], v[160:161], 0, v[138:139]
	v_mul_f32_e32 v160, 0xbfb8aa3b, v82
	v_exp_f32_e32 v232, v160
	v_mul_f32_e32 v160, 0xbfb8aa3b, v83
	v_exp_f32_e32 v233, v160
	v_mul_f32_e32 v160, 0xbfb8aa3b, v84
	v_exp_f32_e32 v178, v160
	v_mul_f32_e32 v160, 0xbfb8aa3b, v85
	v_exp_f32_e32 v179, v160
	v_mul_f32_e32 v160, 0xbfb8aa3b, v70
	v_exp_f32_e32 v176, v160
	v_mul_f32_e32 v160, 0xbfb8aa3b, v71
	v_pk_add_f32 v[178:179], v[178:179], 1.0 op_sel_hi:[1,0]
	v_exp_f32_e32 v177, v160
	v_mul_f32_e32 v160, 0xbfb8aa3b, v72
	v_exp_f32_e32 v172, v160
	v_mul_f32_e32 v160, 0xbfb8aa3b, v73
	v_pk_add_f32 v[176:177], v[176:177], 1.0 op_sel_hi:[1,0]
	v_exp_f32_e32 v173, v160
	v_lshl_add_u64 v[166:167], v[158:159], 0, v[138:139]
	v_mul_f32_e32 v158, 0xbfb8aa3b, v66
	v_exp_f32_e32 v170, v158
	v_mul_f32_e32 v158, 0xbfb8aa3b, v67
	v_exp_f32_e32 v171, v158
	v_mul_f32_e32 v158, 0xbfb8aa3b, v68
	v_exp_f32_e32 v168, v158
	v_mul_f32_e32 v158, 0xbfb8aa3b, v69
	v_pk_add_f32 v[170:171], v[170:171], 1.0 op_sel_hi:[1,0]
	v_exp_f32_e32 v169, v158
	v_or_b32_e32 v158, 64, v140
	v_ashrrev_i32_e32 v159, 31, v158
	v_lshlrev_b64 v[164:165], 12, v[158:159]
	v_pk_add_f32 v[168:169], v[168:169], 1.0 op_sel_hi:[1,0]
	v_lshl_add_u64 v[158:159], v[142:143], 0, v[164:165]
	v_or_b32_e32 v160, 0x50, v140
	v_ashrrev_i32_e32 v161, 31, v160
	v_lshlrev_b64 v[160:161], 12, v[160:161]
	v_lshl_add_u64 v[156:157], v[142:143], 0, v[160:161]
	v_readlane_b32 s50, v254, 57
	v_readlane_b32 s51, v254, 58
	v_readlane_b32 s54, v254, 61
	v_readlane_b32 s55, v254, 62
	v_readlane_b32 s58, v255, 1
	v_readlane_b32 s59, v255, 2
	v_readlane_b32 s60, v255, 3
	v_readlane_b32 s61, v255, 4
	v_readlane_b32 s62, v255, 5
	v_readlane_b32 s63, v255, 6
	s_waitcnt vmcnt(1)
	v_pk_fma_f32 v[180:181], v[234:235], v[184:185], v[180:181]
	v_rcp_f32_e32 v234, v154
	v_mov_b32_e32 v184, v237
	v_mov_b32_e32 v155, v184
	v_mov_b32_e32 v184, v234
	v_mov_b32_e32 v154, v184
	v_pk_add_f32 v[184:185], v[232:233], 1.0 op_sel_hi:[1,0]
	v_pk_mul_f32 v[232:233], v[96:97], v[132:133]
	v_rcp_f32_e32 v234, v185
	v_pk_fma_f32 v[182:183], v[154:155], v[232:233], v[182:183]
	global_store_dwordx4 v[174:175], v[180:183], off
	v_rcp_f32_e32 v232, v184
	global_load_dwordx4 v[180:183], v[152:153], off
	v_mov_b32_e32 v154, v234
	v_mov_b32_e32 v155, v154
	v_mov_b32_e32 v154, v232
	v_rcp_f32_e32 v232, v179
	v_pk_mul_f32 v[184:185], v[90:91], v[134:135]
	s_waitcnt vmcnt(2)
	v_pk_fma_f32 v[200:201], v[154:155], v[184:185], v[200:201]
	v_rcp_f32_e32 v185, v178
	v_mov_b32_e32 v154, v232
	v_mov_b32_e32 v155, v154
	v_mov_b32_e32 v154, v185
	v_rcp_f32_e32 v185, v177
	v_pk_mul_f32 v[178:179], v[92:93], v[136:137]
	s_nop 0
	v_pk_fma_f32 v[202:203], v[154:155], v[178:179], v[202:203]
	global_store_dwordx4 v[174:175], v[200:203], off offset:64
	v_mov_b32_e32 v154, v185
	v_mov_b32_e32 v175, v154
	global_load_dwordx4 v[152:155], v[152:153], off offset:64
	v_rcp_f32_e32 v178, v176
	s_nop 0
	v_mov_b32_e32 v174, v178
	v_pk_add_f32 v[178:179], v[172:173], 1.0 op_sel_hi:[1,0]
	v_rcp_f32_e32 v184, v179
	v_pk_mul_f32 v[172:173], v[78:79], v[130:131]
	s_waitcnt vmcnt(2)
	v_pk_fma_f32 v[172:173], v[174:175], v[172:173], v[180:181]
	v_rcp_f32_e32 v177, v178
	v_mov_b32_e32 v174, v184
	v_mov_b32_e32 v175, v174
	v_mov_b32_e32 v174, v177
	v_rcp_f32_e32 v179, v171
	v_pk_mul_f32 v[176:177], v[80:81], v[132:133]
	s_nop 0
	v_pk_fma_f32 v[174:175], v[174:175], v[176:177], v[182:183]
	global_store_dwordx4 v[166:167], v[172:175], off
	s_nop 1
	v_rcp_f32_e32 v175, v170
	v_mov_b32_e32 v172, v179
	v_mov_b32_e32 v171, v172
	v_mov_b32_e32 v172, v175
	v_rcp_f32_e32 v175, v169
	v_mov_b32_e32 v170, v172
	v_pk_mul_f32 v[172:173], v[74:75], v[134:135]
	s_waitcnt vmcnt(1)
	v_pk_fma_f32 v[152:153], v[170:171], v[172:173], v[152:153]
	v_rcp_f32_e32 v173, v168
	v_mov_b32_e32 v170, v175
	v_mov_b32_e32 v169, v170
	v_mov_b32_e32 v170, v173
	v_mov_b32_e32 v168, v170
	v_pk_mul_f32 v[170:171], v[76:77], v[136:137]
	s_nop 0
	v_pk_fma_f32 v[154:155], v[168:169], v[170:171], v[154:155]
	global_store_dwordx4 v[166:167], v[152:155], off offset:64
	global_load_dwordx4 v[176:179], v[158:159], off
	s_nop 0
	v_mul_f32_e32 v152, 0xbfb8aa3b, v54
	v_mul_f32_e32 v153, 0xbfb8aa3b, v55
	v_exp_f32_e32 v152, v152
	v_exp_f32_e32 v153, v153
	v_mul_f32_e32 v154, 0xbfb8aa3b, v56
	v_exp_f32_e32 v184, v154
	v_mul_f32_e32 v154, 0xbfb8aa3b, v57
	v_pk_add_f32 v[202:203], v[152:153], 1.0 op_sel_hi:[1,0]
	v_exp_f32_e32 v185, v154
	v_rcp_f32_e32 v181, v203
	v_lshl_add_u64 v[154:155], s[52:53], 0, v[164:165]
	v_lshl_add_u64 v[154:155], v[154:155], 0, s[2:3]
	v_lshl_add_u64 v[154:155], v[154:155], 0, v[0:1]
	v_mov_b32_e32 v180, v181
	v_mov_b32_e32 v203, v180
	global_load_dwordx4 v[180:183], v[158:159], off offset:64
	v_rcp_f32_e32 v232, v202
	v_lshl_add_u64 v[170:171], v[154:155], 0, v[138:139]
	v_mov_b32_e32 v187, v232
	v_pk_add_f32 v[158:159], v[184:185], 1.0 op_sel_hi:[1,0]
	v_mov_b32_e32 v202, v187
	v_rcp_f32_e32 v233, v159
	v_pk_mul_f32 v[184:185], v[62:63], v[130:131]
	v_mul_f32_e32 v154, 0xbfb8aa3b, v50
	v_exp_f32_e32 v200, v154
	v_mul_f32_e32 v154, 0xbfb8aa3b, v51
	v_exp_f32_e32 v201, v154
	v_mul_f32_e32 v154, 0xbfb8aa3b, v52
	v_exp_f32_e32 v174, v154
	v_mul_f32_e32 v154, 0xbfb8aa3b, v53
	v_exp_f32_e32 v175, v154
	v_mul_f32_e32 v154, 0xbfb8aa3b, v34
	v_exp_f32_e32 v172, v154
	v_mul_f32_e32 v154, 0xbfb8aa3b, v35
	v_pk_add_f32 v[174:175], v[174:175], 1.0 op_sel_hi:[1,0]
	v_exp_f32_e32 v173, v154
	v_mul_f32_e32 v154, 0xbfb8aa3b, v36
	v_exp_f32_e32 v168, v154
	v_mul_f32_e32 v154, 0xbfb8aa3b, v37
	v_pk_add_f32 v[172:173], v[172:173], 1.0 op_sel_hi:[1,0]
	v_exp_f32_e32 v169, v154
	v_lshl_add_u64 v[154:155], s[52:53], 0, v[160:161]
	v_lshl_add_u64 v[154:155], v[154:155], 0, s[2:3]
	v_lshl_add_u64 v[154:155], v[154:155], 0, v[0:1]
	v_lshl_add_u64 v[160:161], v[154:155], 0, v[138:139]
	v_mul_f32_e32 v154, 0xbfb8aa3b, v30
	v_exp_f32_e32 v166, v154
	v_mul_f32_e32 v154, 0xbfb8aa3b, v31
	v_exp_f32_e32 v167, v154
	v_mul_f32_e32 v154, 0xbfb8aa3b, v32
	v_exp_f32_e32 v164, v154
	v_mul_f32_e32 v154, 0xbfb8aa3b, v33
	v_pk_add_f32 v[166:167], v[166:167], 1.0 op_sel_hi:[1,0]
	v_exp_f32_e32 v165, v154
	v_or_b32_e32 v154, 0x60, v140
	v_ashrrev_i32_e32 v155, 31, v154
	s_waitcnt vmcnt(1)
	v_pk_fma_f32 v[176:177], v[202:203], v[184:185], v[176:177]
	v_rcp_f32_e32 v202, v158
	v_mov_b32_e32 v184, v233
	v_mov_b32_e32 v159, v184
	v_mov_b32_e32 v184, v202
	v_mov_b32_e32 v158, v184
	v_pk_add_f32 v[184:185], v[200:201], 1.0 op_sel_hi:[1,0]
	v_pk_mul_f32 v[200:201], v[64:65], v[132:133]
	v_rcp_f32_e32 v202, v185
	v_pk_fma_f32 v[178:179], v[158:159], v[200:201], v[178:179]
	global_store_dwordx4 v[170:171], v[176:179], off
	v_pk_add_f32 v[164:165], v[164:165], 1.0 op_sel_hi:[1,0]
	v_rcp_f32_e32 v200, v184
	global_load_dwordx4 v[176:179], v[156:157], off
	v_mov_b32_e32 v158, v202
	v_mov_b32_e32 v159, v158
	v_mov_b32_e32 v158, v200
	v_rcp_f32_e32 v200, v175
	v_pk_mul_f32 v[184:185], v[58:59], v[134:135]
	v_lshlrev_b64 v[154:155], 12, v[154:155]
	s_waitcnt vmcnt(2)
	v_pk_fma_f32 v[180:181], v[158:159], v[184:185], v[180:181]
	v_rcp_f32_e32 v185, v174
	v_mov_b32_e32 v158, v200
	v_mov_b32_e32 v159, v158
	v_mov_b32_e32 v158, v185
	v_rcp_f32_e32 v185, v173
	v_pk_mul_f32 v[174:175], v[60:61], v[136:137]
	v_lshl_add_u64 v[152:153], v[142:143], 0, v[154:155]
	v_pk_fma_f32 v[182:183], v[158:159], v[174:175], v[182:183]
	global_store_dwordx4 v[170:171], v[180:183], off offset:64
	v_mov_b32_e32 v158, v185
	v_mov_b32_e32 v171, v158
	global_load_dwordx4 v[156:159], v[156:157], off offset:64
	v_rcp_f32_e32 v174, v172
	v_lshl_add_u64 v[154:155], s[52:53], 0, v[154:155]
	v_lshl_add_u64 v[154:155], v[154:155], 0, s[2:3]
	v_lshl_add_u64 v[154:155], v[154:155], 0, v[0:1]
	v_mov_b32_e32 v170, v174
	v_pk_add_f32 v[174:175], v[168:169], 1.0 op_sel_hi:[1,0]
	v_rcp_f32_e32 v180, v175
	v_pk_mul_f32 v[168:169], v[46:47], v[130:131]
	v_mov_b32_e32 v182, v230
	s_waitcnt vmcnt(2)
	v_pk_fma_f32 v[168:169], v[170:171], v[168:169], v[176:177]
	v_rcp_f32_e32 v173, v174
	v_mov_b32_e32 v170, v180
	v_mov_b32_e32 v171, v170
	v_mov_b32_e32 v183, v229
	v_mov_b32_e32 v170, v173
	v_rcp_f32_e32 v175, v167
	v_pk_mul_f32 v[172:173], v[48:49], v[132:133]
	v_lshl_add_u64 v[154:155], v[154:155], 0, v[138:139]
	v_pk_fma_f32 v[170:171], v[170:171], v[172:173], v[178:179]
	global_store_dwordx4 v[160:161], v[168:171], off
	v_mov_b32_e32 v178, v228
	v_mov_b32_e32 v179, v227
	v_rcp_f32_e32 v171, v166
	v_mov_b32_e32 v168, v175
	v_mov_b32_e32 v167, v168
	v_mov_b32_e32 v168, v171
	v_rcp_f32_e32 v171, v165
	v_mov_b32_e32 v166, v168
	v_pk_mul_f32 v[168:169], v[42:43], v[134:135]
	v_mov_b32_e32 v175, v141
	s_waitcnt vmcnt(1)
	v_pk_fma_f32 v[156:157], v[166:167], v[168:169], v[156:157]
	v_rcp_f32_e32 v169, v164
	v_mov_b32_e32 v166, v171
	v_mov_b32_e32 v165, v166
	v_mov_b32_e32 v166, v169
	v_mov_b32_e32 v164, v166
	v_pk_mul_f32 v[166:167], v[44:45], v[136:137]
	v_mov_b32_e32 v174, v226
	v_pk_fma_f32 v[158:159], v[164:165], v[166:167], v[158:159]
	global_store_dwordx4 v[160:161], v[156:159], off offset:64
	global_load_dwordx4 v[156:159], v[152:153], off
	v_or_b32_e32 v160, 0x70, v140
	v_mul_f32_e32 v140, 0xbfb8aa3b, v22
	v_exp_f32_e32 v164, v140
	v_mul_f32_e32 v140, 0xbfb8aa3b, v23
	v_exp_f32_e32 v165, v140
	v_ashrrev_i32_e32 v161, 31, v160
	v_lshlrev_b64 v[160:161], 12, v[160:161]
	v_lshl_add_u64 v[142:143], v[142:143], 0, v[160:161]
	v_lshl_add_u64 v[160:161], s[52:53], 0, v[160:161]
	v_lshl_add_u64 v[160:161], v[160:161], 0, s[2:3]
	v_pk_add_f32 v[164:165], v[164:165], 1.0 op_sel_hi:[1,0]
	v_lshl_add_u64 v[160:161], v[160:161], 0, v[0:1]
	v_rcp_f32_e32 v146, v165
	v_mul_f32_e32 v140, 0xbfb8aa3b, v24
	v_exp_f32_e32 v166, v140
	v_mul_f32_e32 v140, 0xbfb8aa3b, v25
	v_exp_f32_e32 v167, v140
	v_mul_f32_e32 v140, 0xbfb8aa3b, v18
	v_exp_f32_e32 v168, v140
	v_mul_f32_e32 v140, 0xbfb8aa3b, v19
	v_exp_f32_e32 v169, v140
	v_mul_f32_e32 v140, 0xbfb8aa3b, v20
	v_exp_f32_e32 v170, v140
	v_mul_f32_e32 v140, 0xbfb8aa3b, v21
	v_exp_f32_e32 v171, v140
	v_lshl_add_u64 v[160:161], v[160:161], 0, v[138:139]
	global_load_dwordx4 v[138:141], v[142:143], off
	s_nop 0
	global_load_dwordx4 v[142:145], v[142:143], off offset:64
	v_mov_b32_e32 v0, v146
	global_load_dwordx4 v[146:149], v[152:153], off offset:64
	v_rcp_f32_e32 v187, v164
	v_mov_b32_e32 v165, v0
	v_pk_mul_f32 v[172:173], v[14:15], v[130:131]
	v_pk_mul_f32 v[130:131], v[38:39], v[130:131]
	v_mov_b32_e32 v0, v187
	v_pk_add_f32 v[152:153], v[166:167], 1.0 op_sel_hi:[1,0]
	v_mov_b32_e32 v164, v0
	v_rcp_f32_e32 v167, v153
	v_pk_mul_f32 v[176:177], v[16:17], v[132:133]
	v_pk_mul_f32 v[132:133], v[40:41], v[132:133]
	v_pk_mul_f32 v[180:181], v[10:11], v[134:135]
	v_pk_mul_f32 v[134:135], v[26:27], v[134:135]
	v_pk_mul_f32 v[184:185], v[12:13], v[136:137]
	s_waitcnt vmcnt(3)
	v_pk_fma_f32 v[130:131], v[164:165], v[130:131], v[156:157]
	v_rcp_f32_e32 v164, v152
	v_mov_b32_e32 v0, v167
	v_mov_b32_e32 v153, v0
	v_mov_b32_e32 v0, v164
	v_pk_add_f32 v[156:157], v[168:169], 1.0 op_sel_hi:[1,0]
	v_mov_b32_e32 v152, v0
	v_rcp_f32_e32 v164, v157
	v_pk_fma_f32 v[132:133], v[152:153], v[132:133], v[158:159]
	global_store_dwordx4 v[154:155], v[130:133], off
	s_nop 1
	v_rcp_f32_e32 v132, v156
	v_mov_b32_e32 v0, v164
	v_mov_b32_e32 v131, v0
	v_mov_b32_e32 v0, v132
	v_pk_add_f32 v[132:133], v[170:171], 1.0 op_sel_hi:[1,0]
	v_mov_b32_e32 v130, v0
	v_rcp_f32_e32 v153, v133
	s_waitcnt vmcnt(1)
	v_pk_fma_f32 v[130:131], v[130:131], v[134:135], v[146:147]
	v_rcp_f32_e32 v146, v132
	v_mov_b32_e32 v0, v153
	v_mov_b32_e32 v133, v0
	v_mov_b32_e32 v0, v146
	v_mov_b32_e32 v132, v0
	v_pk_mul_f32 v[134:135], v[28:29], v[136:137]
	s_mov_b64 s[2:3], 0
	v_pk_fma_f32 v[132:133], v[132:133], v[134:135], v[148:149]
	global_store_dwordx4 v[154:155], v[130:133], off offset:64
	s_nop 1
	v_pk_fma_f32 v[130:131], v[174:175], v[172:173], v[138:139]
	v_pk_fma_f32 v[132:133], v[178:179], v[176:177], v[140:141]
	global_store_dwordx4 v[160:161], v[130:133], off
	s_nop 1
	v_pk_fma_f32 v[130:131], v[182:183], v[180:181], v[142:143]
	v_pk_fma_f32 v[132:133], v[150:151], v[184:185], v[144:145]
	global_store_dwordx4 v[160:161], v[130:133], off offset:64
